# MLA: next-tile QK MFMAs interleaved into softmax VALU stream (4-deep K frag ring); GEMM K-loops: removed compiler drain vmcnt(0) before ds_reads (84 sites)
# speedup vs baseline: 1.0194x; 1.0194x over previous
.LBB0_154:
	ds_read_b128 v[180:183], v163
	ds_read_b128 v[184:187], v164
	ds_read_b128 v[188:191], v165
	ds_read_b128 v[196:199], v167
	ds_read_b128 v[200:203], v168
	ds_read_b128 v[204:207], v169
	ds_read_b128 v[208:211], v170
	ds_read_b128 v[212:215], v171
	s_add_u32 s12, s10, 0xfffc0080
	s_addc_u32 s13, s11, -1
	s_cmp_eq_u32 s54, 12
	s_cselect_b32 s37, s5, s13
	s_cselect_b32 s36, s7, s12
	s_cselect_b32 s13, s27, s39
	s_cselect_b32 s12, s29, s38
	s_mov_b32 m0, s85
	v_lshl_add_u64 v[152:153], s[10:11], 0, v[138:139]
	ds_read_b128 v[216:219], v145
	ds_read_b128 v[220:223], v145 offset:1024
	ds_read_b128 v[224:227], v145 offset:2048
	ds_read_b128 v[228:231], v145 offset:3072
	ds_read_b128 v[232:235], v145 offset:4096
	ds_read_b128 v[236:239], v145 offset:5120
	ds_read_b128 v[240:243], v145 offset:6144
	ds_read_b128 v[244:247], v145 offset:7168
	global_load_lds_dwordx4 v[152:153], off
	v_lshl_add_u64 v[152:153], s[10:11], 0, v[140:141]
	s_mov_b32 m0, s86
	s_nop 0
	global_load_lds_dwordx4 v[152:153], off
	s_waitcnt vmcnt(8)
	s_waitcnt lgkmcnt(0)
	s_barrier
	s_setprio 1
	s_waitcnt lgkmcnt(0)
	v_mfma_f32_16x16x32_bf16 v[124:127], v[180:183], v[216:219], v[124:127]
	v_mfma_f32_16x16x32_bf16 v[120:123], v[188:191], v[216:219], v[120:123]
	v_mfma_f32_16x16x32_bf16 v[108:111], v[180:183], v[224:227], v[108:111]
	v_mfma_f32_16x16x32_bf16 v[104:107], v[188:191], v[224:227], v[104:107]
	v_mfma_f32_16x16x32_bf16 v[92:95], v[180:183], v[232:235], v[92:95]
	v_mfma_f32_16x16x32_bf16 v[88:91], v[188:191], v[232:235], v[88:91]
	v_mfma_f32_16x16x32_bf16 v[76:79], v[180:183], v[240:243], v[76:79]
	v_mfma_f32_16x16x32_bf16 v[72:75], v[188:191], v[240:243], v[72:75]
	v_mfma_f32_16x16x32_bf16 v[124:127], v[184:187], v[220:223], v[124:127]
	v_mfma_f32_16x16x32_bf16 v[120:123], v[196:199], v[220:223], v[120:123]
	v_mfma_f32_16x16x32_bf16 v[108:111], v[184:187], v[228:231], v[108:111]
	v_mfma_f32_16x16x32_bf16 v[104:107], v[196:199], v[228:231], v[104:107]
	v_mfma_f32_16x16x32_bf16 v[92:95], v[184:187], v[236:239], v[92:95]
	v_mfma_f32_16x16x32_bf16 v[88:91], v[196:199], v[236:239], v[88:91]
	v_mfma_f32_16x16x32_bf16 v[76:79], v[184:187], v[244:247], v[76:79]
	v_mfma_f32_16x16x32_bf16 v[72:75], v[196:199], v[244:247], v[72:75]
	s_setprio 0
	s_setprio 1
	v_mfma_f32_16x16x32_bf16 v[116:119], v[200:203], v[216:219], v[116:119]
	v_mfma_f32_16x16x32_bf16 v[112:115], v[208:211], v[216:219], v[112:115]
	v_mfma_f32_16x16x32_bf16 v[100:103], v[200:203], v[224:227], v[100:103]
	v_mfma_f32_16x16x32_bf16 v[96:99], v[208:211], v[224:227], v[96:99]
	v_mfma_f32_16x16x32_bf16 v[84:87], v[200:203], v[232:235], v[84:87]
	v_mfma_f32_16x16x32_bf16 v[80:83], v[208:211], v[232:235], v[80:83]
	v_mfma_f32_16x16x32_bf16 v[68:71], v[200:203], v[240:243], v[68:71]
	v_mfma_f32_16x16x32_bf16 v[64:67], v[208:211], v[240:243], v[64:67]
	v_mfma_f32_16x16x32_bf16 v[116:119], v[204:207], v[220:223], v[116:119]
	v_mfma_f32_16x16x32_bf16 v[112:115], v[212:215], v[220:223], v[112:115]
	v_mfma_f32_16x16x32_bf16 v[100:103], v[204:207], v[228:231], v[100:103]
	v_mfma_f32_16x16x32_bf16 v[96:99], v[212:215], v[228:231], v[96:99]
	v_mfma_f32_16x16x32_bf16 v[84:87], v[204:207], v[236:239], v[84:87]
	v_mfma_f32_16x16x32_bf16 v[80:83], v[212:215], v[236:239], v[80:83]
	v_mfma_f32_16x16x32_bf16 v[68:71], v[204:207], v[244:247], v[68:71]
	v_mfma_f32_16x16x32_bf16 v[64:67], v[212:215], v[244:247], v[64:67]
	s_setprio 0
	s_barrier
	s_mov_b32 m0, s25
	v_lshl_add_u64 v[152:153], s[12:13], 0, v[132:133]
	s_add_u32 s56, s12, 0x40000
	ds_read_b128 v[216:219], v145 offset:16384
	ds_read_b128 v[220:223], v145 offset:17408
	ds_read_b128 v[224:227], v145 offset:18432
	ds_read_b128 v[228:231], v145 offset:19456
	ds_read_b128 v[232:235], v145 offset:20480
	ds_read_b128 v[236:239], v145 offset:21504
	ds_read_b128 v[240:243], v145 offset:22528
	ds_read_b128 v[244:247], v145 offset:23552
	global_load_lds_dwordx4 v[152:153], off
	v_lshl_add_u64 v[156:157], s[12:13], 0, v[134:135]
	s_mov_b32 m0, s33
	s_addc_u32 s57, s13, 0
	global_load_lds_dwordx4 v[156:157], off
	v_lshl_add_u64 v[192:193], s[56:57], 0, v[132:133]
	s_mov_b32 m0, s62
	v_lshl_add_u64 v[248:249], s[36:37], 0, v[134:135]
	global_load_lds_dwordx4 v[192:193], off
	v_lshl_add_u64 v[192:193], s[56:57], 0, v[134:135]
	s_mov_b32 m0, s63
	s_nop 0
	global_load_lds_dwordx4 v[192:193], off
	v_lshl_add_u64 v[192:193], s[36:37], 0, v[132:133]
	s_mov_b32 m0, s2
	s_nop 0
	global_load_lds_dwordx4 v[192:193], off
	s_mov_b32 m0, s64
	s_nop 0
	global_load_lds_dwordx4 v[248:249], off
	s_waitcnt vmcnt(8)
	s_waitcnt lgkmcnt(0)
	s_barrier
	s_setprio 1
	s_waitcnt lgkmcnt(0)
	v_mfma_f32_16x16x32_bf16 v[60:63], v[180:183], v[216:219], v[60:63]
	v_mfma_f32_16x16x32_bf16 v[56:59], v[188:191], v[216:219], v[56:59]
	v_mfma_f32_16x16x32_bf16 v[44:47], v[180:183], v[224:227], v[44:47]
	v_mfma_f32_16x16x32_bf16 v[40:43], v[188:191], v[224:227], v[40:43]
	v_mfma_f32_16x16x32_bf16 v[28:31], v[180:183], v[232:235], v[28:31]
	v_mfma_f32_16x16x32_bf16 v[24:27], v[188:191], v[232:235], v[24:27]
	v_mfma_f32_16x16x32_bf16 v[12:15], v[180:183], v[240:243], v[12:15]
	v_mfma_f32_16x16x32_bf16 v[8:11], v[188:191], v[240:243], v[8:11]
	v_mfma_f32_16x16x32_bf16 v[60:63], v[184:187], v[220:223], v[60:63]
	v_mfma_f32_16x16x32_bf16 v[56:59], v[196:199], v[220:223], v[56:59]
	v_mfma_f32_16x16x32_bf16 v[44:47], v[184:187], v[228:231], v[44:47]
	v_mfma_f32_16x16x32_bf16 v[40:43], v[196:199], v[228:231], v[40:43]
	v_mfma_f32_16x16x32_bf16 v[28:31], v[184:187], v[236:239], v[28:31]
	v_mfma_f32_16x16x32_bf16 v[24:27], v[196:199], v[236:239], v[24:27]
	v_mfma_f32_16x16x32_bf16 v[12:15], v[184:187], v[244:247], v[12:15]
	v_mfma_f32_16x16x32_bf16 v[8:11], v[196:199], v[244:247], v[8:11]
	s_setprio 0
	s_setprio 1
	v_mfma_f32_16x16x32_bf16 v[52:55], v[200:203], v[216:219], v[52:55]
	v_mfma_f32_16x16x32_bf16 v[48:51], v[208:211], v[216:219], v[48:51]
	v_mfma_f32_16x16x32_bf16 v[36:39], v[200:203], v[224:227], v[36:39]
	v_mfma_f32_16x16x32_bf16 v[32:35], v[208:211], v[224:227], v[32:35]
	v_mfma_f32_16x16x32_bf16 v[20:23], v[200:203], v[232:235], v[20:23]
	v_mfma_f32_16x16x32_bf16 v[16:19], v[208:211], v[232:235], v[16:19]
	v_mfma_f32_16x16x32_bf16 v[4:7], v[200:203], v[240:243], v[4:7]
	v_mfma_f32_16x16x32_bf16 v[0:3], v[208:211], v[240:243], v[0:3]
	v_mfma_f32_16x16x32_bf16 v[52:55], v[204:207], v[220:223], v[52:55]
	v_mfma_f32_16x16x32_bf16 v[48:51], v[212:215], v[220:223], v[48:51]
	v_mfma_f32_16x16x32_bf16 v[36:39], v[204:207], v[228:231], v[36:39]
	v_mfma_f32_16x16x32_bf16 v[32:35], v[212:215], v[228:231], v[32:35]
	v_mfma_f32_16x16x32_bf16 v[20:23], v[204:207], v[236:239], v[20:23]
	v_mfma_f32_16x16x32_bf16 v[16:19], v[212:215], v[236:239], v[16:19]
	v_mfma_f32_16x16x32_bf16 v[4:7], v[204:207], v[244:247], v[4:7]
	v_mfma_f32_16x16x32_bf16 v[0:3], v[212:215], v[244:247], v[0:3]
	s_setprio 0
	s_barrier
	ds_read_b128 v[180:183], v172
	ds_read_b128 v[184:187], v173
	ds_read_b128 v[188:191], v174
	ds_read_b128 v[196:199], v175
	ds_read_b128 v[200:203], v176
	ds_read_b128 v[204:207], v177
	ds_read_b128 v[208:211], v178
	ds_read_b128 v[212:215], v179
	s_add_u32 s36, s36, 0x40000
	s_addc_u32 s37, s37, 0
	s_mov_b32 m0, s65
	v_lshl_add_u64 v[250:251], s[36:37], 0, v[132:133]
	ds_read_b128 v[216:219], v145 offset:32768
	ds_read_b128 v[220:223], v145 offset:33792
	ds_read_b128 v[224:227], v145 offset:34816
	ds_read_b128 v[228:231], v145 offset:35840
	ds_read_b128 v[232:235], v145 offset:36864
	ds_read_b128 v[236:239], v145 offset:37888
	ds_read_b128 v[240:243], v145 offset:38912
	ds_read_b128 v[244:247], v145 offset:39936
	global_load_lds_dwordx4 v[250:251], off
	v_lshl_add_u64 v[250:251], s[36:37], 0, v[134:135]
	s_mov_b32 m0, s66
	s_nop 0
	global_load_lds_dwordx4 v[250:251], off
	s_waitcnt vmcnt(8)
	s_waitcnt lgkmcnt(0)
	s_barrier
	s_setprio 1
	s_waitcnt lgkmcnt(0)
	v_mfma_f32_16x16x32_bf16 v[124:127], v[180:183], v[216:219], v[124:127]
	v_mfma_f32_16x16x32_bf16 v[120:123], v[188:191], v[216:219], v[120:123]
	v_mfma_f32_16x16x32_bf16 v[108:111], v[180:183], v[224:227], v[108:111]
	v_mfma_f32_16x16x32_bf16 v[104:107], v[188:191], v[224:227], v[104:107]
	v_mfma_f32_16x16x32_bf16 v[92:95], v[180:183], v[232:235], v[92:95]
	v_mfma_f32_16x16x32_bf16 v[88:91], v[188:191], v[232:235], v[88:91]
	v_mfma_f32_16x16x32_bf16 v[76:79], v[180:183], v[240:243], v[76:79]
	v_mfma_f32_16x16x32_bf16 v[72:75], v[188:191], v[240:243], v[72:75]
	v_mfma_f32_16x16x32_bf16 v[124:127], v[184:187], v[220:223], v[124:127]
	v_mfma_f32_16x16x32_bf16 v[120:123], v[196:199], v[220:223], v[120:123]
	v_mfma_f32_16x16x32_bf16 v[108:111], v[184:187], v[228:231], v[108:111]
	v_mfma_f32_16x16x32_bf16 v[104:107], v[196:199], v[228:231], v[104:107]
	v_mfma_f32_16x16x32_bf16 v[92:95], v[184:187], v[236:239], v[92:95]
	v_mfma_f32_16x16x32_bf16 v[88:91], v[196:199], v[236:239], v[88:91]
	v_mfma_f32_16x16x32_bf16 v[76:79], v[184:187], v[244:247], v[76:79]
	v_mfma_f32_16x16x32_bf16 v[72:75], v[196:199], v[244:247], v[72:75]
	s_setprio 0
	s_setprio 1
	v_mfma_f32_16x16x32_bf16 v[116:119], v[200:203], v[216:219], v[116:119]
	v_mfma_f32_16x16x32_bf16 v[112:115], v[208:211], v[216:219], v[112:115]
	v_mfma_f32_16x16x32_bf16 v[100:103], v[200:203], v[224:227], v[100:103]
	v_mfma_f32_16x16x32_bf16 v[96:99], v[208:211], v[224:227], v[96:99]
	v_mfma_f32_16x16x32_bf16 v[84:87], v[200:203], v[232:235], v[84:87]
	v_mfma_f32_16x16x32_bf16 v[80:83], v[208:211], v[232:235], v[80:83]
	v_mfma_f32_16x16x32_bf16 v[68:71], v[200:203], v[240:243], v[68:71]
	v_mfma_f32_16x16x32_bf16 v[64:67], v[208:211], v[240:243], v[64:67]
	v_mfma_f32_16x16x32_bf16 v[116:119], v[204:207], v[220:223], v[116:119]
	v_mfma_f32_16x16x32_bf16 v[112:115], v[212:215], v[220:223], v[112:115]
	v_mfma_f32_16x16x32_bf16 v[100:103], v[204:207], v[228:231], v[100:103]
	v_mfma_f32_16x16x32_bf16 v[96:99], v[212:215], v[228:231], v[96:99]
	v_mfma_f32_16x16x32_bf16 v[84:87], v[204:207], v[236:239], v[84:87]
	v_mfma_f32_16x16x32_bf16 v[80:83], v[212:215], v[236:239], v[80:83]
	v_mfma_f32_16x16x32_bf16 v[68:71], v[204:207], v[244:247], v[68:71]
	v_mfma_f32_16x16x32_bf16 v[64:67], v[212:215], v[244:247], v[64:67]
	s_setprio 0
	s_barrier
	s_mov_b32 m0, s67
	v_lshl_add_u64 v[152:153], v[152:153], 0, s[20:21]
	s_add_u32 s12, s12, 0x40080
	ds_read_b128 v[216:219], v145 offset:49152
	ds_read_b128 v[220:223], v145 offset:50176
	ds_read_b128 v[224:227], v145 offset:51200
	ds_read_b128 v[228:231], v145 offset:52224
	ds_read_b128 v[232:235], v145 offset:53248
	ds_read_b128 v[236:239], v145 offset:54272
	ds_read_b128 v[240:243], v145 offset:55296
	ds_read_b128 v[244:247], v145 offset:56320
	global_load_lds_dwordx4 v[152:153], off
	v_lshl_add_u64 v[152:153], v[156:157], 0, s[20:21]
	s_mov_b32 m0, s72
	s_addc_u32 s13, s13, 0
	global_load_lds_dwordx4 v[152:153], off
	v_lshl_add_u64 v[152:153], s[12:13], 0, v[132:133]
	s_mov_b32 m0, s75
	s_nop 0
	global_load_lds_dwordx4 v[152:153], off
	v_lshl_add_u64 v[152:153], s[12:13], 0, v[134:135]
	s_mov_b32 m0, s78
	s_nop 0
	global_load_lds_dwordx4 v[152:153], off
	v_lshl_add_u64 v[152:153], v[192:193], 0, s[20:21]
	s_mov_b32 m0, s73
	s_nop 0
	global_load_lds_dwordx4 v[152:153], off
	v_lshl_add_u64 v[152:153], v[248:249], 0, s[20:21]
	s_mov_b32 m0, s74
	s_nop 0
	global_load_lds_dwordx4 v[152:153], off
	s_waitcnt vmcnt(8)
	s_waitcnt lgkmcnt(0)
	s_barrier
	s_setprio 1
	s_waitcnt lgkmcnt(0)
	v_mfma_f32_16x16x32_bf16 v[60:63], v[180:183], v[216:219], v[60:63]
	v_mfma_f32_16x16x32_bf16 v[56:59], v[188:191], v[216:219], v[56:59]
	v_mfma_f32_16x16x32_bf16 v[44:47], v[180:183], v[224:227], v[44:47]
	v_mfma_f32_16x16x32_bf16 v[40:43], v[188:191], v[224:227], v[40:43]
	v_mfma_f32_16x16x32_bf16 v[28:31], v[180:183], v[232:235], v[28:31]
	v_mfma_f32_16x16x32_bf16 v[24:27], v[188:191], v[232:235], v[24:27]
	v_mfma_f32_16x16x32_bf16 v[12:15], v[180:183], v[240:243], v[12:15]
	v_mfma_f32_16x16x32_bf16 v[8:11], v[188:191], v[240:243], v[8:11]
	v_mfma_f32_16x16x32_bf16 v[60:63], v[184:187], v[220:223], v[60:63]
	v_mfma_f32_16x16x32_bf16 v[56:59], v[196:199], v[220:223], v[56:59]
	v_mfma_f32_16x16x32_bf16 v[44:47], v[184:187], v[228:231], v[44:47]
	v_mfma_f32_16x16x32_bf16 v[40:43], v[196:199], v[228:231], v[40:43]
	v_mfma_f32_16x16x32_bf16 v[28:31], v[184:187], v[236:239], v[28:31]
	v_mfma_f32_16x16x32_bf16 v[24:27], v[196:199], v[236:239], v[24:27]
	v_mfma_f32_16x16x32_bf16 v[12:15], v[184:187], v[244:247], v[12:15]
	v_mfma_f32_16x16x32_bf16 v[8:11], v[196:199], v[244:247], v[8:11]
	s_setprio 0
	s_setprio 1
	v_mfma_f32_16x16x32_bf16 v[52:55], v[200:203], v[216:219], v[52:55]
	v_mfma_f32_16x16x32_bf16 v[48:51], v[208:211], v[216:219], v[48:51]
	v_mfma_f32_16x16x32_bf16 v[36:39], v[200:203], v[224:227], v[36:39]
	v_mfma_f32_16x16x32_bf16 v[32:35], v[208:211], v[224:227], v[32:35]
	v_mfma_f32_16x16x32_bf16 v[20:23], v[200:203], v[232:235], v[20:23]
	v_mfma_f32_16x16x32_bf16 v[16:19], v[208:211], v[232:235], v[16:19]
	v_mfma_f32_16x16x32_bf16 v[4:7], v[200:203], v[240:243], v[4:7]
	v_mfma_f32_16x16x32_bf16 v[0:3], v[208:211], v[240:243], v[0:3]
	v_mfma_f32_16x16x32_bf16 v[52:55], v[204:207], v[220:223], v[52:55]
	v_mfma_f32_16x16x32_bf16 v[48:51], v[212:215], v[220:223], v[48:51]
	v_mfma_f32_16x16x32_bf16 v[36:39], v[204:207], v[228:231], v[36:39]
	v_mfma_f32_16x16x32_bf16 v[32:35], v[212:215], v[228:231], v[32:35]
	v_mfma_f32_16x16x32_bf16 v[20:23], v[204:207], v[236:239], v[20:23]
	v_mfma_f32_16x16x32_bf16 v[16:19], v[212:215], v[236:239], v[16:19]
	v_mfma_f32_16x16x32_bf16 v[4:7], v[204:207], v[244:247], v[4:7]
	v_mfma_f32_16x16x32_bf16 v[0:3], v[212:215], v[244:247], v[0:3]
	s_setprio 0
	s_barrier
	s_add_i32 s54, s54, 2
	s_add_u32 s10, s10, 0x100
	s_addc_u32 s11, s11, 0
	s_add_u32 s38, s38, 0x100
	s_addc_u32 s39, s39, 0
	s_cmp_gt_u32 s54, 13
	s_cbranch_scc0 .LBB0_154
	s_and_b64 vcc, exec, s[22:23]
	s_cbranch_vccz .LBB0_157
	s_barrier

.LBB0_251:
	ds_read_b128 v[160:163], v165
	ds_read_b128 v[182:185], v167
	ds_read_b128 v[186:189], v168
	ds_read_b128 v[190:193], v169
	ds_read_b128 v[196:199], v170
	ds_read_b128 v[200:203], v171
	ds_read_b128 v[204:207], v172
	ds_read_b128 v[208:211], v173
	s_add_u32 s14, s12, 0xfffc0080
	s_addc_u32 s15, s13, -1
	s_cmp_eq_u32 s54, 12
	s_cselect_b32 s29, s7, s15
	s_cselect_b32 s28, s11, s14
	s_cselect_b32 s15, s21, s39
	s_cselect_b32 s14, s23, s38
	s_mov_b32 m0, s82
	v_lshl_add_u64 v[152:153], s[12:13], 0, v[138:139]
	ds_read_b128 v[212:215], v145
	ds_read_b128 v[216:219], v145 offset:1024
	ds_read_b128 v[220:223], v145 offset:2048
	ds_read_b128 v[224:227], v145 offset:3072
	ds_read_b128 v[228:231], v145 offset:4096
	ds_read_b128 v[232:235], v145 offset:5120
	ds_read_b128 v[236:239], v145 offset:6144
	ds_read_b128 v[240:243], v145 offset:7168
	global_load_lds_dwordx4 v[152:153], off
	v_lshl_add_u64 v[152:153], s[12:13], 0, v[140:141]
	s_mov_b32 m0, s83
	s_nop 0
	global_load_lds_dwordx4 v[152:153], off
	s_waitcnt vmcnt(8)
	s_waitcnt lgkmcnt(0)
	s_barrier
	s_setprio 1
	s_waitcnt lgkmcnt(0)
	v_mfma_f32_16x16x32_bf16 v[124:127], v[160:163], v[212:215], v[124:127]
	v_mfma_f32_16x16x32_bf16 v[120:123], v[186:189], v[212:215], v[120:123]
	v_mfma_f32_16x16x32_bf16 v[108:111], v[160:163], v[220:223], v[108:111]
	v_mfma_f32_16x16x32_bf16 v[104:107], v[186:189], v[220:223], v[104:107]
	v_mfma_f32_16x16x32_bf16 v[92:95], v[160:163], v[228:231], v[92:95]
	v_mfma_f32_16x16x32_bf16 v[88:91], v[186:189], v[228:231], v[88:91]
	v_mfma_f32_16x16x32_bf16 v[76:79], v[160:163], v[236:239], v[76:79]
	v_mfma_f32_16x16x32_bf16 v[72:75], v[186:189], v[236:239], v[72:75]
	v_mfma_f32_16x16x32_bf16 v[124:127], v[182:185], v[216:219], v[124:127]
	v_mfma_f32_16x16x32_bf16 v[120:123], v[190:193], v[216:219], v[120:123]
	v_mfma_f32_16x16x32_bf16 v[108:111], v[182:185], v[224:227], v[108:111]
	v_mfma_f32_16x16x32_bf16 v[104:107], v[190:193], v[224:227], v[104:107]
	v_mfma_f32_16x16x32_bf16 v[92:95], v[182:185], v[232:235], v[92:95]
	v_mfma_f32_16x16x32_bf16 v[88:91], v[190:193], v[232:235], v[88:91]
	v_mfma_f32_16x16x32_bf16 v[76:79], v[182:185], v[240:243], v[76:79]
	v_mfma_f32_16x16x32_bf16 v[72:75], v[190:193], v[240:243], v[72:75]
	s_setprio 0
	s_setprio 1
	v_mfma_f32_16x16x32_bf16 v[116:119], v[196:199], v[212:215], v[116:119]
	v_mfma_f32_16x16x32_bf16 v[112:115], v[204:207], v[212:215], v[112:115]
	v_mfma_f32_16x16x32_bf16 v[100:103], v[196:199], v[220:223], v[100:103]
	v_mfma_f32_16x16x32_bf16 v[96:99], v[204:207], v[220:223], v[96:99]
	v_mfma_f32_16x16x32_bf16 v[84:87], v[196:199], v[228:231], v[84:87]
	v_mfma_f32_16x16x32_bf16 v[80:83], v[204:207], v[228:231], v[80:83]
	v_mfma_f32_16x16x32_bf16 v[68:71], v[196:199], v[236:239], v[68:71]
	v_mfma_f32_16x16x32_bf16 v[64:67], v[204:207], v[236:239], v[64:67]
	v_mfma_f32_16x16x32_bf16 v[116:119], v[200:203], v[216:219], v[116:119]
	v_mfma_f32_16x16x32_bf16 v[112:115], v[208:211], v[216:219], v[112:115]
	v_mfma_f32_16x16x32_bf16 v[100:103], v[200:203], v[224:227], v[100:103]
	v_mfma_f32_16x16x32_bf16 v[96:99], v[208:211], v[224:227], v[96:99]
	v_mfma_f32_16x16x32_bf16 v[84:87], v[200:203], v[232:235], v[84:87]
	v_mfma_f32_16x16x32_bf16 v[80:83], v[208:211], v[232:235], v[80:83]
	v_mfma_f32_16x16x32_bf16 v[68:71], v[200:203], v[240:243], v[68:71]
	v_mfma_f32_16x16x32_bf16 v[64:67], v[208:211], v[240:243], v[64:67]
	s_setprio 0
	s_barrier
	s_mov_b32 m0, s33
	v_lshl_add_u64 v[152:153], s[14:15], 0, v[132:133]
	s_add_u32 s56, s14, 0x40000
	ds_read_b128 v[212:215], v145 offset:16384
	ds_read_b128 v[216:219], v145 offset:17408
	ds_read_b128 v[220:223], v145 offset:18432
	ds_read_b128 v[224:227], v145 offset:19456
	ds_read_b128 v[228:231], v145 offset:20480
	ds_read_b128 v[232:235], v145 offset:21504
	ds_read_b128 v[236:239], v145 offset:22528
	ds_read_b128 v[240:243], v145 offset:23552
	global_load_lds_dwordx4 v[152:153], off
	v_lshl_add_u64 v[244:245], s[14:15], 0, v[134:135]
	s_mov_b32 m0, s34
	s_addc_u32 s57, s15, 0
	global_load_lds_dwordx4 v[244:245], off
	v_lshl_add_u64 v[246:247], s[56:57], 0, v[132:133]
	s_mov_b32 m0, s35
	v_lshl_add_u64 v[248:249], s[28:29], 0, v[134:135]
	global_load_lds_dwordx4 v[246:247], off
	v_lshl_add_u64 v[246:247], s[56:57], 0, v[134:135]
	s_mov_b32 m0, s36
	s_nop 0
	global_load_lds_dwordx4 v[246:247], off
	v_lshl_add_u64 v[246:247], s[28:29], 0, v[132:133]
	s_mov_b32 m0, s31
	s_nop 0
	global_load_lds_dwordx4 v[246:247], off
	s_mov_b32 m0, s37
	s_nop 0
	global_load_lds_dwordx4 v[248:249], off
	s_waitcnt vmcnt(8)
	s_waitcnt lgkmcnt(0)
	s_barrier
	s_setprio 1
	s_waitcnt lgkmcnt(0)
	v_mfma_f32_16x16x32_bf16 v[60:63], v[160:163], v[212:215], v[60:63]
	v_mfma_f32_16x16x32_bf16 v[56:59], v[186:189], v[212:215], v[56:59]
	v_mfma_f32_16x16x32_bf16 v[44:47], v[160:163], v[220:223], v[44:47]
	v_mfma_f32_16x16x32_bf16 v[40:43], v[186:189], v[220:223], v[40:43]
	v_mfma_f32_16x16x32_bf16 v[28:31], v[160:163], v[228:231], v[28:31]
	v_mfma_f32_16x16x32_bf16 v[24:27], v[186:189], v[228:231], v[24:27]
	v_mfma_f32_16x16x32_bf16 v[12:15], v[160:163], v[236:239], v[12:15]
	v_mfma_f32_16x16x32_bf16 v[8:11], v[186:189], v[236:239], v[8:11]
	v_mfma_f32_16x16x32_bf16 v[60:63], v[182:185], v[216:219], v[60:63]
	v_mfma_f32_16x16x32_bf16 v[56:59], v[190:193], v[216:219], v[56:59]
	v_mfma_f32_16x16x32_bf16 v[44:47], v[182:185], v[224:227], v[44:47]
	v_mfma_f32_16x16x32_bf16 v[40:43], v[190:193], v[224:227], v[40:43]
	v_mfma_f32_16x16x32_bf16 v[28:31], v[182:185], v[232:235], v[28:31]
	v_mfma_f32_16x16x32_bf16 v[24:27], v[190:193], v[232:235], v[24:27]
	v_mfma_f32_16x16x32_bf16 v[12:15], v[182:185], v[240:243], v[12:15]
	v_mfma_f32_16x16x32_bf16 v[8:11], v[190:193], v[240:243], v[8:11]
	s_setprio 0
	s_setprio 1
	v_mfma_f32_16x16x32_bf16 v[52:55], v[196:199], v[212:215], v[52:55]
	v_mfma_f32_16x16x32_bf16 v[48:51], v[204:207], v[212:215], v[48:51]
	v_mfma_f32_16x16x32_bf16 v[36:39], v[196:199], v[220:223], v[36:39]
	v_mfma_f32_16x16x32_bf16 v[32:35], v[204:207], v[220:223], v[32:35]
	v_mfma_f32_16x16x32_bf16 v[20:23], v[196:199], v[228:231], v[20:23]
	v_mfma_f32_16x16x32_bf16 v[16:19], v[204:207], v[228:231], v[16:19]
	v_mfma_f32_16x16x32_bf16 v[4:7], v[196:199], v[236:239], v[4:7]
	v_mfma_f32_16x16x32_bf16 v[0:3], v[204:207], v[236:239], v[0:3]
	v_mfma_f32_16x16x32_bf16 v[52:55], v[200:203], v[216:219], v[52:55]
	v_mfma_f32_16x16x32_bf16 v[48:51], v[208:211], v[216:219], v[48:51]
	v_mfma_f32_16x16x32_bf16 v[36:39], v[200:203], v[224:227], v[36:39]
	v_mfma_f32_16x16x32_bf16 v[32:35], v[208:211], v[224:227], v[32:35]
	v_mfma_f32_16x16x32_bf16 v[20:23], v[200:203], v[232:235], v[20:23]
	v_mfma_f32_16x16x32_bf16 v[16:19], v[208:211], v[232:235], v[16:19]
	v_mfma_f32_16x16x32_bf16 v[4:7], v[200:203], v[240:243], v[4:7]
	v_mfma_f32_16x16x32_bf16 v[0:3], v[208:211], v[240:243], v[0:3]
	s_setprio 0
	s_barrier
	ds_read_b128 v[160:163], v174
	ds_read_b128 v[182:185], v175
	ds_read_b128 v[186:189], v176
	ds_read_b128 v[190:193], v177
	ds_read_b128 v[196:199], v178
	ds_read_b128 v[200:203], v179
	ds_read_b128 v[204:207], v180
	ds_read_b128 v[208:211], v181
	s_add_u32 s28, s28, 0x40000
	s_addc_u32 s29, s29, 0
	s_mov_b32 m0, s62
	v_lshl_add_u64 v[250:251], s[28:29], 0, v[132:133]
	ds_read_b128 v[212:215], v145 offset:32768
	ds_read_b128 v[216:219], v145 offset:33792
	ds_read_b128 v[220:223], v145 offset:34816
	ds_read_b128 v[224:227], v145 offset:35840
	ds_read_b128 v[228:231], v145 offset:36864
	ds_read_b128 v[232:235], v145 offset:37888
	ds_read_b128 v[236:239], v145 offset:38912
	ds_read_b128 v[240:243], v145 offset:39936
	global_load_lds_dwordx4 v[250:251], off
	v_lshl_add_u64 v[250:251], s[28:29], 0, v[134:135]
	s_mov_b32 m0, s63
	s_nop 0
	global_load_lds_dwordx4 v[250:251], off
	s_waitcnt vmcnt(8)
	s_waitcnt lgkmcnt(0)
	s_barrier
	s_setprio 1
	s_waitcnt lgkmcnt(0)
	v_mfma_f32_16x16x32_bf16 v[124:127], v[160:163], v[212:215], v[124:127]
	v_mfma_f32_16x16x32_bf16 v[120:123], v[186:189], v[212:215], v[120:123]
	v_mfma_f32_16x16x32_bf16 v[108:111], v[160:163], v[220:223], v[108:111]
	v_mfma_f32_16x16x32_bf16 v[104:107], v[186:189], v[220:223], v[104:107]
	v_mfma_f32_16x16x32_bf16 v[92:95], v[160:163], v[228:231], v[92:95]
	v_mfma_f32_16x16x32_bf16 v[88:91], v[186:189], v[228:231], v[88:91]
	v_mfma_f32_16x16x32_bf16 v[76:79], v[160:163], v[236:239], v[76:79]
	v_mfma_f32_16x16x32_bf16 v[72:75], v[186:189], v[236:239], v[72:75]
	v_mfma_f32_16x16x32_bf16 v[124:127], v[182:185], v[216:219], v[124:127]
	v_mfma_f32_16x16x32_bf16 v[120:123], v[190:193], v[216:219], v[120:123]
	v_mfma_f32_16x16x32_bf16 v[108:111], v[182:185], v[224:227], v[108:111]
	v_mfma_f32_16x16x32_bf16 v[104:107], v[190:193], v[224:227], v[104:107]
	v_mfma_f32_16x16x32_bf16 v[92:95], v[182:185], v[232:235], v[92:95]
	v_mfma_f32_16x16x32_bf16 v[88:91], v[190:193], v[232:235], v[88:91]
	v_mfma_f32_16x16x32_bf16 v[76:79], v[182:185], v[240:243], v[76:79]
	v_mfma_f32_16x16x32_bf16 v[72:75], v[190:193], v[240:243], v[72:75]
	s_setprio 0
	s_setprio 1
	v_mfma_f32_16x16x32_bf16 v[116:119], v[196:199], v[212:215], v[116:119]
	v_mfma_f32_16x16x32_bf16 v[112:115], v[204:207], v[212:215], v[112:115]
	v_mfma_f32_16x16x32_bf16 v[100:103], v[196:199], v[220:223], v[100:103]
	v_mfma_f32_16x16x32_bf16 v[96:99], v[204:207], v[220:223], v[96:99]
	v_mfma_f32_16x16x32_bf16 v[84:87], v[196:199], v[228:231], v[84:87]
	v_mfma_f32_16x16x32_bf16 v[80:83], v[204:207], v[228:231], v[80:83]
	v_mfma_f32_16x16x32_bf16 v[68:71], v[196:199], v[236:239], v[68:71]
	v_mfma_f32_16x16x32_bf16 v[64:67], v[204:207], v[236:239], v[64:67]
	v_mfma_f32_16x16x32_bf16 v[116:119], v[200:203], v[216:219], v[116:119]
	v_mfma_f32_16x16x32_bf16 v[112:115], v[208:211], v[216:219], v[112:115]
	v_mfma_f32_16x16x32_bf16 v[100:103], v[200:203], v[224:227], v[100:103]
	v_mfma_f32_16x16x32_bf16 v[96:99], v[208:211], v[224:227], v[96:99]
	v_mfma_f32_16x16x32_bf16 v[84:87], v[200:203], v[232:235], v[84:87]
	v_mfma_f32_16x16x32_bf16 v[80:83], v[208:211], v[232:235], v[80:83]
	v_mfma_f32_16x16x32_bf16 v[68:71], v[200:203], v[240:243], v[68:71]
	v_mfma_f32_16x16x32_bf16 v[64:67], v[208:211], v[240:243], v[64:67]
	s_setprio 0
	s_barrier
	s_mov_b32 m0, s64
	v_lshl_add_u64 v[152:153], v[152:153], 0, s[16:17]
	s_add_u32 s14, s14, 0x40080
	ds_read_b128 v[212:215], v145 offset:49152
	ds_read_b128 v[216:219], v145 offset:50176
	ds_read_b128 v[220:223], v145 offset:51200
	ds_read_b128 v[224:227], v145 offset:52224
	ds_read_b128 v[228:231], v145 offset:53248
	ds_read_b128 v[232:235], v145 offset:54272
	ds_read_b128 v[236:239], v145 offset:55296
	ds_read_b128 v[240:243], v145 offset:56320
	global_load_lds_dwordx4 v[152:153], off
	v_lshl_add_u64 v[152:153], v[244:245], 0, s[16:17]
	s_mov_b32 m0, s65
	s_addc_u32 s15, s15, 0
	global_load_lds_dwordx4 v[152:153], off
	v_lshl_add_u64 v[152:153], s[14:15], 0, v[132:133]
	s_mov_b32 m0, s72
	s_nop 0
	global_load_lds_dwordx4 v[152:153], off
	v_lshl_add_u64 v[152:153], s[14:15], 0, v[134:135]
	s_mov_b32 m0, s73
	s_nop 0
	global_load_lds_dwordx4 v[152:153], off
	v_lshl_add_u64 v[152:153], v[246:247], 0, s[16:17]
	s_mov_b32 m0, s66
	s_nop 0
	global_load_lds_dwordx4 v[152:153], off
	v_lshl_add_u64 v[152:153], v[248:249], 0, s[16:17]
	s_mov_b32 m0, s67
	s_nop 0
	global_load_lds_dwordx4 v[152:153], off
	s_waitcnt vmcnt(8)
	s_waitcnt lgkmcnt(0)
	s_barrier
	s_setprio 1
	s_waitcnt lgkmcnt(0)
	v_mfma_f32_16x16x32_bf16 v[60:63], v[160:163], v[212:215], v[60:63]
	v_mfma_f32_16x16x32_bf16 v[56:59], v[186:189], v[212:215], v[56:59]
	v_mfma_f32_16x16x32_bf16 v[44:47], v[160:163], v[220:223], v[44:47]
	v_mfma_f32_16x16x32_bf16 v[40:43], v[186:189], v[220:223], v[40:43]
	v_mfma_f32_16x16x32_bf16 v[28:31], v[160:163], v[228:231], v[28:31]
	v_mfma_f32_16x16x32_bf16 v[24:27], v[186:189], v[228:231], v[24:27]
	v_mfma_f32_16x16x32_bf16 v[12:15], v[160:163], v[236:239], v[12:15]
	v_mfma_f32_16x16x32_bf16 v[8:11], v[186:189], v[236:239], v[8:11]
	v_mfma_f32_16x16x32_bf16 v[60:63], v[182:185], v[216:219], v[60:63]
	v_mfma_f32_16x16x32_bf16 v[56:59], v[190:193], v[216:219], v[56:59]
	v_mfma_f32_16x16x32_bf16 v[44:47], v[182:185], v[224:227], v[44:47]
	v_mfma_f32_16x16x32_bf16 v[40:43], v[190:193], v[224:227], v[40:43]
	v_mfma_f32_16x16x32_bf16 v[28:31], v[182:185], v[232:235], v[28:31]
	v_mfma_f32_16x16x32_bf16 v[24:27], v[190:193], v[232:235], v[24:27]
	v_mfma_f32_16x16x32_bf16 v[12:15], v[182:185], v[240:243], v[12:15]
	v_mfma_f32_16x16x32_bf16 v[8:11], v[190:193], v[240:243], v[8:11]
	s_setprio 0
	s_setprio 1
	v_mfma_f32_16x16x32_bf16 v[52:55], v[196:199], v[212:215], v[52:55]
	v_mfma_f32_16x16x32_bf16 v[48:51], v[204:207], v[212:215], v[48:51]
	v_mfma_f32_16x16x32_bf16 v[36:39], v[196:199], v[220:223], v[36:39]
	v_mfma_f32_16x16x32_bf16 v[32:35], v[204:207], v[220:223], v[32:35]
	v_mfma_f32_16x16x32_bf16 v[20:23], v[196:199], v[228:231], v[20:23]
	v_mfma_f32_16x16x32_bf16 v[16:19], v[204:207], v[228:231], v[16:19]
	v_mfma_f32_16x16x32_bf16 v[4:7], v[196:199], v[236:239], v[4:7]
	v_mfma_f32_16x16x32_bf16 v[0:3], v[204:207], v[236:239], v[0:3]
	v_mfma_f32_16x16x32_bf16 v[52:55], v[200:203], v[216:219], v[52:55]
	v_mfma_f32_16x16x32_bf16 v[48:51], v[208:211], v[216:219], v[48:51]
	v_mfma_f32_16x16x32_bf16 v[36:39], v[200:203], v[224:227], v[36:39]
	v_mfma_f32_16x16x32_bf16 v[32:35], v[208:211], v[224:227], v[32:35]
	v_mfma_f32_16x16x32_bf16 v[20:23], v[200:203], v[232:235], v[20:23]
	v_mfma_f32_16x16x32_bf16 v[16:19], v[208:211], v[232:235], v[16:19]
	v_mfma_f32_16x16x32_bf16 v[4:7], v[200:203], v[240:243], v[4:7]
	v_mfma_f32_16x16x32_bf16 v[0:3], v[208:211], v[240:243], v[0:3]
	s_setprio 0
	s_barrier
	s_add_i32 s54, s54, 2
	s_add_u32 s12, s12, 0x100
	s_addc_u32 s13, s13, 0
	s_add_u32 s38, s38, 0x100
	s_addc_u32 s39, s39, 0
	s_cmp_gt_u32 s54, 13
	s_cbranch_scc0 .LBB0_251
	s_and_b64 vcc, exec, s[18:19]
	s_cbranch_vccz .LBB0_254
	s_barrier

.LBB0_586:
	ds_read_b128 v[160:163], v165
	ds_read_b128 v[182:185], v167
	ds_read_b128 v[186:189], v168
	ds_read_b128 v[190:193], v169
	ds_read_b128 v[196:199], v170
	ds_read_b128 v[200:203], v171
	ds_read_b128 v[204:207], v172
	ds_read_b128 v[208:211], v173
	s_add_u32 s12, s10, 0xfffc0080
	s_addc_u32 s13, s11, -1
	s_cmp_eq_u32 s54, 12
	s_cselect_b32 s15, s7, s13
	s_cselect_b32 s14, s9, s12
	s_cselect_b32 s13, s21, s39
	s_cselect_b32 s12, s23, s38
	s_mov_b32 m0, s82
	v_lshl_add_u64 v[152:153], s[10:11], 0, v[138:139]
	ds_read_b128 v[212:215], v145
	ds_read_b128 v[216:219], v145 offset:1024
	ds_read_b128 v[220:223], v145 offset:2048
	ds_read_b128 v[224:227], v145 offset:3072
	ds_read_b128 v[228:231], v145 offset:4096
	ds_read_b128 v[232:235], v145 offset:5120
	ds_read_b128 v[236:239], v145 offset:6144
	ds_read_b128 v[240:243], v145 offset:7168
	global_load_lds_dwordx4 v[152:153], off
	v_lshl_add_u64 v[152:153], s[10:11], 0, v[140:141]
	s_mov_b32 m0, s83
	s_nop 0
	global_load_lds_dwordx4 v[152:153], off
	s_waitcnt vmcnt(8)
	s_waitcnt lgkmcnt(0)
	s_barrier
	s_setprio 1
	s_waitcnt lgkmcnt(0)
	v_mfma_f32_16x16x32_bf16 v[124:127], v[160:163], v[212:215], v[124:127]
	v_mfma_f32_16x16x32_bf16 v[120:123], v[186:189], v[212:215], v[120:123]
	v_mfma_f32_16x16x32_bf16 v[108:111], v[160:163], v[220:223], v[108:111]
	v_mfma_f32_16x16x32_bf16 v[104:107], v[186:189], v[220:223], v[104:107]
	v_mfma_f32_16x16x32_bf16 v[92:95], v[160:163], v[228:231], v[92:95]
	v_mfma_f32_16x16x32_bf16 v[88:91], v[186:189], v[228:231], v[88:91]
	v_mfma_f32_16x16x32_bf16 v[76:79], v[160:163], v[236:239], v[76:79]
	v_mfma_f32_16x16x32_bf16 v[72:75], v[186:189], v[236:239], v[72:75]
	v_mfma_f32_16x16x32_bf16 v[124:127], v[182:185], v[216:219], v[124:127]
	v_mfma_f32_16x16x32_bf16 v[120:123], v[190:193], v[216:219], v[120:123]
	v_mfma_f32_16x16x32_bf16 v[108:111], v[182:185], v[224:227], v[108:111]
	v_mfma_f32_16x16x32_bf16 v[104:107], v[190:193], v[224:227], v[104:107]
	v_mfma_f32_16x16x32_bf16 v[92:95], v[182:185], v[232:235], v[92:95]
	v_mfma_f32_16x16x32_bf16 v[88:91], v[190:193], v[232:235], v[88:91]
	v_mfma_f32_16x16x32_bf16 v[76:79], v[182:185], v[240:243], v[76:79]
	v_mfma_f32_16x16x32_bf16 v[72:75], v[190:193], v[240:243], v[72:75]
	s_setprio 0
	s_setprio 1
	v_mfma_f32_16x16x32_bf16 v[116:119], v[196:199], v[212:215], v[116:119]
	v_mfma_f32_16x16x32_bf16 v[112:115], v[204:207], v[212:215], v[112:115]
	v_mfma_f32_16x16x32_bf16 v[100:103], v[196:199], v[220:223], v[100:103]
	v_mfma_f32_16x16x32_bf16 v[96:99], v[204:207], v[220:223], v[96:99]
	v_mfma_f32_16x16x32_bf16 v[84:87], v[196:199], v[228:231], v[84:87]
	v_mfma_f32_16x16x32_bf16 v[80:83], v[204:207], v[228:231], v[80:83]
	v_mfma_f32_16x16x32_bf16 v[68:71], v[196:199], v[236:239], v[68:71]
	v_mfma_f32_16x16x32_bf16 v[64:67], v[204:207], v[236:239], v[64:67]
	v_mfma_f32_16x16x32_bf16 v[116:119], v[200:203], v[216:219], v[116:119]
	v_mfma_f32_16x16x32_bf16 v[112:115], v[208:211], v[216:219], v[112:115]
	v_mfma_f32_16x16x32_bf16 v[100:103], v[200:203], v[224:227], v[100:103]
	v_mfma_f32_16x16x32_bf16 v[96:99], v[208:211], v[224:227], v[96:99]
	v_mfma_f32_16x16x32_bf16 v[84:87], v[200:203], v[232:235], v[84:87]
	v_mfma_f32_16x16x32_bf16 v[80:83], v[208:211], v[232:235], v[80:83]
	v_mfma_f32_16x16x32_bf16 v[68:71], v[200:203], v[240:243], v[68:71]
	v_mfma_f32_16x16x32_bf16 v[64:67], v[208:211], v[240:243], v[64:67]
	s_setprio 0
	s_barrier
	s_mov_b32 m0, s30
	v_lshl_add_u64 v[152:153], s[12:13], 0, v[132:133]
	s_add_u32 s56, s12, 0x40000
	ds_read_b128 v[212:215], v145 offset:16384
	ds_read_b128 v[216:219], v145 offset:17408
	ds_read_b128 v[220:223], v145 offset:18432
	ds_read_b128 v[224:227], v145 offset:19456
	ds_read_b128 v[228:231], v145 offset:20480
	ds_read_b128 v[232:235], v145 offset:21504
	ds_read_b128 v[236:239], v145 offset:22528
	ds_read_b128 v[240:243], v145 offset:23552
	global_load_lds_dwordx4 v[152:153], off
	v_lshl_add_u64 v[244:245], s[12:13], 0, v[134:135]
	s_mov_b32 m0, s31
	s_addc_u32 s57, s13, 0
	global_load_lds_dwordx4 v[244:245], off
	v_lshl_add_u64 v[246:247], s[56:57], 0, v[132:133]
	s_mov_b32 m0, s33
	v_lshl_add_u64 v[248:249], s[14:15], 0, v[134:135]
	global_load_lds_dwordx4 v[246:247], off
	v_lshl_add_u64 v[246:247], s[56:57], 0, v[134:135]
	s_mov_b32 m0, s34
	s_nop 0
	global_load_lds_dwordx4 v[246:247], off
	v_lshl_add_u64 v[246:247], s[14:15], 0, v[132:133]
	s_mov_b32 m0, s29
	s_nop 0
	global_load_lds_dwordx4 v[246:247], off
	s_mov_b32 m0, s35
	s_nop 0
	global_load_lds_dwordx4 v[248:249], off
	s_waitcnt vmcnt(8)
	s_waitcnt lgkmcnt(0)
	s_barrier
	s_setprio 1
	s_waitcnt lgkmcnt(0)
	v_mfma_f32_16x16x32_bf16 v[60:63], v[160:163], v[212:215], v[60:63]
	v_mfma_f32_16x16x32_bf16 v[56:59], v[186:189], v[212:215], v[56:59]
	v_mfma_f32_16x16x32_bf16 v[44:47], v[160:163], v[220:223], v[44:47]
	v_mfma_f32_16x16x32_bf16 v[40:43], v[186:189], v[220:223], v[40:43]
	v_mfma_f32_16x16x32_bf16 v[28:31], v[160:163], v[228:231], v[28:31]
	v_mfma_f32_16x16x32_bf16 v[24:27], v[186:189], v[228:231], v[24:27]
	v_mfma_f32_16x16x32_bf16 v[12:15], v[160:163], v[236:239], v[12:15]
	v_mfma_f32_16x16x32_bf16 v[8:11], v[186:189], v[236:239], v[8:11]
	v_mfma_f32_16x16x32_bf16 v[60:63], v[182:185], v[216:219], v[60:63]
	v_mfma_f32_16x16x32_bf16 v[56:59], v[190:193], v[216:219], v[56:59]
	v_mfma_f32_16x16x32_bf16 v[44:47], v[182:185], v[224:227], v[44:47]
	v_mfma_f32_16x16x32_bf16 v[40:43], v[190:193], v[224:227], v[40:43]
	v_mfma_f32_16x16x32_bf16 v[28:31], v[182:185], v[232:235], v[28:31]
	v_mfma_f32_16x16x32_bf16 v[24:27], v[190:193], v[232:235], v[24:27]
	v_mfma_f32_16x16x32_bf16 v[12:15], v[182:185], v[240:243], v[12:15]
	v_mfma_f32_16x16x32_bf16 v[8:11], v[190:193], v[240:243], v[8:11]
	s_setprio 0
	s_setprio 1
	v_mfma_f32_16x16x32_bf16 v[52:55], v[196:199], v[212:215], v[52:55]
	v_mfma_f32_16x16x32_bf16 v[48:51], v[204:207], v[212:215], v[48:51]
	v_mfma_f32_16x16x32_bf16 v[36:39], v[196:199], v[220:223], v[36:39]
	v_mfma_f32_16x16x32_bf16 v[32:35], v[204:207], v[220:223], v[32:35]
	v_mfma_f32_16x16x32_bf16 v[20:23], v[196:199], v[228:231], v[20:23]
	v_mfma_f32_16x16x32_bf16 v[16:19], v[204:207], v[228:231], v[16:19]
	v_mfma_f32_16x16x32_bf16 v[4:7], v[196:199], v[236:239], v[4:7]
	v_mfma_f32_16x16x32_bf16 v[0:3], v[204:207], v[236:239], v[0:3]
	v_mfma_f32_16x16x32_bf16 v[52:55], v[200:203], v[216:219], v[52:55]
	v_mfma_f32_16x16x32_bf16 v[48:51], v[208:211], v[216:219], v[48:51]
	v_mfma_f32_16x16x32_bf16 v[36:39], v[200:203], v[224:227], v[36:39]
	v_mfma_f32_16x16x32_bf16 v[32:35], v[208:211], v[224:227], v[32:35]
	v_mfma_f32_16x16x32_bf16 v[20:23], v[200:203], v[232:235], v[20:23]
	v_mfma_f32_16x16x32_bf16 v[16:19], v[208:211], v[232:235], v[16:19]
	v_mfma_f32_16x16x32_bf16 v[4:7], v[200:203], v[240:243], v[4:7]
	v_mfma_f32_16x16x32_bf16 v[0:3], v[208:211], v[240:243], v[0:3]
	s_setprio 0
	s_barrier
	ds_read_b128 v[160:163], v174
	ds_read_b128 v[182:185], v175
	ds_read_b128 v[186:189], v176
	ds_read_b128 v[190:193], v177
	ds_read_b128 v[196:199], v178
	ds_read_b128 v[200:203], v179
	ds_read_b128 v[204:207], v180
	ds_read_b128 v[208:211], v181
	s_add_u32 s14, s14, 0x40000
	s_addc_u32 s15, s15, 0
	s_mov_b32 m0, s36
	v_lshl_add_u64 v[250:251], s[14:15], 0, v[132:133]
	ds_read_b128 v[212:215], v145 offset:32768
	ds_read_b128 v[216:219], v145 offset:33792
	ds_read_b128 v[220:223], v145 offset:34816
	ds_read_b128 v[224:227], v145 offset:35840
	ds_read_b128 v[228:231], v145 offset:36864
	ds_read_b128 v[232:235], v145 offset:37888
	ds_read_b128 v[236:239], v145 offset:38912
	ds_read_b128 v[240:243], v145 offset:39936
	global_load_lds_dwordx4 v[250:251], off
	v_lshl_add_u64 v[250:251], s[14:15], 0, v[134:135]
	s_mov_b32 m0, s37
	s_nop 0
	global_load_lds_dwordx4 v[250:251], off
	s_waitcnt vmcnt(8)
	s_waitcnt lgkmcnt(0)
	s_barrier
	s_setprio 1
	s_waitcnt lgkmcnt(0)
	v_mfma_f32_16x16x32_bf16 v[124:127], v[160:163], v[212:215], v[124:127]
	v_mfma_f32_16x16x32_bf16 v[120:123], v[186:189], v[212:215], v[120:123]
	v_mfma_f32_16x16x32_bf16 v[108:111], v[160:163], v[220:223], v[108:111]
	v_mfma_f32_16x16x32_bf16 v[104:107], v[186:189], v[220:223], v[104:107]
	v_mfma_f32_16x16x32_bf16 v[92:95], v[160:163], v[228:231], v[92:95]
	v_mfma_f32_16x16x32_bf16 v[88:91], v[186:189], v[228:231], v[88:91]
	v_mfma_f32_16x16x32_bf16 v[76:79], v[160:163], v[236:239], v[76:79]
	v_mfma_f32_16x16x32_bf16 v[72:75], v[186:189], v[236:239], v[72:75]
	v_mfma_f32_16x16x32_bf16 v[124:127], v[182:185], v[216:219], v[124:127]
	v_mfma_f32_16x16x32_bf16 v[120:123], v[190:193], v[216:219], v[120:123]
	v_mfma_f32_16x16x32_bf16 v[108:111], v[182:185], v[224:227], v[108:111]
	v_mfma_f32_16x16x32_bf16 v[104:107], v[190:193], v[224:227], v[104:107]
	v_mfma_f32_16x16x32_bf16 v[92:95], v[182:185], v[232:235], v[92:95]
	v_mfma_f32_16x16x32_bf16 v[88:91], v[190:193], v[232:235], v[88:91]
	v_mfma_f32_16x16x32_bf16 v[76:79], v[182:185], v[240:243], v[76:79]
	v_mfma_f32_16x16x32_bf16 v[72:75], v[190:193], v[240:243], v[72:75]
	s_setprio 0
	s_setprio 1
	v_mfma_f32_16x16x32_bf16 v[116:119], v[196:199], v[212:215], v[116:119]
	v_mfma_f32_16x16x32_bf16 v[112:115], v[204:207], v[212:215], v[112:115]
	v_mfma_f32_16x16x32_bf16 v[100:103], v[196:199], v[220:223], v[100:103]
	v_mfma_f32_16x16x32_bf16 v[96:99], v[204:207], v[220:223], v[96:99]
	v_mfma_f32_16x16x32_bf16 v[84:87], v[196:199], v[228:231], v[84:87]
	v_mfma_f32_16x16x32_bf16 v[80:83], v[204:207], v[228:231], v[80:83]
	v_mfma_f32_16x16x32_bf16 v[68:71], v[196:199], v[236:239], v[68:71]
	v_mfma_f32_16x16x32_bf16 v[64:67], v[204:207], v[236:239], v[64:67]
	v_mfma_f32_16x16x32_bf16 v[116:119], v[200:203], v[216:219], v[116:119]
	v_mfma_f32_16x16x32_bf16 v[112:115], v[208:211], v[216:219], v[112:115]
	v_mfma_f32_16x16x32_bf16 v[100:103], v[200:203], v[224:227], v[100:103]
	v_mfma_f32_16x16x32_bf16 v[96:99], v[208:211], v[224:227], v[96:99]
	v_mfma_f32_16x16x32_bf16 v[84:87], v[200:203], v[232:235], v[84:87]
	v_mfma_f32_16x16x32_bf16 v[80:83], v[208:211], v[232:235], v[80:83]
	v_mfma_f32_16x16x32_bf16 v[68:71], v[200:203], v[240:243], v[68:71]
	v_mfma_f32_16x16x32_bf16 v[64:67], v[208:211], v[240:243], v[64:67]
	s_setprio 0
	s_barrier
	s_mov_b32 m0, s64
	v_lshl_add_u64 v[152:153], v[152:153], 0, s[16:17]
	s_add_u32 s12, s12, 0x40080
	ds_read_b128 v[212:215], v145 offset:49152
	ds_read_b128 v[216:219], v145 offset:50176
	ds_read_b128 v[220:223], v145 offset:51200
	ds_read_b128 v[224:227], v145 offset:52224
	ds_read_b128 v[228:231], v145 offset:53248
	ds_read_b128 v[232:235], v145 offset:54272
	ds_read_b128 v[236:239], v145 offset:55296
	ds_read_b128 v[240:243], v145 offset:56320
	global_load_lds_dwordx4 v[152:153], off
	v_lshl_add_u64 v[152:153], v[244:245], 0, s[16:17]
	s_mov_b32 m0, s65
	s_addc_u32 s13, s13, 0
	global_load_lds_dwordx4 v[152:153], off
	v_lshl_add_u64 v[152:153], s[12:13], 0, v[132:133]
	s_mov_b32 m0, s72
	s_nop 0
	global_load_lds_dwordx4 v[152:153], off
	v_lshl_add_u64 v[152:153], s[12:13], 0, v[134:135]
	s_mov_b32 m0, s73
	s_nop 0
	global_load_lds_dwordx4 v[152:153], off
	v_lshl_add_u64 v[152:153], v[246:247], 0, s[16:17]
	s_mov_b32 m0, s66
	s_nop 0
	global_load_lds_dwordx4 v[152:153], off
	v_lshl_add_u64 v[152:153], v[248:249], 0, s[16:17]
	s_mov_b32 m0, s67
	s_nop 0
	global_load_lds_dwordx4 v[152:153], off
	s_waitcnt vmcnt(8)
	s_waitcnt lgkmcnt(0)
	s_barrier
	s_setprio 1
	s_waitcnt lgkmcnt(0)
	v_mfma_f32_16x16x32_bf16 v[60:63], v[160:163], v[212:215], v[60:63]
	v_mfma_f32_16x16x32_bf16 v[56:59], v[186:189], v[212:215], v[56:59]
	v_mfma_f32_16x16x32_bf16 v[44:47], v[160:163], v[220:223], v[44:47]
	v_mfma_f32_16x16x32_bf16 v[40:43], v[186:189], v[220:223], v[40:43]
	v_mfma_f32_16x16x32_bf16 v[28:31], v[160:163], v[228:231], v[28:31]
	v_mfma_f32_16x16x32_bf16 v[24:27], v[186:189], v[228:231], v[24:27]
	v_mfma_f32_16x16x32_bf16 v[12:15], v[160:163], v[236:239], v[12:15]
	v_mfma_f32_16x16x32_bf16 v[8:11], v[186:189], v[236:239], v[8:11]
	v_mfma_f32_16x16x32_bf16 v[60:63], v[182:185], v[216:219], v[60:63]
	v_mfma_f32_16x16x32_bf16 v[56:59], v[190:193], v[216:219], v[56:59]
	v_mfma_f32_16x16x32_bf16 v[44:47], v[182:185], v[224:227], v[44:47]
	v_mfma_f32_16x16x32_bf16 v[40:43], v[190:193], v[224:227], v[40:43]
	v_mfma_f32_16x16x32_bf16 v[28:31], v[182:185], v[232:235], v[28:31]
	v_mfma_f32_16x16x32_bf16 v[24:27], v[190:193], v[232:235], v[24:27]
	v_mfma_f32_16x16x32_bf16 v[12:15], v[182:185], v[240:243], v[12:15]
	v_mfma_f32_16x16x32_bf16 v[8:11], v[190:193], v[240:243], v[8:11]
	s_setprio 0
	s_setprio 1
	v_mfma_f32_16x16x32_bf16 v[52:55], v[196:199], v[212:215], v[52:55]
	v_mfma_f32_16x16x32_bf16 v[48:51], v[204:207], v[212:215], v[48:51]
	v_mfma_f32_16x16x32_bf16 v[36:39], v[196:199], v[220:223], v[36:39]
	v_mfma_f32_16x16x32_bf16 v[32:35], v[204:207], v[220:223], v[32:35]
	v_mfma_f32_16x16x32_bf16 v[20:23], v[196:199], v[228:231], v[20:23]
	v_mfma_f32_16x16x32_bf16 v[16:19], v[204:207], v[228:231], v[16:19]
	v_mfma_f32_16x16x32_bf16 v[4:7], v[196:199], v[236:239], v[4:7]
	v_mfma_f32_16x16x32_bf16 v[0:3], v[204:207], v[236:239], v[0:3]
	v_mfma_f32_16x16x32_bf16 v[52:55], v[200:203], v[216:219], v[52:55]
	v_mfma_f32_16x16x32_bf16 v[48:51], v[208:211], v[216:219], v[48:51]
	v_mfma_f32_16x16x32_bf16 v[36:39], v[200:203], v[224:227], v[36:39]
	v_mfma_f32_16x16x32_bf16 v[32:35], v[208:211], v[224:227], v[32:35]
	v_mfma_f32_16x16x32_bf16 v[20:23], v[200:203], v[232:235], v[20:23]
	v_mfma_f32_16x16x32_bf16 v[16:19], v[208:211], v[232:235], v[16:19]
	v_mfma_f32_16x16x32_bf16 v[4:7], v[200:203], v[240:243], v[4:7]
	v_mfma_f32_16x16x32_bf16 v[0:3], v[208:211], v[240:243], v[0:3]
	s_setprio 0
	s_barrier
	s_add_i32 s54, s54, 2
	s_add_u32 s10, s10, 0x100
	s_addc_u32 s11, s11, 0
	s_add_u32 s38, s38, 0x100
	s_addc_u32 s39, s39, 0
	s_cmp_gt_u32 s54, 13
	s_cbranch_scc0 .LBB0_586
	s_and_b64 vcc, exec, s[18:19]
	s_cbranch_vccz .LBB0_589
	s_barrier

.LBB0_856:
	ds_read_b128 v[178:181], v160
	ds_read_b128 v[182:185], v161
	ds_read_b128 v[186:189], v162
	ds_read_b128 v[190:193], v163
	ds_read_b128 v[198:201], v164
	ds_read_b128 v[202:205], v165
	ds_read_b128 v[206:209], v167
	ds_read_b128 v[210:213], v168
	s_add_u32 s28, s10, 0x100
	s_addc_u32 s29, s11, 0
	s_cmp_eq_u32 s56, 28
	s_cselect_b32 s35, s4, s29
	s_cselect_b32 s34, s5, s28
	s_cselect_b32 s31, s21, vcc_hi
	s_cselect_b32 s30, s23, vcc_lo
	s_mov_b32 m0, s55
	v_lshl_add_u64 v[142:143], s[10:11], 0, v[136:137]
	ds_read_b128 v[214:217], v152
	ds_read_b128 v[218:221], v152 offset:1024
	ds_read_b128 v[222:225], v152 offset:2048
	ds_read_b128 v[226:229], v152 offset:3072
	ds_read_b128 v[230:233], v152 offset:4096
	ds_read_b128 v[234:237], v152 offset:5120
	ds_read_b128 v[238:241], v152 offset:6144
	ds_read_b128 v[242:245], v152 offset:7168
	global_load_lds_dwordx4 v[142:143], off
	v_lshl_add_u64 v[142:143], s[10:11], 0, v[138:139]
	s_mov_b32 m0, s36
	s_nop 0
	global_load_lds_dwordx4 v[142:143], off
	s_waitcnt vmcnt(8)
	s_waitcnt lgkmcnt(0)
	s_barrier
	s_setprio 1
	s_waitcnt lgkmcnt(0)
	v_mfma_f32_16x16x32_bf16 v[124:127], v[178:181], v[214:217], v[124:127]
	v_mfma_f32_16x16x32_bf16 v[120:123], v[186:189], v[214:217], v[120:123]
	v_mfma_f32_16x16x32_bf16 v[108:111], v[178:181], v[222:225], v[108:111]
	v_mfma_f32_16x16x32_bf16 v[104:107], v[186:189], v[222:225], v[104:107]
	v_mfma_f32_16x16x32_bf16 v[92:95], v[178:181], v[230:233], v[92:95]
	v_mfma_f32_16x16x32_bf16 v[88:91], v[186:189], v[230:233], v[88:91]
	v_mfma_f32_16x16x32_bf16 v[76:79], v[178:181], v[238:241], v[76:79]
	v_mfma_f32_16x16x32_bf16 v[72:75], v[186:189], v[238:241], v[72:75]
	v_mfma_f32_16x16x32_bf16 v[124:127], v[182:185], v[218:221], v[124:127]
	v_mfma_f32_16x16x32_bf16 v[120:123], v[190:193], v[218:221], v[120:123]
	v_mfma_f32_16x16x32_bf16 v[108:111], v[182:185], v[226:229], v[108:111]
	v_mfma_f32_16x16x32_bf16 v[104:107], v[190:193], v[226:229], v[104:107]
	v_mfma_f32_16x16x32_bf16 v[92:95], v[182:185], v[234:237], v[92:95]
	v_mfma_f32_16x16x32_bf16 v[88:91], v[190:193], v[234:237], v[88:91]
	v_mfma_f32_16x16x32_bf16 v[76:79], v[182:185], v[242:245], v[76:79]
	v_mfma_f32_16x16x32_bf16 v[72:75], v[190:193], v[242:245], v[72:75]
	s_setprio 0
	s_setprio 1
	v_mfma_f32_16x16x32_bf16 v[116:119], v[198:201], v[214:217], v[116:119]
	v_mfma_f32_16x16x32_bf16 v[112:115], v[206:209], v[214:217], v[112:115]
	v_mfma_f32_16x16x32_bf16 v[100:103], v[198:201], v[222:225], v[100:103]
	v_mfma_f32_16x16x32_bf16 v[96:99], v[206:209], v[222:225], v[96:99]
	v_mfma_f32_16x16x32_bf16 v[84:87], v[198:201], v[230:233], v[84:87]
	v_mfma_f32_16x16x32_bf16 v[80:83], v[206:209], v[230:233], v[80:83]
	v_mfma_f32_16x16x32_bf16 v[68:71], v[198:201], v[238:241], v[68:71]
	v_mfma_f32_16x16x32_bf16 v[64:67], v[206:209], v[238:241], v[64:67]
	v_mfma_f32_16x16x32_bf16 v[116:119], v[202:205], v[218:221], v[116:119]
	v_mfma_f32_16x16x32_bf16 v[112:115], v[210:213], v[218:221], v[112:115]
	v_mfma_f32_16x16x32_bf16 v[100:103], v[202:205], v[226:229], v[100:103]
	v_mfma_f32_16x16x32_bf16 v[96:99], v[210:213], v[226:229], v[96:99]
	v_mfma_f32_16x16x32_bf16 v[84:87], v[202:205], v[234:237], v[84:87]
	v_mfma_f32_16x16x32_bf16 v[80:83], v[210:213], v[234:237], v[80:83]
	v_mfma_f32_16x16x32_bf16 v[68:71], v[202:205], v[242:245], v[68:71]
	v_mfma_f32_16x16x32_bf16 v[64:67], v[210:213], v[242:245], v[64:67]
	s_setprio 0
	s_barrier
	s_mov_b32 m0, s37
	v_lshl_add_u64 v[142:143], s[30:31], 0, v[132:133]
	s_add_u32 s10, s30, 0x80000
	ds_read_b128 v[214:217], v152 offset:16384
	ds_read_b128 v[218:221], v152 offset:17408
	ds_read_b128 v[222:225], v152 offset:18432
	ds_read_b128 v[226:229], v152 offset:19456
	ds_read_b128 v[230:233], v152 offset:20480
	ds_read_b128 v[234:237], v152 offset:21504
	ds_read_b128 v[238:241], v152 offset:22528
	ds_read_b128 v[242:245], v152 offset:23552
	global_load_lds_dwordx4 v[142:143], off
	v_lshl_add_u64 v[246:247], s[30:31], 0, v[134:135]
	s_mov_b32 m0, s41
	s_addc_u32 s11, s31, 0
	global_load_lds_dwordx4 v[246:247], off
	v_lshl_add_u64 v[248:249], s[10:11], 0, v[132:133]
	s_mov_b32 m0, s42
	v_lshl_add_u64 v[250:251], s[34:35], 0, v[134:135]
	global_load_lds_dwordx4 v[248:249], off
	v_lshl_add_u64 v[248:249], s[10:11], 0, v[134:135]
	s_mov_b32 m0, s43
	s_nop 0
	global_load_lds_dwordx4 v[248:249], off
	v_lshl_add_u64 v[248:249], s[34:35], 0, v[132:133]
	s_mov_b32 m0, s40
	s_nop 0
	global_load_lds_dwordx4 v[248:249], off
	s_mov_b32 m0, s72
	s_nop 0
	global_load_lds_dwordx4 v[250:251], off
	s_waitcnt vmcnt(8)
	s_waitcnt lgkmcnt(0)
	s_barrier
	s_setprio 1
	s_waitcnt lgkmcnt(0)
	v_mfma_f32_16x16x32_bf16 v[60:63], v[178:181], v[214:217], v[60:63]
	v_mfma_f32_16x16x32_bf16 v[56:59], v[186:189], v[214:217], v[56:59]
	v_mfma_f32_16x16x32_bf16 v[44:47], v[178:181], v[222:225], v[44:47]
	v_mfma_f32_16x16x32_bf16 v[40:43], v[186:189], v[222:225], v[40:43]
	v_mfma_f32_16x16x32_bf16 v[28:31], v[178:181], v[230:233], v[28:31]
	v_mfma_f32_16x16x32_bf16 v[24:27], v[186:189], v[230:233], v[24:27]
	v_mfma_f32_16x16x32_bf16 v[16:19], v[178:181], v[238:241], v[16:19]
	v_mfma_f32_16x16x32_bf16 v[8:11], v[186:189], v[238:241], v[8:11]
	v_mfma_f32_16x16x32_bf16 v[60:63], v[182:185], v[218:221], v[60:63]
	v_mfma_f32_16x16x32_bf16 v[56:59], v[190:193], v[218:221], v[56:59]
	v_mfma_f32_16x16x32_bf16 v[44:47], v[182:185], v[226:229], v[44:47]
	v_mfma_f32_16x16x32_bf16 v[40:43], v[190:193], v[226:229], v[40:43]
	v_mfma_f32_16x16x32_bf16 v[28:31], v[182:185], v[234:237], v[28:31]
	v_mfma_f32_16x16x32_bf16 v[24:27], v[190:193], v[234:237], v[24:27]
	v_mfma_f32_16x16x32_bf16 v[16:19], v[182:185], v[242:245], v[16:19]
	v_mfma_f32_16x16x32_bf16 v[8:11], v[190:193], v[242:245], v[8:11]
	s_setprio 0
	s_setprio 1
	v_mfma_f32_16x16x32_bf16 v[52:55], v[198:201], v[214:217], v[52:55]
	v_mfma_f32_16x16x32_bf16 v[48:51], v[206:209], v[214:217], v[48:51]
	v_mfma_f32_16x16x32_bf16 v[36:39], v[198:201], v[222:225], v[36:39]
	v_mfma_f32_16x16x32_bf16 v[32:35], v[206:209], v[222:225], v[32:35]
	v_mfma_f32_16x16x32_bf16 v[20:23], v[198:201], v[230:233], v[20:23]
	v_mfma_f32_16x16x32_bf16 v[12:15], v[206:209], v[230:233], v[12:15]
	v_mfma_f32_16x16x32_bf16 v[4:7], v[198:201], v[238:241], v[4:7]
	v_mfma_f32_16x16x32_bf16 v[0:3], v[206:209], v[238:241], v[0:3]
	v_mfma_f32_16x16x32_bf16 v[52:55], v[202:205], v[218:221], v[52:55]
	v_mfma_f32_16x16x32_bf16 v[48:51], v[210:213], v[218:221], v[48:51]
	v_mfma_f32_16x16x32_bf16 v[36:39], v[202:205], v[226:229], v[36:39]
	v_mfma_f32_16x16x32_bf16 v[32:35], v[210:213], v[226:229], v[32:35]
	v_mfma_f32_16x16x32_bf16 v[20:23], v[202:205], v[234:237], v[20:23]
	v_mfma_f32_16x16x32_bf16 v[12:15], v[210:213], v[234:237], v[12:15]
	v_mfma_f32_16x16x32_bf16 v[4:7], v[202:205], v[242:245], v[4:7]
	v_mfma_f32_16x16x32_bf16 v[0:3], v[210:213], v[242:245], v[0:3]
	s_setprio 0
	s_barrier
	ds_read_b128 v[178:181], v169
	ds_read_b128 v[182:185], v170
	ds_read_b128 v[186:189], v171
	ds_read_b128 v[190:193], v172
	ds_read_b128 v[198:201], v173
	ds_read_b128 v[202:205], v174
	ds_read_b128 v[206:209], v175
	ds_read_b128 v[210:213], v176
	s_add_u32 s10, s34, 0x80000
	s_addc_u32 s11, s35, 0
	s_mov_b32 m0, s73
	v_lshl_add_u64 v[252:253], s[10:11], 0, v[132:133]
	ds_read_b128 v[214:217], v152 offset:32768
	ds_read_b128 v[218:221], v152 offset:33792
	ds_read_b128 v[222:225], v152 offset:34816
	ds_read_b128 v[226:229], v152 offset:35840
	ds_read_b128 v[230:233], v152 offset:36864
	ds_read_b128 v[234:237], v152 offset:37888
	ds_read_b128 v[238:241], v152 offset:38912
	ds_read_b128 v[242:245], v152 offset:39936
	global_load_lds_dwordx4 v[252:253], off
	v_lshl_add_u64 v[252:253], s[10:11], 0, v[134:135]
	s_mov_b32 m0, s74
	s_nop 0
	global_load_lds_dwordx4 v[252:253], off
	s_waitcnt vmcnt(8)
	s_waitcnt lgkmcnt(0)
	s_barrier
	s_setprio 1
	s_waitcnt lgkmcnt(0)
	v_mfma_f32_16x16x32_bf16 v[124:127], v[178:181], v[214:217], v[124:127]
	v_mfma_f32_16x16x32_bf16 v[120:123], v[186:189], v[214:217], v[120:123]
	v_mfma_f32_16x16x32_bf16 v[108:111], v[178:181], v[222:225], v[108:111]
	v_mfma_f32_16x16x32_bf16 v[104:107], v[186:189], v[222:225], v[104:107]
	v_mfma_f32_16x16x32_bf16 v[92:95], v[178:181], v[230:233], v[92:95]
	v_mfma_f32_16x16x32_bf16 v[88:91], v[186:189], v[230:233], v[88:91]
	v_mfma_f32_16x16x32_bf16 v[76:79], v[178:181], v[238:241], v[76:79]
	v_mfma_f32_16x16x32_bf16 v[72:75], v[186:189], v[238:241], v[72:75]
	v_mfma_f32_16x16x32_bf16 v[124:127], v[182:185], v[218:221], v[124:127]
	v_mfma_f32_16x16x32_bf16 v[120:123], v[190:193], v[218:221], v[120:123]
	v_mfma_f32_16x16x32_bf16 v[108:111], v[182:185], v[226:229], v[108:111]
	v_mfma_f32_16x16x32_bf16 v[104:107], v[190:193], v[226:229], v[104:107]
	v_mfma_f32_16x16x32_bf16 v[92:95], v[182:185], v[234:237], v[92:95]
	v_mfma_f32_16x16x32_bf16 v[88:91], v[190:193], v[234:237], v[88:91]
	v_mfma_f32_16x16x32_bf16 v[76:79], v[182:185], v[242:245], v[76:79]
	v_mfma_f32_16x16x32_bf16 v[72:75], v[190:193], v[242:245], v[72:75]
	s_setprio 0
	s_setprio 1
	v_mfma_f32_16x16x32_bf16 v[116:119], v[198:201], v[214:217], v[116:119]
	v_mfma_f32_16x16x32_bf16 v[112:115], v[206:209], v[214:217], v[112:115]
	v_mfma_f32_16x16x32_bf16 v[100:103], v[198:201], v[222:225], v[100:103]
	v_mfma_f32_16x16x32_bf16 v[96:99], v[206:209], v[222:225], v[96:99]
	v_mfma_f32_16x16x32_bf16 v[84:87], v[198:201], v[230:233], v[84:87]
	v_mfma_f32_16x16x32_bf16 v[80:83], v[206:209], v[230:233], v[80:83]
	v_mfma_f32_16x16x32_bf16 v[68:71], v[198:201], v[238:241], v[68:71]
	v_mfma_f32_16x16x32_bf16 v[64:67], v[206:209], v[238:241], v[64:67]
	v_mfma_f32_16x16x32_bf16 v[116:119], v[202:205], v[218:221], v[116:119]
	v_mfma_f32_16x16x32_bf16 v[112:115], v[210:213], v[218:221], v[112:115]
	v_mfma_f32_16x16x32_bf16 v[100:103], v[202:205], v[226:229], v[100:103]
	v_mfma_f32_16x16x32_bf16 v[96:99], v[210:213], v[226:229], v[96:99]
	v_mfma_f32_16x16x32_bf16 v[84:87], v[202:205], v[234:237], v[84:87]
	v_mfma_f32_16x16x32_bf16 v[80:83], v[210:213], v[234:237], v[80:83]
	v_mfma_f32_16x16x32_bf16 v[68:71], v[202:205], v[242:245], v[68:71]
	v_mfma_f32_16x16x32_bf16 v[64:67], v[210:213], v[242:245], v[64:67]
	s_setprio 0
	s_barrier
	s_mov_b32 m0, s75
	v_lshl_add_u64 v[142:143], v[142:143], 0, s[14:15]
	s_add_u32 s10, s30, 0x80080
	ds_read_b128 v[214:217], v152 offset:49152
	ds_read_b128 v[218:221], v152 offset:50176
	ds_read_b128 v[222:225], v152 offset:51200
	ds_read_b128 v[226:229], v152 offset:52224
	ds_read_b128 v[230:233], v152 offset:53248
	ds_read_b128 v[234:237], v152 offset:54272
	ds_read_b128 v[238:241], v152 offset:55296
	ds_read_b128 v[242:245], v152 offset:56320
	global_load_lds_dwordx4 v[142:143], off
	v_lshl_add_u64 v[142:143], v[246:247], 0, s[14:15]
	s_mov_b32 m0, s78
	s_addc_u32 s11, s31, 0
	global_load_lds_dwordx4 v[142:143], off
	v_lshl_add_u64 v[142:143], s[10:11], 0, v[132:133]
	s_mov_b32 m0, s83
	s_nop 0
	global_load_lds_dwordx4 v[142:143], off
	v_lshl_add_u64 v[142:143], s[10:11], 0, v[134:135]
	s_mov_b32 m0, s84
	s_nop 0
	global_load_lds_dwordx4 v[142:143], off
	v_lshl_add_u64 v[142:143], v[248:249], 0, s[14:15]
	s_mov_b32 m0, s79
	s_nop 0
	global_load_lds_dwordx4 v[142:143], off
	v_lshl_add_u64 v[142:143], v[250:251], 0, s[14:15]
	s_mov_b32 m0, s82
	s_nop 0
	global_load_lds_dwordx4 v[142:143], off
	s_waitcnt vmcnt(8)
	s_waitcnt lgkmcnt(0)
	s_barrier
	s_setprio 1
	s_waitcnt lgkmcnt(0)
	v_mfma_f32_16x16x32_bf16 v[60:63], v[178:181], v[214:217], v[60:63]
	v_mfma_f32_16x16x32_bf16 v[56:59], v[186:189], v[214:217], v[56:59]
	v_mfma_f32_16x16x32_bf16 v[44:47], v[178:181], v[222:225], v[44:47]
	v_mfma_f32_16x16x32_bf16 v[40:43], v[186:189], v[222:225], v[40:43]
	v_mfma_f32_16x16x32_bf16 v[28:31], v[178:181], v[230:233], v[28:31]
	v_mfma_f32_16x16x32_bf16 v[24:27], v[186:189], v[230:233], v[24:27]
	v_mfma_f32_16x16x32_bf16 v[16:19], v[178:181], v[238:241], v[16:19]
	v_mfma_f32_16x16x32_bf16 v[8:11], v[186:189], v[238:241], v[8:11]
	v_mfma_f32_16x16x32_bf16 v[60:63], v[182:185], v[218:221], v[60:63]
	v_mfma_f32_16x16x32_bf16 v[56:59], v[190:193], v[218:221], v[56:59]
	v_mfma_f32_16x16x32_bf16 v[44:47], v[182:185], v[226:229], v[44:47]
	v_mfma_f32_16x16x32_bf16 v[40:43], v[190:193], v[226:229], v[40:43]
	v_mfma_f32_16x16x32_bf16 v[28:31], v[182:185], v[234:237], v[28:31]
	v_mfma_f32_16x16x32_bf16 v[24:27], v[190:193], v[234:237], v[24:27]
	v_mfma_f32_16x16x32_bf16 v[16:19], v[182:185], v[242:245], v[16:19]
	v_mfma_f32_16x16x32_bf16 v[8:11], v[190:193], v[242:245], v[8:11]
	s_setprio 0
	s_setprio 1
	v_mfma_f32_16x16x32_bf16 v[52:55], v[198:201], v[214:217], v[52:55]
	v_mfma_f32_16x16x32_bf16 v[48:51], v[206:209], v[214:217], v[48:51]
	v_mfma_f32_16x16x32_bf16 v[36:39], v[198:201], v[222:225], v[36:39]
	v_mfma_f32_16x16x32_bf16 v[32:35], v[206:209], v[222:225], v[32:35]
	v_mfma_f32_16x16x32_bf16 v[20:23], v[198:201], v[230:233], v[20:23]
	v_mfma_f32_16x16x32_bf16 v[12:15], v[206:209], v[230:233], v[12:15]
	v_mfma_f32_16x16x32_bf16 v[4:7], v[198:201], v[238:241], v[4:7]
	v_mfma_f32_16x16x32_bf16 v[0:3], v[206:209], v[238:241], v[0:3]
	v_mfma_f32_16x16x32_bf16 v[52:55], v[202:205], v[218:221], v[52:55]
	v_mfma_f32_16x16x32_bf16 v[48:51], v[210:213], v[218:221], v[48:51]
	v_mfma_f32_16x16x32_bf16 v[36:39], v[202:205], v[226:229], v[36:39]
	v_mfma_f32_16x16x32_bf16 v[32:35], v[210:213], v[226:229], v[32:35]
	v_mfma_f32_16x16x32_bf16 v[20:23], v[202:205], v[234:237], v[20:23]
	v_mfma_f32_16x16x32_bf16 v[12:15], v[210:213], v[234:237], v[12:15]
	v_mfma_f32_16x16x32_bf16 v[4:7], v[202:205], v[242:245], v[4:7]
	v_mfma_f32_16x16x32_bf16 v[0:3], v[210:213], v[242:245], v[0:3]
	s_setprio 0
	s_barrier
	s_add_i32 s56, s56, 2
	s_add_u32 vcc_lo, vcc_lo, 0x100
	s_addc_u32 vcc_hi, vcc_hi, 0
	s_cmp_gt_u32 s56, 29
	s_mov_b64 s[10:11], s[28:29]
	s_cbranch_scc0 .LBB0_856
	s_and_b64 vcc, exec, s[16:17]
	s_cbranch_vccz .LBB0_859
	s_barrier

.LBB0_1096:
	ds_read_b128 v[174:177], v143
	ds_read_b128 v[178:181], v153
	ds_read_b128 v[182:185], v159
	ds_read_b128 v[186:189], v160
	ds_read_b128 v[190:193], v161
	ds_read_b128 v[198:201], v162
	ds_read_b128 v[202:205], v163
	ds_read_b128 v[206:209], v164
	s_add_u32 s48, s24, 0xfffc0080
	s_addc_u32 s49, s25, -1
	s_cmp_eq_u32 s55, 12
	s_cselect_b32 s51, s4, s49
	s_cselect_b32 s50, s5, s48
	s_cselect_b32 s49, s15, s54
	s_cselect_b32 s48, s27, s39
	s_mov_b32 m0, s65
	v_lshl_add_u64 v[242:243], s[24:25], 0, v[132:133]
	ds_read_b128 v[210:213], v141
	ds_read_b128 v[214:217], v141 offset:1024
	ds_read_b128 v[218:221], v141 offset:2048
	ds_read_b128 v[222:225], v141 offset:3072
	ds_read_b128 v[226:229], v141 offset:4096
	ds_read_b128 v[230:233], v141 offset:5120
	ds_read_b128 v[234:237], v141 offset:6144
	ds_read_b128 v[238:241], v141 offset:7168
	global_load_lds_dwordx4 v[242:243], off
	v_lshl_add_u64 v[242:243], s[24:25], 0, v[134:135]
	s_mov_b32 m0, s67
	s_nop 0
	global_load_lds_dwordx4 v[242:243], off
	s_waitcnt vmcnt(8)
	s_waitcnt lgkmcnt(0)
	s_barrier
	s_setprio 1
	s_waitcnt lgkmcnt(0)
	v_mfma_f32_16x16x32_bf16 v[124:127], v[174:177], v[210:213], v[124:127]
	v_mfma_f32_16x16x32_bf16 v[120:123], v[182:185], v[210:213], v[120:123]
	v_mfma_f32_16x16x32_bf16 v[108:111], v[174:177], v[218:221], v[108:111]
	v_mfma_f32_16x16x32_bf16 v[104:107], v[182:185], v[218:221], v[104:107]
	v_mfma_f32_16x16x32_bf16 v[92:95], v[174:177], v[226:229], v[92:95]
	v_mfma_f32_16x16x32_bf16 v[88:91], v[182:185], v[226:229], v[88:91]
	v_mfma_f32_16x16x32_bf16 v[76:79], v[174:177], v[234:237], v[76:79]
	v_mfma_f32_16x16x32_bf16 v[72:75], v[182:185], v[234:237], v[72:75]
	v_mfma_f32_16x16x32_bf16 v[124:127], v[178:181], v[214:217], v[124:127]
	v_mfma_f32_16x16x32_bf16 v[120:123], v[186:189], v[214:217], v[120:123]
	v_mfma_f32_16x16x32_bf16 v[108:111], v[178:181], v[222:225], v[108:111]
	v_mfma_f32_16x16x32_bf16 v[104:107], v[186:189], v[222:225], v[104:107]
	v_mfma_f32_16x16x32_bf16 v[92:95], v[178:181], v[230:233], v[92:95]
	v_mfma_f32_16x16x32_bf16 v[88:91], v[186:189], v[230:233], v[88:91]
	v_mfma_f32_16x16x32_bf16 v[76:79], v[178:181], v[238:241], v[76:79]
	v_mfma_f32_16x16x32_bf16 v[72:75], v[186:189], v[238:241], v[72:75]
	s_setprio 0
	s_setprio 1
	v_mfma_f32_16x16x32_bf16 v[116:119], v[190:193], v[210:213], v[116:119]
	v_mfma_f32_16x16x32_bf16 v[112:115], v[202:205], v[210:213], v[112:115]
	v_mfma_f32_16x16x32_bf16 v[100:103], v[190:193], v[218:221], v[100:103]
	v_mfma_f32_16x16x32_bf16 v[96:99], v[202:205], v[218:221], v[96:99]
	v_mfma_f32_16x16x32_bf16 v[84:87], v[190:193], v[226:229], v[84:87]
	v_mfma_f32_16x16x32_bf16 v[80:83], v[202:205], v[226:229], v[80:83]
	v_mfma_f32_16x16x32_bf16 v[68:71], v[190:193], v[234:237], v[68:71]
	v_mfma_f32_16x16x32_bf16 v[64:67], v[202:205], v[234:237], v[64:67]
	v_mfma_f32_16x16x32_bf16 v[116:119], v[198:201], v[214:217], v[116:119]
	v_mfma_f32_16x16x32_bf16 v[112:115], v[206:209], v[214:217], v[112:115]
	v_mfma_f32_16x16x32_bf16 v[100:103], v[198:201], v[222:225], v[100:103]
	v_mfma_f32_16x16x32_bf16 v[96:99], v[206:209], v[222:225], v[96:99]
	v_mfma_f32_16x16x32_bf16 v[84:87], v[198:201], v[230:233], v[84:87]
	v_mfma_f32_16x16x32_bf16 v[80:83], v[206:209], v[230:233], v[80:83]
	v_mfma_f32_16x16x32_bf16 v[68:71], v[198:201], v[238:241], v[68:71]
	v_mfma_f32_16x16x32_bf16 v[64:67], v[206:209], v[238:241], v[64:67]
	s_setprio 0
	s_barrier
	s_mov_b32 m0, s28
	v_lshl_add_u64 v[242:243], s[48:49], 0, v[130:131]
	s_add_u32 s68, s48, 0x40000
	ds_read_b128 v[210:213], v141 offset:16384
	ds_read_b128 v[214:217], v141 offset:17408
	ds_read_b128 v[218:221], v141 offset:18432
	ds_read_b128 v[222:225], v141 offset:19456
	ds_read_b128 v[226:229], v141 offset:20480
	ds_read_b128 v[230:233], v141 offset:21504
	ds_read_b128 v[234:237], v141 offset:22528
	ds_read_b128 v[238:241], v141 offset:23552
	global_load_lds_dwordx4 v[242:243], off
	v_lshl_add_u64 v[244:245], s[48:49], 0, v[128:129]
	s_mov_b32 m0, s29
	s_addc_u32 s69, s49, 0
	global_load_lds_dwordx4 v[244:245], off
	v_lshl_add_u64 v[246:247], s[68:69], 0, v[130:131]
	s_mov_b32 m0, s30
	v_lshl_add_u64 v[248:249], s[50:51], 0, v[128:129]
	global_load_lds_dwordx4 v[246:247], off
	v_lshl_add_u64 v[246:247], s[68:69], 0, v[128:129]
	s_mov_b32 m0, s31
	s_nop 0
	global_load_lds_dwordx4 v[246:247], off
	v_lshl_add_u64 v[246:247], s[50:51], 0, v[130:131]
	s_mov_b32 m0, s2
	s_nop 0
	global_load_lds_dwordx4 v[246:247], off
	s_mov_b32 m0, s33
	s_nop 0
	global_load_lds_dwordx4 v[248:249], off
	s_waitcnt vmcnt(8)
	s_waitcnt lgkmcnt(0)
	s_barrier
	s_setprio 1
	s_waitcnt lgkmcnt(0)
	v_mfma_f32_16x16x32_bf16 v[60:63], v[174:177], v[210:213], v[60:63]
	v_mfma_f32_16x16x32_bf16 v[56:59], v[182:185], v[210:213], v[56:59]
	v_mfma_f32_16x16x32_bf16 v[44:47], v[174:177], v[218:221], v[44:47]
	v_mfma_f32_16x16x32_bf16 v[40:43], v[182:185], v[218:221], v[40:43]
	v_mfma_f32_16x16x32_bf16 v[28:31], v[174:177], v[226:229], v[28:31]
	v_mfma_f32_16x16x32_bf16 v[24:27], v[182:185], v[226:229], v[24:27]
	v_mfma_f32_16x16x32_bf16 v[12:15], v[174:177], v[234:237], v[12:15]
	v_mfma_f32_16x16x32_bf16 v[8:11], v[182:185], v[234:237], v[8:11]
	v_mfma_f32_16x16x32_bf16 v[60:63], v[178:181], v[214:217], v[60:63]
	v_mfma_f32_16x16x32_bf16 v[56:59], v[186:189], v[214:217], v[56:59]
	v_mfma_f32_16x16x32_bf16 v[44:47], v[178:181], v[222:225], v[44:47]
	v_mfma_f32_16x16x32_bf16 v[40:43], v[186:189], v[222:225], v[40:43]
	v_mfma_f32_16x16x32_bf16 v[28:31], v[178:181], v[230:233], v[28:31]
	v_mfma_f32_16x16x32_bf16 v[24:27], v[186:189], v[230:233], v[24:27]
	v_mfma_f32_16x16x32_bf16 v[12:15], v[178:181], v[238:241], v[12:15]
	v_mfma_f32_16x16x32_bf16 v[8:11], v[186:189], v[238:241], v[8:11]
	s_setprio 0
	s_setprio 1
	v_mfma_f32_16x16x32_bf16 v[52:55], v[190:193], v[210:213], v[52:55]
	v_mfma_f32_16x16x32_bf16 v[48:51], v[202:205], v[210:213], v[48:51]
	v_mfma_f32_16x16x32_bf16 v[36:39], v[190:193], v[218:221], v[36:39]
	v_mfma_f32_16x16x32_bf16 v[32:35], v[202:205], v[218:221], v[32:35]
	v_mfma_f32_16x16x32_bf16 v[20:23], v[190:193], v[226:229], v[20:23]
	v_mfma_f32_16x16x32_bf16 v[16:19], v[202:205], v[226:229], v[16:19]
	v_mfma_f32_16x16x32_bf16 v[4:7], v[190:193], v[234:237], v[4:7]
	v_mfma_f32_16x16x32_bf16 v[0:3], v[202:205], v[234:237], v[0:3]
	v_mfma_f32_16x16x32_bf16 v[52:55], v[198:201], v[214:217], v[52:55]
	v_mfma_f32_16x16x32_bf16 v[48:51], v[206:209], v[214:217], v[48:51]
	v_mfma_f32_16x16x32_bf16 v[36:39], v[198:201], v[222:225], v[36:39]
	v_mfma_f32_16x16x32_bf16 v[32:35], v[206:209], v[222:225], v[32:35]
	v_mfma_f32_16x16x32_bf16 v[20:23], v[198:201], v[230:233], v[20:23]
	v_mfma_f32_16x16x32_bf16 v[16:19], v[206:209], v[230:233], v[16:19]
	v_mfma_f32_16x16x32_bf16 v[4:7], v[198:201], v[238:241], v[4:7]
	v_mfma_f32_16x16x32_bf16 v[0:3], v[206:209], v[238:241], v[0:3]
	s_setprio 0
	s_barrier
	ds_read_b128 v[174:177], v165
	ds_read_b128 v[178:181], v166
	ds_read_b128 v[182:185], v167
	ds_read_b128 v[186:189], v168
	ds_read_b128 v[190:193], v169
	ds_read_b128 v[198:201], v170
	ds_read_b128 v[202:205], v171
	ds_read_b128 v[206:209], v172
	s_add_u32 s50, s50, 0x40000
	s_addc_u32 s51, s51, 0
	s_mov_b32 m0, s34
	v_lshl_add_u64 v[250:251], s[50:51], 0, v[130:131]
	ds_read_b128 v[210:213], v141 offset:32768
	ds_read_b128 v[214:217], v141 offset:33792
	ds_read_b128 v[218:221], v141 offset:34816
	ds_read_b128 v[222:225], v141 offset:35840
	ds_read_b128 v[226:229], v141 offset:36864
	ds_read_b128 v[230:233], v141 offset:37888
	ds_read_b128 v[234:237], v141 offset:38912
	ds_read_b128 v[238:241], v141 offset:39936
	global_load_lds_dwordx4 v[250:251], off
	v_lshl_add_u64 v[250:251], s[50:51], 0, v[128:129]
	s_mov_b32 m0, s35
	s_nop 0
	global_load_lds_dwordx4 v[250:251], off
	s_waitcnt vmcnt(8)
	s_waitcnt lgkmcnt(0)
	s_barrier
	s_setprio 1
	s_waitcnt lgkmcnt(0)
	v_mfma_f32_16x16x32_bf16 v[124:127], v[174:177], v[210:213], v[124:127]
	v_mfma_f32_16x16x32_bf16 v[120:123], v[182:185], v[210:213], v[120:123]
	v_mfma_f32_16x16x32_bf16 v[108:111], v[174:177], v[218:221], v[108:111]
	v_mfma_f32_16x16x32_bf16 v[104:107], v[182:185], v[218:221], v[104:107]
	v_mfma_f32_16x16x32_bf16 v[92:95], v[174:177], v[226:229], v[92:95]
	v_mfma_f32_16x16x32_bf16 v[88:91], v[182:185], v[226:229], v[88:91]
	v_mfma_f32_16x16x32_bf16 v[76:79], v[174:177], v[234:237], v[76:79]
	v_mfma_f32_16x16x32_bf16 v[72:75], v[182:185], v[234:237], v[72:75]
	v_mfma_f32_16x16x32_bf16 v[124:127], v[178:181], v[214:217], v[124:127]
	v_mfma_f32_16x16x32_bf16 v[120:123], v[186:189], v[214:217], v[120:123]
	v_mfma_f32_16x16x32_bf16 v[108:111], v[178:181], v[222:225], v[108:111]
	v_mfma_f32_16x16x32_bf16 v[104:107], v[186:189], v[222:225], v[104:107]
	v_mfma_f32_16x16x32_bf16 v[92:95], v[178:181], v[230:233], v[92:95]
	v_mfma_f32_16x16x32_bf16 v[88:91], v[186:189], v[230:233], v[88:91]
	v_mfma_f32_16x16x32_bf16 v[76:79], v[178:181], v[238:241], v[76:79]
	v_mfma_f32_16x16x32_bf16 v[72:75], v[186:189], v[238:241], v[72:75]
	s_setprio 0
	s_setprio 1
	v_mfma_f32_16x16x32_bf16 v[116:119], v[190:193], v[210:213], v[116:119]
	v_mfma_f32_16x16x32_bf16 v[112:115], v[202:205], v[210:213], v[112:115]
	v_mfma_f32_16x16x32_bf16 v[100:103], v[190:193], v[218:221], v[100:103]
	v_mfma_f32_16x16x32_bf16 v[96:99], v[202:205], v[218:221], v[96:99]
	v_mfma_f32_16x16x32_bf16 v[84:87], v[190:193], v[226:229], v[84:87]
	v_mfma_f32_16x16x32_bf16 v[80:83], v[202:205], v[226:229], v[80:83]
	v_mfma_f32_16x16x32_bf16 v[68:71], v[190:193], v[234:237], v[68:71]
	v_mfma_f32_16x16x32_bf16 v[64:67], v[202:205], v[234:237], v[64:67]
	v_mfma_f32_16x16x32_bf16 v[116:119], v[198:201], v[214:217], v[116:119]
	v_mfma_f32_16x16x32_bf16 v[112:115], v[206:209], v[214:217], v[112:115]
	v_mfma_f32_16x16x32_bf16 v[100:103], v[198:201], v[222:225], v[100:103]
	v_mfma_f32_16x16x32_bf16 v[96:99], v[206:209], v[222:225], v[96:99]
	v_mfma_f32_16x16x32_bf16 v[84:87], v[198:201], v[230:233], v[84:87]
	v_mfma_f32_16x16x32_bf16 v[80:83], v[206:209], v[230:233], v[80:83]
	v_mfma_f32_16x16x32_bf16 v[68:71], v[198:201], v[238:241], v[68:71]
	v_mfma_f32_16x16x32_bf16 v[64:67], v[206:209], v[238:241], v[64:67]
	s_setprio 0
	s_barrier
	s_mov_b32 m0, s40
	v_lshl_add_u64 v[242:243], v[242:243], 0, s[8:9]
	s_add_u32 s48, s48, 0x40080
	ds_read_b128 v[210:213], v141 offset:49152
	ds_read_b128 v[214:217], v141 offset:50176
	ds_read_b128 v[218:221], v141 offset:51200
	ds_read_b128 v[222:225], v141 offset:52224
	ds_read_b128 v[226:229], v141 offset:53248
	ds_read_b128 v[230:233], v141 offset:54272
	ds_read_b128 v[234:237], v141 offset:55296
	ds_read_b128 v[238:241], v141 offset:56320
	global_load_lds_dwordx4 v[242:243], off
	v_lshl_add_u64 v[242:243], v[244:245], 0, s[8:9]
	s_mov_b32 m0, s41
	s_addc_u32 s49, s49, 0
	global_load_lds_dwordx4 v[242:243], off
	v_lshl_add_u64 v[242:243], s[48:49], 0, v[130:131]
	s_mov_b32 m0, s53
	s_nop 0
	global_load_lds_dwordx4 v[242:243], off
	v_lshl_add_u64 v[242:243], s[48:49], 0, v[128:129]
	s_mov_b32 m0, s60
	s_nop 0
	global_load_lds_dwordx4 v[242:243], off
	v_lshl_add_u64 v[242:243], v[246:247], 0, s[8:9]
	s_mov_b32 m0, s47
	s_nop 0
	global_load_lds_dwordx4 v[242:243], off
	v_lshl_add_u64 v[242:243], v[248:249], 0, s[8:9]
	s_mov_b32 m0, s52
	s_nop 0
	global_load_lds_dwordx4 v[242:243], off
	s_waitcnt vmcnt(8)
	s_waitcnt lgkmcnt(0)
	s_barrier
	s_setprio 1
	s_waitcnt lgkmcnt(0)
	v_mfma_f32_16x16x32_bf16 v[60:63], v[174:177], v[210:213], v[60:63]
	v_mfma_f32_16x16x32_bf16 v[56:59], v[182:185], v[210:213], v[56:59]
	v_mfma_f32_16x16x32_bf16 v[44:47], v[174:177], v[218:221], v[44:47]
	v_mfma_f32_16x16x32_bf16 v[40:43], v[182:185], v[218:221], v[40:43]
	v_mfma_f32_16x16x32_bf16 v[28:31], v[174:177], v[226:229], v[28:31]
	v_mfma_f32_16x16x32_bf16 v[24:27], v[182:185], v[226:229], v[24:27]
	v_mfma_f32_16x16x32_bf16 v[12:15], v[174:177], v[234:237], v[12:15]
	v_mfma_f32_16x16x32_bf16 v[8:11], v[182:185], v[234:237], v[8:11]
	v_mfma_f32_16x16x32_bf16 v[60:63], v[178:181], v[214:217], v[60:63]
	v_mfma_f32_16x16x32_bf16 v[56:59], v[186:189], v[214:217], v[56:59]
	v_mfma_f32_16x16x32_bf16 v[44:47], v[178:181], v[222:225], v[44:47]
	v_mfma_f32_16x16x32_bf16 v[40:43], v[186:189], v[222:225], v[40:43]
	v_mfma_f32_16x16x32_bf16 v[28:31], v[178:181], v[230:233], v[28:31]
	v_mfma_f32_16x16x32_bf16 v[24:27], v[186:189], v[230:233], v[24:27]
	v_mfma_f32_16x16x32_bf16 v[12:15], v[178:181], v[238:241], v[12:15]
	v_mfma_f32_16x16x32_bf16 v[8:11], v[186:189], v[238:241], v[8:11]
	s_setprio 0
	s_setprio 1
	v_mfma_f32_16x16x32_bf16 v[52:55], v[190:193], v[210:213], v[52:55]
	v_mfma_f32_16x16x32_bf16 v[48:51], v[202:205], v[210:213], v[48:51]
	v_mfma_f32_16x16x32_bf16 v[36:39], v[190:193], v[218:221], v[36:39]
	v_mfma_f32_16x16x32_bf16 v[32:35], v[202:205], v[218:221], v[32:35]
	v_mfma_f32_16x16x32_bf16 v[20:23], v[190:193], v[226:229], v[20:23]
	v_mfma_f32_16x16x32_bf16 v[16:19], v[202:205], v[226:229], v[16:19]
	v_mfma_f32_16x16x32_bf16 v[4:7], v[190:193], v[234:237], v[4:7]
	v_mfma_f32_16x16x32_bf16 v[0:3], v[202:205], v[234:237], v[0:3]
	v_mfma_f32_16x16x32_bf16 v[52:55], v[198:201], v[214:217], v[52:55]
	v_mfma_f32_16x16x32_bf16 v[48:51], v[206:209], v[214:217], v[48:51]
	v_mfma_f32_16x16x32_bf16 v[36:39], v[198:201], v[222:225], v[36:39]
	v_mfma_f32_16x16x32_bf16 v[32:35], v[206:209], v[222:225], v[32:35]
	v_mfma_f32_16x16x32_bf16 v[20:23], v[198:201], v[230:233], v[20:23]
	v_mfma_f32_16x16x32_bf16 v[16:19], v[206:209], v[230:233], v[16:19]
	v_mfma_f32_16x16x32_bf16 v[4:7], v[198:201], v[238:241], v[4:7]
	v_mfma_f32_16x16x32_bf16 v[0:3], v[206:209], v[238:241], v[0:3]
	s_setprio 0
	s_barrier
	s_add_i32 s55, s55, 2
	s_add_u32 s24, s24, 0x100
	s_addc_u32 s25, s25, 0
	s_add_u32 s39, s39, 0x100
	s_addc_u32 s54, s54, 0
	s_cmp_gt_u32 s55, 13
	s_cbranch_scc0 .LBB0_1096
	s_and_b64 vcc, exec, s[12:13]
	s_cbranch_vccz .LBB0_1099
	s_barrier

.LBB0_1176:
	ds_read_b128 v[128:131], v183
	ds_read_b128 v[132:135], v184
	ds_read_b128 v[136:139], v185
	ds_read_b128 v[168:171], v186
	ds_read_b128 v[172:175], v187
	ds_read_b128 v[176:179], v188
	ds_read_b128 v[204:207], v189
	ds_read_b128 v[208:211], v190
	s_add_u32 s46, s24, 0x100
	s_addc_u32 s47, s25, 0
	s_cmp_eq_u32 s66, 40
	s_cselect_b32 s51, s13, s47
	s_cselect_b32 s50, s12, s46
	s_cselect_b32 s49, s45, s5
	s_cselect_b32 s48, s44, s4
	s_mov_b32 m0, s60
	v_lshl_add_u64 v[180:181], s[24:25], 0, v[160:161]
	ds_read_b128 v[212:215], v159
	ds_read_b128 v[216:219], v159 offset:1024
	ds_read_b128 v[220:223], v159 offset:2048
	ds_read_b128 v[224:227], v159 offset:3072
	ds_read_b128 v[228:231], v159 offset:4096
	ds_read_b128 v[232:235], v159 offset:5120
	ds_read_b128 v[236:239], v159 offset:6144
	ds_read_b128 v[240:243], v159 offset:7168
	global_load_lds_dwordx4 v[180:181], off
	v_lshl_add_u64 v[180:181], s[24:25], 0, v[162:163]
	s_mov_b32 m0, s61
	s_nop 0
	global_load_lds_dwordx4 v[180:181], off
	s_waitcnt vmcnt(8)
	s_waitcnt lgkmcnt(0)
	s_barrier
	s_setprio 1
	s_waitcnt lgkmcnt(0)
	v_mfma_f32_16x16x32_bf16 v[124:127], v[128:131], v[212:215], v[124:127]
	v_mfma_f32_16x16x32_bf16 v[120:123], v[136:139], v[212:215], v[120:123]
	v_mfma_f32_16x16x32_bf16 v[108:111], v[128:131], v[220:223], v[108:111]
	v_mfma_f32_16x16x32_bf16 v[104:107], v[136:139], v[220:223], v[104:107]
	v_mfma_f32_16x16x32_bf16 v[92:95], v[128:131], v[228:231], v[92:95]
	v_mfma_f32_16x16x32_bf16 v[88:91], v[136:139], v[228:231], v[88:91]
	v_mfma_f32_16x16x32_bf16 v[76:79], v[128:131], v[236:239], v[76:79]
	v_mfma_f32_16x16x32_bf16 v[72:75], v[136:139], v[236:239], v[72:75]
	v_mfma_f32_16x16x32_bf16 v[124:127], v[132:135], v[216:219], v[124:127]
	v_mfma_f32_16x16x32_bf16 v[120:123], v[168:171], v[216:219], v[120:123]
	v_mfma_f32_16x16x32_bf16 v[108:111], v[132:135], v[224:227], v[108:111]
	v_mfma_f32_16x16x32_bf16 v[104:107], v[168:171], v[224:227], v[104:107]
	v_mfma_f32_16x16x32_bf16 v[92:95], v[132:135], v[232:235], v[92:95]
	v_mfma_f32_16x16x32_bf16 v[88:91], v[168:171], v[232:235], v[88:91]
	v_mfma_f32_16x16x32_bf16 v[76:79], v[132:135], v[240:243], v[76:79]
	v_mfma_f32_16x16x32_bf16 v[72:75], v[168:171], v[240:243], v[72:75]
	s_setprio 0
	s_setprio 1
	v_mfma_f32_16x16x32_bf16 v[116:119], v[172:175], v[212:215], v[116:119]
	v_mfma_f32_16x16x32_bf16 v[112:115], v[204:207], v[212:215], v[112:115]
	v_mfma_f32_16x16x32_bf16 v[100:103], v[172:175], v[220:223], v[100:103]
	v_mfma_f32_16x16x32_bf16 v[96:99], v[204:207], v[220:223], v[96:99]
	v_mfma_f32_16x16x32_bf16 v[84:87], v[172:175], v[228:231], v[84:87]
	v_mfma_f32_16x16x32_bf16 v[80:83], v[204:207], v[228:231], v[80:83]
	v_mfma_f32_16x16x32_bf16 v[68:71], v[172:175], v[236:239], v[68:71]
	v_mfma_f32_16x16x32_bf16 v[64:67], v[204:207], v[236:239], v[64:67]
	v_mfma_f32_16x16x32_bf16 v[116:119], v[176:179], v[216:219], v[116:119]
	v_mfma_f32_16x16x32_bf16 v[112:115], v[208:211], v[216:219], v[112:115]
	v_mfma_f32_16x16x32_bf16 v[100:103], v[176:179], v[224:227], v[100:103]
	v_mfma_f32_16x16x32_bf16 v[96:99], v[208:211], v[224:227], v[96:99]
	v_mfma_f32_16x16x32_bf16 v[84:87], v[176:179], v[232:235], v[84:87]
	v_mfma_f32_16x16x32_bf16 v[80:83], v[208:211], v[232:235], v[80:83]
	v_mfma_f32_16x16x32_bf16 v[68:71], v[176:179], v[240:243], v[68:71]
	v_mfma_f32_16x16x32_bf16 v[64:67], v[208:211], v[240:243], v[64:67]
	s_setprio 0
	s_barrier
	s_mov_b32 m0, s7
	v_lshl_add_u64 v[180:181], s[48:49], 0, v[140:141]
	s_add_u32 s24, s48, 0xb0000
	ds_read_b128 v[212:215], v159 offset:16384
	ds_read_b128 v[216:219], v159 offset:17408
	ds_read_b128 v[220:223], v159 offset:18432
	ds_read_b128 v[224:227], v159 offset:19456
	ds_read_b128 v[228:231], v159 offset:20480
	ds_read_b128 v[232:235], v159 offset:21504
	ds_read_b128 v[236:239], v159 offset:22528
	ds_read_b128 v[240:243], v159 offset:23552
	global_load_lds_dwordx4 v[180:181], off
	v_lshl_add_u64 v[244:245], s[48:49], 0, v[142:143]
	s_mov_b32 m0, s28
	s_addc_u32 s25, s49, 0
	global_load_lds_dwordx4 v[244:245], off
	v_lshl_add_u64 v[246:247], s[24:25], 0, v[140:141]
	s_mov_b32 m0, s29
	v_lshl_add_u64 v[248:249], s[50:51], 0, v[142:143]
	global_load_lds_dwordx4 v[246:247], off
	v_lshl_add_u64 v[246:247], s[24:25], 0, v[142:143]
	s_mov_b32 m0, s30
	s_nop 0
	global_load_lds_dwordx4 v[246:247], off
	v_lshl_add_u64 v[246:247], s[50:51], 0, v[140:141]
	s_mov_b32 m0, s6
	s_nop 0
	global_load_lds_dwordx4 v[246:247], off
	s_mov_b32 m0, s31
	s_nop 0
	global_load_lds_dwordx4 v[248:249], off
	s_waitcnt vmcnt(8)
	s_waitcnt lgkmcnt(0)
	s_barrier
	s_setprio 1
	s_waitcnt lgkmcnt(0)
	v_mfma_f32_16x16x32_bf16 v[60:63], v[128:131], v[212:215], v[60:63]
	v_mfma_f32_16x16x32_bf16 v[56:59], v[136:139], v[212:215], v[56:59]
	v_mfma_f32_16x16x32_bf16 v[44:47], v[128:131], v[220:223], v[44:47]
	v_mfma_f32_16x16x32_bf16 v[40:43], v[136:139], v[220:223], v[40:43]
	v_mfma_f32_16x16x32_bf16 v[28:31], v[128:131], v[228:231], v[28:31]
	v_mfma_f32_16x16x32_bf16 v[24:27], v[136:139], v[228:231], v[24:27]
	v_mfma_f32_16x16x32_bf16 v[12:15], v[128:131], v[236:239], v[12:15]
	v_mfma_f32_16x16x32_bf16 v[8:11], v[136:139], v[236:239], v[8:11]
	v_mfma_f32_16x16x32_bf16 v[60:63], v[132:135], v[216:219], v[60:63]
	v_mfma_f32_16x16x32_bf16 v[56:59], v[168:171], v[216:219], v[56:59]
	v_mfma_f32_16x16x32_bf16 v[44:47], v[132:135], v[224:227], v[44:47]
	v_mfma_f32_16x16x32_bf16 v[40:43], v[168:171], v[224:227], v[40:43]
	v_mfma_f32_16x16x32_bf16 v[28:31], v[132:135], v[232:235], v[28:31]
	v_mfma_f32_16x16x32_bf16 v[24:27], v[168:171], v[232:235], v[24:27]
	v_mfma_f32_16x16x32_bf16 v[12:15], v[132:135], v[240:243], v[12:15]
	v_mfma_f32_16x16x32_bf16 v[8:11], v[168:171], v[240:243], v[8:11]
	s_setprio 0
	s_setprio 1
	v_mfma_f32_16x16x32_bf16 v[52:55], v[172:175], v[212:215], v[52:55]
	v_mfma_f32_16x16x32_bf16 v[48:51], v[204:207], v[212:215], v[48:51]
	v_mfma_f32_16x16x32_bf16 v[36:39], v[172:175], v[220:223], v[36:39]
	v_mfma_f32_16x16x32_bf16 v[32:35], v[204:207], v[220:223], v[32:35]
	v_mfma_f32_16x16x32_bf16 v[20:23], v[172:175], v[228:231], v[20:23]
	v_mfma_f32_16x16x32_bf16 v[16:19], v[204:207], v[228:231], v[16:19]
	v_mfma_f32_16x16x32_bf16 v[4:7], v[172:175], v[236:239], v[4:7]
	v_mfma_f32_16x16x32_bf16 v[0:3], v[204:207], v[236:239], v[0:3]
	v_mfma_f32_16x16x32_bf16 v[52:55], v[176:179], v[216:219], v[52:55]
	v_mfma_f32_16x16x32_bf16 v[48:51], v[208:211], v[216:219], v[48:51]
	v_mfma_f32_16x16x32_bf16 v[36:39], v[176:179], v[224:227], v[36:39]
	v_mfma_f32_16x16x32_bf16 v[32:35], v[208:211], v[224:227], v[32:35]
	v_mfma_f32_16x16x32_bf16 v[20:23], v[176:179], v[232:235], v[20:23]
	v_mfma_f32_16x16x32_bf16 v[16:19], v[208:211], v[232:235], v[16:19]
	v_mfma_f32_16x16x32_bf16 v[4:7], v[176:179], v[240:243], v[4:7]
	v_mfma_f32_16x16x32_bf16 v[0:3], v[208:211], v[240:243], v[0:3]
	s_setprio 0
	s_barrier
	ds_read_b128 v[128:131], v191
	ds_read_b128 v[132:135], v192
	ds_read_b128 v[136:139], v193
	ds_read_b128 v[168:171], v197
	ds_read_b128 v[172:175], v198
	ds_read_b128 v[176:179], v199
	ds_read_b128 v[204:207], v200
	ds_read_b128 v[208:211], v201
	s_add_u32 s24, s50, 0xb0000
	s_addc_u32 s25, s51, 0
	s_mov_b32 m0, s33
	v_lshl_add_u64 v[250:251], s[24:25], 0, v[140:141]
	ds_read_b128 v[212:215], v159 offset:32768
	ds_read_b128 v[216:219], v159 offset:33792
	ds_read_b128 v[220:223], v159 offset:34816
	ds_read_b128 v[224:227], v159 offset:35840
	ds_read_b128 v[228:231], v159 offset:36864
	ds_read_b128 v[232:235], v159 offset:37888
	ds_read_b128 v[236:239], v159 offset:38912
	ds_read_b128 v[240:243], v159 offset:39936
	global_load_lds_dwordx4 v[250:251], off
	v_lshl_add_u64 v[250:251], s[24:25], 0, v[142:143]
	s_mov_b32 m0, s34
	s_nop 0
	global_load_lds_dwordx4 v[250:251], off
	s_waitcnt vmcnt(8)
	s_waitcnt lgkmcnt(0)
	s_barrier
	s_setprio 1
	s_waitcnt lgkmcnt(0)
	v_mfma_f32_16x16x32_bf16 v[124:127], v[128:131], v[212:215], v[124:127]
	v_mfma_f32_16x16x32_bf16 v[120:123], v[136:139], v[212:215], v[120:123]
	v_mfma_f32_16x16x32_bf16 v[108:111], v[128:131], v[220:223], v[108:111]
	v_mfma_f32_16x16x32_bf16 v[104:107], v[136:139], v[220:223], v[104:107]
	v_mfma_f32_16x16x32_bf16 v[92:95], v[128:131], v[228:231], v[92:95]
	v_mfma_f32_16x16x32_bf16 v[88:91], v[136:139], v[228:231], v[88:91]
	v_mfma_f32_16x16x32_bf16 v[76:79], v[128:131], v[236:239], v[76:79]
	v_mfma_f32_16x16x32_bf16 v[72:75], v[136:139], v[236:239], v[72:75]
	v_mfma_f32_16x16x32_bf16 v[124:127], v[132:135], v[216:219], v[124:127]
	v_mfma_f32_16x16x32_bf16 v[120:123], v[168:171], v[216:219], v[120:123]
	v_mfma_f32_16x16x32_bf16 v[108:111], v[132:135], v[224:227], v[108:111]
	v_mfma_f32_16x16x32_bf16 v[104:107], v[168:171], v[224:227], v[104:107]
	v_mfma_f32_16x16x32_bf16 v[92:95], v[132:135], v[232:235], v[92:95]
	v_mfma_f32_16x16x32_bf16 v[88:91], v[168:171], v[232:235], v[88:91]
	v_mfma_f32_16x16x32_bf16 v[76:79], v[132:135], v[240:243], v[76:79]
	v_mfma_f32_16x16x32_bf16 v[72:75], v[168:171], v[240:243], v[72:75]
	s_setprio 0
	s_setprio 1
	v_mfma_f32_16x16x32_bf16 v[116:119], v[172:175], v[212:215], v[116:119]
	v_mfma_f32_16x16x32_bf16 v[112:115], v[204:207], v[212:215], v[112:115]
	v_mfma_f32_16x16x32_bf16 v[100:103], v[172:175], v[220:223], v[100:103]
	v_mfma_f32_16x16x32_bf16 v[96:99], v[204:207], v[220:223], v[96:99]
	v_mfma_f32_16x16x32_bf16 v[84:87], v[172:175], v[228:231], v[84:87]
	v_mfma_f32_16x16x32_bf16 v[80:83], v[204:207], v[228:231], v[80:83]
	v_mfma_f32_16x16x32_bf16 v[68:71], v[172:175], v[236:239], v[68:71]
	v_mfma_f32_16x16x32_bf16 v[64:67], v[204:207], v[236:239], v[64:67]
	v_mfma_f32_16x16x32_bf16 v[116:119], v[176:179], v[216:219], v[116:119]
	v_mfma_f32_16x16x32_bf16 v[112:115], v[208:211], v[216:219], v[112:115]
	v_mfma_f32_16x16x32_bf16 v[100:103], v[176:179], v[224:227], v[100:103]
	v_mfma_f32_16x16x32_bf16 v[96:99], v[208:211], v[224:227], v[96:99]
	v_mfma_f32_16x16x32_bf16 v[84:87], v[176:179], v[232:235], v[84:87]
	v_mfma_f32_16x16x32_bf16 v[80:83], v[208:211], v[232:235], v[80:83]
	v_mfma_f32_16x16x32_bf16 v[68:71], v[176:179], v[240:243], v[68:71]
	v_mfma_f32_16x16x32_bf16 v[64:67], v[208:211], v[240:243], v[64:67]
	s_setprio 0
	s_barrier
	s_mov_b32 m0, s35
	v_lshl_add_u64 v[180:181], v[180:181], 0, s[14:15]
	s_add_u32 s24, s48, 0xb0080
	ds_read_b128 v[212:215], v159 offset:49152
	ds_read_b128 v[216:219], v159 offset:50176
	ds_read_b128 v[220:223], v159 offset:51200
	ds_read_b128 v[224:227], v159 offset:52224
	ds_read_b128 v[228:231], v159 offset:53248
	ds_read_b128 v[232:235], v159 offset:54272
	ds_read_b128 v[236:239], v159 offset:55296
	ds_read_b128 v[240:243], v159 offset:56320
	global_load_lds_dwordx4 v[180:181], off
	v_lshl_add_u64 v[180:181], v[244:245], 0, s[14:15]
	s_mov_b32 m0, s36
	s_addc_u32 s25, s49, 0
	global_load_lds_dwordx4 v[180:181], off
	v_lshl_add_u64 v[180:181], s[24:25], 0, v[140:141]
	s_mov_b32 m0, s41
	s_nop 0
	global_load_lds_dwordx4 v[180:181], off
	v_lshl_add_u64 v[180:181], s[24:25], 0, v[142:143]
	s_mov_b32 m0, s43
	s_nop 0
	global_load_lds_dwordx4 v[180:181], off
	v_lshl_add_u64 v[180:181], v[246:247], 0, s[14:15]
	s_mov_b32 m0, s37
	s_nop 0
	global_load_lds_dwordx4 v[180:181], off
	v_lshl_add_u64 v[180:181], v[248:249], 0, s[14:15]
	s_mov_b32 m0, s40
	s_nop 0
	global_load_lds_dwordx4 v[180:181], off
	s_waitcnt vmcnt(8)
	s_waitcnt lgkmcnt(0)
	s_barrier
	s_setprio 1
	s_waitcnt lgkmcnt(0)
	v_mfma_f32_16x16x32_bf16 v[60:63], v[128:131], v[212:215], v[60:63]
	v_mfma_f32_16x16x32_bf16 v[56:59], v[136:139], v[212:215], v[56:59]
	v_mfma_f32_16x16x32_bf16 v[44:47], v[128:131], v[220:223], v[44:47]
	v_mfma_f32_16x16x32_bf16 v[40:43], v[136:139], v[220:223], v[40:43]
	v_mfma_f32_16x16x32_bf16 v[28:31], v[128:131], v[228:231], v[28:31]
	v_mfma_f32_16x16x32_bf16 v[24:27], v[136:139], v[228:231], v[24:27]
	v_mfma_f32_16x16x32_bf16 v[12:15], v[128:131], v[236:239], v[12:15]
	v_mfma_f32_16x16x32_bf16 v[8:11], v[136:139], v[236:239], v[8:11]
	v_mfma_f32_16x16x32_bf16 v[60:63], v[132:135], v[216:219], v[60:63]
	v_mfma_f32_16x16x32_bf16 v[56:59], v[168:171], v[216:219], v[56:59]
	v_mfma_f32_16x16x32_bf16 v[44:47], v[132:135], v[224:227], v[44:47]
	v_mfma_f32_16x16x32_bf16 v[40:43], v[168:171], v[224:227], v[40:43]
	v_mfma_f32_16x16x32_bf16 v[28:31], v[132:135], v[232:235], v[28:31]
	v_mfma_f32_16x16x32_bf16 v[24:27], v[168:171], v[232:235], v[24:27]
	v_mfma_f32_16x16x32_bf16 v[12:15], v[132:135], v[240:243], v[12:15]
	v_mfma_f32_16x16x32_bf16 v[8:11], v[168:171], v[240:243], v[8:11]
	s_setprio 0
	s_setprio 1
	v_mfma_f32_16x16x32_bf16 v[52:55], v[172:175], v[212:215], v[52:55]
	v_mfma_f32_16x16x32_bf16 v[48:51], v[204:207], v[212:215], v[48:51]
	v_mfma_f32_16x16x32_bf16 v[36:39], v[172:175], v[220:223], v[36:39]
	v_mfma_f32_16x16x32_bf16 v[32:35], v[204:207], v[220:223], v[32:35]
	v_mfma_f32_16x16x32_bf16 v[20:23], v[172:175], v[228:231], v[20:23]
	v_mfma_f32_16x16x32_bf16 v[16:19], v[204:207], v[228:231], v[16:19]
	v_mfma_f32_16x16x32_bf16 v[4:7], v[172:175], v[236:239], v[4:7]
	v_mfma_f32_16x16x32_bf16 v[0:3], v[204:207], v[236:239], v[0:3]
	v_mfma_f32_16x16x32_bf16 v[52:55], v[176:179], v[216:219], v[52:55]
	v_mfma_f32_16x16x32_bf16 v[48:51], v[208:211], v[216:219], v[48:51]
	v_mfma_f32_16x16x32_bf16 v[36:39], v[176:179], v[224:227], v[36:39]
	v_mfma_f32_16x16x32_bf16 v[32:35], v[208:211], v[224:227], v[32:35]
	v_mfma_f32_16x16x32_bf16 v[20:23], v[176:179], v[232:235], v[20:23]
	v_mfma_f32_16x16x32_bf16 v[16:19], v[208:211], v[232:235], v[16:19]
	v_mfma_f32_16x16x32_bf16 v[4:7], v[176:179], v[240:243], v[4:7]
	v_mfma_f32_16x16x32_bf16 v[0:3], v[208:211], v[240:243], v[0:3]
	s_setprio 0
	s_barrier
	s_add_i32 s66, s66, 2
	s_add_u32 s4, s4, 0x100
	s_addc_u32 s5, s5, 0
	s_cmp_gt_u32 s66, 41
	s_mov_b64 s[24:25], s[46:47]
	s_cbranch_scc0 .LBB0_1176
	s_mov_b64 s[88:89], s[78:79]
	s_and_b64 vcc, exec, s[26:27]
	s_cbranch_vccz .LBB0_1179
	s_barrier

.LBB0_1334:
	ds_read_b128 v[160:163], v167
	ds_read_b128 v[184:187], v168
	ds_read_b128 v[188:191], v169
	ds_read_b128 v[198:201], v170
	ds_read_b128 v[202:205], v171
	ds_read_b128 v[206:209], v172
	ds_read_b128 v[210:213], v173
	ds_read_b128 v[214:217], v174
	s_add_u32 s24, s14, 0xfffc0080
	s_addc_u32 s25, s15, -1
	s_cmp_eq_u32 s66, 12
	s_cselect_b32 s65, s4, s25
	s_cselect_b32 s64, s5, s24
	s_cselect_b32 s25, s11, s49
	s_cselect_b32 s24, s13, s47
	s_mov_b32 m0, s61
	v_lshl_add_u64 v[142:143], s[14:15], 0, v[134:135]
	ds_read_b128 v[218:221], v159
	ds_read_b128 v[222:225], v159 offset:1024
	ds_read_b128 v[226:229], v159 offset:2048
	ds_read_b128 v[230:233], v159 offset:3072
	ds_read_b128 v[234:237], v159 offset:4096
	ds_read_b128 v[238:241], v159 offset:5120
	ds_read_b128 v[242:245], v159 offset:6144
	ds_read_b128 v[246:249], v159 offset:7168
	global_load_lds_dwordx4 v[142:143], off
	v_lshl_add_u64 v[142:143], s[14:15], 0, v[136:137]
	s_mov_b32 m0, s67
	s_nop 0
	global_load_lds_dwordx4 v[142:143], off
	s_waitcnt vmcnt(8)
	s_waitcnt lgkmcnt(0)
	s_barrier
	s_setprio 1
	s_waitcnt lgkmcnt(0)
	v_mfma_f32_16x16x32_bf16 v[124:127], v[160:163], v[218:221], v[124:127]
	v_mfma_f32_16x16x32_bf16 v[120:123], v[188:191], v[218:221], v[120:123]
	v_mfma_f32_16x16x32_bf16 v[108:111], v[160:163], v[226:229], v[108:111]
	v_mfma_f32_16x16x32_bf16 v[104:107], v[188:191], v[226:229], v[104:107]
	v_mfma_f32_16x16x32_bf16 v[92:95], v[160:163], v[234:237], v[92:95]
	v_mfma_f32_16x16x32_bf16 v[88:91], v[188:191], v[234:237], v[88:91]
	v_mfma_f32_16x16x32_bf16 v[76:79], v[160:163], v[242:245], v[76:79]
	v_mfma_f32_16x16x32_bf16 v[72:75], v[188:191], v[242:245], v[72:75]
	v_mfma_f32_16x16x32_bf16 v[124:127], v[184:187], v[222:225], v[124:127]
	v_mfma_f32_16x16x32_bf16 v[120:123], v[198:201], v[222:225], v[120:123]
	v_mfma_f32_16x16x32_bf16 v[108:111], v[184:187], v[230:233], v[108:111]
	v_mfma_f32_16x16x32_bf16 v[104:107], v[198:201], v[230:233], v[104:107]
	v_mfma_f32_16x16x32_bf16 v[92:95], v[184:187], v[238:241], v[92:95]
	v_mfma_f32_16x16x32_bf16 v[88:91], v[198:201], v[238:241], v[88:91]
	v_mfma_f32_16x16x32_bf16 v[76:79], v[184:187], v[246:249], v[76:79]
	v_mfma_f32_16x16x32_bf16 v[72:75], v[198:201], v[246:249], v[72:75]
	s_setprio 0
	s_setprio 1
	v_mfma_f32_16x16x32_bf16 v[116:119], v[202:205], v[218:221], v[116:119]
	v_mfma_f32_16x16x32_bf16 v[112:115], v[210:213], v[218:221], v[112:115]
	v_mfma_f32_16x16x32_bf16 v[100:103], v[202:205], v[226:229], v[100:103]
	v_mfma_f32_16x16x32_bf16 v[96:99], v[210:213], v[226:229], v[96:99]
	v_mfma_f32_16x16x32_bf16 v[84:87], v[202:205], v[234:237], v[84:87]
	v_mfma_f32_16x16x32_bf16 v[80:83], v[210:213], v[234:237], v[80:83]
	v_mfma_f32_16x16x32_bf16 v[68:71], v[202:205], v[242:245], v[68:71]
	v_mfma_f32_16x16x32_bf16 v[64:67], v[210:213], v[242:245], v[64:67]
	v_mfma_f32_16x16x32_bf16 v[116:119], v[206:209], v[222:225], v[116:119]
	v_mfma_f32_16x16x32_bf16 v[112:115], v[214:217], v[222:225], v[112:115]
	v_mfma_f32_16x16x32_bf16 v[100:103], v[206:209], v[230:233], v[100:103]
	v_mfma_f32_16x16x32_bf16 v[96:99], v[214:217], v[230:233], v[96:99]
	v_mfma_f32_16x16x32_bf16 v[84:87], v[206:209], v[238:241], v[84:87]
	v_mfma_f32_16x16x32_bf16 v[80:83], v[214:217], v[238:241], v[80:83]
	v_mfma_f32_16x16x32_bf16 v[68:71], v[206:209], v[246:249], v[68:71]
	v_mfma_f32_16x16x32_bf16 v[64:67], v[214:217], v[246:249], v[64:67]
	s_setprio 0
	s_barrier
	s_mov_b32 m0, s6
	v_lshl_add_u64 v[142:143], s[24:25], 0, v[128:129]
	s_add_u32 s68, s24, 0x40000
	ds_read_b128 v[218:221], v159 offset:16384
	ds_read_b128 v[222:225], v159 offset:17408
	ds_read_b128 v[226:229], v159 offset:18432
	ds_read_b128 v[230:233], v159 offset:19456
	ds_read_b128 v[234:237], v159 offset:20480
	ds_read_b128 v[238:241], v159 offset:21504
	ds_read_b128 v[242:245], v159 offset:22528
	ds_read_b128 v[246:249], v159 offset:23552
	global_load_lds_dwordx4 v[142:143], off
	v_lshl_add_u64 v[164:165], s[24:25], 0, v[130:131]
	s_mov_b32 m0, s7
	s_addc_u32 s69, s25, 0
	global_load_lds_dwordx4 v[164:165], off
	v_lshl_add_u64 v[192:193], s[68:69], 0, v[128:129]
	s_mov_b32 m0, s28
	v_lshl_add_u64 v[250:251], s[64:65], 0, v[130:131]
	global_load_lds_dwordx4 v[192:193], off
	v_lshl_add_u64 v[192:193], s[68:69], 0, v[130:131]
	s_mov_b32 m0, s29
	s_nop 0
	global_load_lds_dwordx4 v[192:193], off
	v_lshl_add_u64 v[192:193], s[64:65], 0, v[128:129]
	s_mov_b32 m0, s2
	s_nop 0
	global_load_lds_dwordx4 v[192:193], off
	s_mov_b32 m0, s30
	s_nop 0
	global_load_lds_dwordx4 v[250:251], off
	s_waitcnt vmcnt(8)
	s_waitcnt lgkmcnt(0)
	s_barrier
	s_setprio 1
	s_waitcnt lgkmcnt(0)
	v_mfma_f32_16x16x32_bf16 v[60:63], v[160:163], v[218:221], v[60:63]
	v_mfma_f32_16x16x32_bf16 v[56:59], v[188:191], v[218:221], v[56:59]
	v_mfma_f32_16x16x32_bf16 v[44:47], v[160:163], v[226:229], v[44:47]
	v_mfma_f32_16x16x32_bf16 v[40:43], v[188:191], v[226:229], v[40:43]
	v_mfma_f32_16x16x32_bf16 v[28:31], v[160:163], v[234:237], v[28:31]
	v_mfma_f32_16x16x32_bf16 v[24:27], v[188:191], v[234:237], v[24:27]
	v_mfma_f32_16x16x32_bf16 v[12:15], v[160:163], v[242:245], v[12:15]
	v_mfma_f32_16x16x32_bf16 v[8:11], v[188:191], v[242:245], v[8:11]
	v_mfma_f32_16x16x32_bf16 v[60:63], v[184:187], v[222:225], v[60:63]
	v_mfma_f32_16x16x32_bf16 v[56:59], v[198:201], v[222:225], v[56:59]
	v_mfma_f32_16x16x32_bf16 v[44:47], v[184:187], v[230:233], v[44:47]
	v_mfma_f32_16x16x32_bf16 v[40:43], v[198:201], v[230:233], v[40:43]
	v_mfma_f32_16x16x32_bf16 v[28:31], v[184:187], v[238:241], v[28:31]
	v_mfma_f32_16x16x32_bf16 v[24:27], v[198:201], v[238:241], v[24:27]
	v_mfma_f32_16x16x32_bf16 v[12:15], v[184:187], v[246:249], v[12:15]
	v_mfma_f32_16x16x32_bf16 v[8:11], v[198:201], v[246:249], v[8:11]
	s_setprio 0
	s_setprio 1
	v_mfma_f32_16x16x32_bf16 v[52:55], v[202:205], v[218:221], v[52:55]
	v_mfma_f32_16x16x32_bf16 v[48:51], v[210:213], v[218:221], v[48:51]
	v_mfma_f32_16x16x32_bf16 v[36:39], v[202:205], v[226:229], v[36:39]
	v_mfma_f32_16x16x32_bf16 v[32:35], v[210:213], v[226:229], v[32:35]
	v_mfma_f32_16x16x32_bf16 v[20:23], v[202:205], v[234:237], v[20:23]
	v_mfma_f32_16x16x32_bf16 v[16:19], v[210:213], v[234:237], v[16:19]
	v_mfma_f32_16x16x32_bf16 v[4:7], v[202:205], v[242:245], v[4:7]
	v_mfma_f32_16x16x32_bf16 v[0:3], v[210:213], v[242:245], v[0:3]
	v_mfma_f32_16x16x32_bf16 v[52:55], v[206:209], v[222:225], v[52:55]
	v_mfma_f32_16x16x32_bf16 v[48:51], v[214:217], v[222:225], v[48:51]
	v_mfma_f32_16x16x32_bf16 v[36:39], v[206:209], v[230:233], v[36:39]
	v_mfma_f32_16x16x32_bf16 v[32:35], v[214:217], v[230:233], v[32:35]
	v_mfma_f32_16x16x32_bf16 v[20:23], v[206:209], v[238:241], v[20:23]
	v_mfma_f32_16x16x32_bf16 v[16:19], v[214:217], v[238:241], v[16:19]
	v_mfma_f32_16x16x32_bf16 v[4:7], v[206:209], v[246:249], v[4:7]
	v_mfma_f32_16x16x32_bf16 v[0:3], v[214:217], v[246:249], v[0:3]
	s_setprio 0
	s_barrier
	ds_read_b128 v[160:163], v175
	ds_read_b128 v[184:187], v176
	ds_read_b128 v[188:191], v177
	ds_read_b128 v[198:201], v178
	ds_read_b128 v[202:205], v179
	ds_read_b128 v[206:209], v180
	ds_read_b128 v[210:213], v181
	ds_read_b128 v[214:217], v182
	s_add_u32 s64, s64, 0x40000
	s_addc_u32 s65, s65, 0
	s_mov_b32 m0, s31
	v_lshl_add_u64 v[252:253], s[64:65], 0, v[128:129]
	ds_read_b128 v[218:221], v159 offset:32768
	ds_read_b128 v[222:225], v159 offset:33792
	ds_read_b128 v[226:229], v159 offset:34816
	ds_read_b128 v[230:233], v159 offset:35840
	ds_read_b128 v[234:237], v159 offset:36864
	ds_read_b128 v[238:241], v159 offset:37888
	ds_read_b128 v[242:245], v159 offset:38912
	ds_read_b128 v[246:249], v159 offset:39936
	global_load_lds_dwordx4 v[252:253], off
	v_lshl_add_u64 v[252:253], s[64:65], 0, v[130:131]
	s_mov_b32 m0, s33
	s_nop 0
	global_load_lds_dwordx4 v[252:253], off
	s_waitcnt vmcnt(8)
	s_waitcnt lgkmcnt(0)
	s_barrier
	s_setprio 1
	s_waitcnt lgkmcnt(0)
	v_mfma_f32_16x16x32_bf16 v[124:127], v[160:163], v[218:221], v[124:127]
	v_mfma_f32_16x16x32_bf16 v[120:123], v[188:191], v[218:221], v[120:123]
	v_mfma_f32_16x16x32_bf16 v[108:111], v[160:163], v[226:229], v[108:111]
	v_mfma_f32_16x16x32_bf16 v[104:107], v[188:191], v[226:229], v[104:107]
	v_mfma_f32_16x16x32_bf16 v[92:95], v[160:163], v[234:237], v[92:95]
	v_mfma_f32_16x16x32_bf16 v[88:91], v[188:191], v[234:237], v[88:91]
	v_mfma_f32_16x16x32_bf16 v[76:79], v[160:163], v[242:245], v[76:79]
	v_mfma_f32_16x16x32_bf16 v[72:75], v[188:191], v[242:245], v[72:75]
	v_mfma_f32_16x16x32_bf16 v[124:127], v[184:187], v[222:225], v[124:127]
	v_mfma_f32_16x16x32_bf16 v[120:123], v[198:201], v[222:225], v[120:123]
	v_mfma_f32_16x16x32_bf16 v[108:111], v[184:187], v[230:233], v[108:111]
	v_mfma_f32_16x16x32_bf16 v[104:107], v[198:201], v[230:233], v[104:107]
	v_mfma_f32_16x16x32_bf16 v[92:95], v[184:187], v[238:241], v[92:95]
	v_mfma_f32_16x16x32_bf16 v[88:91], v[198:201], v[238:241], v[88:91]
	v_mfma_f32_16x16x32_bf16 v[76:79], v[184:187], v[246:249], v[76:79]
	v_mfma_f32_16x16x32_bf16 v[72:75], v[198:201], v[246:249], v[72:75]
	s_setprio 0
	s_setprio 1
	v_mfma_f32_16x16x32_bf16 v[116:119], v[202:205], v[218:221], v[116:119]
	v_mfma_f32_16x16x32_bf16 v[112:115], v[210:213], v[218:221], v[112:115]
	v_mfma_f32_16x16x32_bf16 v[100:103], v[202:205], v[226:229], v[100:103]
	v_mfma_f32_16x16x32_bf16 v[96:99], v[210:213], v[226:229], v[96:99]
	v_mfma_f32_16x16x32_bf16 v[84:87], v[202:205], v[234:237], v[84:87]
	v_mfma_f32_16x16x32_bf16 v[80:83], v[210:213], v[234:237], v[80:83]
	v_mfma_f32_16x16x32_bf16 v[68:71], v[202:205], v[242:245], v[68:71]
	v_mfma_f32_16x16x32_bf16 v[64:67], v[210:213], v[242:245], v[64:67]
	v_mfma_f32_16x16x32_bf16 v[116:119], v[206:209], v[222:225], v[116:119]
	v_mfma_f32_16x16x32_bf16 v[112:115], v[214:217], v[222:225], v[112:115]
	v_mfma_f32_16x16x32_bf16 v[100:103], v[206:209], v[230:233], v[100:103]
	v_mfma_f32_16x16x32_bf16 v[96:99], v[214:217], v[230:233], v[96:99]
	v_mfma_f32_16x16x32_bf16 v[84:87], v[206:209], v[238:241], v[84:87]
	v_mfma_f32_16x16x32_bf16 v[80:83], v[214:217], v[238:241], v[80:83]
	v_mfma_f32_16x16x32_bf16 v[68:71], v[206:209], v[246:249], v[68:71]
	v_mfma_f32_16x16x32_bf16 v[64:67], v[214:217], v[246:249], v[64:67]
	s_setprio 0
	s_barrier
	s_mov_b32 m0, s34
	v_lshl_add_u64 v[142:143], v[142:143], 0, s[38:39]
	s_add_u32 s24, s24, 0x40080
	ds_read_b128 v[218:221], v159 offset:49152
	ds_read_b128 v[222:225], v159 offset:50176
	ds_read_b128 v[226:229], v159 offset:51200
	ds_read_b128 v[230:233], v159 offset:52224
	ds_read_b128 v[234:237], v159 offset:53248
	ds_read_b128 v[238:241], v159 offset:54272
	ds_read_b128 v[242:245], v159 offset:55296
	ds_read_b128 v[246:249], v159 offset:56320
	global_load_lds_dwordx4 v[142:143], off
	v_lshl_add_u64 v[142:143], v[164:165], 0, s[38:39]
	s_mov_b32 m0, s35
	s_addc_u32 s25, s25, 0
	global_load_lds_dwordx4 v[142:143], off
	v_lshl_add_u64 v[142:143], s[24:25], 0, v[128:129]
	s_mov_b32 m0, s40
	s_nop 0
	global_load_lds_dwordx4 v[142:143], off
	v_lshl_add_u64 v[142:143], s[24:25], 0, v[130:131]
	s_mov_b32 m0, s41
	s_nop 0
	global_load_lds_dwordx4 v[142:143], off
	v_lshl_add_u64 v[142:143], v[192:193], 0, s[38:39]
	s_mov_b32 m0, s36
	s_nop 0
	global_load_lds_dwordx4 v[142:143], off
	v_lshl_add_u64 v[142:143], v[250:251], 0, s[38:39]
	s_mov_b32 m0, s37
	s_nop 0
	global_load_lds_dwordx4 v[142:143], off
	s_waitcnt vmcnt(8)
	s_waitcnt lgkmcnt(0)
	s_barrier
	s_setprio 1
	s_waitcnt lgkmcnt(0)
	v_mfma_f32_16x16x32_bf16 v[60:63], v[160:163], v[218:221], v[60:63]
	v_mfma_f32_16x16x32_bf16 v[56:59], v[188:191], v[218:221], v[56:59]
	v_mfma_f32_16x16x32_bf16 v[44:47], v[160:163], v[226:229], v[44:47]
	v_mfma_f32_16x16x32_bf16 v[40:43], v[188:191], v[226:229], v[40:43]
	v_mfma_f32_16x16x32_bf16 v[28:31], v[160:163], v[234:237], v[28:31]
	v_mfma_f32_16x16x32_bf16 v[24:27], v[188:191], v[234:237], v[24:27]
	v_mfma_f32_16x16x32_bf16 v[12:15], v[160:163], v[242:245], v[12:15]
	v_mfma_f32_16x16x32_bf16 v[8:11], v[188:191], v[242:245], v[8:11]
	v_mfma_f32_16x16x32_bf16 v[60:63], v[184:187], v[222:225], v[60:63]
	v_mfma_f32_16x16x32_bf16 v[56:59], v[198:201], v[222:225], v[56:59]
	v_mfma_f32_16x16x32_bf16 v[44:47], v[184:187], v[230:233], v[44:47]
	v_mfma_f32_16x16x32_bf16 v[40:43], v[198:201], v[230:233], v[40:43]
	v_mfma_f32_16x16x32_bf16 v[28:31], v[184:187], v[238:241], v[28:31]
	v_mfma_f32_16x16x32_bf16 v[24:27], v[198:201], v[238:241], v[24:27]
	v_mfma_f32_16x16x32_bf16 v[12:15], v[184:187], v[246:249], v[12:15]
	v_mfma_f32_16x16x32_bf16 v[8:11], v[198:201], v[246:249], v[8:11]
	s_setprio 0
	s_setprio 1
	v_mfma_f32_16x16x32_bf16 v[52:55], v[202:205], v[218:221], v[52:55]
	v_mfma_f32_16x16x32_bf16 v[48:51], v[210:213], v[218:221], v[48:51]
	v_mfma_f32_16x16x32_bf16 v[36:39], v[202:205], v[226:229], v[36:39]
	v_mfma_f32_16x16x32_bf16 v[32:35], v[210:213], v[226:229], v[32:35]
	v_mfma_f32_16x16x32_bf16 v[20:23], v[202:205], v[234:237], v[20:23]
	v_mfma_f32_16x16x32_bf16 v[16:19], v[210:213], v[234:237], v[16:19]
	v_mfma_f32_16x16x32_bf16 v[4:7], v[202:205], v[242:245], v[4:7]
	v_mfma_f32_16x16x32_bf16 v[0:3], v[210:213], v[242:245], v[0:3]
	v_mfma_f32_16x16x32_bf16 v[52:55], v[206:209], v[222:225], v[52:55]
	v_mfma_f32_16x16x32_bf16 v[48:51], v[214:217], v[222:225], v[48:51]
	v_mfma_f32_16x16x32_bf16 v[36:39], v[206:209], v[230:233], v[36:39]
	v_mfma_f32_16x16x32_bf16 v[32:35], v[214:217], v[230:233], v[32:35]
	v_mfma_f32_16x16x32_bf16 v[20:23], v[206:209], v[238:241], v[20:23]
	v_mfma_f32_16x16x32_bf16 v[16:19], v[214:217], v[238:241], v[16:19]
	v_mfma_f32_16x16x32_bf16 v[4:7], v[206:209], v[246:249], v[4:7]
	v_mfma_f32_16x16x32_bf16 v[0:3], v[214:217], v[246:249], v[0:3]
	s_setprio 0
	s_barrier
	s_add_i32 s66, s66, 2
	s_add_u32 s14, s14, 0x100
	s_addc_u32 s15, s15, 0
	s_add_u32 s47, s47, 0x100
	s_addc_u32 s49, s49, 0
	s_cmp_gt_u32 s66, 13
	s_cbranch_scc0 .LBB0_1334
	s_and_b64 vcc, exec, s[42:43]
	s_cbranch_vccz .LBB0_1337
	s_barrier

.LBB0_1497:
	ds_read_b128 v[176:179], v159
	ds_read_b128 v[180:183], v160
	ds_read_b128 v[184:187], v161
	ds_read_b128 v[188:191], v162
	ds_read_b128 v[198:201], v163
	ds_read_b128 v[202:205], v164
	ds_read_b128 v[206:209], v165
	ds_read_b128 v[210:213], v166
	s_add_u32 s50, s24, 0x100
	s_addc_u32 s51, s25, 0
	s_cmp_eq_u32 s68, 12
	s_cselect_b32 s65, s4, s51
	s_cselect_b32 s64, s5, s50
	s_cselect_b32 s55, s39, s87
	s_cselect_b32 s54, s43, s86
	s_mov_b32 m0, s76
	v_lshl_add_u64 v[140:141], s[24:25], 0, v[132:133]
	ds_read_b128 v[214:217], v143
	ds_read_b128 v[218:221], v143 offset:1024
	ds_read_b128 v[222:225], v143 offset:2048
	ds_read_b128 v[226:229], v143 offset:3072
	ds_read_b128 v[230:233], v143 offset:4096
	ds_read_b128 v[234:237], v143 offset:5120
	ds_read_b128 v[238:241], v143 offset:6144
	ds_read_b128 v[242:245], v143 offset:7168
	global_load_lds_dwordx4 v[140:141], off
	v_lshl_add_u64 v[140:141], s[24:25], 0, v[134:135]
	s_mov_b32 m0, s77
	s_nop 0
	global_load_lds_dwordx4 v[140:141], off
	s_waitcnt vmcnt(8)
	s_waitcnt lgkmcnt(0)
	s_barrier
	s_setprio 1
	s_waitcnt lgkmcnt(0)
	v_mfma_f32_16x16x32_bf16 v[124:127], v[176:179], v[214:217], v[124:127]
	v_mfma_f32_16x16x32_bf16 v[120:123], v[184:187], v[214:217], v[120:123]
	v_mfma_f32_16x16x32_bf16 v[108:111], v[176:179], v[222:225], v[108:111]
	v_mfma_f32_16x16x32_bf16 v[104:107], v[184:187], v[222:225], v[104:107]
	v_mfma_f32_16x16x32_bf16 v[92:95], v[176:179], v[230:233], v[92:95]
	v_mfma_f32_16x16x32_bf16 v[88:91], v[184:187], v[230:233], v[88:91]
	v_mfma_f32_16x16x32_bf16 v[76:79], v[176:179], v[238:241], v[76:79]
	v_mfma_f32_16x16x32_bf16 v[72:75], v[184:187], v[238:241], v[72:75]
	v_mfma_f32_16x16x32_bf16 v[124:127], v[180:183], v[218:221], v[124:127]
	v_mfma_f32_16x16x32_bf16 v[120:123], v[188:191], v[218:221], v[120:123]
	v_mfma_f32_16x16x32_bf16 v[108:111], v[180:183], v[226:229], v[108:111]
	v_mfma_f32_16x16x32_bf16 v[104:107], v[188:191], v[226:229], v[104:107]
	v_mfma_f32_16x16x32_bf16 v[92:95], v[180:183], v[234:237], v[92:95]
	v_mfma_f32_16x16x32_bf16 v[88:91], v[188:191], v[234:237], v[88:91]
	v_mfma_f32_16x16x32_bf16 v[76:79], v[180:183], v[242:245], v[76:79]
	v_mfma_f32_16x16x32_bf16 v[72:75], v[188:191], v[242:245], v[72:75]
	s_setprio 0
	s_setprio 1
	v_mfma_f32_16x16x32_bf16 v[116:119], v[198:201], v[214:217], v[116:119]
	v_mfma_f32_16x16x32_bf16 v[112:115], v[206:209], v[214:217], v[112:115]
	v_mfma_f32_16x16x32_bf16 v[100:103], v[198:201], v[222:225], v[100:103]
	v_mfma_f32_16x16x32_bf16 v[96:99], v[206:209], v[222:225], v[96:99]
	v_mfma_f32_16x16x32_bf16 v[84:87], v[198:201], v[230:233], v[84:87]
	v_mfma_f32_16x16x32_bf16 v[80:83], v[206:209], v[230:233], v[80:83]
	v_mfma_f32_16x16x32_bf16 v[68:71], v[198:201], v[238:241], v[68:71]
	v_mfma_f32_16x16x32_bf16 v[64:67], v[206:209], v[238:241], v[64:67]
	v_mfma_f32_16x16x32_bf16 v[116:119], v[202:205], v[218:221], v[116:119]
	v_mfma_f32_16x16x32_bf16 v[112:115], v[210:213], v[218:221], v[112:115]
	v_mfma_f32_16x16x32_bf16 v[100:103], v[202:205], v[226:229], v[100:103]
	v_mfma_f32_16x16x32_bf16 v[96:99], v[210:213], v[226:229], v[96:99]
	v_mfma_f32_16x16x32_bf16 v[84:87], v[202:205], v[234:237], v[84:87]
	v_mfma_f32_16x16x32_bf16 v[80:83], v[210:213], v[234:237], v[80:83]
	v_mfma_f32_16x16x32_bf16 v[68:71], v[202:205], v[242:245], v[68:71]
	v_mfma_f32_16x16x32_bf16 v[64:67], v[210:213], v[242:245], v[64:67]
	s_setprio 0
	s_barrier
	s_mov_b32 m0, s29
	v_lshl_add_u64 v[140:141], s[54:55], 0, v[128:129]
	s_add_u32 s24, s54, 0x40000
	ds_read_b128 v[214:217], v143 offset:16384
	ds_read_b128 v[218:221], v143 offset:17408
	ds_read_b128 v[222:225], v143 offset:18432
	ds_read_b128 v[226:229], v143 offset:19456
	ds_read_b128 v[230:233], v143 offset:20480
	ds_read_b128 v[234:237], v143 offset:21504
	ds_read_b128 v[238:241], v143 offset:22528
	ds_read_b128 v[242:245], v143 offset:23552
	global_load_lds_dwordx4 v[140:141], off
	v_lshl_add_u64 v[192:193], s[54:55], 0, v[130:131]
	s_mov_b32 m0, s30
	s_addc_u32 s25, s55, 0
	global_load_lds_dwordx4 v[192:193], off
	v_lshl_add_u64 v[246:247], s[24:25], 0, v[128:129]
	s_mov_b32 m0, s31
	v_lshl_add_u64 v[248:249], s[64:65], 0, v[130:131]
	global_load_lds_dwordx4 v[246:247], off
	v_lshl_add_u64 v[246:247], s[24:25], 0, v[130:131]
	s_mov_b32 m0, s33
	s_nop 0
	global_load_lds_dwordx4 v[246:247], off
	v_lshl_add_u64 v[246:247], s[64:65], 0, v[128:129]
	s_mov_b32 m0, s28
	s_nop 0
	global_load_lds_dwordx4 v[246:247], off
	s_mov_b32 m0, s34
	s_nop 0
	global_load_lds_dwordx4 v[248:249], off
	s_waitcnt vmcnt(8)
	s_waitcnt lgkmcnt(0)
	s_barrier
	s_setprio 1
	s_waitcnt lgkmcnt(0)
	v_mfma_f32_16x16x32_bf16 v[60:63], v[176:179], v[214:217], v[60:63]
	v_mfma_f32_16x16x32_bf16 v[56:59], v[184:187], v[214:217], v[56:59]
	v_mfma_f32_16x16x32_bf16 v[44:47], v[176:179], v[222:225], v[44:47]
	v_mfma_f32_16x16x32_bf16 v[40:43], v[184:187], v[222:225], v[40:43]
	v_mfma_f32_16x16x32_bf16 v[28:31], v[176:179], v[230:233], v[28:31]
	v_mfma_f32_16x16x32_bf16 v[24:27], v[184:187], v[230:233], v[24:27]
	v_mfma_f32_16x16x32_bf16 v[12:15], v[176:179], v[238:241], v[12:15]
	v_mfma_f32_16x16x32_bf16 v[8:11], v[184:187], v[238:241], v[8:11]
	v_mfma_f32_16x16x32_bf16 v[60:63], v[180:183], v[218:221], v[60:63]
	v_mfma_f32_16x16x32_bf16 v[56:59], v[188:191], v[218:221], v[56:59]
	v_mfma_f32_16x16x32_bf16 v[44:47], v[180:183], v[226:229], v[44:47]
	v_mfma_f32_16x16x32_bf16 v[40:43], v[188:191], v[226:229], v[40:43]
	v_mfma_f32_16x16x32_bf16 v[28:31], v[180:183], v[234:237], v[28:31]
	v_mfma_f32_16x16x32_bf16 v[24:27], v[188:191], v[234:237], v[24:27]
	v_mfma_f32_16x16x32_bf16 v[12:15], v[180:183], v[242:245], v[12:15]
	v_mfma_f32_16x16x32_bf16 v[8:11], v[188:191], v[242:245], v[8:11]
	s_setprio 0
	s_setprio 1
	v_mfma_f32_16x16x32_bf16 v[52:55], v[198:201], v[214:217], v[52:55]
	v_mfma_f32_16x16x32_bf16 v[48:51], v[206:209], v[214:217], v[48:51]
	v_mfma_f32_16x16x32_bf16 v[36:39], v[198:201], v[222:225], v[36:39]
	v_mfma_f32_16x16x32_bf16 v[32:35], v[206:209], v[222:225], v[32:35]
	v_mfma_f32_16x16x32_bf16 v[20:23], v[198:201], v[230:233], v[20:23]
	v_mfma_f32_16x16x32_bf16 v[16:19], v[206:209], v[230:233], v[16:19]
	v_mfma_f32_16x16x32_bf16 v[4:7], v[198:201], v[238:241], v[4:7]
	v_mfma_f32_16x16x32_bf16 v[0:3], v[206:209], v[238:241], v[0:3]
	v_mfma_f32_16x16x32_bf16 v[52:55], v[202:205], v[218:221], v[52:55]
	v_mfma_f32_16x16x32_bf16 v[48:51], v[210:213], v[218:221], v[48:51]
	v_mfma_f32_16x16x32_bf16 v[36:39], v[202:205], v[226:229], v[36:39]
	v_mfma_f32_16x16x32_bf16 v[32:35], v[210:213], v[226:229], v[32:35]
	v_mfma_f32_16x16x32_bf16 v[20:23], v[202:205], v[234:237], v[20:23]
	v_mfma_f32_16x16x32_bf16 v[16:19], v[210:213], v[234:237], v[16:19]
	v_mfma_f32_16x16x32_bf16 v[4:7], v[202:205], v[242:245], v[4:7]
	v_mfma_f32_16x16x32_bf16 v[0:3], v[210:213], v[242:245], v[0:3]
	s_setprio 0
	s_barrier
	ds_read_b128 v[176:179], v167
	ds_read_b128 v[180:183], v168
	ds_read_b128 v[184:187], v169
	ds_read_b128 v[188:191], v170
	ds_read_b128 v[198:201], v171
	ds_read_b128 v[202:205], v172
	ds_read_b128 v[206:209], v173
	ds_read_b128 v[210:213], v174
	s_add_u32 s24, s64, 0x40000
	s_addc_u32 s25, s65, 0
	s_mov_b32 m0, s35
	v_lshl_add_u64 v[250:251], s[24:25], 0, v[128:129]
	ds_read_b128 v[214:217], v143 offset:32768
	ds_read_b128 v[218:221], v143 offset:33792
	ds_read_b128 v[222:225], v143 offset:34816
	ds_read_b128 v[226:229], v143 offset:35840
	ds_read_b128 v[230:233], v143 offset:36864
	ds_read_b128 v[234:237], v143 offset:37888
	ds_read_b128 v[238:241], v143 offset:38912
	ds_read_b128 v[242:245], v143 offset:39936
	global_load_lds_dwordx4 v[250:251], off
	v_lshl_add_u64 v[250:251], s[24:25], 0, v[130:131]
	s_mov_b32 m0, s36
	s_nop 0
	global_load_lds_dwordx4 v[250:251], off
	s_waitcnt vmcnt(8)
	s_waitcnt lgkmcnt(0)
	s_barrier
	s_setprio 1
	s_waitcnt lgkmcnt(0)
	v_mfma_f32_16x16x32_bf16 v[124:127], v[176:179], v[214:217], v[124:127]
	v_mfma_f32_16x16x32_bf16 v[120:123], v[184:187], v[214:217], v[120:123]
	v_mfma_f32_16x16x32_bf16 v[108:111], v[176:179], v[222:225], v[108:111]
	v_mfma_f32_16x16x32_bf16 v[104:107], v[184:187], v[222:225], v[104:107]
	v_mfma_f32_16x16x32_bf16 v[92:95], v[176:179], v[230:233], v[92:95]
	v_mfma_f32_16x16x32_bf16 v[88:91], v[184:187], v[230:233], v[88:91]
	v_mfma_f32_16x16x32_bf16 v[76:79], v[176:179], v[238:241], v[76:79]
	v_mfma_f32_16x16x32_bf16 v[72:75], v[184:187], v[238:241], v[72:75]
	v_mfma_f32_16x16x32_bf16 v[124:127], v[180:183], v[218:221], v[124:127]
	v_mfma_f32_16x16x32_bf16 v[120:123], v[188:191], v[218:221], v[120:123]
	v_mfma_f32_16x16x32_bf16 v[108:111], v[180:183], v[226:229], v[108:111]
	v_mfma_f32_16x16x32_bf16 v[104:107], v[188:191], v[226:229], v[104:107]
	v_mfma_f32_16x16x32_bf16 v[92:95], v[180:183], v[234:237], v[92:95]
	v_mfma_f32_16x16x32_bf16 v[88:91], v[188:191], v[234:237], v[88:91]
	v_mfma_f32_16x16x32_bf16 v[76:79], v[180:183], v[242:245], v[76:79]
	v_mfma_f32_16x16x32_bf16 v[72:75], v[188:191], v[242:245], v[72:75]
	s_setprio 0
	s_setprio 1
	v_mfma_f32_16x16x32_bf16 v[116:119], v[198:201], v[214:217], v[116:119]
	v_mfma_f32_16x16x32_bf16 v[112:115], v[206:209], v[214:217], v[112:115]
	v_mfma_f32_16x16x32_bf16 v[100:103], v[198:201], v[222:225], v[100:103]
	v_mfma_f32_16x16x32_bf16 v[96:99], v[206:209], v[222:225], v[96:99]
	v_mfma_f32_16x16x32_bf16 v[84:87], v[198:201], v[230:233], v[84:87]
	v_mfma_f32_16x16x32_bf16 v[80:83], v[206:209], v[230:233], v[80:83]
	v_mfma_f32_16x16x32_bf16 v[68:71], v[198:201], v[238:241], v[68:71]
	v_mfma_f32_16x16x32_bf16 v[64:67], v[206:209], v[238:241], v[64:67]
	v_mfma_f32_16x16x32_bf16 v[116:119], v[202:205], v[218:221], v[116:119]
	v_mfma_f32_16x16x32_bf16 v[112:115], v[210:213], v[218:221], v[112:115]
	v_mfma_f32_16x16x32_bf16 v[100:103], v[202:205], v[226:229], v[100:103]
	v_mfma_f32_16x16x32_bf16 v[96:99], v[210:213], v[226:229], v[96:99]
	v_mfma_f32_16x16x32_bf16 v[84:87], v[202:205], v[234:237], v[84:87]
	v_mfma_f32_16x16x32_bf16 v[80:83], v[210:213], v[234:237], v[80:83]
	v_mfma_f32_16x16x32_bf16 v[68:71], v[202:205], v[242:245], v[68:71]
	v_mfma_f32_16x16x32_bf16 v[64:67], v[210:213], v[242:245], v[64:67]
	s_setprio 0
	s_barrier
	s_mov_b32 m0, s40
	v_lshl_add_u64 v[140:141], v[140:141], 0, s[10:11]
	s_add_u32 s24, s54, 0x40080
	ds_read_b128 v[214:217], v143 offset:49152
	ds_read_b128 v[218:221], v143 offset:50176
	ds_read_b128 v[222:225], v143 offset:51200
	ds_read_b128 v[226:229], v143 offset:52224
	ds_read_b128 v[230:233], v143 offset:53248
	ds_read_b128 v[234:237], v143 offset:54272
	ds_read_b128 v[238:241], v143 offset:55296
	ds_read_b128 v[242:245], v143 offset:56320
	global_load_lds_dwordx4 v[140:141], off
	v_lshl_add_u64 v[140:141], v[192:193], 0, s[10:11]
	s_mov_b32 m0, s41
	s_addc_u32 s25, s55, 0
	global_load_lds_dwordx4 v[140:141], off
	v_lshl_add_u64 v[140:141], s[24:25], 0, v[128:129]
	s_mov_b32 m0, s53
	s_nop 0
	global_load_lds_dwordx4 v[140:141], off
	v_lshl_add_u64 v[140:141], s[24:25], 0, v[130:131]
	s_mov_b32 m0, s60
	s_nop 0
	global_load_lds_dwordx4 v[140:141], off
	v_lshl_add_u64 v[140:141], v[246:247], 0, s[10:11]
	s_mov_b32 m0, s49
	s_nop 0
	global_load_lds_dwordx4 v[140:141], off
	v_lshl_add_u64 v[140:141], v[248:249], 0, s[10:11]
	s_mov_b32 m0, s52
	s_nop 0
	global_load_lds_dwordx4 v[140:141], off
	s_waitcnt vmcnt(8)
	s_waitcnt lgkmcnt(0)
	s_barrier
	s_setprio 1
	s_waitcnt lgkmcnt(0)
	v_mfma_f32_16x16x32_bf16 v[60:63], v[176:179], v[214:217], v[60:63]
	v_mfma_f32_16x16x32_bf16 v[56:59], v[184:187], v[214:217], v[56:59]
	v_mfma_f32_16x16x32_bf16 v[44:47], v[176:179], v[222:225], v[44:47]
	v_mfma_f32_16x16x32_bf16 v[40:43], v[184:187], v[222:225], v[40:43]
	v_mfma_f32_16x16x32_bf16 v[28:31], v[176:179], v[230:233], v[28:31]
	v_mfma_f32_16x16x32_bf16 v[24:27], v[184:187], v[230:233], v[24:27]
	v_mfma_f32_16x16x32_bf16 v[12:15], v[176:179], v[238:241], v[12:15]
	v_mfma_f32_16x16x32_bf16 v[8:11], v[184:187], v[238:241], v[8:11]
	v_mfma_f32_16x16x32_bf16 v[60:63], v[180:183], v[218:221], v[60:63]
	v_mfma_f32_16x16x32_bf16 v[56:59], v[188:191], v[218:221], v[56:59]
	v_mfma_f32_16x16x32_bf16 v[44:47], v[180:183], v[226:229], v[44:47]
	v_mfma_f32_16x16x32_bf16 v[40:43], v[188:191], v[226:229], v[40:43]
	v_mfma_f32_16x16x32_bf16 v[28:31], v[180:183], v[234:237], v[28:31]
	v_mfma_f32_16x16x32_bf16 v[24:27], v[188:191], v[234:237], v[24:27]
	v_mfma_f32_16x16x32_bf16 v[12:15], v[180:183], v[242:245], v[12:15]
	v_mfma_f32_16x16x32_bf16 v[8:11], v[188:191], v[242:245], v[8:11]
	s_setprio 0
	s_setprio 1
	v_mfma_f32_16x16x32_bf16 v[52:55], v[198:201], v[214:217], v[52:55]
	v_mfma_f32_16x16x32_bf16 v[48:51], v[206:209], v[214:217], v[48:51]
	v_mfma_f32_16x16x32_bf16 v[36:39], v[198:201], v[222:225], v[36:39]
	v_mfma_f32_16x16x32_bf16 v[32:35], v[206:209], v[222:225], v[32:35]
	v_mfma_f32_16x16x32_bf16 v[20:23], v[198:201], v[230:233], v[20:23]
	v_mfma_f32_16x16x32_bf16 v[16:19], v[206:209], v[230:233], v[16:19]
	v_mfma_f32_16x16x32_bf16 v[4:7], v[198:201], v[238:241], v[4:7]
	v_mfma_f32_16x16x32_bf16 v[0:3], v[206:209], v[238:241], v[0:3]
	v_mfma_f32_16x16x32_bf16 v[52:55], v[202:205], v[218:221], v[52:55]
	v_mfma_f32_16x16x32_bf16 v[48:51], v[210:213], v[218:221], v[48:51]
	v_mfma_f32_16x16x32_bf16 v[36:39], v[202:205], v[226:229], v[36:39]
	v_mfma_f32_16x16x32_bf16 v[32:35], v[210:213], v[226:229], v[32:35]
	v_mfma_f32_16x16x32_bf16 v[20:23], v[202:205], v[234:237], v[20:23]
	v_mfma_f32_16x16x32_bf16 v[16:19], v[210:213], v[234:237], v[16:19]
	v_mfma_f32_16x16x32_bf16 v[4:7], v[202:205], v[242:245], v[4:7]
	v_mfma_f32_16x16x32_bf16 v[0:3], v[210:213], v[242:245], v[0:3]
	s_setprio 0
	s_barrier
	s_add_i32 s68, s68, 2
	s_add_u32 s86, s86, 0x100
	s_addc_u32 s87, s87, 0
	s_cmp_gt_u32 s68, 13
	s_mov_b64 s[24:25], s[50:51]
	s_cbranch_scc0 .LBB0_1497
	s_and_b64 vcc, exec, s[14:15]
	s_cbranch_vccz .LBB0_1500
	s_barrier

.LBB0_1766:
	ds_read_b128 v[128:131], v199
	ds_read_b128 v[132:135], v200
	ds_read_b128 v[136:139], v201
	ds_read_b128 v[140:143], v202
	ds_read_b128 v[172:175], v203
	ds_read_b128 v[176:179], v204
	ds_read_b128 v[180:183], v205
	ds_read_b128 v[184:187], v206
	s_add_u32 s74, s24, 0x100
	s_addc_u32 s75, s25, 0
	s_cmp_eq_u32 s68, 12
	s_cselect_b32 s85, s4, s75
	s_cselect_b32 s84, s5, s74
	s_cselect_b32 s81, s47, s87
	s_cselect_b32 s80, s49, s86
	s_mov_b32 m0, s65
	v_lshl_add_u64 v[192:193], s[24:25], 0, v[164:165]
	ds_read_b128 v[188:191], v159
	ds_read_b128 v[216:219], v159 offset:1024
	ds_read_b128 v[220:223], v159 offset:2048
	ds_read_b128 v[224:227], v159 offset:3072
	ds_read_b128 v[228:231], v159 offset:4096
	ds_read_b128 v[232:235], v159 offset:5120
	ds_read_b128 v[236:239], v159 offset:6144
	ds_read_b128 v[240:243], v159 offset:7168
	global_load_lds_dwordx4 v[192:193], off
	v_lshl_add_u64 v[192:193], s[24:25], 0, v[166:167]
	s_mov_b32 m0, s67
	s_nop 0
	global_load_lds_dwordx4 v[192:193], off
	s_waitcnt vmcnt(8)
	s_waitcnt lgkmcnt(0)
	s_barrier
	s_setprio 1
	s_waitcnt lgkmcnt(0)
	v_mfma_f32_16x16x32_bf16 v[124:127], v[128:131], v[188:191], v[124:127]
	v_mfma_f32_16x16x32_bf16 v[120:123], v[136:139], v[188:191], v[120:123]
	v_mfma_f32_16x16x32_bf16 v[108:111], v[128:131], v[220:223], v[108:111]
	v_mfma_f32_16x16x32_bf16 v[104:107], v[136:139], v[220:223], v[104:107]
	v_mfma_f32_16x16x32_bf16 v[92:95], v[128:131], v[228:231], v[92:95]
	v_mfma_f32_16x16x32_bf16 v[88:91], v[136:139], v[228:231], v[88:91]
	v_mfma_f32_16x16x32_bf16 v[76:79], v[128:131], v[236:239], v[76:79]
	v_mfma_f32_16x16x32_bf16 v[72:75], v[136:139], v[236:239], v[72:75]
	v_mfma_f32_16x16x32_bf16 v[124:127], v[132:135], v[216:219], v[124:127]
	v_mfma_f32_16x16x32_bf16 v[120:123], v[140:143], v[216:219], v[120:123]
	v_mfma_f32_16x16x32_bf16 v[108:111], v[132:135], v[224:227], v[108:111]
	v_mfma_f32_16x16x32_bf16 v[104:107], v[140:143], v[224:227], v[104:107]
	v_mfma_f32_16x16x32_bf16 v[92:95], v[132:135], v[232:235], v[92:95]
	v_mfma_f32_16x16x32_bf16 v[88:91], v[140:143], v[232:235], v[88:91]
	v_mfma_f32_16x16x32_bf16 v[76:79], v[132:135], v[240:243], v[76:79]
	v_mfma_f32_16x16x32_bf16 v[72:75], v[140:143], v[240:243], v[72:75]
	s_setprio 0
	s_setprio 1
	v_mfma_f32_16x16x32_bf16 v[116:119], v[172:175], v[188:191], v[116:119]
	v_mfma_f32_16x16x32_bf16 v[112:115], v[180:183], v[188:191], v[112:115]
	v_mfma_f32_16x16x32_bf16 v[100:103], v[172:175], v[220:223], v[100:103]
	v_mfma_f32_16x16x32_bf16 v[96:99], v[180:183], v[220:223], v[96:99]
	v_mfma_f32_16x16x32_bf16 v[84:87], v[172:175], v[228:231], v[84:87]
	v_mfma_f32_16x16x32_bf16 v[80:83], v[180:183], v[228:231], v[80:83]
	v_mfma_f32_16x16x32_bf16 v[68:71], v[172:175], v[236:239], v[68:71]
	v_mfma_f32_16x16x32_bf16 v[64:67], v[180:183], v[236:239], v[64:67]
	v_mfma_f32_16x16x32_bf16 v[116:119], v[176:179], v[216:219], v[116:119]
	v_mfma_f32_16x16x32_bf16 v[112:115], v[184:187], v[216:219], v[112:115]
	v_mfma_f32_16x16x32_bf16 v[100:103], v[176:179], v[224:227], v[100:103]
	v_mfma_f32_16x16x32_bf16 v[96:99], v[184:187], v[224:227], v[96:99]
	v_mfma_f32_16x16x32_bf16 v[84:87], v[176:179], v[232:235], v[84:87]
	v_mfma_f32_16x16x32_bf16 v[80:83], v[184:187], v[232:235], v[80:83]
	v_mfma_f32_16x16x32_bf16 v[68:71], v[176:179], v[240:243], v[68:71]
	v_mfma_f32_16x16x32_bf16 v[64:67], v[184:187], v[240:243], v[64:67]
	s_setprio 0
	s_barrier
	s_mov_b32 m0, s7
	v_lshl_add_u64 v[192:193], s[80:81], 0, v[160:161]
	s_add_u32 s24, s80, 0x40000
	ds_read_b128 v[188:191], v159 offset:16384
	ds_read_b128 v[216:219], v159 offset:17408
	ds_read_b128 v[220:223], v159 offset:18432
	ds_read_b128 v[224:227], v159 offset:19456
	ds_read_b128 v[228:231], v159 offset:20480
	ds_read_b128 v[232:235], v159 offset:21504
	ds_read_b128 v[236:239], v159 offset:22528
	ds_read_b128 v[240:243], v159 offset:23552
	global_load_lds_dwordx4 v[192:193], off
	v_lshl_add_u64 v[244:245], s[80:81], 0, v[162:163]
	s_mov_b32 m0, s28
	s_addc_u32 s25, s81, 0
	global_load_lds_dwordx4 v[244:245], off
	v_lshl_add_u64 v[246:247], s[24:25], 0, v[160:161]
	s_mov_b32 m0, s29
	v_lshl_add_u64 v[248:249], s[84:85], 0, v[162:163]
	global_load_lds_dwordx4 v[246:247], off
	v_lshl_add_u64 v[246:247], s[24:25], 0, v[162:163]
	s_mov_b32 m0, s30
	s_nop 0
	global_load_lds_dwordx4 v[246:247], off
	v_lshl_add_u64 v[246:247], s[84:85], 0, v[160:161]
	s_mov_b32 m0, s6
	s_nop 0
	global_load_lds_dwordx4 v[246:247], off
	s_mov_b32 m0, s31
	s_nop 0
	global_load_lds_dwordx4 v[248:249], off
	s_waitcnt vmcnt(8)
	s_waitcnt lgkmcnt(0)
	s_barrier
	s_setprio 1
	s_waitcnt lgkmcnt(0)
	v_mfma_f32_16x16x32_bf16 v[60:63], v[128:131], v[188:191], v[60:63]
	v_mfma_f32_16x16x32_bf16 v[56:59], v[136:139], v[188:191], v[56:59]
	v_mfma_f32_16x16x32_bf16 v[44:47], v[128:131], v[220:223], v[44:47]
	v_mfma_f32_16x16x32_bf16 v[40:43], v[136:139], v[220:223], v[40:43]
	v_mfma_f32_16x16x32_bf16 v[28:31], v[128:131], v[228:231], v[28:31]
	v_mfma_f32_16x16x32_bf16 v[24:27], v[136:139], v[228:231], v[24:27]
	v_mfma_f32_16x16x32_bf16 v[12:15], v[128:131], v[236:239], v[12:15]
	v_mfma_f32_16x16x32_bf16 v[8:11], v[136:139], v[236:239], v[8:11]
	v_mfma_f32_16x16x32_bf16 v[60:63], v[132:135], v[216:219], v[60:63]
	v_mfma_f32_16x16x32_bf16 v[56:59], v[140:143], v[216:219], v[56:59]
	v_mfma_f32_16x16x32_bf16 v[44:47], v[132:135], v[224:227], v[44:47]
	v_mfma_f32_16x16x32_bf16 v[40:43], v[140:143], v[224:227], v[40:43]
	v_mfma_f32_16x16x32_bf16 v[28:31], v[132:135], v[232:235], v[28:31]
	v_mfma_f32_16x16x32_bf16 v[24:27], v[140:143], v[232:235], v[24:27]
	v_mfma_f32_16x16x32_bf16 v[12:15], v[132:135], v[240:243], v[12:15]
	v_mfma_f32_16x16x32_bf16 v[8:11], v[140:143], v[240:243], v[8:11]
	s_setprio 0
	s_setprio 1
	v_mfma_f32_16x16x32_bf16 v[52:55], v[172:175], v[188:191], v[52:55]
	v_mfma_f32_16x16x32_bf16 v[48:51], v[180:183], v[188:191], v[48:51]
	v_mfma_f32_16x16x32_bf16 v[36:39], v[172:175], v[220:223], v[36:39]
	v_mfma_f32_16x16x32_bf16 v[32:35], v[180:183], v[220:223], v[32:35]
	v_mfma_f32_16x16x32_bf16 v[20:23], v[172:175], v[228:231], v[20:23]
	v_mfma_f32_16x16x32_bf16 v[16:19], v[180:183], v[228:231], v[16:19]
	v_mfma_f32_16x16x32_bf16 v[4:7], v[172:175], v[236:239], v[4:7]
	v_mfma_f32_16x16x32_bf16 v[0:3], v[180:183], v[236:239], v[0:3]
	v_mfma_f32_16x16x32_bf16 v[52:55], v[176:179], v[216:219], v[52:55]
	v_mfma_f32_16x16x32_bf16 v[48:51], v[184:187], v[216:219], v[48:51]
	v_mfma_f32_16x16x32_bf16 v[36:39], v[176:179], v[224:227], v[36:39]
	v_mfma_f32_16x16x32_bf16 v[32:35], v[184:187], v[224:227], v[32:35]
	v_mfma_f32_16x16x32_bf16 v[20:23], v[176:179], v[232:235], v[20:23]
	v_mfma_f32_16x16x32_bf16 v[16:19], v[184:187], v[232:235], v[16:19]
	v_mfma_f32_16x16x32_bf16 v[4:7], v[176:179], v[240:243], v[4:7]
	v_mfma_f32_16x16x32_bf16 v[0:3], v[184:187], v[240:243], v[0:3]
	s_setprio 0
	s_barrier
	ds_read_b128 v[128:131], v207
	ds_read_b128 v[132:135], v208
	ds_read_b128 v[136:139], v209
	ds_read_b128 v[140:143], v210
	ds_read_b128 v[172:175], v211
	ds_read_b128 v[176:179], v212
	ds_read_b128 v[180:183], v213
	ds_read_b128 v[184:187], v214
	s_add_u32 s24, s84, 0x40000
	s_addc_u32 s25, s85, 0
	s_mov_b32 m0, s33
	v_lshl_add_u64 v[250:251], s[24:25], 0, v[160:161]
	ds_read_b128 v[188:191], v159 offset:32768
	ds_read_b128 v[216:219], v159 offset:33792
	ds_read_b128 v[220:223], v159 offset:34816
	ds_read_b128 v[224:227], v159 offset:35840
	ds_read_b128 v[228:231], v159 offset:36864
	ds_read_b128 v[232:235], v159 offset:37888
	ds_read_b128 v[236:239], v159 offset:38912
	ds_read_b128 v[240:243], v159 offset:39936
	global_load_lds_dwordx4 v[250:251], off
	v_lshl_add_u64 v[250:251], s[24:25], 0, v[162:163]
	s_mov_b32 m0, s34
	s_nop 0
	global_load_lds_dwordx4 v[250:251], off
	s_waitcnt vmcnt(8)
	s_waitcnt lgkmcnt(0)
	s_barrier
	s_setprio 1
	s_waitcnt lgkmcnt(0)
	v_mfma_f32_16x16x32_bf16 v[124:127], v[128:131], v[188:191], v[124:127]
	v_mfma_f32_16x16x32_bf16 v[120:123], v[136:139], v[188:191], v[120:123]
	v_mfma_f32_16x16x32_bf16 v[108:111], v[128:131], v[220:223], v[108:111]
	v_mfma_f32_16x16x32_bf16 v[104:107], v[136:139], v[220:223], v[104:107]
	v_mfma_f32_16x16x32_bf16 v[92:95], v[128:131], v[228:231], v[92:95]
	v_mfma_f32_16x16x32_bf16 v[88:91], v[136:139], v[228:231], v[88:91]
	v_mfma_f32_16x16x32_bf16 v[76:79], v[128:131], v[236:239], v[76:79]
	v_mfma_f32_16x16x32_bf16 v[72:75], v[136:139], v[236:239], v[72:75]
	v_mfma_f32_16x16x32_bf16 v[124:127], v[132:135], v[216:219], v[124:127]
	v_mfma_f32_16x16x32_bf16 v[120:123], v[140:143], v[216:219], v[120:123]
	v_mfma_f32_16x16x32_bf16 v[108:111], v[132:135], v[224:227], v[108:111]
	v_mfma_f32_16x16x32_bf16 v[104:107], v[140:143], v[224:227], v[104:107]
	v_mfma_f32_16x16x32_bf16 v[92:95], v[132:135], v[232:235], v[92:95]
	v_mfma_f32_16x16x32_bf16 v[88:91], v[140:143], v[232:235], v[88:91]
	v_mfma_f32_16x16x32_bf16 v[76:79], v[132:135], v[240:243], v[76:79]
	v_mfma_f32_16x16x32_bf16 v[72:75], v[140:143], v[240:243], v[72:75]
	s_setprio 0
	s_setprio 1
	v_mfma_f32_16x16x32_bf16 v[116:119], v[172:175], v[188:191], v[116:119]
	v_mfma_f32_16x16x32_bf16 v[112:115], v[180:183], v[188:191], v[112:115]
	v_mfma_f32_16x16x32_bf16 v[100:103], v[172:175], v[220:223], v[100:103]
	v_mfma_f32_16x16x32_bf16 v[96:99], v[180:183], v[220:223], v[96:99]
	v_mfma_f32_16x16x32_bf16 v[84:87], v[172:175], v[228:231], v[84:87]
	v_mfma_f32_16x16x32_bf16 v[80:83], v[180:183], v[228:231], v[80:83]
	v_mfma_f32_16x16x32_bf16 v[68:71], v[172:175], v[236:239], v[68:71]
	v_mfma_f32_16x16x32_bf16 v[64:67], v[180:183], v[236:239], v[64:67]
	v_mfma_f32_16x16x32_bf16 v[116:119], v[176:179], v[216:219], v[116:119]
	v_mfma_f32_16x16x32_bf16 v[112:115], v[184:187], v[216:219], v[112:115]
	v_mfma_f32_16x16x32_bf16 v[100:103], v[176:179], v[224:227], v[100:103]
	v_mfma_f32_16x16x32_bf16 v[96:99], v[184:187], v[224:227], v[96:99]
	v_mfma_f32_16x16x32_bf16 v[84:87], v[176:179], v[232:235], v[84:87]
	v_mfma_f32_16x16x32_bf16 v[80:83], v[184:187], v[232:235], v[80:83]
	v_mfma_f32_16x16x32_bf16 v[68:71], v[176:179], v[240:243], v[68:71]
	v_mfma_f32_16x16x32_bf16 v[64:67], v[184:187], v[240:243], v[64:67]
	s_setprio 0
	s_barrier
	s_mov_b32 m0, s35
	v_lshl_add_u64 v[192:193], v[192:193], 0, s[38:39]
	s_add_u32 s24, s80, 0x40080
	ds_read_b128 v[188:191], v159 offset:49152
	ds_read_b128 v[216:219], v159 offset:50176
	ds_read_b128 v[220:223], v159 offset:51200
	ds_read_b128 v[224:227], v159 offset:52224
	ds_read_b128 v[228:231], v159 offset:53248
	ds_read_b128 v[232:235], v159 offset:54272
	ds_read_b128 v[236:239], v159 offset:55296
	ds_read_b128 v[240:243], v159 offset:56320
	global_load_lds_dwordx4 v[192:193], off
	v_lshl_add_u64 v[192:193], v[244:245], 0, s[38:39]
	s_mov_b32 m0, s36
	s_addc_u32 s25, s81, 0
	global_load_lds_dwordx4 v[192:193], off
	v_lshl_add_u64 v[192:193], s[24:25], 0, v[160:161]
	s_mov_b32 m0, s41
	s_nop 0
	global_load_lds_dwordx4 v[192:193], off
	v_lshl_add_u64 v[192:193], s[24:25], 0, v[162:163]
	s_mov_b32 m0, s45
	s_nop 0
	global_load_lds_dwordx4 v[192:193], off
	v_lshl_add_u64 v[192:193], v[246:247], 0, s[38:39]
	s_mov_b32 m0, s37
	s_nop 0
	global_load_lds_dwordx4 v[192:193], off
	v_lshl_add_u64 v[192:193], v[248:249], 0, s[38:39]
	s_mov_b32 m0, s40
	s_nop 0
	global_load_lds_dwordx4 v[192:193], off
	s_waitcnt vmcnt(8)
	s_waitcnt lgkmcnt(0)
	s_barrier
	s_setprio 1
	s_waitcnt lgkmcnt(0)
	v_mfma_f32_16x16x32_bf16 v[60:63], v[128:131], v[188:191], v[60:63]
	v_mfma_f32_16x16x32_bf16 v[56:59], v[136:139], v[188:191], v[56:59]
	v_mfma_f32_16x16x32_bf16 v[44:47], v[128:131], v[220:223], v[44:47]
	v_mfma_f32_16x16x32_bf16 v[40:43], v[136:139], v[220:223], v[40:43]
	v_mfma_f32_16x16x32_bf16 v[28:31], v[128:131], v[228:231], v[28:31]
	v_mfma_f32_16x16x32_bf16 v[24:27], v[136:139], v[228:231], v[24:27]
	v_mfma_f32_16x16x32_bf16 v[12:15], v[128:131], v[236:239], v[12:15]
	v_mfma_f32_16x16x32_bf16 v[8:11], v[136:139], v[236:239], v[8:11]
	v_mfma_f32_16x16x32_bf16 v[60:63], v[132:135], v[216:219], v[60:63]
	v_mfma_f32_16x16x32_bf16 v[56:59], v[140:143], v[216:219], v[56:59]
	v_mfma_f32_16x16x32_bf16 v[44:47], v[132:135], v[224:227], v[44:47]
	v_mfma_f32_16x16x32_bf16 v[40:43], v[140:143], v[224:227], v[40:43]
	v_mfma_f32_16x16x32_bf16 v[28:31], v[132:135], v[232:235], v[28:31]
	v_mfma_f32_16x16x32_bf16 v[24:27], v[140:143], v[232:235], v[24:27]
	v_mfma_f32_16x16x32_bf16 v[12:15], v[132:135], v[240:243], v[12:15]
	v_mfma_f32_16x16x32_bf16 v[8:11], v[140:143], v[240:243], v[8:11]
	s_setprio 0
	s_setprio 1
	v_mfma_f32_16x16x32_bf16 v[52:55], v[172:175], v[188:191], v[52:55]
	v_mfma_f32_16x16x32_bf16 v[48:51], v[180:183], v[188:191], v[48:51]
	v_mfma_f32_16x16x32_bf16 v[36:39], v[172:175], v[220:223], v[36:39]
	v_mfma_f32_16x16x32_bf16 v[32:35], v[180:183], v[220:223], v[32:35]
	v_mfma_f32_16x16x32_bf16 v[20:23], v[172:175], v[228:231], v[20:23]
	v_mfma_f32_16x16x32_bf16 v[16:19], v[180:183], v[228:231], v[16:19]
	v_mfma_f32_16x16x32_bf16 v[4:7], v[172:175], v[236:239], v[4:7]
	v_mfma_f32_16x16x32_bf16 v[0:3], v[180:183], v[236:239], v[0:3]
	v_mfma_f32_16x16x32_bf16 v[52:55], v[176:179], v[216:219], v[52:55]
	v_mfma_f32_16x16x32_bf16 v[48:51], v[184:187], v[216:219], v[48:51]
	v_mfma_f32_16x16x32_bf16 v[36:39], v[176:179], v[224:227], v[36:39]
	v_mfma_f32_16x16x32_bf16 v[32:35], v[184:187], v[224:227], v[32:35]
	v_mfma_f32_16x16x32_bf16 v[20:23], v[176:179], v[232:235], v[20:23]
	v_mfma_f32_16x16x32_bf16 v[16:19], v[184:187], v[232:235], v[16:19]
	v_mfma_f32_16x16x32_bf16 v[4:7], v[176:179], v[240:243], v[4:7]
	v_mfma_f32_16x16x32_bf16 v[0:3], v[184:187], v[240:243], v[0:3]
	s_setprio 0
	s_barrier
	s_add_i32 s68, s68, 2
	s_add_u32 s86, s86, 0x100
	s_addc_u32 s87, s87, 0
	s_cmp_gt_u32 s68, 13
	s_mov_b64 s[24:25], s[74:75]
	s_cbranch_scc0 .LBB0_1766
	s_and_b64 vcc, exec, s[42:43]
	s_cbranch_vccz .LBB0_1769
	s_barrier

.LBB0_1914:
	ds_read_b128 v[174:177], v143
	ds_read_b128 v[178:181], v153
	ds_read_b128 v[182:185], v159
	ds_read_b128 v[186:189], v160
	ds_read_b128 v[190:193], v161
	ds_read_b128 v[198:201], v162
	ds_read_b128 v[202:205], v163
	ds_read_b128 v[206:209], v164
	s_add_u32 s48, s24, 0xfffc0080
	s_addc_u32 s49, s25, -1
	s_cmp_eq_u32 s75, 12
	s_cselect_b32 s51, s4, s49
	s_cselect_b32 s50, s5, s48
	s_cselect_b32 s49, s39, s74
	s_cselect_b32 s48, s41, s67
	s_mov_b32 m0, s61
	v_lshl_add_u64 v[242:243], s[24:25], 0, v[132:133]
	ds_read_b128 v[210:213], v141
	ds_read_b128 v[214:217], v141 offset:1024
	ds_read_b128 v[218:221], v141 offset:2048
	ds_read_b128 v[222:225], v141 offset:3072
	ds_read_b128 v[226:229], v141 offset:4096
	ds_read_b128 v[230:233], v141 offset:5120
	ds_read_b128 v[234:237], v141 offset:6144
	ds_read_b128 v[238:241], v141 offset:7168
	global_load_lds_dwordx4 v[242:243], off
	v_lshl_add_u64 v[242:243], s[24:25], 0, v[134:135]
	s_mov_b32 m0, s64
	s_nop 0
	global_load_lds_dwordx4 v[242:243], off
	s_waitcnt vmcnt(8)
	s_waitcnt lgkmcnt(0)
	s_barrier
	s_setprio 1
	s_waitcnt lgkmcnt(0)
	v_mfma_f32_16x16x32_bf16 v[124:127], v[174:177], v[210:213], v[124:127]
	v_mfma_f32_16x16x32_bf16 v[120:123], v[182:185], v[210:213], v[120:123]
	v_mfma_f32_16x16x32_bf16 v[108:111], v[174:177], v[218:221], v[108:111]
	v_mfma_f32_16x16x32_bf16 v[104:107], v[182:185], v[218:221], v[104:107]
	v_mfma_f32_16x16x32_bf16 v[92:95], v[174:177], v[226:229], v[92:95]
	v_mfma_f32_16x16x32_bf16 v[88:91], v[182:185], v[226:229], v[88:91]
	v_mfma_f32_16x16x32_bf16 v[76:79], v[174:177], v[234:237], v[76:79]
	v_mfma_f32_16x16x32_bf16 v[72:75], v[182:185], v[234:237], v[72:75]
	v_mfma_f32_16x16x32_bf16 v[124:127], v[178:181], v[214:217], v[124:127]
	v_mfma_f32_16x16x32_bf16 v[120:123], v[186:189], v[214:217], v[120:123]
	v_mfma_f32_16x16x32_bf16 v[108:111], v[178:181], v[222:225], v[108:111]
	v_mfma_f32_16x16x32_bf16 v[104:107], v[186:189], v[222:225], v[104:107]
	v_mfma_f32_16x16x32_bf16 v[92:95], v[178:181], v[230:233], v[92:95]
	v_mfma_f32_16x16x32_bf16 v[88:91], v[186:189], v[230:233], v[88:91]
	v_mfma_f32_16x16x32_bf16 v[76:79], v[178:181], v[238:241], v[76:79]
	v_mfma_f32_16x16x32_bf16 v[72:75], v[186:189], v[238:241], v[72:75]
	s_setprio 0
	s_setprio 1
	v_mfma_f32_16x16x32_bf16 v[116:119], v[190:193], v[210:213], v[116:119]
	v_mfma_f32_16x16x32_bf16 v[112:115], v[202:205], v[210:213], v[112:115]
	v_mfma_f32_16x16x32_bf16 v[100:103], v[190:193], v[218:221], v[100:103]
	v_mfma_f32_16x16x32_bf16 v[96:99], v[202:205], v[218:221], v[96:99]
	v_mfma_f32_16x16x32_bf16 v[84:87], v[190:193], v[226:229], v[84:87]
	v_mfma_f32_16x16x32_bf16 v[80:83], v[202:205], v[226:229], v[80:83]
	v_mfma_f32_16x16x32_bf16 v[68:71], v[190:193], v[234:237], v[68:71]
	v_mfma_f32_16x16x32_bf16 v[64:67], v[202:205], v[234:237], v[64:67]
	v_mfma_f32_16x16x32_bf16 v[116:119], v[198:201], v[214:217], v[116:119]
	v_mfma_f32_16x16x32_bf16 v[112:115], v[206:209], v[214:217], v[112:115]
	v_mfma_f32_16x16x32_bf16 v[100:103], v[198:201], v[222:225], v[100:103]
	v_mfma_f32_16x16x32_bf16 v[96:99], v[206:209], v[222:225], v[96:99]
	v_mfma_f32_16x16x32_bf16 v[84:87], v[198:201], v[230:233], v[84:87]
	v_mfma_f32_16x16x32_bf16 v[80:83], v[206:209], v[230:233], v[80:83]
	v_mfma_f32_16x16x32_bf16 v[68:71], v[198:201], v[238:241], v[68:71]
	v_mfma_f32_16x16x32_bf16 v[64:67], v[206:209], v[238:241], v[64:67]
	s_setprio 0
	s_barrier
	s_mov_b32 m0, s8
	v_lshl_add_u64 v[242:243], s[48:49], 0, v[130:131]
	s_add_u32 s68, s48, 0x40000
	ds_read_b128 v[210:213], v141 offset:16384
	ds_read_b128 v[214:217], v141 offset:17408
	ds_read_b128 v[218:221], v141 offset:18432
	ds_read_b128 v[222:225], v141 offset:19456
	ds_read_b128 v[226:229], v141 offset:20480
	ds_read_b128 v[230:233], v141 offset:21504
	ds_read_b128 v[234:237], v141 offset:22528
	ds_read_b128 v[238:241], v141 offset:23552
	global_load_lds_dwordx4 v[242:243], off
	v_lshl_add_u64 v[244:245], s[48:49], 0, v[128:129]
	s_mov_b32 m0, s9
	s_addc_u32 s69, s49, 0
	global_load_lds_dwordx4 v[244:245], off
	v_lshl_add_u64 v[246:247], s[68:69], 0, v[130:131]
	s_mov_b32 m0, s28
	v_lshl_add_u64 v[248:249], s[50:51], 0, v[128:129]
	global_load_lds_dwordx4 v[246:247], off
	v_lshl_add_u64 v[246:247], s[68:69], 0, v[128:129]
	s_mov_b32 m0, s29
	s_nop 0
	global_load_lds_dwordx4 v[246:247], off
	v_lshl_add_u64 v[246:247], s[50:51], 0, v[130:131]
	s_mov_b32 m0, s2
	s_nop 0
	global_load_lds_dwordx4 v[246:247], off
	s_mov_b32 m0, s30
	s_nop 0
	global_load_lds_dwordx4 v[248:249], off
	s_waitcnt vmcnt(8)
	s_waitcnt lgkmcnt(0)
	s_barrier
	s_setprio 1
	s_waitcnt lgkmcnt(0)
	v_mfma_f32_16x16x32_bf16 v[60:63], v[174:177], v[210:213], v[60:63]
	v_mfma_f32_16x16x32_bf16 v[56:59], v[182:185], v[210:213], v[56:59]
	v_mfma_f32_16x16x32_bf16 v[44:47], v[174:177], v[218:221], v[44:47]
	v_mfma_f32_16x16x32_bf16 v[40:43], v[182:185], v[218:221], v[40:43]
	v_mfma_f32_16x16x32_bf16 v[28:31], v[174:177], v[226:229], v[28:31]
	v_mfma_f32_16x16x32_bf16 v[24:27], v[182:185], v[226:229], v[24:27]
	v_mfma_f32_16x16x32_bf16 v[12:15], v[174:177], v[234:237], v[12:15]
	v_mfma_f32_16x16x32_bf16 v[8:11], v[182:185], v[234:237], v[8:11]
	v_mfma_f32_16x16x32_bf16 v[60:63], v[178:181], v[214:217], v[60:63]
	v_mfma_f32_16x16x32_bf16 v[56:59], v[186:189], v[214:217], v[56:59]
	v_mfma_f32_16x16x32_bf16 v[44:47], v[178:181], v[222:225], v[44:47]
	v_mfma_f32_16x16x32_bf16 v[40:43], v[186:189], v[222:225], v[40:43]
	v_mfma_f32_16x16x32_bf16 v[28:31], v[178:181], v[230:233], v[28:31]
	v_mfma_f32_16x16x32_bf16 v[24:27], v[186:189], v[230:233], v[24:27]
	v_mfma_f32_16x16x32_bf16 v[12:15], v[178:181], v[238:241], v[12:15]
	v_mfma_f32_16x16x32_bf16 v[8:11], v[186:189], v[238:241], v[8:11]
	s_setprio 0
	s_setprio 1
	v_mfma_f32_16x16x32_bf16 v[52:55], v[190:193], v[210:213], v[52:55]
	v_mfma_f32_16x16x32_bf16 v[48:51], v[202:205], v[210:213], v[48:51]
	v_mfma_f32_16x16x32_bf16 v[36:39], v[190:193], v[218:221], v[36:39]
	v_mfma_f32_16x16x32_bf16 v[32:35], v[202:205], v[218:221], v[32:35]
	v_mfma_f32_16x16x32_bf16 v[20:23], v[190:193], v[226:229], v[20:23]
	v_mfma_f32_16x16x32_bf16 v[16:19], v[202:205], v[226:229], v[16:19]
	v_mfma_f32_16x16x32_bf16 v[4:7], v[190:193], v[234:237], v[4:7]
	v_mfma_f32_16x16x32_bf16 v[0:3], v[202:205], v[234:237], v[0:3]
	v_mfma_f32_16x16x32_bf16 v[52:55], v[198:201], v[214:217], v[52:55]
	v_mfma_f32_16x16x32_bf16 v[48:51], v[206:209], v[214:217], v[48:51]
	v_mfma_f32_16x16x32_bf16 v[36:39], v[198:201], v[222:225], v[36:39]
	v_mfma_f32_16x16x32_bf16 v[32:35], v[206:209], v[222:225], v[32:35]
	v_mfma_f32_16x16x32_bf16 v[20:23], v[198:201], v[230:233], v[20:23]
	v_mfma_f32_16x16x32_bf16 v[16:19], v[206:209], v[230:233], v[16:19]
	v_mfma_f32_16x16x32_bf16 v[4:7], v[198:201], v[238:241], v[4:7]
	v_mfma_f32_16x16x32_bf16 v[0:3], v[206:209], v[238:241], v[0:3]
	s_setprio 0
	s_barrier
	ds_read_b128 v[174:177], v165
	ds_read_b128 v[178:181], v166
	ds_read_b128 v[182:185], v167
	ds_read_b128 v[186:189], v168
	ds_read_b128 v[190:193], v169
	ds_read_b128 v[198:201], v170
	ds_read_b128 v[202:205], v171
	ds_read_b128 v[206:209], v172
	s_add_u32 s50, s50, 0x40000
	s_addc_u32 s51, s51, 0
	s_mov_b32 m0, s31
	v_lshl_add_u64 v[250:251], s[50:51], 0, v[130:131]
	ds_read_b128 v[210:213], v141 offset:32768
	ds_read_b128 v[214:217], v141 offset:33792
	ds_read_b128 v[218:221], v141 offset:34816
	ds_read_b128 v[222:225], v141 offset:35840
	ds_read_b128 v[226:229], v141 offset:36864
	ds_read_b128 v[230:233], v141 offset:37888
	ds_read_b128 v[234:237], v141 offset:38912
	ds_read_b128 v[238:241], v141 offset:39936
	global_load_lds_dwordx4 v[250:251], off
	v_lshl_add_u64 v[250:251], s[50:51], 0, v[128:129]
	s_mov_b32 m0, s33
	s_nop 0
	global_load_lds_dwordx4 v[250:251], off
	s_waitcnt vmcnt(8)
	s_waitcnt lgkmcnt(0)
	s_barrier
	s_setprio 1
	s_waitcnt lgkmcnt(0)
	v_mfma_f32_16x16x32_bf16 v[124:127], v[174:177], v[210:213], v[124:127]
	v_mfma_f32_16x16x32_bf16 v[120:123], v[182:185], v[210:213], v[120:123]
	v_mfma_f32_16x16x32_bf16 v[108:111], v[174:177], v[218:221], v[108:111]
	v_mfma_f32_16x16x32_bf16 v[104:107], v[182:185], v[218:221], v[104:107]
	v_mfma_f32_16x16x32_bf16 v[92:95], v[174:177], v[226:229], v[92:95]
	v_mfma_f32_16x16x32_bf16 v[88:91], v[182:185], v[226:229], v[88:91]
	v_mfma_f32_16x16x32_bf16 v[76:79], v[174:177], v[234:237], v[76:79]
	v_mfma_f32_16x16x32_bf16 v[72:75], v[182:185], v[234:237], v[72:75]
	v_mfma_f32_16x16x32_bf16 v[124:127], v[178:181], v[214:217], v[124:127]
	v_mfma_f32_16x16x32_bf16 v[120:123], v[186:189], v[214:217], v[120:123]
	v_mfma_f32_16x16x32_bf16 v[108:111], v[178:181], v[222:225], v[108:111]
	v_mfma_f32_16x16x32_bf16 v[104:107], v[186:189], v[222:225], v[104:107]
	v_mfma_f32_16x16x32_bf16 v[92:95], v[178:181], v[230:233], v[92:95]
	v_mfma_f32_16x16x32_bf16 v[88:91], v[186:189], v[230:233], v[88:91]
	v_mfma_f32_16x16x32_bf16 v[76:79], v[178:181], v[238:241], v[76:79]
	v_mfma_f32_16x16x32_bf16 v[72:75], v[186:189], v[238:241], v[72:75]
	s_setprio 0
	s_setprio 1
	v_mfma_f32_16x16x32_bf16 v[116:119], v[190:193], v[210:213], v[116:119]
	v_mfma_f32_16x16x32_bf16 v[112:115], v[202:205], v[210:213], v[112:115]
	v_mfma_f32_16x16x32_bf16 v[100:103], v[190:193], v[218:221], v[100:103]
	v_mfma_f32_16x16x32_bf16 v[96:99], v[202:205], v[218:221], v[96:99]
	v_mfma_f32_16x16x32_bf16 v[84:87], v[190:193], v[226:229], v[84:87]
	v_mfma_f32_16x16x32_bf16 v[80:83], v[202:205], v[226:229], v[80:83]
	v_mfma_f32_16x16x32_bf16 v[68:71], v[190:193], v[234:237], v[68:71]
	v_mfma_f32_16x16x32_bf16 v[64:67], v[202:205], v[234:237], v[64:67]
	v_mfma_f32_16x16x32_bf16 v[116:119], v[198:201], v[214:217], v[116:119]
	v_mfma_f32_16x16x32_bf16 v[112:115], v[206:209], v[214:217], v[112:115]
	v_mfma_f32_16x16x32_bf16 v[100:103], v[198:201], v[222:225], v[100:103]
	v_mfma_f32_16x16x32_bf16 v[96:99], v[206:209], v[222:225], v[96:99]
	v_mfma_f32_16x16x32_bf16 v[84:87], v[198:201], v[230:233], v[84:87]
	v_mfma_f32_16x16x32_bf16 v[80:83], v[206:209], v[230:233], v[80:83]
	v_mfma_f32_16x16x32_bf16 v[68:71], v[198:201], v[238:241], v[68:71]
	v_mfma_f32_16x16x32_bf16 v[64:67], v[206:209], v[238:241], v[64:67]
	s_setprio 0
	s_barrier
	s_mov_b32 m0, s36
	v_lshl_add_u64 v[242:243], v[242:243], 0, s[12:13]
	s_add_u32 s48, s48, 0x40080
	ds_read_b128 v[210:213], v141 offset:49152
	ds_read_b128 v[214:217], v141 offset:50176
	ds_read_b128 v[218:221], v141 offset:51200
	ds_read_b128 v[222:225], v141 offset:52224
	ds_read_b128 v[226:229], v141 offset:53248
	ds_read_b128 v[230:233], v141 offset:54272
	ds_read_b128 v[234:237], v141 offset:55296
	ds_read_b128 v[238:241], v141 offset:56320
	global_load_lds_dwordx4 v[242:243], off
	v_lshl_add_u64 v[242:243], v[244:245], 0, s[12:13]
	s_mov_b32 m0, s37
	s_addc_u32 s49, s49, 0
	global_load_lds_dwordx4 v[242:243], off
	v_lshl_add_u64 v[242:243], s[48:49], 0, v[130:131]
	s_mov_b32 m0, s53
	s_nop 0
	global_load_lds_dwordx4 v[242:243], off
	v_lshl_add_u64 v[242:243], s[48:49], 0, v[128:129]
	s_mov_b32 m0, s54
	s_nop 0
	global_load_lds_dwordx4 v[242:243], off
	v_lshl_add_u64 v[242:243], v[246:247], 0, s[12:13]
	s_mov_b32 m0, s47
	s_nop 0
	global_load_lds_dwordx4 v[242:243], off
	v_lshl_add_u64 v[242:243], v[248:249], 0, s[12:13]
	s_mov_b32 m0, s52
	s_nop 0
	global_load_lds_dwordx4 v[242:243], off
	s_waitcnt vmcnt(8)
	s_waitcnt lgkmcnt(0)
	s_barrier
	s_setprio 1
	s_waitcnt lgkmcnt(0)
	v_mfma_f32_16x16x32_bf16 v[60:63], v[174:177], v[210:213], v[60:63]
	v_mfma_f32_16x16x32_bf16 v[56:59], v[182:185], v[210:213], v[56:59]
	v_mfma_f32_16x16x32_bf16 v[44:47], v[174:177], v[218:221], v[44:47]
	v_mfma_f32_16x16x32_bf16 v[40:43], v[182:185], v[218:221], v[40:43]
	v_mfma_f32_16x16x32_bf16 v[28:31], v[174:177], v[226:229], v[28:31]
	v_mfma_f32_16x16x32_bf16 v[24:27], v[182:185], v[226:229], v[24:27]
	v_mfma_f32_16x16x32_bf16 v[12:15], v[174:177], v[234:237], v[12:15]
	v_mfma_f32_16x16x32_bf16 v[8:11], v[182:185], v[234:237], v[8:11]
	v_mfma_f32_16x16x32_bf16 v[60:63], v[178:181], v[214:217], v[60:63]
	v_mfma_f32_16x16x32_bf16 v[56:59], v[186:189], v[214:217], v[56:59]
	v_mfma_f32_16x16x32_bf16 v[44:47], v[178:181], v[222:225], v[44:47]
	v_mfma_f32_16x16x32_bf16 v[40:43], v[186:189], v[222:225], v[40:43]
	v_mfma_f32_16x16x32_bf16 v[28:31], v[178:181], v[230:233], v[28:31]
	v_mfma_f32_16x16x32_bf16 v[24:27], v[186:189], v[230:233], v[24:27]
	v_mfma_f32_16x16x32_bf16 v[12:15], v[178:181], v[238:241], v[12:15]
	v_mfma_f32_16x16x32_bf16 v[8:11], v[186:189], v[238:241], v[8:11]
	s_setprio 0
	s_setprio 1
	v_mfma_f32_16x16x32_bf16 v[52:55], v[190:193], v[210:213], v[52:55]
	v_mfma_f32_16x16x32_bf16 v[48:51], v[202:205], v[210:213], v[48:51]
	v_mfma_f32_16x16x32_bf16 v[36:39], v[190:193], v[218:221], v[36:39]
	v_mfma_f32_16x16x32_bf16 v[32:35], v[202:205], v[218:221], v[32:35]
	v_mfma_f32_16x16x32_bf16 v[20:23], v[190:193], v[226:229], v[20:23]
	v_mfma_f32_16x16x32_bf16 v[16:19], v[202:205], v[226:229], v[16:19]
	v_mfma_f32_16x16x32_bf16 v[4:7], v[190:193], v[234:237], v[4:7]
	v_mfma_f32_16x16x32_bf16 v[0:3], v[202:205], v[234:237], v[0:3]
	v_mfma_f32_16x16x32_bf16 v[52:55], v[198:201], v[214:217], v[52:55]
	v_mfma_f32_16x16x32_bf16 v[48:51], v[206:209], v[214:217], v[48:51]
	v_mfma_f32_16x16x32_bf16 v[36:39], v[198:201], v[222:225], v[36:39]
	v_mfma_f32_16x16x32_bf16 v[32:35], v[206:209], v[222:225], v[32:35]
	v_mfma_f32_16x16x32_bf16 v[20:23], v[198:201], v[230:233], v[20:23]
	v_mfma_f32_16x16x32_bf16 v[16:19], v[206:209], v[230:233], v[16:19]
	v_mfma_f32_16x16x32_bf16 v[4:7], v[198:201], v[238:241], v[4:7]
	v_mfma_f32_16x16x32_bf16 v[0:3], v[206:209], v[238:241], v[0:3]
	s_setprio 0
	s_barrier
	s_add_i32 s75, s75, 2
	s_add_u32 s24, s24, 0x100
	s_addc_u32 s25, s25, 0
	s_add_u32 s67, s67, 0x100
	s_addc_u32 s74, s74, 0
	s_cmp_gt_u32 s75, 13
	s_cbranch_scc0 .LBB0_1914
	s_and_b64 vcc, exec, s[14:15]
	s_cbranch_vccz .LBB0_1917
	s_barrier

.LBB0_1994:
	ds_read_b128 v[128:131], v199
	ds_read_b128 v[132:135], v200
	ds_read_b128 v[136:139], v201
	ds_read_b128 v[140:143], v202
	ds_read_b128 v[172:175], v203
	ds_read_b128 v[176:179], v204
	ds_read_b128 v[180:183], v205
	ds_read_b128 v[184:187], v206
	s_add_u32 s48, s24, 0x100
	s_addc_u32 s49, s25, 0
	s_cmp_eq_u32 s68, 40
	s_cselect_b32 s55, s13, s49
	s_cselect_b32 s54, s12, s48
	s_cselect_b32 s51, s47, s5
	s_cselect_b32 s50, s46, s4
	s_mov_b32 m0, s64
	v_lshl_add_u64 v[192:193], s[24:25], 0, v[164:165]
	ds_read_b128 v[188:191], v159
	ds_read_b128 v[216:219], v159 offset:1024
	ds_read_b128 v[220:223], v159 offset:2048
	ds_read_b128 v[224:227], v159 offset:3072
	ds_read_b128 v[228:231], v159 offset:4096
	ds_read_b128 v[232:235], v159 offset:5120
	ds_read_b128 v[236:239], v159 offset:6144
	ds_read_b128 v[240:243], v159 offset:7168
	global_load_lds_dwordx4 v[192:193], off
	v_lshl_add_u64 v[192:193], s[24:25], 0, v[166:167]
	s_mov_b32 m0, s65
	s_nop 0
	global_load_lds_dwordx4 v[192:193], off
	s_waitcnt vmcnt(8)
	s_waitcnt lgkmcnt(0)
	s_barrier
	s_setprio 1
	s_waitcnt lgkmcnt(0)
	v_mfma_f32_16x16x32_bf16 v[124:127], v[128:131], v[188:191], v[124:127]
	v_mfma_f32_16x16x32_bf16 v[120:123], v[136:139], v[188:191], v[120:123]
	v_mfma_f32_16x16x32_bf16 v[108:111], v[128:131], v[220:223], v[108:111]
	v_mfma_f32_16x16x32_bf16 v[104:107], v[136:139], v[220:223], v[104:107]
	v_mfma_f32_16x16x32_bf16 v[92:95], v[128:131], v[228:231], v[92:95]
	v_mfma_f32_16x16x32_bf16 v[88:91], v[136:139], v[228:231], v[88:91]
	v_mfma_f32_16x16x32_bf16 v[76:79], v[128:131], v[236:239], v[76:79]
	v_mfma_f32_16x16x32_bf16 v[72:75], v[136:139], v[236:239], v[72:75]
	v_mfma_f32_16x16x32_bf16 v[124:127], v[132:135], v[216:219], v[124:127]
	v_mfma_f32_16x16x32_bf16 v[120:123], v[140:143], v[216:219], v[120:123]
	v_mfma_f32_16x16x32_bf16 v[108:111], v[132:135], v[224:227], v[108:111]
	v_mfma_f32_16x16x32_bf16 v[104:107], v[140:143], v[224:227], v[104:107]
	v_mfma_f32_16x16x32_bf16 v[92:95], v[132:135], v[232:235], v[92:95]
	v_mfma_f32_16x16x32_bf16 v[88:91], v[140:143], v[232:235], v[88:91]
	v_mfma_f32_16x16x32_bf16 v[76:79], v[132:135], v[240:243], v[76:79]
	v_mfma_f32_16x16x32_bf16 v[72:75], v[140:143], v[240:243], v[72:75]
	s_setprio 0
	s_setprio 1
	v_mfma_f32_16x16x32_bf16 v[116:119], v[172:175], v[188:191], v[116:119]
	v_mfma_f32_16x16x32_bf16 v[112:115], v[180:183], v[188:191], v[112:115]
	v_mfma_f32_16x16x32_bf16 v[100:103], v[172:175], v[220:223], v[100:103]
	v_mfma_f32_16x16x32_bf16 v[96:99], v[180:183], v[220:223], v[96:99]
	v_mfma_f32_16x16x32_bf16 v[84:87], v[172:175], v[228:231], v[84:87]
	v_mfma_f32_16x16x32_bf16 v[80:83], v[180:183], v[228:231], v[80:83]
	v_mfma_f32_16x16x32_bf16 v[68:71], v[172:175], v[236:239], v[68:71]
	v_mfma_f32_16x16x32_bf16 v[64:67], v[180:183], v[236:239], v[64:67]
	v_mfma_f32_16x16x32_bf16 v[116:119], v[176:179], v[216:219], v[116:119]
	v_mfma_f32_16x16x32_bf16 v[112:115], v[184:187], v[216:219], v[112:115]
	v_mfma_f32_16x16x32_bf16 v[100:103], v[176:179], v[224:227], v[100:103]
	v_mfma_f32_16x16x32_bf16 v[96:99], v[184:187], v[224:227], v[96:99]
	v_mfma_f32_16x16x32_bf16 v[84:87], v[176:179], v[232:235], v[84:87]
	v_mfma_f32_16x16x32_bf16 v[80:83], v[184:187], v[232:235], v[80:83]
	v_mfma_f32_16x16x32_bf16 v[68:71], v[176:179], v[240:243], v[68:71]
	v_mfma_f32_16x16x32_bf16 v[64:67], v[184:187], v[240:243], v[64:67]
	s_setprio 0
	s_barrier
	s_mov_b32 m0, s7
	v_lshl_add_u64 v[192:193], s[50:51], 0, v[160:161]
	s_add_u32 s24, s50, 0xb0000
	ds_read_b128 v[188:191], v159 offset:16384
	ds_read_b128 v[216:219], v159 offset:17408
	ds_read_b128 v[220:223], v159 offset:18432
	ds_read_b128 v[224:227], v159 offset:19456
	ds_read_b128 v[228:231], v159 offset:20480
	ds_read_b128 v[232:235], v159 offset:21504
	ds_read_b128 v[236:239], v159 offset:22528
	ds_read_b128 v[240:243], v159 offset:23552
	global_load_lds_dwordx4 v[192:193], off
	v_lshl_add_u64 v[244:245], s[50:51], 0, v[162:163]
	s_mov_b32 m0, s8
	s_addc_u32 s25, s51, 0
	global_load_lds_dwordx4 v[244:245], off
	v_lshl_add_u64 v[246:247], s[24:25], 0, v[160:161]
	s_mov_b32 m0, s9
	v_lshl_add_u64 v[248:249], s[54:55], 0, v[162:163]
	global_load_lds_dwordx4 v[246:247], off
	v_lshl_add_u64 v[246:247], s[24:25], 0, v[162:163]
	s_mov_b32 m0, s28
	s_nop 0
	global_load_lds_dwordx4 v[246:247], off
	v_lshl_add_u64 v[246:247], s[54:55], 0, v[160:161]
	s_mov_b32 m0, s6
	s_nop 0
	global_load_lds_dwordx4 v[246:247], off
	s_mov_b32 m0, s29
	s_nop 0
	global_load_lds_dwordx4 v[248:249], off
	s_waitcnt vmcnt(8)
	s_waitcnt lgkmcnt(0)
	s_barrier
	s_setprio 1
	s_waitcnt lgkmcnt(0)
	v_mfma_f32_16x16x32_bf16 v[60:63], v[128:131], v[188:191], v[60:63]
	v_mfma_f32_16x16x32_bf16 v[56:59], v[136:139], v[188:191], v[56:59]
	v_mfma_f32_16x16x32_bf16 v[44:47], v[128:131], v[220:223], v[44:47]
	v_mfma_f32_16x16x32_bf16 v[40:43], v[136:139], v[220:223], v[40:43]
	v_mfma_f32_16x16x32_bf16 v[28:31], v[128:131], v[228:231], v[28:31]
	v_mfma_f32_16x16x32_bf16 v[24:27], v[136:139], v[228:231], v[24:27]
	v_mfma_f32_16x16x32_bf16 v[12:15], v[128:131], v[236:239], v[12:15]
	v_mfma_f32_16x16x32_bf16 v[8:11], v[136:139], v[236:239], v[8:11]
	v_mfma_f32_16x16x32_bf16 v[60:63], v[132:135], v[216:219], v[60:63]
	v_mfma_f32_16x16x32_bf16 v[56:59], v[140:143], v[216:219], v[56:59]
	v_mfma_f32_16x16x32_bf16 v[44:47], v[132:135], v[224:227], v[44:47]
	v_mfma_f32_16x16x32_bf16 v[40:43], v[140:143], v[224:227], v[40:43]
	v_mfma_f32_16x16x32_bf16 v[28:31], v[132:135], v[232:235], v[28:31]
	v_mfma_f32_16x16x32_bf16 v[24:27], v[140:143], v[232:235], v[24:27]
	v_mfma_f32_16x16x32_bf16 v[12:15], v[132:135], v[240:243], v[12:15]
	v_mfma_f32_16x16x32_bf16 v[8:11], v[140:143], v[240:243], v[8:11]
	s_setprio 0
	s_setprio 1
	v_mfma_f32_16x16x32_bf16 v[52:55], v[172:175], v[188:191], v[52:55]
	v_mfma_f32_16x16x32_bf16 v[48:51], v[180:183], v[188:191], v[48:51]
	v_mfma_f32_16x16x32_bf16 v[36:39], v[172:175], v[220:223], v[36:39]
	v_mfma_f32_16x16x32_bf16 v[32:35], v[180:183], v[220:223], v[32:35]
	v_mfma_f32_16x16x32_bf16 v[20:23], v[172:175], v[228:231], v[20:23]
	v_mfma_f32_16x16x32_bf16 v[16:19], v[180:183], v[228:231], v[16:19]
	v_mfma_f32_16x16x32_bf16 v[4:7], v[172:175], v[236:239], v[4:7]
	v_mfma_f32_16x16x32_bf16 v[0:3], v[180:183], v[236:239], v[0:3]
	v_mfma_f32_16x16x32_bf16 v[52:55], v[176:179], v[216:219], v[52:55]
	v_mfma_f32_16x16x32_bf16 v[48:51], v[184:187], v[216:219], v[48:51]
	v_mfma_f32_16x16x32_bf16 v[36:39], v[176:179], v[224:227], v[36:39]
	v_mfma_f32_16x16x32_bf16 v[32:35], v[184:187], v[224:227], v[32:35]
	v_mfma_f32_16x16x32_bf16 v[20:23], v[176:179], v[232:235], v[20:23]
	v_mfma_f32_16x16x32_bf16 v[16:19], v[184:187], v[232:235], v[16:19]
	v_mfma_f32_16x16x32_bf16 v[4:7], v[176:179], v[240:243], v[4:7]
	v_mfma_f32_16x16x32_bf16 v[0:3], v[184:187], v[240:243], v[0:3]
	s_setprio 0
	s_barrier
	ds_read_b128 v[128:131], v207
	ds_read_b128 v[132:135], v208
	ds_read_b128 v[136:139], v209
	ds_read_b128 v[140:143], v210
	ds_read_b128 v[172:175], v211
	ds_read_b128 v[176:179], v212
	ds_read_b128 v[180:183], v213
	ds_read_b128 v[184:187], v214
	s_add_u32 s24, s54, 0xb0000
	s_addc_u32 s25, s55, 0
	s_mov_b32 m0, s30
	v_lshl_add_u64 v[250:251], s[24:25], 0, v[160:161]
	ds_read_b128 v[188:191], v159 offset:32768
	ds_read_b128 v[216:219], v159 offset:33792
	ds_read_b128 v[220:223], v159 offset:34816
	ds_read_b128 v[224:227], v159 offset:35840
	ds_read_b128 v[228:231], v159 offset:36864
	ds_read_b128 v[232:235], v159 offset:37888
	ds_read_b128 v[236:239], v159 offset:38912
	ds_read_b128 v[240:243], v159 offset:39936
	global_load_lds_dwordx4 v[250:251], off
	v_lshl_add_u64 v[250:251], s[24:25], 0, v[162:163]
	s_mov_b32 m0, s31
	s_nop 0
	global_load_lds_dwordx4 v[250:251], off
	s_waitcnt vmcnt(8)
	s_waitcnt lgkmcnt(0)
	s_barrier
	s_setprio 1
	s_waitcnt lgkmcnt(0)
	v_mfma_f32_16x16x32_bf16 v[124:127], v[128:131], v[188:191], v[124:127]
	v_mfma_f32_16x16x32_bf16 v[120:123], v[136:139], v[188:191], v[120:123]
	v_mfma_f32_16x16x32_bf16 v[108:111], v[128:131], v[220:223], v[108:111]
	v_mfma_f32_16x16x32_bf16 v[104:107], v[136:139], v[220:223], v[104:107]
	v_mfma_f32_16x16x32_bf16 v[92:95], v[128:131], v[228:231], v[92:95]
	v_mfma_f32_16x16x32_bf16 v[88:91], v[136:139], v[228:231], v[88:91]
	v_mfma_f32_16x16x32_bf16 v[76:79], v[128:131], v[236:239], v[76:79]
	v_mfma_f32_16x16x32_bf16 v[72:75], v[136:139], v[236:239], v[72:75]
	v_mfma_f32_16x16x32_bf16 v[124:127], v[132:135], v[216:219], v[124:127]
	v_mfma_f32_16x16x32_bf16 v[120:123], v[140:143], v[216:219], v[120:123]
	v_mfma_f32_16x16x32_bf16 v[108:111], v[132:135], v[224:227], v[108:111]
	v_mfma_f32_16x16x32_bf16 v[104:107], v[140:143], v[224:227], v[104:107]
	v_mfma_f32_16x16x32_bf16 v[92:95], v[132:135], v[232:235], v[92:95]
	v_mfma_f32_16x16x32_bf16 v[88:91], v[140:143], v[232:235], v[88:91]
	v_mfma_f32_16x16x32_bf16 v[76:79], v[132:135], v[240:243], v[76:79]
	v_mfma_f32_16x16x32_bf16 v[72:75], v[140:143], v[240:243], v[72:75]
	s_setprio 0
	s_setprio 1
	v_mfma_f32_16x16x32_bf16 v[116:119], v[172:175], v[188:191], v[116:119]
	v_mfma_f32_16x16x32_bf16 v[112:115], v[180:183], v[188:191], v[112:115]
	v_mfma_f32_16x16x32_bf16 v[100:103], v[172:175], v[220:223], v[100:103]
	v_mfma_f32_16x16x32_bf16 v[96:99], v[180:183], v[220:223], v[96:99]
	v_mfma_f32_16x16x32_bf16 v[84:87], v[172:175], v[228:231], v[84:87]
	v_mfma_f32_16x16x32_bf16 v[80:83], v[180:183], v[228:231], v[80:83]
	v_mfma_f32_16x16x32_bf16 v[68:71], v[172:175], v[236:239], v[68:71]
	v_mfma_f32_16x16x32_bf16 v[64:67], v[180:183], v[236:239], v[64:67]
	v_mfma_f32_16x16x32_bf16 v[116:119], v[176:179], v[216:219], v[116:119]
	v_mfma_f32_16x16x32_bf16 v[112:115], v[184:187], v[216:219], v[112:115]
	v_mfma_f32_16x16x32_bf16 v[100:103], v[176:179], v[224:227], v[100:103]
	v_mfma_f32_16x16x32_bf16 v[96:99], v[184:187], v[224:227], v[96:99]
	v_mfma_f32_16x16x32_bf16 v[84:87], v[176:179], v[232:235], v[84:87]
	v_mfma_f32_16x16x32_bf16 v[80:83], v[184:187], v[232:235], v[80:83]
	v_mfma_f32_16x16x32_bf16 v[68:71], v[176:179], v[240:243], v[68:71]
	v_mfma_f32_16x16x32_bf16 v[64:67], v[184:187], v[240:243], v[64:67]
	s_setprio 0
	s_barrier
	s_mov_b32 m0, s33
	v_lshl_add_u64 v[192:193], v[192:193], 0, s[40:41]
	s_add_u32 s24, s50, 0xb0080
	ds_read_b128 v[188:191], v159 offset:49152
	ds_read_b128 v[216:219], v159 offset:50176
	ds_read_b128 v[220:223], v159 offset:51200
	ds_read_b128 v[224:227], v159 offset:52224
	ds_read_b128 v[228:231], v159 offset:53248
	ds_read_b128 v[232:235], v159 offset:54272
	ds_read_b128 v[236:239], v159 offset:55296
	ds_read_b128 v[240:243], v159 offset:56320
	global_load_lds_dwordx4 v[192:193], off
	v_lshl_add_u64 v[192:193], v[244:245], 0, s[40:41]
	s_mov_b32 m0, s34
	s_addc_u32 s25, s51, 0
	global_load_lds_dwordx4 v[192:193], off
	v_lshl_add_u64 v[192:193], s[24:25], 0, v[160:161]
	s_mov_b32 m0, s37
	s_nop 0
	global_load_lds_dwordx4 v[192:193], off
	v_lshl_add_u64 v[192:193], s[24:25], 0, v[162:163]
	s_mov_b32 m0, s45
	s_nop 0
	global_load_lds_dwordx4 v[192:193], off
	v_lshl_add_u64 v[192:193], v[246:247], 0, s[40:41]
	s_mov_b32 m0, s35
	s_nop 0
	global_load_lds_dwordx4 v[192:193], off
	v_lshl_add_u64 v[192:193], v[248:249], 0, s[40:41]
	s_mov_b32 m0, s36
	s_nop 0
	global_load_lds_dwordx4 v[192:193], off
	s_waitcnt vmcnt(8)
	s_waitcnt lgkmcnt(0)
	s_barrier
	s_setprio 1
	s_waitcnt lgkmcnt(0)
	v_mfma_f32_16x16x32_bf16 v[60:63], v[128:131], v[188:191], v[60:63]
	v_mfma_f32_16x16x32_bf16 v[56:59], v[136:139], v[188:191], v[56:59]
	v_mfma_f32_16x16x32_bf16 v[44:47], v[128:131], v[220:223], v[44:47]
	v_mfma_f32_16x16x32_bf16 v[40:43], v[136:139], v[220:223], v[40:43]
	v_mfma_f32_16x16x32_bf16 v[28:31], v[128:131], v[228:231], v[28:31]
	v_mfma_f32_16x16x32_bf16 v[24:27], v[136:139], v[228:231], v[24:27]
	v_mfma_f32_16x16x32_bf16 v[12:15], v[128:131], v[236:239], v[12:15]
	v_mfma_f32_16x16x32_bf16 v[8:11], v[136:139], v[236:239], v[8:11]
	v_mfma_f32_16x16x32_bf16 v[60:63], v[132:135], v[216:219], v[60:63]
	v_mfma_f32_16x16x32_bf16 v[56:59], v[140:143], v[216:219], v[56:59]
	v_mfma_f32_16x16x32_bf16 v[44:47], v[132:135], v[224:227], v[44:47]
	v_mfma_f32_16x16x32_bf16 v[40:43], v[140:143], v[224:227], v[40:43]
	v_mfma_f32_16x16x32_bf16 v[28:31], v[132:135], v[232:235], v[28:31]
	v_mfma_f32_16x16x32_bf16 v[24:27], v[140:143], v[232:235], v[24:27]
	v_mfma_f32_16x16x32_bf16 v[12:15], v[132:135], v[240:243], v[12:15]
	v_mfma_f32_16x16x32_bf16 v[8:11], v[140:143], v[240:243], v[8:11]
	s_setprio 0
	s_setprio 1
	v_mfma_f32_16x16x32_bf16 v[52:55], v[172:175], v[188:191], v[52:55]
	v_mfma_f32_16x16x32_bf16 v[48:51], v[180:183], v[188:191], v[48:51]
	v_mfma_f32_16x16x32_bf16 v[36:39], v[172:175], v[220:223], v[36:39]
	v_mfma_f32_16x16x32_bf16 v[32:35], v[180:183], v[220:223], v[32:35]
	v_mfma_f32_16x16x32_bf16 v[20:23], v[172:175], v[228:231], v[20:23]
	v_mfma_f32_16x16x32_bf16 v[16:19], v[180:183], v[228:231], v[16:19]
	v_mfma_f32_16x16x32_bf16 v[4:7], v[172:175], v[236:239], v[4:7]
	v_mfma_f32_16x16x32_bf16 v[0:3], v[180:183], v[236:239], v[0:3]
	v_mfma_f32_16x16x32_bf16 v[52:55], v[176:179], v[216:219], v[52:55]
	v_mfma_f32_16x16x32_bf16 v[48:51], v[184:187], v[216:219], v[48:51]
	v_mfma_f32_16x16x32_bf16 v[36:39], v[176:179], v[224:227], v[36:39]
	v_mfma_f32_16x16x32_bf16 v[32:35], v[184:187], v[224:227], v[32:35]
	v_mfma_f32_16x16x32_bf16 v[20:23], v[176:179], v[232:235], v[20:23]
	v_mfma_f32_16x16x32_bf16 v[16:19], v[184:187], v[232:235], v[16:19]
	v_mfma_f32_16x16x32_bf16 v[4:7], v[176:179], v[240:243], v[4:7]
	v_mfma_f32_16x16x32_bf16 v[0:3], v[184:187], v[240:243], v[0:3]
	s_setprio 0
	s_barrier
	s_add_i32 s68, s68, 2
	s_add_u32 s4, s4, 0x100
	s_addc_u32 s5, s5, 0
	s_cmp_gt_u32 s68, 41
	s_mov_b64 s[24:25], s[48:49]
	s_cbranch_scc0 .LBB0_1994
	s_and_b64 vcc, exec, s[42:43]
	s_cbranch_vccz .LBB0_1997
	s_barrier

.LBB0_2152:
	ds_read_b128 v[160:163], v169
	ds_read_b128 v[164:167], v170
	ds_read_b128 v[186:189], v171
	ds_read_b128 v[190:193], v172
	ds_read_b128 v[198:201], v173
	ds_read_b128 v[202:205], v174
	ds_read_b128 v[206:209], v175
	ds_read_b128 v[210:213], v176
	s_add_u32 s18, s16, 0xfffc0080
	s_addc_u32 s19, s17, -1
	s_cmp_eq_u32 s66, 12
	s_cselect_b32 s25, s4, s19
	s_cselect_b32 s24, s5, s18
	s_cselect_b32 s19, s13, s49
	s_cselect_b32 s18, s15, s47
	s_mov_b32 m0, s64
	v_lshl_add_u64 v[142:143], s[16:17], 0, v[134:135]
	ds_read_b128 v[214:217], v159
	ds_read_b128 v[218:221], v159 offset:1024
	ds_read_b128 v[222:225], v159 offset:2048
	ds_read_b128 v[226:229], v159 offset:3072
	ds_read_b128 v[230:233], v159 offset:4096
	ds_read_b128 v[234:237], v159 offset:5120
	ds_read_b128 v[238:241], v159 offset:6144
	ds_read_b128 v[242:245], v159 offset:7168
	global_load_lds_dwordx4 v[142:143], off
	v_lshl_add_u64 v[142:143], s[16:17], 0, v[136:137]
	s_mov_b32 m0, s65
	s_nop 0
	global_load_lds_dwordx4 v[142:143], off
	s_waitcnt vmcnt(8)
	s_waitcnt lgkmcnt(0)
	s_barrier
	s_setprio 1
	s_waitcnt lgkmcnt(0)
	v_mfma_f32_16x16x32_bf16 v[124:127], v[160:163], v[214:217], v[124:127]
	v_mfma_f32_16x16x32_bf16 v[120:123], v[186:189], v[214:217], v[120:123]
	v_mfma_f32_16x16x32_bf16 v[108:111], v[160:163], v[222:225], v[108:111]
	v_mfma_f32_16x16x32_bf16 v[104:107], v[186:189], v[222:225], v[104:107]
	v_mfma_f32_16x16x32_bf16 v[92:95], v[160:163], v[230:233], v[92:95]
	v_mfma_f32_16x16x32_bf16 v[88:91], v[186:189], v[230:233], v[88:91]
	v_mfma_f32_16x16x32_bf16 v[76:79], v[160:163], v[238:241], v[76:79]
	v_mfma_f32_16x16x32_bf16 v[72:75], v[186:189], v[238:241], v[72:75]
	v_mfma_f32_16x16x32_bf16 v[124:127], v[164:167], v[218:221], v[124:127]
	v_mfma_f32_16x16x32_bf16 v[120:123], v[190:193], v[218:221], v[120:123]
	v_mfma_f32_16x16x32_bf16 v[108:111], v[164:167], v[226:229], v[108:111]
	v_mfma_f32_16x16x32_bf16 v[104:107], v[190:193], v[226:229], v[104:107]
	v_mfma_f32_16x16x32_bf16 v[92:95], v[164:167], v[234:237], v[92:95]
	v_mfma_f32_16x16x32_bf16 v[88:91], v[190:193], v[234:237], v[88:91]
	v_mfma_f32_16x16x32_bf16 v[76:79], v[164:167], v[242:245], v[76:79]
	v_mfma_f32_16x16x32_bf16 v[72:75], v[190:193], v[242:245], v[72:75]
	s_setprio 0
	s_setprio 1
	v_mfma_f32_16x16x32_bf16 v[116:119], v[198:201], v[214:217], v[116:119]
	v_mfma_f32_16x16x32_bf16 v[112:115], v[206:209], v[214:217], v[112:115]
	v_mfma_f32_16x16x32_bf16 v[100:103], v[198:201], v[222:225], v[100:103]
	v_mfma_f32_16x16x32_bf16 v[96:99], v[206:209], v[222:225], v[96:99]
	v_mfma_f32_16x16x32_bf16 v[84:87], v[198:201], v[230:233], v[84:87]
	v_mfma_f32_16x16x32_bf16 v[80:83], v[206:209], v[230:233], v[80:83]
	v_mfma_f32_16x16x32_bf16 v[68:71], v[198:201], v[238:241], v[68:71]
	v_mfma_f32_16x16x32_bf16 v[64:67], v[206:209], v[238:241], v[64:67]
	v_mfma_f32_16x16x32_bf16 v[116:119], v[202:205], v[218:221], v[116:119]
	v_mfma_f32_16x16x32_bf16 v[112:115], v[210:213], v[218:221], v[112:115]
	v_mfma_f32_16x16x32_bf16 v[100:103], v[202:205], v[226:229], v[100:103]
	v_mfma_f32_16x16x32_bf16 v[96:99], v[210:213], v[226:229], v[96:99]
	v_mfma_f32_16x16x32_bf16 v[84:87], v[202:205], v[234:237], v[84:87]
	v_mfma_f32_16x16x32_bf16 v[80:83], v[210:213], v[234:237], v[80:83]
	v_mfma_f32_16x16x32_bf16 v[68:71], v[202:205], v[242:245], v[68:71]
	v_mfma_f32_16x16x32_bf16 v[64:67], v[210:213], v[242:245], v[64:67]
	s_setprio 0
	s_barrier
	s_mov_b32 m0, s6
	v_lshl_add_u64 v[142:143], s[18:19], 0, v[128:129]
	s_add_u32 s68, s18, 0x40000
	ds_read_b128 v[214:217], v159 offset:16384
	ds_read_b128 v[218:221], v159 offset:17408
	ds_read_b128 v[222:225], v159 offset:18432
	ds_read_b128 v[226:229], v159 offset:19456
	ds_read_b128 v[230:233], v159 offset:20480
	ds_read_b128 v[234:237], v159 offset:21504
	ds_read_b128 v[238:241], v159 offset:22528
	ds_read_b128 v[242:245], v159 offset:23552
	global_load_lds_dwordx4 v[142:143], off
	v_lshl_add_u64 v[246:247], s[18:19], 0, v[130:131]
	s_mov_b32 m0, s7
	s_addc_u32 s69, s19, 0
	global_load_lds_dwordx4 v[246:247], off
	v_lshl_add_u64 v[248:249], s[68:69], 0, v[128:129]
	s_mov_b32 m0, s8
	v_lshl_add_u64 v[250:251], s[24:25], 0, v[130:131]
	global_load_lds_dwordx4 v[248:249], off
	v_lshl_add_u64 v[248:249], s[68:69], 0, v[130:131]
	s_mov_b32 m0, s9
	s_nop 0
	global_load_lds_dwordx4 v[248:249], off
	v_lshl_add_u64 v[248:249], s[24:25], 0, v[128:129]
	s_mov_b32 m0, s2
	s_nop 0
	global_load_lds_dwordx4 v[248:249], off
	s_mov_b32 m0, s28
	s_nop 0
	global_load_lds_dwordx4 v[250:251], off
	s_waitcnt vmcnt(8)
	s_waitcnt lgkmcnt(0)
	s_barrier
	s_setprio 1
	s_waitcnt lgkmcnt(0)
	v_mfma_f32_16x16x32_bf16 v[60:63], v[160:163], v[214:217], v[60:63]
	v_mfma_f32_16x16x32_bf16 v[56:59], v[186:189], v[214:217], v[56:59]
	v_mfma_f32_16x16x32_bf16 v[44:47], v[160:163], v[222:225], v[44:47]
	v_mfma_f32_16x16x32_bf16 v[40:43], v[186:189], v[222:225], v[40:43]
	v_mfma_f32_16x16x32_bf16 v[28:31], v[160:163], v[230:233], v[28:31]
	v_mfma_f32_16x16x32_bf16 v[24:27], v[186:189], v[230:233], v[24:27]
	v_mfma_f32_16x16x32_bf16 v[12:15], v[160:163], v[238:241], v[12:15]
	v_mfma_f32_16x16x32_bf16 v[8:11], v[186:189], v[238:241], v[8:11]
	v_mfma_f32_16x16x32_bf16 v[60:63], v[164:167], v[218:221], v[60:63]
	v_mfma_f32_16x16x32_bf16 v[56:59], v[190:193], v[218:221], v[56:59]
	v_mfma_f32_16x16x32_bf16 v[44:47], v[164:167], v[226:229], v[44:47]
	v_mfma_f32_16x16x32_bf16 v[40:43], v[190:193], v[226:229], v[40:43]
	v_mfma_f32_16x16x32_bf16 v[28:31], v[164:167], v[234:237], v[28:31]
	v_mfma_f32_16x16x32_bf16 v[24:27], v[190:193], v[234:237], v[24:27]
	v_mfma_f32_16x16x32_bf16 v[12:15], v[164:167], v[242:245], v[12:15]
	v_mfma_f32_16x16x32_bf16 v[8:11], v[190:193], v[242:245], v[8:11]
	s_setprio 0
	s_setprio 1
	v_mfma_f32_16x16x32_bf16 v[52:55], v[198:201], v[214:217], v[52:55]
	v_mfma_f32_16x16x32_bf16 v[48:51], v[206:209], v[214:217], v[48:51]
	v_mfma_f32_16x16x32_bf16 v[36:39], v[198:201], v[222:225], v[36:39]
	v_mfma_f32_16x16x32_bf16 v[32:35], v[206:209], v[222:225], v[32:35]
	v_mfma_f32_16x16x32_bf16 v[20:23], v[198:201], v[230:233], v[20:23]
	v_mfma_f32_16x16x32_bf16 v[16:19], v[206:209], v[230:233], v[16:19]
	v_mfma_f32_16x16x32_bf16 v[4:7], v[198:201], v[238:241], v[4:7]
	v_mfma_f32_16x16x32_bf16 v[0:3], v[206:209], v[238:241], v[0:3]
	v_mfma_f32_16x16x32_bf16 v[52:55], v[202:205], v[218:221], v[52:55]
	v_mfma_f32_16x16x32_bf16 v[48:51], v[210:213], v[218:221], v[48:51]
	v_mfma_f32_16x16x32_bf16 v[36:39], v[202:205], v[226:229], v[36:39]
	v_mfma_f32_16x16x32_bf16 v[32:35], v[210:213], v[226:229], v[32:35]
	v_mfma_f32_16x16x32_bf16 v[20:23], v[202:205], v[234:237], v[20:23]
	v_mfma_f32_16x16x32_bf16 v[16:19], v[210:213], v[234:237], v[16:19]
	v_mfma_f32_16x16x32_bf16 v[4:7], v[202:205], v[242:245], v[4:7]
	v_mfma_f32_16x16x32_bf16 v[0:3], v[210:213], v[242:245], v[0:3]
	s_setprio 0
	s_barrier
	ds_read_b128 v[160:163], v177
	ds_read_b128 v[164:167], v178
	ds_read_b128 v[186:189], v179
	ds_read_b128 v[190:193], v180
	ds_read_b128 v[198:201], v181
	ds_read_b128 v[202:205], v182
	ds_read_b128 v[206:209], v183
	ds_read_b128 v[210:213], v184
	s_add_u32 s24, s24, 0x40000
	s_addc_u32 s25, s25, 0
	s_mov_b32 m0, s29
	v_lshl_add_u64 v[252:253], s[24:25], 0, v[128:129]
	ds_read_b128 v[214:217], v159 offset:32768
	ds_read_b128 v[218:221], v159 offset:33792
	ds_read_b128 v[222:225], v159 offset:34816
	ds_read_b128 v[226:229], v159 offset:35840
	ds_read_b128 v[230:233], v159 offset:36864
	ds_read_b128 v[234:237], v159 offset:37888
	ds_read_b128 v[238:241], v159 offset:38912
	ds_read_b128 v[242:245], v159 offset:39936
	global_load_lds_dwordx4 v[252:253], off
	v_lshl_add_u64 v[252:253], s[24:25], 0, v[130:131]
	s_mov_b32 m0, s30
	s_nop 0
	global_load_lds_dwordx4 v[252:253], off
	s_waitcnt vmcnt(8)
	s_waitcnt lgkmcnt(0)
	s_barrier
	s_setprio 1
	s_waitcnt lgkmcnt(0)
	v_mfma_f32_16x16x32_bf16 v[124:127], v[160:163], v[214:217], v[124:127]
	v_mfma_f32_16x16x32_bf16 v[120:123], v[186:189], v[214:217], v[120:123]
	v_mfma_f32_16x16x32_bf16 v[108:111], v[160:163], v[222:225], v[108:111]
	v_mfma_f32_16x16x32_bf16 v[104:107], v[186:189], v[222:225], v[104:107]
	v_mfma_f32_16x16x32_bf16 v[92:95], v[160:163], v[230:233], v[92:95]
	v_mfma_f32_16x16x32_bf16 v[88:91], v[186:189], v[230:233], v[88:91]
	v_mfma_f32_16x16x32_bf16 v[76:79], v[160:163], v[238:241], v[76:79]
	v_mfma_f32_16x16x32_bf16 v[72:75], v[186:189], v[238:241], v[72:75]
	v_mfma_f32_16x16x32_bf16 v[124:127], v[164:167], v[218:221], v[124:127]
	v_mfma_f32_16x16x32_bf16 v[120:123], v[190:193], v[218:221], v[120:123]
	v_mfma_f32_16x16x32_bf16 v[108:111], v[164:167], v[226:229], v[108:111]
	v_mfma_f32_16x16x32_bf16 v[104:107], v[190:193], v[226:229], v[104:107]
	v_mfma_f32_16x16x32_bf16 v[92:95], v[164:167], v[234:237], v[92:95]
	v_mfma_f32_16x16x32_bf16 v[88:91], v[190:193], v[234:237], v[88:91]
	v_mfma_f32_16x16x32_bf16 v[76:79], v[164:167], v[242:245], v[76:79]
	v_mfma_f32_16x16x32_bf16 v[72:75], v[190:193], v[242:245], v[72:75]
	s_setprio 0
	s_setprio 1
	v_mfma_f32_16x16x32_bf16 v[116:119], v[198:201], v[214:217], v[116:119]
	v_mfma_f32_16x16x32_bf16 v[112:115], v[206:209], v[214:217], v[112:115]
	v_mfma_f32_16x16x32_bf16 v[100:103], v[198:201], v[222:225], v[100:103]
	v_mfma_f32_16x16x32_bf16 v[96:99], v[206:209], v[222:225], v[96:99]
	v_mfma_f32_16x16x32_bf16 v[84:87], v[198:201], v[230:233], v[84:87]
	v_mfma_f32_16x16x32_bf16 v[80:83], v[206:209], v[230:233], v[80:83]
	v_mfma_f32_16x16x32_bf16 v[68:71], v[198:201], v[238:241], v[68:71]
	v_mfma_f32_16x16x32_bf16 v[64:67], v[206:209], v[238:241], v[64:67]
	v_mfma_f32_16x16x32_bf16 v[116:119], v[202:205], v[218:221], v[116:119]
	v_mfma_f32_16x16x32_bf16 v[112:115], v[210:213], v[218:221], v[112:115]
	v_mfma_f32_16x16x32_bf16 v[100:103], v[202:205], v[226:229], v[100:103]
	v_mfma_f32_16x16x32_bf16 v[96:99], v[210:213], v[226:229], v[96:99]
	v_mfma_f32_16x16x32_bf16 v[84:87], v[202:205], v[234:237], v[84:87]
	v_mfma_f32_16x16x32_bf16 v[80:83], v[210:213], v[234:237], v[80:83]
	v_mfma_f32_16x16x32_bf16 v[68:71], v[202:205], v[242:245], v[68:71]
	v_mfma_f32_16x16x32_bf16 v[64:67], v[210:213], v[242:245], v[64:67]
	s_setprio 0
	s_barrier
	s_mov_b32 m0, s31
	v_lshl_add_u64 v[142:143], v[142:143], 0, s[42:43]
	s_add_u32 s18, s18, 0x40080
	ds_read_b128 v[214:217], v159 offset:49152
	ds_read_b128 v[218:221], v159 offset:50176
	ds_read_b128 v[222:225], v159 offset:51200
	ds_read_b128 v[226:229], v159 offset:52224
	ds_read_b128 v[230:233], v159 offset:53248
	ds_read_b128 v[234:237], v159 offset:54272
	ds_read_b128 v[238:241], v159 offset:55296
	ds_read_b128 v[242:245], v159 offset:56320
	global_load_lds_dwordx4 v[142:143], off
	v_lshl_add_u64 v[142:143], v[246:247], 0, s[42:43]
	s_mov_b32 m0, s33
	s_addc_u32 s19, s19, 0
	global_load_lds_dwordx4 v[142:143], off
	v_lshl_add_u64 v[142:143], s[18:19], 0, v[128:129]
	s_mov_b32 m0, s36
	s_nop 0
	global_load_lds_dwordx4 v[142:143], off
	v_lshl_add_u64 v[142:143], s[18:19], 0, v[130:131]
	s_mov_b32 m0, s37
	s_nop 0
	global_load_lds_dwordx4 v[142:143], off
	v_lshl_add_u64 v[142:143], v[248:249], 0, s[42:43]
	s_mov_b32 m0, s34
	s_nop 0
	global_load_lds_dwordx4 v[142:143], off
	v_lshl_add_u64 v[142:143], v[250:251], 0, s[42:43]
	s_mov_b32 m0, s35
	s_nop 0
	global_load_lds_dwordx4 v[142:143], off
	s_waitcnt vmcnt(8)
	s_waitcnt lgkmcnt(0)
	s_barrier
	s_setprio 1
	s_waitcnt lgkmcnt(0)
	v_mfma_f32_16x16x32_bf16 v[60:63], v[160:163], v[214:217], v[60:63]
	v_mfma_f32_16x16x32_bf16 v[56:59], v[186:189], v[214:217], v[56:59]
	v_mfma_f32_16x16x32_bf16 v[44:47], v[160:163], v[222:225], v[44:47]
	v_mfma_f32_16x16x32_bf16 v[40:43], v[186:189], v[222:225], v[40:43]
	v_mfma_f32_16x16x32_bf16 v[28:31], v[160:163], v[230:233], v[28:31]
	v_mfma_f32_16x16x32_bf16 v[24:27], v[186:189], v[230:233], v[24:27]
	v_mfma_f32_16x16x32_bf16 v[12:15], v[160:163], v[238:241], v[12:15]
	v_mfma_f32_16x16x32_bf16 v[8:11], v[186:189], v[238:241], v[8:11]
	v_mfma_f32_16x16x32_bf16 v[60:63], v[164:167], v[218:221], v[60:63]
	v_mfma_f32_16x16x32_bf16 v[56:59], v[190:193], v[218:221], v[56:59]
	v_mfma_f32_16x16x32_bf16 v[44:47], v[164:167], v[226:229], v[44:47]
	v_mfma_f32_16x16x32_bf16 v[40:43], v[190:193], v[226:229], v[40:43]
	v_mfma_f32_16x16x32_bf16 v[28:31], v[164:167], v[234:237], v[28:31]
	v_mfma_f32_16x16x32_bf16 v[24:27], v[190:193], v[234:237], v[24:27]
	v_mfma_f32_16x16x32_bf16 v[12:15], v[164:167], v[242:245], v[12:15]
	v_mfma_f32_16x16x32_bf16 v[8:11], v[190:193], v[242:245], v[8:11]
	s_setprio 0
	s_setprio 1
	v_mfma_f32_16x16x32_bf16 v[52:55], v[198:201], v[214:217], v[52:55]
	v_mfma_f32_16x16x32_bf16 v[48:51], v[206:209], v[214:217], v[48:51]
	v_mfma_f32_16x16x32_bf16 v[36:39], v[198:201], v[222:225], v[36:39]
	v_mfma_f32_16x16x32_bf16 v[32:35], v[206:209], v[222:225], v[32:35]
	v_mfma_f32_16x16x32_bf16 v[20:23], v[198:201], v[230:233], v[20:23]
	v_mfma_f32_16x16x32_bf16 v[16:19], v[206:209], v[230:233], v[16:19]
	v_mfma_f32_16x16x32_bf16 v[4:7], v[198:201], v[238:241], v[4:7]
	v_mfma_f32_16x16x32_bf16 v[0:3], v[206:209], v[238:241], v[0:3]
	v_mfma_f32_16x16x32_bf16 v[52:55], v[202:205], v[218:221], v[52:55]
	v_mfma_f32_16x16x32_bf16 v[48:51], v[210:213], v[218:221], v[48:51]
	v_mfma_f32_16x16x32_bf16 v[36:39], v[202:205], v[226:229], v[36:39]
	v_mfma_f32_16x16x32_bf16 v[32:35], v[210:213], v[226:229], v[32:35]
	v_mfma_f32_16x16x32_bf16 v[20:23], v[202:205], v[234:237], v[20:23]
	v_mfma_f32_16x16x32_bf16 v[16:19], v[210:213], v[234:237], v[16:19]
	v_mfma_f32_16x16x32_bf16 v[4:7], v[202:205], v[242:245], v[4:7]
	v_mfma_f32_16x16x32_bf16 v[0:3], v[210:213], v[242:245], v[0:3]
	s_setprio 0
	s_barrier
	s_add_i32 s66, s66, 2
	s_add_u32 s16, s16, 0x100
	s_addc_u32 s17, s17, 0
	s_add_u32 s47, s47, 0x100
	s_addc_u32 s49, s49, 0
	s_cmp_gt_u32 s66, 13
	s_cbranch_scc0 .LBB0_2152
	s_and_b64 vcc, exec, s[44:45]
	s_cbranch_vccz .LBB0_2155
	s_barrier

.LBB0_2530:
	ds_read_b128 v[140:143], v162
	ds_read_b128 v[178:181], v163
	ds_read_b128 v[182:185], v164
	ds_read_b128 v[186:189], v165
	ds_read_b128 v[190:193], v166
	ds_read_b128 v[198:201], v167
	ds_read_b128 v[202:205], v168
	ds_read_b128 v[206:209], v169
	s_add_u32 s16, s0, 0xfffe0080
	s_addc_u32 s17, s1, -1
	s_cmp_eq_u32 s64, 4
	s_cselect_b32 s19, s4, s17
	s_cselect_b32 s18, s5, s16
	s_cselect_b32 s17, s13, s51
	s_cselect_b32 s16, s15, s49
	s_mov_b32 m0, s77
	v_lshl_add_u64 v[158:159], s[0:1], 0, v[132:133]
	ds_read_b128 v[210:213], v160
	ds_read_b128 v[214:217], v160 offset:1024
	ds_read_b128 v[218:221], v160 offset:2048
	ds_read_b128 v[222:225], v160 offset:3072
	ds_read_b128 v[226:229], v160 offset:4096
	ds_read_b128 v[230:233], v160 offset:5120
	ds_read_b128 v[234:237], v160 offset:6144
	ds_read_b128 v[238:241], v160 offset:7168
	global_load_lds_dwordx4 v[158:159], off
	v_lshl_add_u64 v[158:159], s[0:1], 0, v[134:135]
	s_mov_b32 m0, s78
	s_nop 0
	global_load_lds_dwordx4 v[158:159], off
	s_waitcnt vmcnt(8)
	s_waitcnt lgkmcnt(0)
	s_barrier
	s_setprio 1
	s_waitcnt lgkmcnt(0)
	v_mfma_f32_16x16x32_bf16 v[124:127], v[140:143], v[210:213], v[124:127]
	v_mfma_f32_16x16x32_bf16 v[120:123], v[182:185], v[210:213], v[120:123]
	v_mfma_f32_16x16x32_bf16 v[108:111], v[140:143], v[218:221], v[108:111]
	v_mfma_f32_16x16x32_bf16 v[104:107], v[182:185], v[218:221], v[104:107]
	v_mfma_f32_16x16x32_bf16 v[92:95], v[140:143], v[226:229], v[92:95]
	v_mfma_f32_16x16x32_bf16 v[88:91], v[182:185], v[226:229], v[88:91]
	v_mfma_f32_16x16x32_bf16 v[76:79], v[140:143], v[234:237], v[76:79]
	v_mfma_f32_16x16x32_bf16 v[72:75], v[182:185], v[234:237], v[72:75]
	v_mfma_f32_16x16x32_bf16 v[124:127], v[178:181], v[214:217], v[124:127]
	v_mfma_f32_16x16x32_bf16 v[120:123], v[186:189], v[214:217], v[120:123]
	v_mfma_f32_16x16x32_bf16 v[108:111], v[178:181], v[222:225], v[108:111]
	v_mfma_f32_16x16x32_bf16 v[104:107], v[186:189], v[222:225], v[104:107]
	v_mfma_f32_16x16x32_bf16 v[92:95], v[178:181], v[230:233], v[92:95]
	v_mfma_f32_16x16x32_bf16 v[88:91], v[186:189], v[230:233], v[88:91]
	v_mfma_f32_16x16x32_bf16 v[76:79], v[178:181], v[238:241], v[76:79]
	v_mfma_f32_16x16x32_bf16 v[72:75], v[186:189], v[238:241], v[72:75]
	s_setprio 0
	s_setprio 1
	v_mfma_f32_16x16x32_bf16 v[116:119], v[190:193], v[210:213], v[116:119]
	v_mfma_f32_16x16x32_bf16 v[112:115], v[202:205], v[210:213], v[112:115]
	v_mfma_f32_16x16x32_bf16 v[100:103], v[190:193], v[218:221], v[100:103]
	v_mfma_f32_16x16x32_bf16 v[96:99], v[202:205], v[218:221], v[96:99]
	v_mfma_f32_16x16x32_bf16 v[84:87], v[190:193], v[226:229], v[84:87]
	v_mfma_f32_16x16x32_bf16 v[80:83], v[202:205], v[226:229], v[80:83]
	v_mfma_f32_16x16x32_bf16 v[68:71], v[190:193], v[234:237], v[68:71]
	v_mfma_f32_16x16x32_bf16 v[64:67], v[202:205], v[234:237], v[64:67]
	v_mfma_f32_16x16x32_bf16 v[116:119], v[198:201], v[214:217], v[116:119]
	v_mfma_f32_16x16x32_bf16 v[112:115], v[206:209], v[214:217], v[112:115]
	v_mfma_f32_16x16x32_bf16 v[100:103], v[198:201], v[222:225], v[100:103]
	v_mfma_f32_16x16x32_bf16 v[96:99], v[206:209], v[222:225], v[96:99]
	v_mfma_f32_16x16x32_bf16 v[84:87], v[198:201], v[230:233], v[84:87]
	v_mfma_f32_16x16x32_bf16 v[80:83], v[206:209], v[230:233], v[80:83]
	v_mfma_f32_16x16x32_bf16 v[68:71], v[198:201], v[238:241], v[68:71]
	v_mfma_f32_16x16x32_bf16 v[64:67], v[206:209], v[238:241], v[64:67]
	s_setprio 0
	s_barrier
	s_mov_b32 m0, s6
	v_lshl_add_u64 v[158:159], s[16:17], 0, v[128:129]
	s_add_u32 s68, s16, 0x20000
	ds_read_b128 v[210:213], v160 offset:16384
	ds_read_b128 v[214:217], v160 offset:17408
	ds_read_b128 v[218:221], v160 offset:18432
	ds_read_b128 v[222:225], v160 offset:19456
	ds_read_b128 v[226:229], v160 offset:20480
	ds_read_b128 v[230:233], v160 offset:21504
	ds_read_b128 v[234:237], v160 offset:22528
	ds_read_b128 v[238:241], v160 offset:23552
	global_load_lds_dwordx4 v[158:159], off
	v_lshl_add_u64 v[242:243], s[16:17], 0, v[130:131]
	s_mov_b32 m0, s7
	s_addc_u32 s69, s17, 0
	global_load_lds_dwordx4 v[242:243], off
	v_lshl_add_u64 v[244:245], s[68:69], 0, v[128:129]
	s_mov_b32 m0, s8
	v_lshl_add_u64 v[246:247], s[18:19], 0, v[130:131]
	global_load_lds_dwordx4 v[244:245], off
	v_lshl_add_u64 v[244:245], s[68:69], 0, v[130:131]
	s_mov_b32 m0, s9
	s_nop 0
	global_load_lds_dwordx4 v[244:245], off
	v_lshl_add_u64 v[244:245], s[18:19], 0, v[128:129]
	s_mov_b32 m0, s2
	s_nop 0
	global_load_lds_dwordx4 v[244:245], off
	s_mov_b32 m0, s28
	s_nop 0
	global_load_lds_dwordx4 v[246:247], off
	s_waitcnt vmcnt(8)
	s_waitcnt lgkmcnt(0)
	s_barrier
	s_setprio 1
	s_waitcnt lgkmcnt(0)
	v_mfma_f32_16x16x32_bf16 v[60:63], v[140:143], v[210:213], v[60:63]
	v_mfma_f32_16x16x32_bf16 v[56:59], v[182:185], v[210:213], v[56:59]
	v_mfma_f32_16x16x32_bf16 v[44:47], v[140:143], v[218:221], v[44:47]
	v_mfma_f32_16x16x32_bf16 v[40:43], v[182:185], v[218:221], v[40:43]
	v_mfma_f32_16x16x32_bf16 v[28:31], v[140:143], v[226:229], v[28:31]
	v_mfma_f32_16x16x32_bf16 v[24:27], v[182:185], v[226:229], v[24:27]
	v_mfma_f32_16x16x32_bf16 v[12:15], v[140:143], v[234:237], v[12:15]
	v_mfma_f32_16x16x32_bf16 v[8:11], v[182:185], v[234:237], v[8:11]
	v_mfma_f32_16x16x32_bf16 v[60:63], v[178:181], v[214:217], v[60:63]
	v_mfma_f32_16x16x32_bf16 v[56:59], v[186:189], v[214:217], v[56:59]
	v_mfma_f32_16x16x32_bf16 v[44:47], v[178:181], v[222:225], v[44:47]
	v_mfma_f32_16x16x32_bf16 v[40:43], v[186:189], v[222:225], v[40:43]
	v_mfma_f32_16x16x32_bf16 v[28:31], v[178:181], v[230:233], v[28:31]
	v_mfma_f32_16x16x32_bf16 v[24:27], v[186:189], v[230:233], v[24:27]
	v_mfma_f32_16x16x32_bf16 v[12:15], v[178:181], v[238:241], v[12:15]
	v_mfma_f32_16x16x32_bf16 v[8:11], v[186:189], v[238:241], v[8:11]
	s_setprio 0
	s_setprio 1
	v_mfma_f32_16x16x32_bf16 v[52:55], v[190:193], v[210:213], v[52:55]
	v_mfma_f32_16x16x32_bf16 v[48:51], v[202:205], v[210:213], v[48:51]
	v_mfma_f32_16x16x32_bf16 v[36:39], v[190:193], v[218:221], v[36:39]
	v_mfma_f32_16x16x32_bf16 v[32:35], v[202:205], v[218:221], v[32:35]
	v_mfma_f32_16x16x32_bf16 v[20:23], v[190:193], v[226:229], v[20:23]
	v_mfma_f32_16x16x32_bf16 v[16:19], v[202:205], v[226:229], v[16:19]
	v_mfma_f32_16x16x32_bf16 v[4:7], v[190:193], v[234:237], v[4:7]
	v_mfma_f32_16x16x32_bf16 v[0:3], v[202:205], v[234:237], v[0:3]
	v_mfma_f32_16x16x32_bf16 v[52:55], v[198:201], v[214:217], v[52:55]
	v_mfma_f32_16x16x32_bf16 v[48:51], v[206:209], v[214:217], v[48:51]
	v_mfma_f32_16x16x32_bf16 v[36:39], v[198:201], v[222:225], v[36:39]
	v_mfma_f32_16x16x32_bf16 v[32:35], v[206:209], v[222:225], v[32:35]
	v_mfma_f32_16x16x32_bf16 v[20:23], v[198:201], v[230:233], v[20:23]
	v_mfma_f32_16x16x32_bf16 v[16:19], v[206:209], v[230:233], v[16:19]
	v_mfma_f32_16x16x32_bf16 v[4:7], v[198:201], v[238:241], v[4:7]
	v_mfma_f32_16x16x32_bf16 v[0:3], v[206:209], v[238:241], v[0:3]
	s_setprio 0
	s_barrier
	ds_read_b128 v[140:143], v170
	ds_read_b128 v[178:181], v171
	ds_read_b128 v[182:185], v172
	ds_read_b128 v[186:189], v173
	ds_read_b128 v[190:193], v174
	ds_read_b128 v[198:201], v175
	ds_read_b128 v[202:205], v176
	ds_read_b128 v[206:209], v177
	s_add_u32 s18, s18, 0x20000
	s_addc_u32 s19, s19, 0
	s_mov_b32 m0, s29
	v_lshl_add_u64 v[248:249], s[18:19], 0, v[128:129]
	ds_read_b128 v[210:213], v160 offset:32768
	ds_read_b128 v[214:217], v160 offset:33792
	ds_read_b128 v[218:221], v160 offset:34816
	ds_read_b128 v[222:225], v160 offset:35840
	ds_read_b128 v[226:229], v160 offset:36864
	ds_read_b128 v[230:233], v160 offset:37888
	ds_read_b128 v[234:237], v160 offset:38912
	ds_read_b128 v[238:241], v160 offset:39936
	global_load_lds_dwordx4 v[248:249], off
	v_lshl_add_u64 v[248:249], s[18:19], 0, v[130:131]
	s_mov_b32 m0, s30
	s_nop 0
	global_load_lds_dwordx4 v[248:249], off
	s_waitcnt vmcnt(8)
	s_waitcnt lgkmcnt(0)
	s_barrier
	s_setprio 1
	s_waitcnt lgkmcnt(0)
	v_mfma_f32_16x16x32_bf16 v[124:127], v[140:143], v[210:213], v[124:127]
	v_mfma_f32_16x16x32_bf16 v[120:123], v[182:185], v[210:213], v[120:123]
	v_mfma_f32_16x16x32_bf16 v[108:111], v[140:143], v[218:221], v[108:111]
	v_mfma_f32_16x16x32_bf16 v[104:107], v[182:185], v[218:221], v[104:107]
	v_mfma_f32_16x16x32_bf16 v[92:95], v[140:143], v[226:229], v[92:95]
	v_mfma_f32_16x16x32_bf16 v[88:91], v[182:185], v[226:229], v[88:91]
	v_mfma_f32_16x16x32_bf16 v[76:79], v[140:143], v[234:237], v[76:79]
	v_mfma_f32_16x16x32_bf16 v[72:75], v[182:185], v[234:237], v[72:75]
	v_mfma_f32_16x16x32_bf16 v[124:127], v[178:181], v[214:217], v[124:127]
	v_mfma_f32_16x16x32_bf16 v[120:123], v[186:189], v[214:217], v[120:123]
	v_mfma_f32_16x16x32_bf16 v[108:111], v[178:181], v[222:225], v[108:111]
	v_mfma_f32_16x16x32_bf16 v[104:107], v[186:189], v[222:225], v[104:107]
	v_mfma_f32_16x16x32_bf16 v[92:95], v[178:181], v[230:233], v[92:95]
	v_mfma_f32_16x16x32_bf16 v[88:91], v[186:189], v[230:233], v[88:91]
	v_mfma_f32_16x16x32_bf16 v[76:79], v[178:181], v[238:241], v[76:79]
	v_mfma_f32_16x16x32_bf16 v[72:75], v[186:189], v[238:241], v[72:75]
	s_setprio 0
	s_setprio 1
	v_mfma_f32_16x16x32_bf16 v[116:119], v[190:193], v[210:213], v[116:119]
	v_mfma_f32_16x16x32_bf16 v[112:115], v[202:205], v[210:213], v[112:115]
	v_mfma_f32_16x16x32_bf16 v[100:103], v[190:193], v[218:221], v[100:103]
	v_mfma_f32_16x16x32_bf16 v[96:99], v[202:205], v[218:221], v[96:99]
	v_mfma_f32_16x16x32_bf16 v[84:87], v[190:193], v[226:229], v[84:87]
	v_mfma_f32_16x16x32_bf16 v[80:83], v[202:205], v[226:229], v[80:83]
	v_mfma_f32_16x16x32_bf16 v[68:71], v[190:193], v[234:237], v[68:71]
	v_mfma_f32_16x16x32_bf16 v[64:67], v[202:205], v[234:237], v[64:67]
	v_mfma_f32_16x16x32_bf16 v[116:119], v[198:201], v[214:217], v[116:119]
	v_mfma_f32_16x16x32_bf16 v[112:115], v[206:209], v[214:217], v[112:115]
	v_mfma_f32_16x16x32_bf16 v[100:103], v[198:201], v[222:225], v[100:103]
	v_mfma_f32_16x16x32_bf16 v[96:99], v[206:209], v[222:225], v[96:99]
	v_mfma_f32_16x16x32_bf16 v[84:87], v[198:201], v[230:233], v[84:87]
	v_mfma_f32_16x16x32_bf16 v[80:83], v[206:209], v[230:233], v[80:83]
	v_mfma_f32_16x16x32_bf16 v[68:71], v[198:201], v[238:241], v[68:71]
	v_mfma_f32_16x16x32_bf16 v[64:67], v[206:209], v[238:241], v[64:67]
	s_setprio 0
	s_barrier
	s_mov_b32 m0, s31
	v_lshl_add_u64 v[158:159], v[158:159], 0, s[44:45]
	s_add_u32 s16, s16, 0x20080
	ds_read_b128 v[210:213], v160 offset:49152
	ds_read_b128 v[214:217], v160 offset:50176
	ds_read_b128 v[218:221], v160 offset:51200
	ds_read_b128 v[222:225], v160 offset:52224
	ds_read_b128 v[226:229], v160 offset:53248
	ds_read_b128 v[230:233], v160 offset:54272
	ds_read_b128 v[234:237], v160 offset:55296
	ds_read_b128 v[238:241], v160 offset:56320
	global_load_lds_dwordx4 v[158:159], off
	v_lshl_add_u64 v[158:159], v[242:243], 0, s[44:45]
	s_mov_b32 m0, s33
	s_addc_u32 s17, s17, 0
	global_load_lds_dwordx4 v[158:159], off
	v_lshl_add_u64 v[158:159], s[16:17], 0, v[128:129]
	s_mov_b32 m0, s36
	s_nop 0
	global_load_lds_dwordx4 v[158:159], off
	v_lshl_add_u64 v[158:159], s[16:17], 0, v[130:131]
	s_mov_b32 m0, s37
	s_nop 0
	global_load_lds_dwordx4 v[158:159], off
	v_lshl_add_u64 v[158:159], v[244:245], 0, s[44:45]
	s_mov_b32 m0, s34
	s_nop 0
	global_load_lds_dwordx4 v[158:159], off
	v_lshl_add_u64 v[158:159], v[246:247], 0, s[44:45]
	s_mov_b32 m0, s35
	s_nop 0
	global_load_lds_dwordx4 v[158:159], off
	s_waitcnt vmcnt(8)
	s_waitcnt lgkmcnt(0)
	s_barrier
	s_setprio 1
	s_waitcnt lgkmcnt(0)
	v_mfma_f32_16x16x32_bf16 v[60:63], v[140:143], v[210:213], v[60:63]
	v_mfma_f32_16x16x32_bf16 v[56:59], v[182:185], v[210:213], v[56:59]
	v_mfma_f32_16x16x32_bf16 v[44:47], v[140:143], v[218:221], v[44:47]
	v_mfma_f32_16x16x32_bf16 v[40:43], v[182:185], v[218:221], v[40:43]
	v_mfma_f32_16x16x32_bf16 v[28:31], v[140:143], v[226:229], v[28:31]
	v_mfma_f32_16x16x32_bf16 v[24:27], v[182:185], v[226:229], v[24:27]
	v_mfma_f32_16x16x32_bf16 v[12:15], v[140:143], v[234:237], v[12:15]
	v_mfma_f32_16x16x32_bf16 v[8:11], v[182:185], v[234:237], v[8:11]
	v_mfma_f32_16x16x32_bf16 v[60:63], v[178:181], v[214:217], v[60:63]
	v_mfma_f32_16x16x32_bf16 v[56:59], v[186:189], v[214:217], v[56:59]
	v_mfma_f32_16x16x32_bf16 v[44:47], v[178:181], v[222:225], v[44:47]
	v_mfma_f32_16x16x32_bf16 v[40:43], v[186:189], v[222:225], v[40:43]
	v_mfma_f32_16x16x32_bf16 v[28:31], v[178:181], v[230:233], v[28:31]
	v_mfma_f32_16x16x32_bf16 v[24:27], v[186:189], v[230:233], v[24:27]
	v_mfma_f32_16x16x32_bf16 v[12:15], v[178:181], v[238:241], v[12:15]
	v_mfma_f32_16x16x32_bf16 v[8:11], v[186:189], v[238:241], v[8:11]
	s_setprio 0
	s_setprio 1
	v_mfma_f32_16x16x32_bf16 v[52:55], v[190:193], v[210:213], v[52:55]
	v_mfma_f32_16x16x32_bf16 v[48:51], v[202:205], v[210:213], v[48:51]
	v_mfma_f32_16x16x32_bf16 v[36:39], v[190:193], v[218:221], v[36:39]
	v_mfma_f32_16x16x32_bf16 v[32:35], v[202:205], v[218:221], v[32:35]
	v_mfma_f32_16x16x32_bf16 v[20:23], v[190:193], v[226:229], v[20:23]
	v_mfma_f32_16x16x32_bf16 v[16:19], v[202:205], v[226:229], v[16:19]
	v_mfma_f32_16x16x32_bf16 v[4:7], v[190:193], v[234:237], v[4:7]
	v_mfma_f32_16x16x32_bf16 v[0:3], v[202:205], v[234:237], v[0:3]
	v_mfma_f32_16x16x32_bf16 v[52:55], v[198:201], v[214:217], v[52:55]
	v_mfma_f32_16x16x32_bf16 v[48:51], v[206:209], v[214:217], v[48:51]
	v_mfma_f32_16x16x32_bf16 v[36:39], v[198:201], v[222:225], v[36:39]
	v_mfma_f32_16x16x32_bf16 v[32:35], v[206:209], v[222:225], v[32:35]
	v_mfma_f32_16x16x32_bf16 v[20:23], v[198:201], v[230:233], v[20:23]
	v_mfma_f32_16x16x32_bf16 v[16:19], v[206:209], v[230:233], v[16:19]
	v_mfma_f32_16x16x32_bf16 v[4:7], v[198:201], v[238:241], v[4:7]
	v_mfma_f32_16x16x32_bf16 v[0:3], v[206:209], v[238:241], v[0:3]
	s_setprio 0
	s_barrier
	s_add_i32 s64, s64, 2
	s_add_u32 s0, s0, 0x100
	s_addc_u32 s1, s1, 0
	s_add_u32 s49, s49, 0x100
	s_addc_u32 s51, s51, 0
	s_cmp_gt_u32 s64, 5
	s_cbranch_scc0 .LBB0_2530
	s_and_b64 vcc, exec, s[46:47]
	s_cbranch_vccz .LBB0_2533
	s_barrier

.LBB0_2628:
	s_add_u32 s65, s48, s64
	s_addc_u32 s70, s49, 0
	s_add_u32 s71, s65, 0x100
	s_addc_u32 s74, s70, 0
	s_and_b64 s[68:69], s[54:55], exec
	s_cselect_b32 s75, s4, s74
	s_cselect_b32 s74, s5, s71
	s_add_u32 s64, s46, s64
	s_addc_u32 s68, s47, 0
	s_add_u32 s64, s64, 0x100
	ds_read_b128 v[170:173], v141
	ds_read_b128 v[174:177], v142
	ds_read_b128 v[178:181], v143
	ds_read_b128 v[182:185], v153
	ds_read_b128 v[186:189], v158
	ds_read_b128 v[190:193], v159
	ds_read_b128 v[196:199], v160
	ds_read_b128 v[200:203], v161
	s_addc_u32 s68, s68, 0
	s_and_b64 s[54:55], s[54:55], exec
	s_cselect_b32 s79, s21, s68
	s_cselect_b32 s78, s23, s64
	s_add_u32 s82, s65, 0x10080
	s_addc_u32 s83, s70, 0
	s_add_u32 s80, s78, 0x10000
	s_addc_u32 s81, s79, 0
	s_add_u32 s64, s74, 0x10000
	s_addc_u32 s65, s75, 0
	s_add_u32 s54, s78, 0x10080
	s_addc_u32 s55, s79, 0
	s_mov_b32 m0, s35
	v_lshl_add_u64 v[136:137], s[82:83], 0, v[128:129]
	ds_read_b128 v[204:207], v139
	ds_read_b128 v[208:211], v139 offset:1024
	ds_read_b128 v[212:215], v139 offset:2048
	ds_read_b128 v[216:219], v139 offset:3072
	ds_read_b128 v[220:223], v139 offset:4096
	ds_read_b128 v[224:227], v139 offset:5120
	ds_read_b128 v[228:231], v139 offset:6144
	ds_read_b128 v[232:235], v139 offset:7168
	global_load_lds_dwordx4 v[136:137], off
	v_lshl_add_u64 v[136:137], s[82:83], 0, v[130:131]
	s_mov_b32 m0, s60
	s_nop 0
	global_load_lds_dwordx4 v[136:137], off
	s_waitcnt vmcnt(8)
	s_waitcnt lgkmcnt(0)
	s_barrier
	s_setprio 1
	s_waitcnt lgkmcnt(0)
	v_mfma_f32_16x16x32_bf16 v[124:127], v[170:173], v[204:207], v[124:127]
	v_mfma_f32_16x16x32_bf16 v[120:123], v[178:181], v[204:207], v[120:123]
	v_mfma_f32_16x16x32_bf16 v[108:111], v[170:173], v[212:215], v[108:111]
	v_mfma_f32_16x16x32_bf16 v[104:107], v[178:181], v[212:215], v[104:107]
	v_mfma_f32_16x16x32_bf16 v[92:95], v[170:173], v[220:223], v[92:95]
	v_mfma_f32_16x16x32_bf16 v[88:91], v[178:181], v[220:223], v[88:91]
	v_mfma_f32_16x16x32_bf16 v[76:79], v[170:173], v[228:231], v[76:79]
	v_mfma_f32_16x16x32_bf16 v[72:75], v[178:181], v[228:231], v[72:75]
	v_mfma_f32_16x16x32_bf16 v[124:127], v[174:177], v[208:211], v[124:127]
	v_mfma_f32_16x16x32_bf16 v[120:123], v[182:185], v[208:211], v[120:123]
	v_mfma_f32_16x16x32_bf16 v[108:111], v[174:177], v[216:219], v[108:111]
	v_mfma_f32_16x16x32_bf16 v[104:107], v[182:185], v[216:219], v[104:107]
	v_mfma_f32_16x16x32_bf16 v[92:95], v[174:177], v[224:227], v[92:95]
	v_mfma_f32_16x16x32_bf16 v[88:91], v[182:185], v[224:227], v[88:91]
	v_mfma_f32_16x16x32_bf16 v[76:79], v[174:177], v[232:235], v[76:79]
	v_mfma_f32_16x16x32_bf16 v[72:75], v[182:185], v[232:235], v[72:75]
	s_setprio 0
	s_setprio 1
	v_mfma_f32_16x16x32_bf16 v[116:119], v[186:189], v[204:207], v[116:119]
	v_mfma_f32_16x16x32_bf16 v[112:115], v[196:199], v[204:207], v[112:115]
	v_mfma_f32_16x16x32_bf16 v[100:103], v[186:189], v[212:215], v[100:103]
	v_mfma_f32_16x16x32_bf16 v[96:99], v[196:199], v[212:215], v[96:99]
	v_mfma_f32_16x16x32_bf16 v[84:87], v[186:189], v[220:223], v[84:87]
	v_mfma_f32_16x16x32_bf16 v[80:83], v[196:199], v[220:223], v[80:83]
	v_mfma_f32_16x16x32_bf16 v[68:71], v[186:189], v[228:231], v[68:71]
	v_mfma_f32_16x16x32_bf16 v[64:67], v[196:199], v[228:231], v[64:67]
	v_mfma_f32_16x16x32_bf16 v[116:119], v[190:193], v[208:211], v[116:119]
	v_mfma_f32_16x16x32_bf16 v[112:115], v[200:203], v[208:211], v[112:115]
	v_mfma_f32_16x16x32_bf16 v[100:103], v[190:193], v[216:219], v[100:103]
	v_mfma_f32_16x16x32_bf16 v[96:99], v[200:203], v[216:219], v[96:99]
	v_mfma_f32_16x16x32_bf16 v[84:87], v[190:193], v[224:227], v[84:87]
	v_mfma_f32_16x16x32_bf16 v[80:83], v[200:203], v[224:227], v[80:83]
	v_mfma_f32_16x16x32_bf16 v[68:71], v[190:193], v[232:235], v[68:71]
	v_mfma_f32_16x16x32_bf16 v[64:67], v[200:203], v[232:235], v[64:67]
	s_setprio 0
	s_barrier
	s_mov_b32 m0, s45
	v_lshl_add_u64 v[136:137], s[78:79], 0, v[128:129]
	ds_read_b128 v[204:207], v139 offset:16384
	ds_read_b128 v[208:211], v139 offset:17408
	ds_read_b128 v[212:215], v139 offset:18432
	ds_read_b128 v[216:219], v139 offset:19456
	ds_read_b128 v[220:223], v139 offset:20480
	ds_read_b128 v[224:227], v139 offset:21504
	ds_read_b128 v[228:231], v139 offset:22528
	ds_read_b128 v[232:235], v139 offset:23552
	global_load_lds_dwordx4 v[136:137], off
	v_lshl_add_u64 v[236:237], s[78:79], 0, v[130:131]
	s_mov_b32 m0, s67
	v_lshl_add_u64 v[238:239], s[80:81], 0, v[128:129]
	global_load_lds_dwordx4 v[236:237], off
	s_mov_b32 m0, s84
	v_lshl_add_u64 v[240:241], s[74:75], 0, v[130:131]
	global_load_lds_dwordx4 v[238:239], off
	v_lshl_add_u64 v[238:239], s[80:81], 0, v[130:131]
	s_mov_b32 m0, s85
	s_nop 0
	global_load_lds_dwordx4 v[238:239], off
	v_lshl_add_u64 v[238:239], s[74:75], 0, v[128:129]
	s_mov_b32 m0, s30
	s_nop 0
	global_load_lds_dwordx4 v[238:239], off
	s_mov_b32 m0, s86
	s_nop 0
	global_load_lds_dwordx4 v[240:241], off
	s_waitcnt vmcnt(8)
	s_waitcnt lgkmcnt(0)
	s_barrier
	s_setprio 1
	s_waitcnt lgkmcnt(0)
	v_mfma_f32_16x16x32_bf16 v[60:63], v[170:173], v[204:207], v[60:63]
	v_mfma_f32_16x16x32_bf16 v[56:59], v[178:181], v[204:207], v[56:59]
	v_mfma_f32_16x16x32_bf16 v[44:47], v[170:173], v[212:215], v[44:47]
	v_mfma_f32_16x16x32_bf16 v[40:43], v[178:181], v[212:215], v[40:43]
	v_mfma_f32_16x16x32_bf16 v[28:31], v[170:173], v[220:223], v[28:31]
	v_mfma_f32_16x16x32_bf16 v[24:27], v[178:181], v[220:223], v[24:27]
	v_mfma_f32_16x16x32_bf16 v[12:15], v[170:173], v[228:231], v[12:15]
	v_mfma_f32_16x16x32_bf16 v[8:11], v[178:181], v[228:231], v[8:11]
	v_mfma_f32_16x16x32_bf16 v[60:63], v[174:177], v[208:211], v[60:63]
	v_mfma_f32_16x16x32_bf16 v[56:59], v[182:185], v[208:211], v[56:59]
	v_mfma_f32_16x16x32_bf16 v[44:47], v[174:177], v[216:219], v[44:47]
	v_mfma_f32_16x16x32_bf16 v[40:43], v[182:185], v[216:219], v[40:43]
	v_mfma_f32_16x16x32_bf16 v[28:31], v[174:177], v[224:227], v[28:31]
	v_mfma_f32_16x16x32_bf16 v[24:27], v[182:185], v[224:227], v[24:27]
	v_mfma_f32_16x16x32_bf16 v[12:15], v[174:177], v[232:235], v[12:15]
	v_mfma_f32_16x16x32_bf16 v[8:11], v[182:185], v[232:235], v[8:11]
	s_setprio 0
	s_setprio 1
	v_mfma_f32_16x16x32_bf16 v[52:55], v[186:189], v[204:207], v[52:55]
	v_mfma_f32_16x16x32_bf16 v[48:51], v[196:199], v[204:207], v[48:51]
	v_mfma_f32_16x16x32_bf16 v[36:39], v[186:189], v[212:215], v[36:39]
	v_mfma_f32_16x16x32_bf16 v[32:35], v[196:199], v[212:215], v[32:35]
	v_mfma_f32_16x16x32_bf16 v[20:23], v[186:189], v[220:223], v[20:23]
	v_mfma_f32_16x16x32_bf16 v[16:19], v[196:199], v[220:223], v[16:19]
	v_mfma_f32_16x16x32_bf16 v[4:7], v[186:189], v[228:231], v[4:7]
	v_mfma_f32_16x16x32_bf16 v[0:3], v[196:199], v[228:231], v[0:3]
	v_mfma_f32_16x16x32_bf16 v[52:55], v[190:193], v[208:211], v[52:55]
	v_mfma_f32_16x16x32_bf16 v[48:51], v[200:203], v[208:211], v[48:51]
	v_mfma_f32_16x16x32_bf16 v[36:39], v[190:193], v[216:219], v[36:39]
	v_mfma_f32_16x16x32_bf16 v[32:35], v[200:203], v[216:219], v[32:35]
	v_mfma_f32_16x16x32_bf16 v[20:23], v[190:193], v[224:227], v[20:23]
	v_mfma_f32_16x16x32_bf16 v[16:19], v[200:203], v[224:227], v[16:19]
	v_mfma_f32_16x16x32_bf16 v[4:7], v[190:193], v[232:235], v[4:7]
	v_mfma_f32_16x16x32_bf16 v[0:3], v[200:203], v[232:235], v[0:3]
	s_setprio 0
	s_barrier
	ds_read_b128 v[170:173], v162
	ds_read_b128 v[174:177], v163
	ds_read_b128 v[178:181], v164
	ds_read_b128 v[182:185], v165
	ds_read_b128 v[186:189], v166
	ds_read_b128 v[190:193], v167
	ds_read_b128 v[196:199], v168
	ds_read_b128 v[200:203], v169
	s_mov_b32 m0, s87
	v_lshl_add_u64 v[242:243], s[64:65], 0, v[128:129]
	ds_read_b128 v[204:207], v139 offset:32768
	ds_read_b128 v[208:211], v139 offset:33792
	ds_read_b128 v[212:215], v139 offset:34816
	ds_read_b128 v[216:219], v139 offset:35840
	ds_read_b128 v[220:223], v139 offset:36864
	ds_read_b128 v[224:227], v139 offset:37888
	ds_read_b128 v[228:231], v139 offset:38912
	ds_read_b128 v[232:235], v139 offset:39936
	global_load_lds_dwordx4 v[242:243], off
	v_lshl_add_u64 v[242:243], s[64:65], 0, v[130:131]
	s_mov_b32 m0, s90
	s_nop 0
	global_load_lds_dwordx4 v[242:243], off
	s_waitcnt vmcnt(8)
	s_waitcnt lgkmcnt(0)
	s_barrier
	s_setprio 1
	s_waitcnt lgkmcnt(0)
	v_mfma_f32_16x16x32_bf16 v[124:127], v[170:173], v[204:207], v[124:127]
	v_mfma_f32_16x16x32_bf16 v[120:123], v[178:181], v[204:207], v[120:123]
	v_mfma_f32_16x16x32_bf16 v[108:111], v[170:173], v[212:215], v[108:111]
	v_mfma_f32_16x16x32_bf16 v[104:107], v[178:181], v[212:215], v[104:107]
	v_mfma_f32_16x16x32_bf16 v[92:95], v[170:173], v[220:223], v[92:95]
	v_mfma_f32_16x16x32_bf16 v[88:91], v[178:181], v[220:223], v[88:91]
	v_mfma_f32_16x16x32_bf16 v[76:79], v[170:173], v[228:231], v[76:79]
	v_mfma_f32_16x16x32_bf16 v[72:75], v[178:181], v[228:231], v[72:75]
	v_mfma_f32_16x16x32_bf16 v[124:127], v[174:177], v[208:211], v[124:127]
	v_mfma_f32_16x16x32_bf16 v[120:123], v[182:185], v[208:211], v[120:123]
	v_mfma_f32_16x16x32_bf16 v[108:111], v[174:177], v[216:219], v[108:111]
	v_mfma_f32_16x16x32_bf16 v[104:107], v[182:185], v[216:219], v[104:107]
	v_mfma_f32_16x16x32_bf16 v[92:95], v[174:177], v[224:227], v[92:95]
	v_mfma_f32_16x16x32_bf16 v[88:91], v[182:185], v[224:227], v[88:91]
	v_mfma_f32_16x16x32_bf16 v[76:79], v[174:177], v[232:235], v[76:79]
	v_mfma_f32_16x16x32_bf16 v[72:75], v[182:185], v[232:235], v[72:75]
	s_setprio 0
	s_setprio 1
	v_mfma_f32_16x16x32_bf16 v[116:119], v[186:189], v[204:207], v[116:119]
	v_mfma_f32_16x16x32_bf16 v[112:115], v[196:199], v[204:207], v[112:115]
	v_mfma_f32_16x16x32_bf16 v[100:103], v[186:189], v[212:215], v[100:103]
	v_mfma_f32_16x16x32_bf16 v[96:99], v[196:199], v[212:215], v[96:99]
	v_mfma_f32_16x16x32_bf16 v[84:87], v[186:189], v[220:223], v[84:87]
	v_mfma_f32_16x16x32_bf16 v[80:83], v[196:199], v[220:223], v[80:83]
	v_mfma_f32_16x16x32_bf16 v[68:71], v[186:189], v[228:231], v[68:71]
	v_mfma_f32_16x16x32_bf16 v[64:67], v[196:199], v[228:231], v[64:67]
	v_mfma_f32_16x16x32_bf16 v[116:119], v[190:193], v[208:211], v[116:119]
	v_mfma_f32_16x16x32_bf16 v[112:115], v[200:203], v[208:211], v[112:115]
	v_mfma_f32_16x16x32_bf16 v[100:103], v[190:193], v[216:219], v[100:103]
	v_mfma_f32_16x16x32_bf16 v[96:99], v[200:203], v[216:219], v[96:99]
	v_mfma_f32_16x16x32_bf16 v[84:87], v[190:193], v[224:227], v[84:87]
	v_mfma_f32_16x16x32_bf16 v[80:83], v[200:203], v[224:227], v[80:83]
	v_mfma_f32_16x16x32_bf16 v[68:71], v[190:193], v[232:235], v[68:71]
	v_mfma_f32_16x16x32_bf16 v[64:67], v[200:203], v[232:235], v[64:67]
	s_setprio 0
	s_barrier
	s_mov_b32 m0, s33
	v_lshl_add_u64 v[136:137], v[136:137], 0, s[16:17]
	ds_read_b128 v[204:207], v139 offset:49152
	ds_read_b128 v[208:211], v139 offset:50176
	ds_read_b128 v[212:215], v139 offset:51200
	ds_read_b128 v[216:219], v139 offset:52224
	ds_read_b128 v[220:223], v139 offset:53248
	ds_read_b128 v[224:227], v139 offset:54272
	ds_read_b128 v[228:231], v139 offset:55296
	ds_read_b128 v[232:235], v139 offset:56320
	global_load_lds_dwordx4 v[136:137], off
	v_lshl_add_u64 v[136:137], v[236:237], 0, s[16:17]
	s_mov_b32 m0, s9
	s_nop 0
	global_load_lds_dwordx4 v[136:137], off
	v_lshl_add_u64 v[136:137], s[54:55], 0, v[128:129]
	s_mov_b32 m0, s52
	s_nop 0
	global_load_lds_dwordx4 v[136:137], off
	v_lshl_add_u64 v[136:137], s[54:55], 0, v[130:131]
	s_mov_b32 m0, s61
	s_nop 0
	global_load_lds_dwordx4 v[136:137], off
	v_lshl_add_u64 v[136:137], v[238:239], 0, s[16:17]
	s_mov_b32 m0, s8
	s_nop 0
	global_load_lds_dwordx4 v[136:137], off
	v_lshl_add_u64 v[136:137], v[240:241], 0, s[16:17]
	s_mov_b32 m0, s53
	s_nop 0
	global_load_lds_dwordx4 v[136:137], off
	s_waitcnt vmcnt(8)
	s_waitcnt lgkmcnt(0)
	s_barrier
	s_setprio 1
	s_waitcnt lgkmcnt(0)
	v_mfma_f32_16x16x32_bf16 v[60:63], v[170:173], v[204:207], v[60:63]
	v_mfma_f32_16x16x32_bf16 v[56:59], v[178:181], v[204:207], v[56:59]
	v_mfma_f32_16x16x32_bf16 v[44:47], v[170:173], v[212:215], v[44:47]
	v_mfma_f32_16x16x32_bf16 v[40:43], v[178:181], v[212:215], v[40:43]
	v_mfma_f32_16x16x32_bf16 v[28:31], v[170:173], v[220:223], v[28:31]
	v_mfma_f32_16x16x32_bf16 v[24:27], v[178:181], v[220:223], v[24:27]
	v_mfma_f32_16x16x32_bf16 v[12:15], v[170:173], v[228:231], v[12:15]
	v_mfma_f32_16x16x32_bf16 v[8:11], v[178:181], v[228:231], v[8:11]
	v_mfma_f32_16x16x32_bf16 v[60:63], v[174:177], v[208:211], v[60:63]
	v_mfma_f32_16x16x32_bf16 v[56:59], v[182:185], v[208:211], v[56:59]
	v_mfma_f32_16x16x32_bf16 v[44:47], v[174:177], v[216:219], v[44:47]
	v_mfma_f32_16x16x32_bf16 v[40:43], v[182:185], v[216:219], v[40:43]
	v_mfma_f32_16x16x32_bf16 v[28:31], v[174:177], v[224:227], v[28:31]
	v_mfma_f32_16x16x32_bf16 v[24:27], v[182:185], v[224:227], v[24:27]
	v_mfma_f32_16x16x32_bf16 v[12:15], v[174:177], v[232:235], v[12:15]
	v_mfma_f32_16x16x32_bf16 v[8:11], v[182:185], v[232:235], v[8:11]
	s_setprio 0
	s_setprio 1
	v_mfma_f32_16x16x32_bf16 v[52:55], v[186:189], v[204:207], v[52:55]
	v_mfma_f32_16x16x32_bf16 v[48:51], v[196:199], v[204:207], v[48:51]
	v_mfma_f32_16x16x32_bf16 v[36:39], v[186:189], v[212:215], v[36:39]
	v_mfma_f32_16x16x32_bf16 v[32:35], v[196:199], v[212:215], v[32:35]
	v_mfma_f32_16x16x32_bf16 v[20:23], v[186:189], v[220:223], v[20:23]
	v_mfma_f32_16x16x32_bf16 v[16:19], v[196:199], v[220:223], v[16:19]
	v_mfma_f32_16x16x32_bf16 v[4:7], v[186:189], v[228:231], v[4:7]
	v_mfma_f32_16x16x32_bf16 v[0:3], v[196:199], v[228:231], v[0:3]
	v_mfma_f32_16x16x32_bf16 v[52:55], v[190:193], v[208:211], v[52:55]
	v_mfma_f32_16x16x32_bf16 v[48:51], v[200:203], v[208:211], v[48:51]
	v_mfma_f32_16x16x32_bf16 v[36:39], v[190:193], v[216:219], v[36:39]
	v_mfma_f32_16x16x32_bf16 v[32:35], v[200:203], v[216:219], v[32:35]
	v_mfma_f32_16x16x32_bf16 v[20:23], v[190:193], v[224:227], v[20:23]
	v_mfma_f32_16x16x32_bf16 v[16:19], v[200:203], v[224:227], v[16:19]
	v_mfma_f32_16x16x32_bf16 v[4:7], v[190:193], v[232:235], v[4:7]
	v_mfma_f32_16x16x32_bf16 v[0:3], v[200:203], v[232:235], v[0:3]
	s_setprio 0
	s_barrier
	s_movk_i32 s64, 0x100
	s_andn2_b64 vcc, exec, s[50:51]
	s_mov_b64 s[54:55], -1
	s_mov_b64 s[50:51], 0
	s_cbranch_vccz .LBB0_2628
	s_and_b64 vcc, exec, s[18:19]
	s_cbranch_vccz .LBB0_2631
	s_barrier

.LBB0_2717:
	s_mul_i32 s4, s13, 0x3400
	v_add_u32_e32 v227, s4, v184
	ds_read_b128 v[236:239], v227
	ds_read_b128 v[240:243], v227 offset:32
	ds_read_b128 v[244:247], v227 offset:64
	ds_read_b128 v[248:251], v227 offset:96
	v_max_f32_e32 v193, v48, v48
	v_max_f32_e32 v96, v49, v49
	v_max_f32_e32 v96, v193, v96
	v_max3_f32 v96, v96, v50, v51
	v_max3_f32 v96, v96, v52, v53
	v_max3_f32 v96, v96, v54, v55
	s_waitcnt lgkmcnt(3)
	v_mfma_f32_32x32x16_bf16 v[80:95], v[236:239], v[100:103], 0
	ds_read_b128 v[236:239], v227 offset:128
	v_max3_f32 v96, v96, v56, v57
	v_max3_f32 v96, v96, v58, v59
	v_max3_f32 v96, v96, v60, v61
	v_max3_f32 v96, v96, v62, v63
	s_waitcnt lgkmcnt(3)
	v_mfma_f32_32x32x16_bf16 v[80:95], v[240:243], v[104:107], v[80:95]
	ds_read_b128 v[240:243], v227 offset:160
	v_max3_f32 v96, v96, v32, v33
	v_max3_f32 v96, v96, v34, v35
	v_max3_f32 v96, v96, v36, v37
	v_max3_f32 v96, v96, v38, v39
	s_waitcnt lgkmcnt(3)
	v_mfma_f32_32x32x16_bf16 v[80:95], v[244:247], v[108:111], v[80:95]
	ds_read_b128 v[244:247], v227 offset:6656
	v_max3_f32 v96, v96, v40, v41
	v_max3_f32 v96, v96, v42, v43
	v_max3_f32 v96, v96, v44, v45
	v_max3_f32 v96, v96, v46, v47
	v_add_f32_e32 v193, 0x41000000, v191
	v_cmp_gt_f32_e32 vcc, v96, v193
	s_waitcnt lgkmcnt(3)
	v_mfma_f32_32x32x16_bf16 v[80:95], v[248:251], v[112:115], v[80:95]
	ds_read_b128 v[248:251], v227 offset:6688
	s_cbranch_vccz .LBB0_2719
	ds_bpermute_b32 v193, v186, v96
	s_waitcnt lgkmcnt(0)
	v_max3_f32 v193, v191, v96, v193
	v_sub_f32_e32 v96, v191, v193
	v_exp_f32_e32 v96, v96
	v_mov_b32_e32 v191, v193
	v_mul_f32_e32 v192, v192, v96
	v_pk_mul_f32 v[30:31], v[30:31], v[96:97] op_sel_hi:[1,0]
	v_pk_mul_f32 v[28:29], v[28:29], v[96:97] op_sel_hi:[1,0]
	v_pk_mul_f32 v[26:27], v[26:27], v[96:97] op_sel_hi:[1,0]
	v_pk_mul_f32 v[24:25], v[24:25], v[96:97] op_sel_hi:[1,0]
	v_pk_mul_f32 v[22:23], v[22:23], v[96:97] op_sel_hi:[1,0]
	v_pk_mul_f32 v[20:21], v[20:21], v[96:97] op_sel_hi:[1,0]
	v_pk_mul_f32 v[18:19], v[18:19], v[96:97] op_sel_hi:[1,0]
	v_pk_mul_f32 v[16:17], v[16:17], v[96:97] op_sel_hi:[1,0]
	v_pk_mul_f32 v[14:15], v[14:15], v[96:97] op_sel_hi:[1,0]
	v_pk_mul_f32 v[12:13], v[12:13], v[96:97] op_sel_hi:[1,0]
	v_pk_mul_f32 v[10:11], v[10:11], v[96:97] op_sel_hi:[1,0]
	v_pk_mul_f32 v[8:9], v[8:9], v[96:97] op_sel_hi:[1,0]
	v_pk_mul_f32 v[6:7], v[6:7], v[96:97] op_sel_hi:[1,0]
	v_pk_mul_f32 v[4:5], v[4:5], v[96:97] op_sel_hi:[1,0]
	v_pk_mul_f32 v[2:3], v[2:3], v[96:97] op_sel_hi:[1,0]
	v_pk_mul_f32 v[0:1], v[0:1], v[96:97] op_sel_hi:[1,0]
.LBB0_2719:
	v_sub_f32_e32 v48, v48, v191
	v_exp_f32_e32 v193, v48
	v_sub_f32_e32 v48, v49, v191
	v_exp_f32_e32 v195, v48
	s_waitcnt lgkmcnt(3)
	v_mfma_f32_32x32x16_bf16 v[80:95], v[236:239], v[116:119], v[80:95]
	ds_read_b128 v[236:239], v227 offset:6720
	v_sub_f32_e32 v48, v50, v191
	v_exp_f32_e32 v196, v48
	v_sub_f32_e32 v48, v51, v191
	v_exp_f32_e32 v197, v48
	s_waitcnt lgkmcnt(3)
	v_mfma_f32_32x32x16_bf16 v[80:95], v[240:243], v[120:123], v[80:95]
	ds_read_b128 v[240:243], v227 offset:6752
	v_sub_f32_e32 v48, v52, v191
	v_exp_f32_e32 v199, v48
	v_sub_f32_e32 v48, v53, v191
	v_exp_f32_e32 v200, v48
	s_waitcnt lgkmcnt(3)
	v_mfma_f32_32x32x16_bf16 v[64:79], v[244:247], v[100:103], 0
	ds_read_b128 v[244:247], v227 offset:6784
	v_sub_f32_e32 v48, v54, v191
	v_exp_f32_e32 v201, v48
	v_sub_f32_e32 v48, v55, v191
	v_exp_f32_e32 v202, v48
	s_waitcnt lgkmcnt(3)
	v_mfma_f32_32x32x16_bf16 v[64:79], v[248:251], v[104:107], v[64:79]
	ds_read_b128 v[248:251], v227 offset:6816
	v_sub_f32_e32 v48, v56, v191
	v_exp_f32_e32 v203, v48
	v_sub_f32_e32 v48, v57, v191
	v_exp_f32_e32 v204, v48
	s_waitcnt lgkmcnt(3)
	v_mfma_f32_32x32x16_bf16 v[64:79], v[236:239], v[108:111], v[64:79]
	v_sub_f32_e32 v48, v58, v191
	v_exp_f32_e32 v205, v48
	v_sub_f32_e32 v48, v59, v191
	v_sub_f32_e32 v32, v32, v191
	s_waitcnt lgkmcnt(2)
	v_mfma_f32_32x32x16_bf16 v[64:79], v[240:243], v[112:115], v[64:79]
	s_mul_i32 s20, s12, 0x2400
	v_exp_f32_e32 v206, v48
	v_sub_f32_e32 v48, v60, v191
	v_exp_f32_e32 v211, v32
	v_sub_f32_e32 v32, v33, v191
	s_waitcnt lgkmcnt(1)
	v_mfma_f32_32x32x16_bf16 v[64:79], v[244:247], v[116:119], v[64:79]
	v_lshlrev_b32_e32 v33, 1, v185
	v_lshlrev_b32_e32 v96, 1, v160
	v_exp_f32_e32 v207, v48
	v_sub_f32_e32 v48, v61, v191
	s_waitcnt lgkmcnt(0)
	v_mfma_f32_32x32x16_bf16 v[64:79], v[248:251], v[120:123], v[64:79]
	v_add3_u32 v52, s20, v33, v96
	v_exp_f32_e32 v208, v48
	v_sub_f32_e32 v48, v62, v191
	v_add_u32_e32 v58, 0xa800, v52
	v_exp_f32_e32 v209, v48
	v_sub_f32_e32 v48, v63, v191
	v_add_u32_e32 v56, 0x9800, v52
	ds_read2_b64 v[52:55], v58 offset0:192 offset1:194
	v_exp_f32_e32 v210, v48
	ds_read2_b64 v[48:51], v56 offset0:128 offset1:130
	v_sub_f32_e32 v36, v36, v191
	v_exp_f32_e32 v212, v32
	v_sub_f32_e32 v32, v34, v191
	v_exp_f32_e32 v215, v36
	v_sub_f32_e32 v36, v37, v191
	v_exp_f32_e32 v213, v32
	v_sub_f32_e32 v57, v35, v191
	v_cvt_pk_bf16_f32 v32, v193, v195
	v_cvt_pk_bf16_f32 v33, v196, v197
	v_cvt_pk_bf16_f32 v34, v199, v200
	v_cvt_pk_bf16_f32 v35, v201, v202
	v_exp_f32_e32 v216, v36
	v_sub_f32_e32 v36, v38, v191
	s_waitcnt lgkmcnt(1)
	v_mfma_f32_32x32x16_bf16 v[0:15], v[52:55], v[32:35], v[0:15]
	v_exp_f32_e32 v217, v36
	v_sub_f32_e32 v52, v39, v191
	ds_read2_b64 v[36:39], v58 offset0:196 offset1:198
	v_sub_f32_e32 v40, v40, v191
	v_exp_f32_e32 v214, v57
	v_exp_f32_e32 v218, v52
	v_exp_f32_e32 v219, v40
	s_waitcnt lgkmcnt(1)
	v_mfma_f32_32x32x16_bf16 v[16:31], v[48:51], v[32:35], v[16:31]
	ds_read2_b64 v[48:51], v56 offset0:132 offset1:134
	v_cvt_pk_bf16_f32 v32, v203, v204
	v_cvt_pk_bf16_f32 v33, v205, v206
	v_cvt_pk_bf16_f32 v34, v207, v208
	v_cvt_pk_bf16_f32 v35, v209, v210
	v_sub_f32_e32 v40, v41, v191
	v_exp_f32_e32 v220, v40
	s_waitcnt lgkmcnt(1)
	v_mfma_f32_32x32x16_bf16 v[0:15], v[36:39], v[32:35], v[0:15]
	ds_read2_b64 v[36:39], v58 offset0:200 offset1:202
	v_sub_f32_e32 v40, v42, v191
	v_exp_f32_e32 v221, v40
	v_sub_f32_e32 v40, v43, v191
	v_exp_f32_e32 v222, v40
	v_sub_f32_e32 v40, v44, v191
	v_exp_f32_e32 v223, v40
	s_waitcnt lgkmcnt(1)
	v_mfma_f32_32x32x16_bf16 v[16:31], v[48:51], v[32:35], v[16:31]
	ds_read2_b64 v[48:51], v56 offset0:136 offset1:138
	v_cvt_pk_bf16_f32 v32, v211, v212
	v_cvt_pk_bf16_f32 v33, v213, v214
	v_cvt_pk_bf16_f32 v34, v215, v216
	v_cvt_pk_bf16_f32 v35, v217, v218
	v_sub_f32_e32 v40, v45, v191
	v_exp_f32_e32 v224, v40
	ds_read2_b64 v[40:43], v56 offset0:140 offset1:142
	s_waitcnt lgkmcnt(2)
	v_mfma_f32_32x32x16_bf16 v[0:15], v[36:39], v[32:35], v[0:15]
	ds_read2_b64 v[36:39], v58 offset0:204 offset1:206
	v_sub_f32_e32 v44, v46, v191
	v_exp_f32_e32 v225, v44
	s_add_i32 s4, s16, -4
	s_cmp_ge_u32 s4, s9
	s_waitcnt lgkmcnt(0)
	s_barrier
	v_mfma_f32_32x32x16_bf16 v[16:31], v[48:51], v[32:35], v[16:31]
	v_sub_f32_e32 v32, v47, v191
	v_exp_f32_e32 v226, v32
	v_cvt_pk_bf16_f32 v32, v219, v220
	v_cvt_pk_bf16_f32 v33, v221, v222
	v_cvt_pk_bf16_f32 v34, v223, v224
	v_cvt_pk_bf16_f32 v35, v225, v226
	s_nop 1
	v_mfma_f32_32x32x16_bf16 v[16:31], v[40:43], v[32:35], v[16:31]
	v_mfma_f32_32x32x16_bf16 v[0:15], v[36:39], v[32:35], v[0:15]
	s_cbranch_scc1 .LBB0_2726
	s_mul_i32 s21, s12, 0x3400
	v_add3_u32 v32, s21, v190, v198
	s_waitcnt vmcnt(1)
	ds_write_b128 v32, v[128:131]
	s_and_saveexec_b64 s[4:5], s[10:11]
	v_lshlrev_b32_e32 v32, 1, v180
	v_lshlrev_b32_e32 v33, 1, v142
	v_add3_u32 v32, s21, v32, v33
	ds_write_b128 v32, v[124:127]
	s_or_b64 exec, exec, s[4:5]
	v_lshlrev_b32_e32 v32, 1, v182
	v_add3_u32 v32, s20, v32, v158
	s_cmp_ge_u32 s16, s8
	s_waitcnt vmcnt(0)
	ds_write_b128 v32, v[132:135] offset:39936
	s_cbranch_scc1 .LBB0_2726
	v_lshl_add_u64 v[32:33], s[90:91], 0, v[178:179]
	v_add_co_u32_e32 v32, vcc, 0x159c0000, v32
	s_nop 1
	v_addc_co_u32_e32 v33, vcc, 0, v33, vcc
	global_load_dwordx4 v[128:131], v[32:33], off
	s_and_saveexec_b64 s[4:5], s[10:11]
	s_cbranch_execz .LBB0_2725
	v_lshl_add_u64 v[32:33], s[90:91], 0, v[176:177]
	v_add_co_u32_e32 v32, vcc, 0x159c0000, v32
	s_nop 1
	v_addc_co_u32_e32 v33, vcc, 0, v33, vcc
	global_load_dwordx4 v[124:127], v[32:33], off

.LBB0_2726:
	v_add_u32_e32 v198, s19, v184
	ds_read_b128 v[236:239], v198
	ds_read_b128 v[240:243], v198 offset:32
	ds_read_b128 v[244:247], v198 offset:64
	ds_read_b128 v[248:251], v198 offset:96
.LBB0_2728:
	v_add_f32_e32 v193, 0, v193
	v_add_f32_e32 v195, 0, v195
	v_add_f32_e32 v193, v196, v193
	v_add_f32_e32 v195, v197, v195
	s_waitcnt lgkmcnt(3)
	v_mfma_f32_32x32x16_bf16 v[48:63], v[236:239], v[100:103], 0
	ds_read_b128 v[236:239], v198 offset:128
	v_add_f32_e32 v193, v199, v193
	v_add_f32_e32 v195, v200, v195
	v_add_f32_e32 v193, v201, v193
	v_add_f32_e32 v195, v202, v195
	s_waitcnt lgkmcnt(3)
	v_mfma_f32_32x32x16_bf16 v[48:63], v[240:243], v[104:107], v[48:63]
	ds_read_b128 v[240:243], v198 offset:160
	v_add_f32_e32 v193, v203, v193
	v_add_f32_e32 v195, v204, v195
	v_add_f32_e32 v193, v205, v193
	v_add_f32_e32 v195, v206, v195
	s_waitcnt lgkmcnt(3)
	v_mfma_f32_32x32x16_bf16 v[48:63], v[244:247], v[108:111], v[48:63]
	ds_read_b128 v[244:247], v198 offset:6656
	v_add_f32_e32 v193, v207, v193
	v_add_f32_e32 v195, v208, v195
	v_add_f32_e32 v193, v209, v193
	v_add_f32_e32 v195, v210, v195
	s_waitcnt lgkmcnt(3)
	v_mfma_f32_32x32x16_bf16 v[48:63], v[248:251], v[112:115], v[48:63]
	ds_read_b128 v[248:251], v198 offset:6688
	v_add_f32_e32 v193, v211, v193
	v_add_f32_e32 v195, v212, v195
	v_add_f32_e32 v193, v213, v193
	v_add_f32_e32 v195, v214, v195
	s_waitcnt lgkmcnt(3)
	v_mfma_f32_32x32x16_bf16 v[48:63], v[236:239], v[116:119], v[48:63]
	ds_read_b128 v[236:239], v198 offset:6720
	v_add_f32_e32 v193, v215, v193
	v_add_f32_e32 v195, v216, v195
	v_add_f32_e32 v193, v217, v193
	v_add_f32_e32 v195, v218, v195
	s_waitcnt lgkmcnt(3)
	v_mfma_f32_32x32x16_bf16 v[48:63], v[240:243], v[120:123], v[48:63]
	ds_read_b128 v[240:243], v198 offset:6752
	v_add_f32_e32 v193, v219, v193
	v_add_f32_e32 v195, v220, v195
	v_add_f32_e32 v193, v221, v193
	v_add_f32_e32 v195, v222, v195
	s_waitcnt lgkmcnt(3)
	v_mfma_f32_32x32x16_bf16 v[32:47], v[244:247], v[100:103], 0
	ds_read_b128 v[244:247], v198 offset:6784
	v_add_f32_e32 v193, v223, v193
	v_add_f32_e32 v195, v224, v195
	v_add_f32_e32 v193, v225, v193
	v_add_f32_e32 v195, v226, v195
	s_waitcnt lgkmcnt(3)
	v_mfma_f32_32x32x16_bf16 v[32:47], v[248:251], v[104:107], v[32:47]
	ds_read_b128 v[248:251], v198 offset:6816
	v_add_f32_e32 v193, v195, v193
	v_add_f32_e32 v192, v192, v193
	v_max_f32_e32 v193, v81, v81
	v_max_f32_e32 v195, v80, v80
	s_waitcnt lgkmcnt(3)
	v_mfma_f32_32x32x16_bf16 v[32:47], v[236:239], v[108:111], v[32:47]
	v_max_f32_e32 v193, v195, v193
	v_max3_f32 v193, v193, v82, v83
	v_max3_f32 v193, v193, v84, v85
	v_max3_f32 v193, v193, v86, v87
	s_waitcnt lgkmcnt(2)
	v_mfma_f32_32x32x16_bf16 v[32:47], v[240:243], v[112:115], v[32:47]
	v_max3_f32 v193, v193, v88, v89
	v_max3_f32 v193, v193, v90, v91
	v_max3_f32 v193, v193, v92, v93
	v_max3_f32 v193, v193, v94, v95
	s_waitcnt lgkmcnt(1)
	v_mfma_f32_32x32x16_bf16 v[32:47], v[244:247], v[116:119], v[32:47]
	v_max3_f32 v193, v193, v64, v65
	v_max3_f32 v193, v193, v66, v67
	v_max3_f32 v193, v193, v68, v69
	v_max3_f32 v193, v193, v70, v71
	s_waitcnt lgkmcnt(0)
	v_mfma_f32_32x32x16_bf16 v[32:47], v[248:251], v[120:123], v[32:47]
	v_max3_f32 v193, v193, v72, v73
	v_max3_f32 v193, v193, v74, v75
	v_max3_f32 v193, v193, v76, v77
	v_max3_f32 v193, v193, v78, v79
	v_add_f32_e32 v195, 0x41000000, v191
	v_cmp_gt_f32_e32 vcc, v193, v195
	s_cbranch_vccz .LBB0_2730
	ds_bpermute_b32 v195, v186, v193
	s_waitcnt lgkmcnt(0)
	v_max3_f32 v193, v191, v193, v195
	v_sub_f32_e32 v191, v191, v193
	v_exp_f32_e32 v196, v191
	v_mov_b32_e32 v191, v193
	v_mul_f32_e32 v192, v192, v196
	v_pk_mul_f32 v[30:31], v[30:31], v[196:197] op_sel_hi:[1,0]
	v_pk_mul_f32 v[28:29], v[28:29], v[196:197] op_sel_hi:[1,0]
	v_pk_mul_f32 v[26:27], v[26:27], v[196:197] op_sel_hi:[1,0]
	v_pk_mul_f32 v[24:25], v[24:25], v[196:197] op_sel_hi:[1,0]
	v_pk_mul_f32 v[22:23], v[22:23], v[196:197] op_sel_hi:[1,0]
	v_pk_mul_f32 v[20:21], v[20:21], v[196:197] op_sel_hi:[1,0]
	v_pk_mul_f32 v[18:19], v[18:19], v[196:197] op_sel_hi:[1,0]
	v_pk_mul_f32 v[16:17], v[16:17], v[196:197] op_sel_hi:[1,0]
	v_pk_mul_f32 v[14:15], v[14:15], v[196:197] op_sel_hi:[1,0]
	v_pk_mul_f32 v[12:13], v[12:13], v[196:197] op_sel_hi:[1,0]
	v_pk_mul_f32 v[10:11], v[10:11], v[196:197] op_sel_hi:[1,0]
	v_pk_mul_f32 v[8:9], v[8:9], v[196:197] op_sel_hi:[1,0]
	v_pk_mul_f32 v[6:7], v[6:7], v[196:197] op_sel_hi:[1,0]
	v_pk_mul_f32 v[4:5], v[4:5], v[196:197] op_sel_hi:[1,0]
	v_pk_mul_f32 v[2:3], v[2:3], v[196:197] op_sel_hi:[1,0]
	v_pk_mul_f32 v[0:1], v[0:1], v[196:197] op_sel_hi:[1,0]

.LBB0_2801:
	ds_read_b128 v[128:131], v195
	ds_read_b128 v[132:135], v196
	ds_read_b128 v[136:139], v197
	ds_read_b128 v[140:143], v198
	ds_read_b128 v[170:173], v199
	ds_read_b128 v[174:177], v200
	ds_read_b128 v[178:181], v201
	ds_read_b128 v[182:185], v202
	s_add_u32 s46, s44, 0x100
	s_addc_u32 s47, s45, 0
	s_cmp_eq_u32 s68, 12
	s_cselect_b32 s51, s4, s47
	s_cselect_b32 s50, s5, s46
	s_cselect_b32 s49, s25, s67
	s_cselect_b32 s48, s27, s66
	s_mov_b32 m0, s55
	v_lshl_add_u64 v[190:191], s[44:45], 0, v[162:163]
	ds_read_b128 v[186:189], v192
	ds_read_b128 v[212:215], v192 offset:1024
	ds_read_b128 v[216:219], v192 offset:2048
	ds_read_b128 v[220:223], v192 offset:3072
	ds_read_b128 v[224:227], v192 offset:4096
	ds_read_b128 v[228:231], v192 offset:5120
	ds_read_b128 v[232:235], v192 offset:6144
	ds_read_b128 v[236:239], v192 offset:7168
	global_load_lds_dwordx4 v[190:191], off
	v_lshl_add_u64 v[190:191], s[44:45], 0, v[164:165]
	s_mov_b32 m0, s60
	s_nop 0
	global_load_lds_dwordx4 v[190:191], off
	s_waitcnt vmcnt(8)
	s_waitcnt lgkmcnt(0)
	s_barrier
	s_setprio 1
	s_waitcnt lgkmcnt(0)
	v_mfma_f32_16x16x32_bf16 v[124:127], v[128:131], v[186:189], v[124:127]
	v_mfma_f32_16x16x32_bf16 v[120:123], v[136:139], v[186:189], v[120:123]
	v_mfma_f32_16x16x32_bf16 v[108:111], v[128:131], v[216:219], v[108:111]
	v_mfma_f32_16x16x32_bf16 v[104:107], v[136:139], v[216:219], v[104:107]
	v_mfma_f32_16x16x32_bf16 v[92:95], v[128:131], v[224:227], v[92:95]
	v_mfma_f32_16x16x32_bf16 v[88:91], v[136:139], v[224:227], v[88:91]
	v_mfma_f32_16x16x32_bf16 v[76:79], v[128:131], v[232:235], v[76:79]
	v_mfma_f32_16x16x32_bf16 v[72:75], v[136:139], v[232:235], v[72:75]
	v_mfma_f32_16x16x32_bf16 v[124:127], v[132:135], v[212:215], v[124:127]
	v_mfma_f32_16x16x32_bf16 v[120:123], v[140:143], v[212:215], v[120:123]
	v_mfma_f32_16x16x32_bf16 v[108:111], v[132:135], v[220:223], v[108:111]
	v_mfma_f32_16x16x32_bf16 v[104:107], v[140:143], v[220:223], v[104:107]
	v_mfma_f32_16x16x32_bf16 v[92:95], v[132:135], v[228:231], v[92:95]
	v_mfma_f32_16x16x32_bf16 v[88:91], v[140:143], v[228:231], v[88:91]
	v_mfma_f32_16x16x32_bf16 v[76:79], v[132:135], v[236:239], v[76:79]
	v_mfma_f32_16x16x32_bf16 v[72:75], v[140:143], v[236:239], v[72:75]
	s_setprio 0
	s_setprio 1
	v_mfma_f32_16x16x32_bf16 v[116:119], v[170:173], v[186:189], v[116:119]
	v_mfma_f32_16x16x32_bf16 v[112:115], v[178:181], v[186:189], v[112:115]
	v_mfma_f32_16x16x32_bf16 v[100:103], v[170:173], v[216:219], v[100:103]
	v_mfma_f32_16x16x32_bf16 v[96:99], v[178:181], v[216:219], v[96:99]
	v_mfma_f32_16x16x32_bf16 v[84:87], v[170:173], v[224:227], v[84:87]
	v_mfma_f32_16x16x32_bf16 v[80:83], v[178:181], v[224:227], v[80:83]
	v_mfma_f32_16x16x32_bf16 v[68:71], v[170:173], v[232:235], v[68:71]
	v_mfma_f32_16x16x32_bf16 v[64:67], v[178:181], v[232:235], v[64:67]
	v_mfma_f32_16x16x32_bf16 v[116:119], v[174:177], v[212:215], v[116:119]
	v_mfma_f32_16x16x32_bf16 v[112:115], v[182:185], v[212:215], v[112:115]
	v_mfma_f32_16x16x32_bf16 v[100:103], v[174:177], v[220:223], v[100:103]
	v_mfma_f32_16x16x32_bf16 v[96:99], v[182:185], v[220:223], v[96:99]
	v_mfma_f32_16x16x32_bf16 v[84:87], v[174:177], v[228:231], v[84:87]
	v_mfma_f32_16x16x32_bf16 v[80:83], v[182:185], v[228:231], v[80:83]
	v_mfma_f32_16x16x32_bf16 v[68:71], v[174:177], v[236:239], v[68:71]
	v_mfma_f32_16x16x32_bf16 v[64:67], v[182:185], v[236:239], v[64:67]
	s_setprio 0
	s_barrier
	s_mov_b32 m0, s7
	v_lshl_add_u64 v[190:191], s[48:49], 0, v[158:159]
	s_add_u32 s44, s48, 0x40000
	ds_read_b128 v[186:189], v192 offset:16384
	ds_read_b128 v[212:215], v192 offset:17408
	ds_read_b128 v[216:219], v192 offset:18432
	ds_read_b128 v[220:223], v192 offset:19456
	ds_read_b128 v[224:227], v192 offset:20480
	ds_read_b128 v[228:231], v192 offset:21504
	ds_read_b128 v[232:235], v192 offset:22528
	ds_read_b128 v[236:239], v192 offset:23552
	global_load_lds_dwordx4 v[190:191], off
	v_lshl_add_u64 v[240:241], s[48:49], 0, v[160:161]
	s_mov_b32 m0, s8
	s_addc_u32 s45, s49, 0
	global_load_lds_dwordx4 v[240:241], off
	v_lshl_add_u64 v[242:243], s[44:45], 0, v[158:159]
	s_mov_b32 m0, s9
	v_lshl_add_u64 v[244:245], s[50:51], 0, v[160:161]
	global_load_lds_dwordx4 v[242:243], off
	v_lshl_add_u64 v[242:243], s[44:45], 0, v[160:161]
	s_mov_b32 m0, s23
	s_nop 0
	global_load_lds_dwordx4 v[242:243], off
	v_lshl_add_u64 v[242:243], s[50:51], 0, v[158:159]
	s_mov_b32 m0, s6
	s_nop 0
	global_load_lds_dwordx4 v[242:243], off
	s_mov_b32 m0, s28
	s_nop 0
	global_load_lds_dwordx4 v[244:245], off
	s_waitcnt vmcnt(8)
	s_waitcnt lgkmcnt(0)
	s_barrier
	s_setprio 1
	s_waitcnt lgkmcnt(0)
	v_mfma_f32_16x16x32_bf16 v[60:63], v[128:131], v[186:189], v[60:63]
	v_mfma_f32_16x16x32_bf16 v[56:59], v[136:139], v[186:189], v[56:59]
	v_mfma_f32_16x16x32_bf16 v[44:47], v[128:131], v[216:219], v[44:47]
	v_mfma_f32_16x16x32_bf16 v[40:43], v[136:139], v[216:219], v[40:43]
	v_mfma_f32_16x16x32_bf16 v[28:31], v[128:131], v[224:227], v[28:31]
	v_mfma_f32_16x16x32_bf16 v[24:27], v[136:139], v[224:227], v[24:27]
	v_mfma_f32_16x16x32_bf16 v[12:15], v[128:131], v[232:235], v[12:15]
	v_mfma_f32_16x16x32_bf16 v[8:11], v[136:139], v[232:235], v[8:11]
	v_mfma_f32_16x16x32_bf16 v[60:63], v[132:135], v[212:215], v[60:63]
	v_mfma_f32_16x16x32_bf16 v[56:59], v[140:143], v[212:215], v[56:59]
	v_mfma_f32_16x16x32_bf16 v[44:47], v[132:135], v[220:223], v[44:47]
	v_mfma_f32_16x16x32_bf16 v[40:43], v[140:143], v[220:223], v[40:43]
	v_mfma_f32_16x16x32_bf16 v[28:31], v[132:135], v[228:231], v[28:31]
	v_mfma_f32_16x16x32_bf16 v[24:27], v[140:143], v[228:231], v[24:27]
	v_mfma_f32_16x16x32_bf16 v[12:15], v[132:135], v[236:239], v[12:15]
	v_mfma_f32_16x16x32_bf16 v[8:11], v[140:143], v[236:239], v[8:11]
	s_setprio 0
	s_setprio 1
	v_mfma_f32_16x16x32_bf16 v[52:55], v[170:173], v[186:189], v[52:55]
	v_mfma_f32_16x16x32_bf16 v[48:51], v[178:181], v[186:189], v[48:51]
	v_mfma_f32_16x16x32_bf16 v[36:39], v[170:173], v[216:219], v[36:39]
	v_mfma_f32_16x16x32_bf16 v[32:35], v[178:181], v[216:219], v[32:35]
	v_mfma_f32_16x16x32_bf16 v[20:23], v[170:173], v[224:227], v[20:23]
	v_mfma_f32_16x16x32_bf16 v[16:19], v[178:181], v[224:227], v[16:19]
	v_mfma_f32_16x16x32_bf16 v[4:7], v[170:173], v[232:235], v[4:7]
	v_mfma_f32_16x16x32_bf16 v[0:3], v[178:181], v[232:235], v[0:3]
	v_mfma_f32_16x16x32_bf16 v[52:55], v[174:177], v[212:215], v[52:55]
	v_mfma_f32_16x16x32_bf16 v[48:51], v[182:185], v[212:215], v[48:51]
	v_mfma_f32_16x16x32_bf16 v[36:39], v[174:177], v[220:223], v[36:39]
	v_mfma_f32_16x16x32_bf16 v[32:35], v[182:185], v[220:223], v[32:35]
	v_mfma_f32_16x16x32_bf16 v[20:23], v[174:177], v[228:231], v[20:23]
	v_mfma_f32_16x16x32_bf16 v[16:19], v[182:185], v[228:231], v[16:19]
	v_mfma_f32_16x16x32_bf16 v[4:7], v[174:177], v[236:239], v[4:7]
	v_mfma_f32_16x16x32_bf16 v[0:3], v[182:185], v[236:239], v[0:3]
	s_setprio 0
	s_barrier
	ds_read_b128 v[128:131], v203
	ds_read_b128 v[132:135], v204
	ds_read_b128 v[136:139], v205
	ds_read_b128 v[140:143], v206
	ds_read_b128 v[170:173], v207
	ds_read_b128 v[174:177], v208
	ds_read_b128 v[178:181], v209
	ds_read_b128 v[182:185], v210
	s_add_u32 s44, s50, 0x40000
	s_addc_u32 s45, s51, 0
	s_mov_b32 m0, s29
	v_lshl_add_u64 v[246:247], s[44:45], 0, v[158:159]
	ds_read_b128 v[186:189], v192 offset:32768
	ds_read_b128 v[212:215], v192 offset:33792
	ds_read_b128 v[216:219], v192 offset:34816
	ds_read_b128 v[220:223], v192 offset:35840
	ds_read_b128 v[224:227], v192 offset:36864
	ds_read_b128 v[228:231], v192 offset:37888
	ds_read_b128 v[232:235], v192 offset:38912
	ds_read_b128 v[236:239], v192 offset:39936
	global_load_lds_dwordx4 v[246:247], off
	v_lshl_add_u64 v[246:247], s[44:45], 0, v[160:161]
	s_mov_b32 m0, s30
	s_nop 0
	global_load_lds_dwordx4 v[246:247], off
	s_waitcnt vmcnt(8)
	s_waitcnt lgkmcnt(0)
	s_barrier
	s_setprio 1
	s_waitcnt lgkmcnt(0)
	v_mfma_f32_16x16x32_bf16 v[124:127], v[128:131], v[186:189], v[124:127]
	v_mfma_f32_16x16x32_bf16 v[120:123], v[136:139], v[186:189], v[120:123]
	v_mfma_f32_16x16x32_bf16 v[108:111], v[128:131], v[216:219], v[108:111]
	v_mfma_f32_16x16x32_bf16 v[104:107], v[136:139], v[216:219], v[104:107]
	v_mfma_f32_16x16x32_bf16 v[92:95], v[128:131], v[224:227], v[92:95]
	v_mfma_f32_16x16x32_bf16 v[88:91], v[136:139], v[224:227], v[88:91]
	v_mfma_f32_16x16x32_bf16 v[76:79], v[128:131], v[232:235], v[76:79]
	v_mfma_f32_16x16x32_bf16 v[72:75], v[136:139], v[232:235], v[72:75]
	v_mfma_f32_16x16x32_bf16 v[124:127], v[132:135], v[212:215], v[124:127]
	v_mfma_f32_16x16x32_bf16 v[120:123], v[140:143], v[212:215], v[120:123]
	v_mfma_f32_16x16x32_bf16 v[108:111], v[132:135], v[220:223], v[108:111]
	v_mfma_f32_16x16x32_bf16 v[104:107], v[140:143], v[220:223], v[104:107]
	v_mfma_f32_16x16x32_bf16 v[92:95], v[132:135], v[228:231], v[92:95]
	v_mfma_f32_16x16x32_bf16 v[88:91], v[140:143], v[228:231], v[88:91]
	v_mfma_f32_16x16x32_bf16 v[76:79], v[132:135], v[236:239], v[76:79]
	v_mfma_f32_16x16x32_bf16 v[72:75], v[140:143], v[236:239], v[72:75]
	s_setprio 0
	s_setprio 1
	v_mfma_f32_16x16x32_bf16 v[116:119], v[170:173], v[186:189], v[116:119]
	v_mfma_f32_16x16x32_bf16 v[112:115], v[178:181], v[186:189], v[112:115]
	v_mfma_f32_16x16x32_bf16 v[100:103], v[170:173], v[216:219], v[100:103]
	v_mfma_f32_16x16x32_bf16 v[96:99], v[178:181], v[216:219], v[96:99]
	v_mfma_f32_16x16x32_bf16 v[84:87], v[170:173], v[224:227], v[84:87]
	v_mfma_f32_16x16x32_bf16 v[80:83], v[178:181], v[224:227], v[80:83]
	v_mfma_f32_16x16x32_bf16 v[68:71], v[170:173], v[232:235], v[68:71]
	v_mfma_f32_16x16x32_bf16 v[64:67], v[178:181], v[232:235], v[64:67]
	v_mfma_f32_16x16x32_bf16 v[116:119], v[174:177], v[212:215], v[116:119]
	v_mfma_f32_16x16x32_bf16 v[112:115], v[182:185], v[212:215], v[112:115]
	v_mfma_f32_16x16x32_bf16 v[100:103], v[174:177], v[220:223], v[100:103]
	v_mfma_f32_16x16x32_bf16 v[96:99], v[182:185], v[220:223], v[96:99]
	v_mfma_f32_16x16x32_bf16 v[84:87], v[174:177], v[228:231], v[84:87]
	v_mfma_f32_16x16x32_bf16 v[80:83], v[182:185], v[228:231], v[80:83]
	v_mfma_f32_16x16x32_bf16 v[68:71], v[174:177], v[236:239], v[68:71]
	v_mfma_f32_16x16x32_bf16 v[64:67], v[182:185], v[236:239], v[64:67]
	s_setprio 0
	s_barrier
	s_mov_b32 m0, s31
	v_lshl_add_u64 v[190:191], v[190:191], 0, s[18:19]
	s_add_u32 s44, s48, 0x40080
	ds_read_b128 v[186:189], v192 offset:49152
	ds_read_b128 v[212:215], v192 offset:50176
	ds_read_b128 v[216:219], v192 offset:51200
	ds_read_b128 v[220:223], v192 offset:52224
	ds_read_b128 v[224:227], v192 offset:53248
	ds_read_b128 v[228:231], v192 offset:54272
	ds_read_b128 v[232:235], v192 offset:55296
	ds_read_b128 v[236:239], v192 offset:56320
	global_load_lds_dwordx4 v[190:191], off
	v_lshl_add_u64 v[190:191], v[240:241], 0, s[18:19]
	s_mov_b32 m0, s33
	s_addc_u32 s45, s49, 0
	global_load_lds_dwordx4 v[190:191], off
	v_lshl_add_u64 v[190:191], s[44:45], 0, v[158:159]
	s_mov_b32 m0, s36
	s_nop 0
	global_load_lds_dwordx4 v[190:191], off
	v_lshl_add_u64 v[190:191], s[44:45], 0, v[160:161]
	s_mov_b32 m0, s37
	s_nop 0
	global_load_lds_dwordx4 v[190:191], off
	v_lshl_add_u64 v[190:191], v[242:243], 0, s[18:19]
	s_mov_b32 m0, s34
	s_nop 0
	global_load_lds_dwordx4 v[190:191], off
	v_lshl_add_u64 v[190:191], v[244:245], 0, s[18:19]
	s_mov_b32 m0, s35
	s_nop 0
	global_load_lds_dwordx4 v[190:191], off
	s_waitcnt vmcnt(8)
	s_waitcnt lgkmcnt(0)
	s_barrier
	s_setprio 1
	s_waitcnt lgkmcnt(0)
	v_mfma_f32_16x16x32_bf16 v[60:63], v[128:131], v[186:189], v[60:63]
	v_mfma_f32_16x16x32_bf16 v[56:59], v[136:139], v[186:189], v[56:59]
	v_mfma_f32_16x16x32_bf16 v[44:47], v[128:131], v[216:219], v[44:47]
	v_mfma_f32_16x16x32_bf16 v[40:43], v[136:139], v[216:219], v[40:43]
	v_mfma_f32_16x16x32_bf16 v[28:31], v[128:131], v[224:227], v[28:31]
	v_mfma_f32_16x16x32_bf16 v[24:27], v[136:139], v[224:227], v[24:27]
	v_mfma_f32_16x16x32_bf16 v[12:15], v[128:131], v[232:235], v[12:15]
	v_mfma_f32_16x16x32_bf16 v[8:11], v[136:139], v[232:235], v[8:11]
	v_mfma_f32_16x16x32_bf16 v[60:63], v[132:135], v[212:215], v[60:63]
	v_mfma_f32_16x16x32_bf16 v[56:59], v[140:143], v[212:215], v[56:59]
	v_mfma_f32_16x16x32_bf16 v[44:47], v[132:135], v[220:223], v[44:47]
	v_mfma_f32_16x16x32_bf16 v[40:43], v[140:143], v[220:223], v[40:43]
	v_mfma_f32_16x16x32_bf16 v[28:31], v[132:135], v[228:231], v[28:31]
	v_mfma_f32_16x16x32_bf16 v[24:27], v[140:143], v[228:231], v[24:27]
	v_mfma_f32_16x16x32_bf16 v[12:15], v[132:135], v[236:239], v[12:15]
	v_mfma_f32_16x16x32_bf16 v[8:11], v[140:143], v[236:239], v[8:11]
	s_setprio 0
	s_setprio 1
	v_mfma_f32_16x16x32_bf16 v[52:55], v[170:173], v[186:189], v[52:55]
	v_mfma_f32_16x16x32_bf16 v[48:51], v[178:181], v[186:189], v[48:51]
	v_mfma_f32_16x16x32_bf16 v[36:39], v[170:173], v[216:219], v[36:39]
	v_mfma_f32_16x16x32_bf16 v[32:35], v[178:181], v[216:219], v[32:35]
	v_mfma_f32_16x16x32_bf16 v[20:23], v[170:173], v[224:227], v[20:23]
	v_mfma_f32_16x16x32_bf16 v[16:19], v[178:181], v[224:227], v[16:19]
	v_mfma_f32_16x16x32_bf16 v[4:7], v[170:173], v[232:235], v[4:7]
	v_mfma_f32_16x16x32_bf16 v[0:3], v[178:181], v[232:235], v[0:3]
	v_mfma_f32_16x16x32_bf16 v[52:55], v[174:177], v[212:215], v[52:55]
	v_mfma_f32_16x16x32_bf16 v[48:51], v[182:185], v[212:215], v[48:51]
	v_mfma_f32_16x16x32_bf16 v[36:39], v[174:177], v[220:223], v[36:39]
	v_mfma_f32_16x16x32_bf16 v[32:35], v[182:185], v[220:223], v[32:35]
	v_mfma_f32_16x16x32_bf16 v[20:23], v[174:177], v[228:231], v[20:23]
	v_mfma_f32_16x16x32_bf16 v[16:19], v[182:185], v[228:231], v[16:19]
	v_mfma_f32_16x16x32_bf16 v[4:7], v[174:177], v[236:239], v[4:7]
	v_mfma_f32_16x16x32_bf16 v[0:3], v[182:185], v[236:239], v[0:3]
	s_setprio 0
	s_barrier
	s_add_i32 s68, s68, 2
	s_add_u32 s66, s66, 0x100
	s_addc_u32 s67, s67, 0
	s_cmp_gt_u32 s68, 13
	s_mov_b64 s[44:45], s[46:47]
	s_cbranch_scc0 .LBB0_2801
	s_and_b64 vcc, exec, s[20:21]
	s_cbranch_vccz .LBB0_2804
	s_barrier

.LBB0_2949:
	ds_read_b128 v[172:175], v143
	ds_read_b128 v[176:179], v153
	ds_read_b128 v[180:183], v158
	ds_read_b128 v[184:187], v159
	ds_read_b128 v[188:191], v160
	ds_read_b128 v[196:199], v161
	ds_read_b128 v[200:203], v162
	ds_read_b128 v[204:207], v163
	s_add_u32 s26, s24, 0xfffc0080
	s_addc_u32 s27, s25, -1
	s_cmp_eq_u32 s53, 12
	s_cselect_b32 s37, s4, s27
	s_cselect_b32 s36, s5, s26
	s_cselect_b32 s27, s15, s52
	s_cselect_b32 s26, s17, s51
	s_mov_b32 m0, s47
	v_lshl_add_u64 v[192:193], s[24:25], 0, v[132:133]
	ds_read_b128 v[208:211], v141
	ds_read_b128 v[212:215], v141 offset:1024
	ds_read_b128 v[216:219], v141 offset:2048
	ds_read_b128 v[220:223], v141 offset:3072
	ds_read_b128 v[224:227], v141 offset:4096
	ds_read_b128 v[228:231], v141 offset:5120
	ds_read_b128 v[232:235], v141 offset:6144
	ds_read_b128 v[236:239], v141 offset:7168
	global_load_lds_dwordx4 v[192:193], off
	v_lshl_add_u64 v[192:193], s[24:25], 0, v[134:135]
	s_mov_b32 m0, s48
	s_nop 0
	global_load_lds_dwordx4 v[192:193], off
	s_waitcnt vmcnt(8)
	s_waitcnt lgkmcnt(0)
	s_barrier
	s_setprio 1
	s_waitcnt lgkmcnt(0)
	v_mfma_f32_16x16x32_bf16 v[124:127], v[172:175], v[208:211], v[124:127]
	v_mfma_f32_16x16x32_bf16 v[120:123], v[180:183], v[208:211], v[120:123]
	v_mfma_f32_16x16x32_bf16 v[108:111], v[172:175], v[216:219], v[108:111]
	v_mfma_f32_16x16x32_bf16 v[104:107], v[180:183], v[216:219], v[104:107]
	v_mfma_f32_16x16x32_bf16 v[92:95], v[172:175], v[224:227], v[92:95]
	v_mfma_f32_16x16x32_bf16 v[88:91], v[180:183], v[224:227], v[88:91]
	v_mfma_f32_16x16x32_bf16 v[76:79], v[172:175], v[232:235], v[76:79]
	v_mfma_f32_16x16x32_bf16 v[72:75], v[180:183], v[232:235], v[72:75]
	v_mfma_f32_16x16x32_bf16 v[124:127], v[176:179], v[212:215], v[124:127]
	v_mfma_f32_16x16x32_bf16 v[120:123], v[184:187], v[212:215], v[120:123]
	v_mfma_f32_16x16x32_bf16 v[108:111], v[176:179], v[220:223], v[108:111]
	v_mfma_f32_16x16x32_bf16 v[104:107], v[184:187], v[220:223], v[104:107]
	v_mfma_f32_16x16x32_bf16 v[92:95], v[176:179], v[228:231], v[92:95]
	v_mfma_f32_16x16x32_bf16 v[88:91], v[184:187], v[228:231], v[88:91]
	v_mfma_f32_16x16x32_bf16 v[76:79], v[176:179], v[236:239], v[76:79]
	v_mfma_f32_16x16x32_bf16 v[72:75], v[184:187], v[236:239], v[72:75]
	s_setprio 0
	s_setprio 1
	v_mfma_f32_16x16x32_bf16 v[116:119], v[188:191], v[208:211], v[116:119]
	v_mfma_f32_16x16x32_bf16 v[112:115], v[200:203], v[208:211], v[112:115]
	v_mfma_f32_16x16x32_bf16 v[100:103], v[188:191], v[216:219], v[100:103]
	v_mfma_f32_16x16x32_bf16 v[96:99], v[200:203], v[216:219], v[96:99]
	v_mfma_f32_16x16x32_bf16 v[84:87], v[188:191], v[224:227], v[84:87]
	v_mfma_f32_16x16x32_bf16 v[80:83], v[200:203], v[224:227], v[80:83]
	v_mfma_f32_16x16x32_bf16 v[68:71], v[188:191], v[232:235], v[68:71]
	v_mfma_f32_16x16x32_bf16 v[64:67], v[200:203], v[232:235], v[64:67]
	v_mfma_f32_16x16x32_bf16 v[116:119], v[196:199], v[212:215], v[116:119]
	v_mfma_f32_16x16x32_bf16 v[112:115], v[204:207], v[212:215], v[112:115]
	v_mfma_f32_16x16x32_bf16 v[100:103], v[196:199], v[220:223], v[100:103]
	v_mfma_f32_16x16x32_bf16 v[96:99], v[204:207], v[220:223], v[96:99]
	v_mfma_f32_16x16x32_bf16 v[84:87], v[196:199], v[228:231], v[84:87]
	v_mfma_f32_16x16x32_bf16 v[80:83], v[204:207], v[228:231], v[80:83]
	v_mfma_f32_16x16x32_bf16 v[68:71], v[196:199], v[236:239], v[68:71]
	v_mfma_f32_16x16x32_bf16 v[64:67], v[204:207], v[236:239], v[64:67]
	s_setprio 0
	s_barrier
	s_mov_b32 m0, s23
	v_lshl_add_u64 v[192:193], s[26:27], 0, v[130:131]
	s_add_u32 s54, s26, 0x40000
	ds_read_b128 v[208:211], v141 offset:16384
	ds_read_b128 v[212:215], v141 offset:17408
	ds_read_b128 v[216:219], v141 offset:18432
	ds_read_b128 v[220:223], v141 offset:19456
	ds_read_b128 v[224:227], v141 offset:20480
	ds_read_b128 v[228:231], v141 offset:21504
	ds_read_b128 v[232:235], v141 offset:22528
	ds_read_b128 v[236:239], v141 offset:23552
	global_load_lds_dwordx4 v[192:193], off
	v_lshl_add_u64 v[240:241], s[26:27], 0, v[128:129]
	s_mov_b32 m0, s28
	s_addc_u32 s55, s27, 0
	global_load_lds_dwordx4 v[240:241], off
	v_lshl_add_u64 v[242:243], s[54:55], 0, v[130:131]
	s_mov_b32 m0, s29
	v_lshl_add_u64 v[244:245], s[36:37], 0, v[128:129]
	global_load_lds_dwordx4 v[242:243], off
	v_lshl_add_u64 v[242:243], s[54:55], 0, v[128:129]
	s_mov_b32 m0, s30
	s_nop 0
	global_load_lds_dwordx4 v[242:243], off
	v_lshl_add_u64 v[242:243], s[36:37], 0, v[130:131]
	s_mov_b32 m0, s2
	s_nop 0
	global_load_lds_dwordx4 v[242:243], off
	s_mov_b32 m0, s31
	s_nop 0
	global_load_lds_dwordx4 v[244:245], off
	s_waitcnt vmcnt(8)
	s_waitcnt lgkmcnt(0)
	s_barrier
	s_setprio 1
	s_waitcnt lgkmcnt(0)
	v_mfma_f32_16x16x32_bf16 v[60:63], v[172:175], v[208:211], v[60:63]
	v_mfma_f32_16x16x32_bf16 v[56:59], v[180:183], v[208:211], v[56:59]
	v_mfma_f32_16x16x32_bf16 v[44:47], v[172:175], v[216:219], v[44:47]
	v_mfma_f32_16x16x32_bf16 v[40:43], v[180:183], v[216:219], v[40:43]
	v_mfma_f32_16x16x32_bf16 v[28:31], v[172:175], v[224:227], v[28:31]
	v_mfma_f32_16x16x32_bf16 v[24:27], v[180:183], v[224:227], v[24:27]
	v_mfma_f32_16x16x32_bf16 v[12:15], v[172:175], v[232:235], v[12:15]
	v_mfma_f32_16x16x32_bf16 v[8:11], v[180:183], v[232:235], v[8:11]
	v_mfma_f32_16x16x32_bf16 v[60:63], v[176:179], v[212:215], v[60:63]
	v_mfma_f32_16x16x32_bf16 v[56:59], v[184:187], v[212:215], v[56:59]
	v_mfma_f32_16x16x32_bf16 v[44:47], v[176:179], v[220:223], v[44:47]
	v_mfma_f32_16x16x32_bf16 v[40:43], v[184:187], v[220:223], v[40:43]
	v_mfma_f32_16x16x32_bf16 v[28:31], v[176:179], v[228:231], v[28:31]
	v_mfma_f32_16x16x32_bf16 v[24:27], v[184:187], v[228:231], v[24:27]
	v_mfma_f32_16x16x32_bf16 v[12:15], v[176:179], v[236:239], v[12:15]
	v_mfma_f32_16x16x32_bf16 v[8:11], v[184:187], v[236:239], v[8:11]
	s_setprio 0
	s_setprio 1
	v_mfma_f32_16x16x32_bf16 v[52:55], v[188:191], v[208:211], v[52:55]
	v_mfma_f32_16x16x32_bf16 v[48:51], v[200:203], v[208:211], v[48:51]
	v_mfma_f32_16x16x32_bf16 v[36:39], v[188:191], v[216:219], v[36:39]
	v_mfma_f32_16x16x32_bf16 v[32:35], v[200:203], v[216:219], v[32:35]
	v_mfma_f32_16x16x32_bf16 v[20:23], v[188:191], v[224:227], v[20:23]
	v_mfma_f32_16x16x32_bf16 v[16:19], v[200:203], v[224:227], v[16:19]
	v_mfma_f32_16x16x32_bf16 v[4:7], v[188:191], v[232:235], v[4:7]
	v_mfma_f32_16x16x32_bf16 v[0:3], v[200:203], v[232:235], v[0:3]
	v_mfma_f32_16x16x32_bf16 v[52:55], v[196:199], v[212:215], v[52:55]
	v_mfma_f32_16x16x32_bf16 v[48:51], v[204:207], v[212:215], v[48:51]
	v_mfma_f32_16x16x32_bf16 v[36:39], v[196:199], v[220:223], v[36:39]
	v_mfma_f32_16x16x32_bf16 v[32:35], v[204:207], v[220:223], v[32:35]
	v_mfma_f32_16x16x32_bf16 v[20:23], v[196:199], v[228:231], v[20:23]
	v_mfma_f32_16x16x32_bf16 v[16:19], v[204:207], v[228:231], v[16:19]
	v_mfma_f32_16x16x32_bf16 v[4:7], v[196:199], v[236:239], v[4:7]
	v_mfma_f32_16x16x32_bf16 v[0:3], v[204:207], v[236:239], v[0:3]
	s_setprio 0
	s_barrier
	ds_read_b128 v[172:175], v164
	ds_read_b128 v[176:179], v165
	ds_read_b128 v[180:183], v166
	ds_read_b128 v[184:187], v167
	ds_read_b128 v[188:191], v168
	ds_read_b128 v[196:199], v169
	ds_read_b128 v[200:203], v170
	ds_read_b128 v[204:207], v171
	s_add_u32 s36, s36, 0x40000
	s_addc_u32 s37, s37, 0
	s_mov_b32 m0, s33
	v_lshl_add_u64 v[246:247], s[36:37], 0, v[130:131]
	ds_read_b128 v[208:211], v141 offset:32768
	ds_read_b128 v[212:215], v141 offset:33792
	ds_read_b128 v[216:219], v141 offset:34816
	ds_read_b128 v[220:223], v141 offset:35840
	ds_read_b128 v[224:227], v141 offset:36864
	ds_read_b128 v[228:231], v141 offset:37888
	ds_read_b128 v[232:235], v141 offset:38912
	ds_read_b128 v[236:239], v141 offset:39936
	global_load_lds_dwordx4 v[246:247], off
	v_lshl_add_u64 v[246:247], s[36:37], 0, v[128:129]
	s_mov_b32 m0, s34
	s_nop 0
	global_load_lds_dwordx4 v[246:247], off
	s_waitcnt vmcnt(8)
	s_waitcnt lgkmcnt(0)
	s_barrier
	s_setprio 1
	s_waitcnt lgkmcnt(0)
	v_mfma_f32_16x16x32_bf16 v[124:127], v[172:175], v[208:211], v[124:127]
	v_mfma_f32_16x16x32_bf16 v[120:123], v[180:183], v[208:211], v[120:123]
	v_mfma_f32_16x16x32_bf16 v[108:111], v[172:175], v[216:219], v[108:111]
	v_mfma_f32_16x16x32_bf16 v[104:107], v[180:183], v[216:219], v[104:107]
	v_mfma_f32_16x16x32_bf16 v[92:95], v[172:175], v[224:227], v[92:95]
	v_mfma_f32_16x16x32_bf16 v[88:91], v[180:183], v[224:227], v[88:91]
	v_mfma_f32_16x16x32_bf16 v[76:79], v[172:175], v[232:235], v[76:79]
	v_mfma_f32_16x16x32_bf16 v[72:75], v[180:183], v[232:235], v[72:75]
	v_mfma_f32_16x16x32_bf16 v[124:127], v[176:179], v[212:215], v[124:127]
	v_mfma_f32_16x16x32_bf16 v[120:123], v[184:187], v[212:215], v[120:123]
	v_mfma_f32_16x16x32_bf16 v[108:111], v[176:179], v[220:223], v[108:111]
	v_mfma_f32_16x16x32_bf16 v[104:107], v[184:187], v[220:223], v[104:107]
	v_mfma_f32_16x16x32_bf16 v[92:95], v[176:179], v[228:231], v[92:95]
	v_mfma_f32_16x16x32_bf16 v[88:91], v[184:187], v[228:231], v[88:91]
	v_mfma_f32_16x16x32_bf16 v[76:79], v[176:179], v[236:239], v[76:79]
	v_mfma_f32_16x16x32_bf16 v[72:75], v[184:187], v[236:239], v[72:75]
	s_setprio 0
	s_setprio 1
	v_mfma_f32_16x16x32_bf16 v[116:119], v[188:191], v[208:211], v[116:119]
	v_mfma_f32_16x16x32_bf16 v[112:115], v[200:203], v[208:211], v[112:115]
	v_mfma_f32_16x16x32_bf16 v[100:103], v[188:191], v[216:219], v[100:103]
	v_mfma_f32_16x16x32_bf16 v[96:99], v[200:203], v[216:219], v[96:99]
	v_mfma_f32_16x16x32_bf16 v[84:87], v[188:191], v[224:227], v[84:87]
	v_mfma_f32_16x16x32_bf16 v[80:83], v[200:203], v[224:227], v[80:83]
	v_mfma_f32_16x16x32_bf16 v[68:71], v[188:191], v[232:235], v[68:71]
	v_mfma_f32_16x16x32_bf16 v[64:67], v[200:203], v[232:235], v[64:67]
	v_mfma_f32_16x16x32_bf16 v[116:119], v[196:199], v[212:215], v[116:119]
	v_mfma_f32_16x16x32_bf16 v[112:115], v[204:207], v[212:215], v[112:115]
	v_mfma_f32_16x16x32_bf16 v[100:103], v[196:199], v[220:223], v[100:103]
	v_mfma_f32_16x16x32_bf16 v[96:99], v[204:207], v[220:223], v[96:99]
	v_mfma_f32_16x16x32_bf16 v[84:87], v[196:199], v[228:231], v[84:87]
	v_mfma_f32_16x16x32_bf16 v[80:83], v[204:207], v[228:231], v[80:83]
	v_mfma_f32_16x16x32_bf16 v[68:71], v[196:199], v[236:239], v[68:71]
	v_mfma_f32_16x16x32_bf16 v[64:67], v[204:207], v[236:239], v[64:67]
	s_setprio 0
	s_barrier
	s_mov_b32 m0, s39
	v_lshl_add_u64 v[192:193], v[192:193], 0, s[10:11]
	s_add_u32 s26, s26, 0x40080
	ds_read_b128 v[208:211], v141 offset:49152
	ds_read_b128 v[212:215], v141 offset:50176
	ds_read_b128 v[216:219], v141 offset:51200
	ds_read_b128 v[220:223], v141 offset:52224
	ds_read_b128 v[224:227], v141 offset:53248
	ds_read_b128 v[228:231], v141 offset:54272
	ds_read_b128 v[232:235], v141 offset:55296
	ds_read_b128 v[236:239], v141 offset:56320
	global_load_lds_dwordx4 v[192:193], off
	v_lshl_add_u64 v[192:193], v[240:241], 0, s[10:11]
	s_mov_b32 m0, s40
	s_addc_u32 s27, s27, 0
	global_load_lds_dwordx4 v[192:193], off
	v_lshl_add_u64 v[192:193], s[26:27], 0, v[130:131]
	s_mov_b32 m0, s43
	s_nop 0
	global_load_lds_dwordx4 v[192:193], off
	v_lshl_add_u64 v[192:193], s[26:27], 0, v[128:129]
	s_mov_b32 m0, s44
	s_nop 0
	global_load_lds_dwordx4 v[192:193], off
	v_lshl_add_u64 v[192:193], v[242:243], 0, s[10:11]
	s_mov_b32 m0, s41
	s_nop 0
	global_load_lds_dwordx4 v[192:193], off
	v_lshl_add_u64 v[192:193], v[244:245], 0, s[10:11]
	s_mov_b32 m0, s42
	s_nop 0
	global_load_lds_dwordx4 v[192:193], off
	s_waitcnt vmcnt(8)
	s_waitcnt lgkmcnt(0)
	s_barrier
	s_setprio 1
	s_waitcnt lgkmcnt(0)
	v_mfma_f32_16x16x32_bf16 v[60:63], v[172:175], v[208:211], v[60:63]
	v_mfma_f32_16x16x32_bf16 v[56:59], v[180:183], v[208:211], v[56:59]
	v_mfma_f32_16x16x32_bf16 v[44:47], v[172:175], v[216:219], v[44:47]
	v_mfma_f32_16x16x32_bf16 v[40:43], v[180:183], v[216:219], v[40:43]
	v_mfma_f32_16x16x32_bf16 v[28:31], v[172:175], v[224:227], v[28:31]
	v_mfma_f32_16x16x32_bf16 v[24:27], v[180:183], v[224:227], v[24:27]
	v_mfma_f32_16x16x32_bf16 v[12:15], v[172:175], v[232:235], v[12:15]
	v_mfma_f32_16x16x32_bf16 v[8:11], v[180:183], v[232:235], v[8:11]
	v_mfma_f32_16x16x32_bf16 v[60:63], v[176:179], v[212:215], v[60:63]
	v_mfma_f32_16x16x32_bf16 v[56:59], v[184:187], v[212:215], v[56:59]
	v_mfma_f32_16x16x32_bf16 v[44:47], v[176:179], v[220:223], v[44:47]
	v_mfma_f32_16x16x32_bf16 v[40:43], v[184:187], v[220:223], v[40:43]
	v_mfma_f32_16x16x32_bf16 v[28:31], v[176:179], v[228:231], v[28:31]
	v_mfma_f32_16x16x32_bf16 v[24:27], v[184:187], v[228:231], v[24:27]
	v_mfma_f32_16x16x32_bf16 v[12:15], v[176:179], v[236:239], v[12:15]
	v_mfma_f32_16x16x32_bf16 v[8:11], v[184:187], v[236:239], v[8:11]
	s_setprio 0
	s_setprio 1
	v_mfma_f32_16x16x32_bf16 v[52:55], v[188:191], v[208:211], v[52:55]
	v_mfma_f32_16x16x32_bf16 v[48:51], v[200:203], v[208:211], v[48:51]
	v_mfma_f32_16x16x32_bf16 v[36:39], v[188:191], v[216:219], v[36:39]
	v_mfma_f32_16x16x32_bf16 v[32:35], v[200:203], v[216:219], v[32:35]
	v_mfma_f32_16x16x32_bf16 v[20:23], v[188:191], v[224:227], v[20:23]
	v_mfma_f32_16x16x32_bf16 v[16:19], v[200:203], v[224:227], v[16:19]
	v_mfma_f32_16x16x32_bf16 v[4:7], v[188:191], v[232:235], v[4:7]
	v_mfma_f32_16x16x32_bf16 v[0:3], v[200:203], v[232:235], v[0:3]
	v_mfma_f32_16x16x32_bf16 v[52:55], v[196:199], v[212:215], v[52:55]
	v_mfma_f32_16x16x32_bf16 v[48:51], v[204:207], v[212:215], v[48:51]
	v_mfma_f32_16x16x32_bf16 v[36:39], v[196:199], v[220:223], v[36:39]
	v_mfma_f32_16x16x32_bf16 v[32:35], v[204:207], v[220:223], v[32:35]
	v_mfma_f32_16x16x32_bf16 v[20:23], v[196:199], v[228:231], v[20:23]
	v_mfma_f32_16x16x32_bf16 v[16:19], v[204:207], v[228:231], v[16:19]
	v_mfma_f32_16x16x32_bf16 v[4:7], v[196:199], v[236:239], v[4:7]
	v_mfma_f32_16x16x32_bf16 v[0:3], v[204:207], v[236:239], v[0:3]
	s_setprio 0
	s_barrier
	s_add_i32 s53, s53, 2
	s_add_u32 s24, s24, 0x100
	s_addc_u32 s25, s25, 0
	s_add_u32 s51, s51, 0x100
	s_addc_u32 s52, s52, 0
	s_cmp_gt_u32 s53, 13
	s_cbranch_scc0 .LBB0_2949
	s_and_b64 vcc, exec, s[12:13]
	s_cbranch_vccz .LBB0_2952
	s_barrier

.LBB0_3029:
	ds_read_b128 v[128:131], v195
	ds_read_b128 v[132:135], v196
	ds_read_b128 v[136:139], v197
	ds_read_b128 v[140:143], v198
	ds_read_b128 v[170:173], v199
	ds_read_b128 v[174:177], v200
	ds_read_b128 v[178:181], v201
	ds_read_b128 v[182:185], v202
	s_add_u32 s34, s26, 0x100
	s_addc_u32 s35, s27, 0
	s_cmp_eq_u32 s64, 40
	s_cselect_b32 s39, s11, s35
	s_cselect_b32 s38, s10, s34
	s_cselect_b32 s37, s25, s5
	s_cselect_b32 s36, s24, s4
	s_mov_b32 m0, s50
	v_lshl_add_u64 v[190:191], s[26:27], 0, v[162:163]
	ds_read_b128 v[186:189], v192
	ds_read_b128 v[212:215], v192 offset:1024
	ds_read_b128 v[216:219], v192 offset:2048
	ds_read_b128 v[220:223], v192 offset:3072
	ds_read_b128 v[224:227], v192 offset:4096
	ds_read_b128 v[228:231], v192 offset:5120
	ds_read_b128 v[232:235], v192 offset:6144
	ds_read_b128 v[236:239], v192 offset:7168
	global_load_lds_dwordx4 v[190:191], off
	v_lshl_add_u64 v[190:191], s[26:27], 0, v[164:165]
	s_mov_b32 m0, s51
	s_nop 0
	global_load_lds_dwordx4 v[190:191], off
	s_waitcnt vmcnt(8)
	s_waitcnt lgkmcnt(0)
	s_barrier
	s_setprio 1
	s_waitcnt lgkmcnt(0)
	v_mfma_f32_16x16x32_bf16 v[124:127], v[128:131], v[186:189], v[124:127]
	v_mfma_f32_16x16x32_bf16 v[120:123], v[136:139], v[186:189], v[120:123]
	v_mfma_f32_16x16x32_bf16 v[108:111], v[128:131], v[216:219], v[108:111]
	v_mfma_f32_16x16x32_bf16 v[104:107], v[136:139], v[216:219], v[104:107]
	v_mfma_f32_16x16x32_bf16 v[92:95], v[128:131], v[224:227], v[92:95]
	v_mfma_f32_16x16x32_bf16 v[88:91], v[136:139], v[224:227], v[88:91]
	v_mfma_f32_16x16x32_bf16 v[76:79], v[128:131], v[232:235], v[76:79]
	v_mfma_f32_16x16x32_bf16 v[72:75], v[136:139], v[232:235], v[72:75]
	v_mfma_f32_16x16x32_bf16 v[124:127], v[132:135], v[212:215], v[124:127]
	v_mfma_f32_16x16x32_bf16 v[120:123], v[140:143], v[212:215], v[120:123]
	v_mfma_f32_16x16x32_bf16 v[108:111], v[132:135], v[220:223], v[108:111]
	v_mfma_f32_16x16x32_bf16 v[104:107], v[140:143], v[220:223], v[104:107]
	v_mfma_f32_16x16x32_bf16 v[92:95], v[132:135], v[228:231], v[92:95]
	v_mfma_f32_16x16x32_bf16 v[88:91], v[140:143], v[228:231], v[88:91]
	v_mfma_f32_16x16x32_bf16 v[76:79], v[132:135], v[236:239], v[76:79]
	v_mfma_f32_16x16x32_bf16 v[72:75], v[140:143], v[236:239], v[72:75]
	s_setprio 0
	s_setprio 1
	v_mfma_f32_16x16x32_bf16 v[116:119], v[170:173], v[186:189], v[116:119]
	v_mfma_f32_16x16x32_bf16 v[112:115], v[178:181], v[186:189], v[112:115]
	v_mfma_f32_16x16x32_bf16 v[100:103], v[170:173], v[216:219], v[100:103]
	v_mfma_f32_16x16x32_bf16 v[96:99], v[178:181], v[216:219], v[96:99]
	v_mfma_f32_16x16x32_bf16 v[84:87], v[170:173], v[224:227], v[84:87]
	v_mfma_f32_16x16x32_bf16 v[80:83], v[178:181], v[224:227], v[80:83]
	v_mfma_f32_16x16x32_bf16 v[68:71], v[170:173], v[232:235], v[68:71]
	v_mfma_f32_16x16x32_bf16 v[64:67], v[178:181], v[232:235], v[64:67]
	v_mfma_f32_16x16x32_bf16 v[116:119], v[174:177], v[212:215], v[116:119]
	v_mfma_f32_16x16x32_bf16 v[112:115], v[182:185], v[212:215], v[112:115]
	v_mfma_f32_16x16x32_bf16 v[100:103], v[174:177], v[220:223], v[100:103]
	v_mfma_f32_16x16x32_bf16 v[96:99], v[182:185], v[220:223], v[96:99]
	v_mfma_f32_16x16x32_bf16 v[84:87], v[174:177], v[228:231], v[84:87]
	v_mfma_f32_16x16x32_bf16 v[80:83], v[182:185], v[228:231], v[80:83]
	v_mfma_f32_16x16x32_bf16 v[68:71], v[174:177], v[236:239], v[68:71]
	v_mfma_f32_16x16x32_bf16 v[64:67], v[182:185], v[236:239], v[64:67]
	s_setprio 0
	s_barrier
	s_mov_b32 m0, s7
	v_lshl_add_u64 v[190:191], s[36:37], 0, v[158:159]
	s_add_u32 s26, s36, 0xb0000
	ds_read_b128 v[186:189], v192 offset:16384
	ds_read_b128 v[212:215], v192 offset:17408
	ds_read_b128 v[216:219], v192 offset:18432
	ds_read_b128 v[220:223], v192 offset:19456
	ds_read_b128 v[224:227], v192 offset:20480
	ds_read_b128 v[228:231], v192 offset:21504
	ds_read_b128 v[232:235], v192 offset:22528
	ds_read_b128 v[236:239], v192 offset:23552
	global_load_lds_dwordx4 v[190:191], off
	v_lshl_add_u64 v[240:241], s[36:37], 0, v[160:161]
	s_mov_b32 m0, s23
	s_addc_u32 s27, s37, 0
	global_load_lds_dwordx4 v[240:241], off
	v_lshl_add_u64 v[242:243], s[26:27], 0, v[158:159]
	s_mov_b32 m0, s28
	v_lshl_add_u64 v[244:245], s[38:39], 0, v[160:161]
	global_load_lds_dwordx4 v[242:243], off
	v_lshl_add_u64 v[242:243], s[26:27], 0, v[160:161]
	s_mov_b32 m0, s29
	s_nop 0
	global_load_lds_dwordx4 v[242:243], off
	v_lshl_add_u64 v[242:243], s[38:39], 0, v[158:159]
	s_mov_b32 m0, s6
	s_nop 0
	global_load_lds_dwordx4 v[242:243], off
	s_mov_b32 m0, s30
	s_nop 0
	global_load_lds_dwordx4 v[244:245], off
	s_waitcnt vmcnt(8)
	s_waitcnt lgkmcnt(0)
	s_barrier
	s_setprio 1
	s_waitcnt lgkmcnt(0)
	v_mfma_f32_16x16x32_bf16 v[60:63], v[128:131], v[186:189], v[60:63]
	v_mfma_f32_16x16x32_bf16 v[56:59], v[136:139], v[186:189], v[56:59]
	v_mfma_f32_16x16x32_bf16 v[44:47], v[128:131], v[216:219], v[44:47]
	v_mfma_f32_16x16x32_bf16 v[40:43], v[136:139], v[216:219], v[40:43]
	v_mfma_f32_16x16x32_bf16 v[28:31], v[128:131], v[224:227], v[28:31]
	v_mfma_f32_16x16x32_bf16 v[24:27], v[136:139], v[224:227], v[24:27]
	v_mfma_f32_16x16x32_bf16 v[12:15], v[128:131], v[232:235], v[12:15]
	v_mfma_f32_16x16x32_bf16 v[8:11], v[136:139], v[232:235], v[8:11]
	v_mfma_f32_16x16x32_bf16 v[60:63], v[132:135], v[212:215], v[60:63]
	v_mfma_f32_16x16x32_bf16 v[56:59], v[140:143], v[212:215], v[56:59]
	v_mfma_f32_16x16x32_bf16 v[44:47], v[132:135], v[220:223], v[44:47]
	v_mfma_f32_16x16x32_bf16 v[40:43], v[140:143], v[220:223], v[40:43]
	v_mfma_f32_16x16x32_bf16 v[28:31], v[132:135], v[228:231], v[28:31]
	v_mfma_f32_16x16x32_bf16 v[24:27], v[140:143], v[228:231], v[24:27]
	v_mfma_f32_16x16x32_bf16 v[12:15], v[132:135], v[236:239], v[12:15]
	v_mfma_f32_16x16x32_bf16 v[8:11], v[140:143], v[236:239], v[8:11]
	s_setprio 0
	s_setprio 1
	v_mfma_f32_16x16x32_bf16 v[52:55], v[170:173], v[186:189], v[52:55]
	v_mfma_f32_16x16x32_bf16 v[48:51], v[178:181], v[186:189], v[48:51]
	v_mfma_f32_16x16x32_bf16 v[36:39], v[170:173], v[216:219], v[36:39]
	v_mfma_f32_16x16x32_bf16 v[32:35], v[178:181], v[216:219], v[32:35]
	v_mfma_f32_16x16x32_bf16 v[20:23], v[170:173], v[224:227], v[20:23]
	v_mfma_f32_16x16x32_bf16 v[16:19], v[178:181], v[224:227], v[16:19]
	v_mfma_f32_16x16x32_bf16 v[4:7], v[170:173], v[232:235], v[4:7]
	v_mfma_f32_16x16x32_bf16 v[0:3], v[178:181], v[232:235], v[0:3]
	v_mfma_f32_16x16x32_bf16 v[52:55], v[174:177], v[212:215], v[52:55]
	v_mfma_f32_16x16x32_bf16 v[48:51], v[182:185], v[212:215], v[48:51]
	v_mfma_f32_16x16x32_bf16 v[36:39], v[174:177], v[220:223], v[36:39]
	v_mfma_f32_16x16x32_bf16 v[32:35], v[182:185], v[220:223], v[32:35]
	v_mfma_f32_16x16x32_bf16 v[20:23], v[174:177], v[228:231], v[20:23]
	v_mfma_f32_16x16x32_bf16 v[16:19], v[182:185], v[228:231], v[16:19]
	v_mfma_f32_16x16x32_bf16 v[4:7], v[174:177], v[236:239], v[4:7]
	v_mfma_f32_16x16x32_bf16 v[0:3], v[182:185], v[236:239], v[0:3]
	s_setprio 0
	s_barrier
	ds_read_b128 v[128:131], v203
	ds_read_b128 v[132:135], v204
	ds_read_b128 v[136:139], v205
	ds_read_b128 v[140:143], v206
	ds_read_b128 v[170:173], v207
	ds_read_b128 v[174:177], v208
	ds_read_b128 v[178:181], v209
	ds_read_b128 v[182:185], v210
	s_add_u32 s26, s38, 0xb0000
	s_addc_u32 s27, s39, 0
	s_mov_b32 m0, s31
	v_lshl_add_u64 v[246:247], s[26:27], 0, v[158:159]
	ds_read_b128 v[186:189], v192 offset:32768
	ds_read_b128 v[212:215], v192 offset:33792
	ds_read_b128 v[216:219], v192 offset:34816
	ds_read_b128 v[220:223], v192 offset:35840
	ds_read_b128 v[224:227], v192 offset:36864
	ds_read_b128 v[228:231], v192 offset:37888
	ds_read_b128 v[232:235], v192 offset:38912
	ds_read_b128 v[236:239], v192 offset:39936
	global_load_lds_dwordx4 v[246:247], off
	v_lshl_add_u64 v[246:247], s[26:27], 0, v[160:161]
	s_mov_b32 m0, s33
	s_nop 0
	global_load_lds_dwordx4 v[246:247], off
	s_waitcnt vmcnt(8)
	s_waitcnt lgkmcnt(0)
	s_barrier
	s_setprio 1
	s_waitcnt lgkmcnt(0)
	v_mfma_f32_16x16x32_bf16 v[124:127], v[128:131], v[186:189], v[124:127]
	v_mfma_f32_16x16x32_bf16 v[120:123], v[136:139], v[186:189], v[120:123]
	v_mfma_f32_16x16x32_bf16 v[108:111], v[128:131], v[216:219], v[108:111]
	v_mfma_f32_16x16x32_bf16 v[104:107], v[136:139], v[216:219], v[104:107]
	v_mfma_f32_16x16x32_bf16 v[92:95], v[128:131], v[224:227], v[92:95]
	v_mfma_f32_16x16x32_bf16 v[88:91], v[136:139], v[224:227], v[88:91]
	v_mfma_f32_16x16x32_bf16 v[76:79], v[128:131], v[232:235], v[76:79]
	v_mfma_f32_16x16x32_bf16 v[72:75], v[136:139], v[232:235], v[72:75]
	v_mfma_f32_16x16x32_bf16 v[124:127], v[132:135], v[212:215], v[124:127]
	v_mfma_f32_16x16x32_bf16 v[120:123], v[140:143], v[212:215], v[120:123]
	v_mfma_f32_16x16x32_bf16 v[108:111], v[132:135], v[220:223], v[108:111]
	v_mfma_f32_16x16x32_bf16 v[104:107], v[140:143], v[220:223], v[104:107]
	v_mfma_f32_16x16x32_bf16 v[92:95], v[132:135], v[228:231], v[92:95]
	v_mfma_f32_16x16x32_bf16 v[88:91], v[140:143], v[228:231], v[88:91]
	v_mfma_f32_16x16x32_bf16 v[76:79], v[132:135], v[236:239], v[76:79]
	v_mfma_f32_16x16x32_bf16 v[72:75], v[140:143], v[236:239], v[72:75]
	s_setprio 0
	s_setprio 1
	v_mfma_f32_16x16x32_bf16 v[116:119], v[170:173], v[186:189], v[116:119]
	v_mfma_f32_16x16x32_bf16 v[112:115], v[178:181], v[186:189], v[112:115]
	v_mfma_f32_16x16x32_bf16 v[100:103], v[170:173], v[216:219], v[100:103]
	v_mfma_f32_16x16x32_bf16 v[96:99], v[178:181], v[216:219], v[96:99]
	v_mfma_f32_16x16x32_bf16 v[84:87], v[170:173], v[224:227], v[84:87]
	v_mfma_f32_16x16x32_bf16 v[80:83], v[178:181], v[224:227], v[80:83]
	v_mfma_f32_16x16x32_bf16 v[68:71], v[170:173], v[232:235], v[68:71]
	v_mfma_f32_16x16x32_bf16 v[64:67], v[178:181], v[232:235], v[64:67]
	v_mfma_f32_16x16x32_bf16 v[116:119], v[174:177], v[212:215], v[116:119]
	v_mfma_f32_16x16x32_bf16 v[112:115], v[182:185], v[212:215], v[112:115]
	v_mfma_f32_16x16x32_bf16 v[100:103], v[174:177], v[220:223], v[100:103]
	v_mfma_f32_16x16x32_bf16 v[96:99], v[182:185], v[220:223], v[96:99]
	v_mfma_f32_16x16x32_bf16 v[84:87], v[174:177], v[228:231], v[84:87]
	v_mfma_f32_16x16x32_bf16 v[80:83], v[182:185], v[228:231], v[80:83]
	v_mfma_f32_16x16x32_bf16 v[68:71], v[174:177], v[236:239], v[68:71]
	v_mfma_f32_16x16x32_bf16 v[64:67], v[182:185], v[236:239], v[64:67]
	s_setprio 0
	s_barrier
	s_mov_b32 m0, s40
	v_lshl_add_u64 v[190:191], v[190:191], 0, s[18:19]
	s_add_u32 s26, s36, 0xb0080
	ds_read_b128 v[186:189], v192 offset:49152
	ds_read_b128 v[212:215], v192 offset:50176
	ds_read_b128 v[216:219], v192 offset:51200
	ds_read_b128 v[220:223], v192 offset:52224
	ds_read_b128 v[224:227], v192 offset:53248
	ds_read_b128 v[228:231], v192 offset:54272
	ds_read_b128 v[232:235], v192 offset:55296
	ds_read_b128 v[236:239], v192 offset:56320
	global_load_lds_dwordx4 v[190:191], off
	v_lshl_add_u64 v[190:191], v[240:241], 0, s[18:19]
	s_mov_b32 m0, s41
	s_addc_u32 s27, s37, 0
	global_load_lds_dwordx4 v[190:191], off
	v_lshl_add_u64 v[190:191], s[26:27], 0, v[158:159]
	s_mov_b32 m0, s44
	s_nop 0
	global_load_lds_dwordx4 v[190:191], off
	v_lshl_add_u64 v[190:191], s[26:27], 0, v[160:161]
	s_mov_b32 m0, s45
	s_nop 0
	global_load_lds_dwordx4 v[190:191], off
	v_lshl_add_u64 v[190:191], v[242:243], 0, s[18:19]
	s_mov_b32 m0, s42
	s_nop 0
	global_load_lds_dwordx4 v[190:191], off
	v_lshl_add_u64 v[190:191], v[244:245], 0, s[18:19]
	s_mov_b32 m0, s43
	s_nop 0
	global_load_lds_dwordx4 v[190:191], off
	s_waitcnt vmcnt(8)
	s_waitcnt lgkmcnt(0)
	s_barrier
	s_setprio 1
	s_waitcnt lgkmcnt(0)
	v_mfma_f32_16x16x32_bf16 v[60:63], v[128:131], v[186:189], v[60:63]
	v_mfma_f32_16x16x32_bf16 v[56:59], v[136:139], v[186:189], v[56:59]
	v_mfma_f32_16x16x32_bf16 v[44:47], v[128:131], v[216:219], v[44:47]
	v_mfma_f32_16x16x32_bf16 v[40:43], v[136:139], v[216:219], v[40:43]
	v_mfma_f32_16x16x32_bf16 v[28:31], v[128:131], v[224:227], v[28:31]
	v_mfma_f32_16x16x32_bf16 v[24:27], v[136:139], v[224:227], v[24:27]
	v_mfma_f32_16x16x32_bf16 v[12:15], v[128:131], v[232:235], v[12:15]
	v_mfma_f32_16x16x32_bf16 v[8:11], v[136:139], v[232:235], v[8:11]
	v_mfma_f32_16x16x32_bf16 v[60:63], v[132:135], v[212:215], v[60:63]
	v_mfma_f32_16x16x32_bf16 v[56:59], v[140:143], v[212:215], v[56:59]
	v_mfma_f32_16x16x32_bf16 v[44:47], v[132:135], v[220:223], v[44:47]
	v_mfma_f32_16x16x32_bf16 v[40:43], v[140:143], v[220:223], v[40:43]
	v_mfma_f32_16x16x32_bf16 v[28:31], v[132:135], v[228:231], v[28:31]
	v_mfma_f32_16x16x32_bf16 v[24:27], v[140:143], v[228:231], v[24:27]
	v_mfma_f32_16x16x32_bf16 v[12:15], v[132:135], v[236:239], v[12:15]
	v_mfma_f32_16x16x32_bf16 v[8:11], v[140:143], v[236:239], v[8:11]
	s_setprio 0
	s_setprio 1
	v_mfma_f32_16x16x32_bf16 v[52:55], v[170:173], v[186:189], v[52:55]
	v_mfma_f32_16x16x32_bf16 v[48:51], v[178:181], v[186:189], v[48:51]
	v_mfma_f32_16x16x32_bf16 v[36:39], v[170:173], v[216:219], v[36:39]
	v_mfma_f32_16x16x32_bf16 v[32:35], v[178:181], v[216:219], v[32:35]
	v_mfma_f32_16x16x32_bf16 v[20:23], v[170:173], v[224:227], v[20:23]
	v_mfma_f32_16x16x32_bf16 v[16:19], v[178:181], v[224:227], v[16:19]
	v_mfma_f32_16x16x32_bf16 v[4:7], v[170:173], v[232:235], v[4:7]
	v_mfma_f32_16x16x32_bf16 v[0:3], v[178:181], v[232:235], v[0:3]
	v_mfma_f32_16x16x32_bf16 v[52:55], v[174:177], v[212:215], v[52:55]
	v_mfma_f32_16x16x32_bf16 v[48:51], v[182:185], v[212:215], v[48:51]
	v_mfma_f32_16x16x32_bf16 v[36:39], v[174:177], v[220:223], v[36:39]
	v_mfma_f32_16x16x32_bf16 v[32:35], v[182:185], v[220:223], v[32:35]
	v_mfma_f32_16x16x32_bf16 v[20:23], v[174:177], v[228:231], v[20:23]
	v_mfma_f32_16x16x32_bf16 v[16:19], v[182:185], v[228:231], v[16:19]
	v_mfma_f32_16x16x32_bf16 v[4:7], v[174:177], v[236:239], v[4:7]
	v_mfma_f32_16x16x32_bf16 v[0:3], v[182:185], v[236:239], v[0:3]
	s_setprio 0
	s_barrier
	s_add_i32 s64, s64, 2
	s_add_u32 s4, s4, 0x100
	s_addc_u32 s5, s5, 0
	s_cmp_gt_u32 s64, 41
	s_mov_b64 s[26:27], s[34:35]
	s_cbranch_scc0 .LBB0_3029
	s_and_b64 vcc, exec, s[20:21]
	s_cbranch_vccz .LBB0_3032
	s_barrier

.LBB0_3179:
	ds_read_b128 v[140:143], v154
	ds_read_b128 v[170:173], v155
	ds_read_b128 v[174:177], v156
	ds_read_b128 v[178:181], v157
	ds_read_b128 v[182:185], v158
	ds_read_b128 v[186:189], v159
	ds_read_b128 v[190:193], v160
	ds_read_b128 v[194:197], v161
	s_add_u32 s34, s14, 0xfffc0080
	s_addc_u32 s35, s15, -1
	s_cmp_eq_u32 s54, 12
	s_cselect_b32 s37, s4, s35
	s_cselect_b32 s36, s5, s34
	s_cselect_b32 s35, s11, s25
	s_cselect_b32 s34, s13, s23
	s_mov_b32 m0, s51
	v_lshl_add_u64 v[230:231], s[14:15], 0, v[132:133]
	ds_read_b128 v[198:201], v149
	ds_read_b128 v[202:205], v149 offset:1024
	ds_read_b128 v[206:209], v149 offset:2048
	ds_read_b128 v[210:213], v149 offset:3072
	ds_read_b128 v[214:217], v149 offset:4096
	ds_read_b128 v[218:221], v149 offset:5120
	ds_read_b128 v[222:225], v149 offset:6144
	ds_read_b128 v[226:229], v149 offset:7168
	global_load_lds_dwordx4 v[230:231], off
	v_lshl_add_u64 v[230:231], s[14:15], 0, v[134:135]
	s_mov_b32 m0, s52
	s_nop 0
	global_load_lds_dwordx4 v[230:231], off
	s_waitcnt vmcnt(8)
	s_waitcnt lgkmcnt(0)
	s_barrier
	s_setprio 1
	s_waitcnt lgkmcnt(0)
	v_mfma_f32_16x16x32_bf16 v[124:127], v[140:143], v[198:201], v[124:127]
	v_mfma_f32_16x16x32_bf16 v[120:123], v[174:177], v[198:201], v[120:123]
	v_mfma_f32_16x16x32_bf16 v[108:111], v[140:143], v[206:209], v[108:111]
	v_mfma_f32_16x16x32_bf16 v[104:107], v[174:177], v[206:209], v[104:107]
	v_mfma_f32_16x16x32_bf16 v[92:95], v[140:143], v[214:217], v[92:95]
	v_mfma_f32_16x16x32_bf16 v[88:91], v[174:177], v[214:217], v[88:91]
	v_mfma_f32_16x16x32_bf16 v[76:79], v[140:143], v[222:225], v[76:79]
	v_mfma_f32_16x16x32_bf16 v[72:75], v[174:177], v[222:225], v[72:75]
	v_mfma_f32_16x16x32_bf16 v[124:127], v[170:173], v[202:205], v[124:127]
	v_mfma_f32_16x16x32_bf16 v[120:123], v[178:181], v[202:205], v[120:123]
	v_mfma_f32_16x16x32_bf16 v[108:111], v[170:173], v[210:213], v[108:111]
	v_mfma_f32_16x16x32_bf16 v[104:107], v[178:181], v[210:213], v[104:107]
	v_mfma_f32_16x16x32_bf16 v[92:95], v[170:173], v[218:221], v[92:95]
	v_mfma_f32_16x16x32_bf16 v[88:91], v[178:181], v[218:221], v[88:91]
	v_mfma_f32_16x16x32_bf16 v[76:79], v[170:173], v[226:229], v[76:79]
	v_mfma_f32_16x16x32_bf16 v[72:75], v[178:181], v[226:229], v[72:75]
	s_setprio 0
	s_setprio 1
	v_mfma_f32_16x16x32_bf16 v[116:119], v[182:185], v[198:201], v[116:119]
	v_mfma_f32_16x16x32_bf16 v[112:115], v[190:193], v[198:201], v[112:115]
	v_mfma_f32_16x16x32_bf16 v[100:103], v[182:185], v[206:209], v[100:103]
	v_mfma_f32_16x16x32_bf16 v[96:99], v[190:193], v[206:209], v[96:99]
	v_mfma_f32_16x16x32_bf16 v[84:87], v[182:185], v[214:217], v[84:87]
	v_mfma_f32_16x16x32_bf16 v[80:83], v[190:193], v[214:217], v[80:83]
	v_mfma_f32_16x16x32_bf16 v[68:71], v[182:185], v[222:225], v[68:71]
	v_mfma_f32_16x16x32_bf16 v[64:67], v[190:193], v[222:225], v[64:67]
	v_mfma_f32_16x16x32_bf16 v[116:119], v[186:189], v[202:205], v[116:119]
	v_mfma_f32_16x16x32_bf16 v[112:115], v[194:197], v[202:205], v[112:115]
	v_mfma_f32_16x16x32_bf16 v[100:103], v[186:189], v[210:213], v[100:103]
	v_mfma_f32_16x16x32_bf16 v[96:99], v[194:197], v[210:213], v[96:99]
	v_mfma_f32_16x16x32_bf16 v[84:87], v[186:189], v[218:221], v[84:87]
	v_mfma_f32_16x16x32_bf16 v[80:83], v[194:197], v[218:221], v[80:83]
	v_mfma_f32_16x16x32_bf16 v[68:71], v[186:189], v[226:229], v[68:71]
	v_mfma_f32_16x16x32_bf16 v[64:67], v[194:197], v[226:229], v[64:67]
	s_setprio 0
	s_barrier
	s_mov_b32 m0, s6
	v_lshl_add_u64 v[230:231], s[34:35], 0, v[128:129]
	s_add_u32 s60, s34, 0x40000
	ds_read_b128 v[198:201], v149 offset:16384
	ds_read_b128 v[202:205], v149 offset:17408
	ds_read_b128 v[206:209], v149 offset:18432
	ds_read_b128 v[210:213], v149 offset:19456
	ds_read_b128 v[214:217], v149 offset:20480
	ds_read_b128 v[218:221], v149 offset:21504
	ds_read_b128 v[222:225], v149 offset:22528
	ds_read_b128 v[226:229], v149 offset:23552
	global_load_lds_dwordx4 v[230:231], off
	v_lshl_add_u64 v[232:233], s[34:35], 0, v[130:131]
	s_mov_b32 m0, s7
	s_addc_u32 s61, s35, 0
	global_load_lds_dwordx4 v[232:233], off
	v_lshl_add_u64 v[234:235], s[60:61], 0, v[128:129]
	s_mov_b32 m0, s21
	v_lshl_add_u64 v[236:237], s[36:37], 0, v[130:131]
	global_load_lds_dwordx4 v[234:235], off
	v_lshl_add_u64 v[234:235], s[60:61], 0, v[130:131]
	s_mov_b32 m0, s28
	s_nop 0
	global_load_lds_dwordx4 v[234:235], off
	v_lshl_add_u64 v[234:235], s[36:37], 0, v[128:129]
	s_mov_b32 m0, s2
	s_nop 0
	global_load_lds_dwordx4 v[234:235], off
	s_mov_b32 m0, s29
	s_nop 0
	global_load_lds_dwordx4 v[236:237], off
	s_waitcnt vmcnt(8)
	s_waitcnt lgkmcnt(0)
	s_barrier
	s_setprio 1
	s_waitcnt lgkmcnt(0)
	v_mfma_f32_16x16x32_bf16 v[60:63], v[140:143], v[198:201], v[60:63]
	v_mfma_f32_16x16x32_bf16 v[56:59], v[174:177], v[198:201], v[56:59]
	v_mfma_f32_16x16x32_bf16 v[44:47], v[140:143], v[206:209], v[44:47]
	v_mfma_f32_16x16x32_bf16 v[40:43], v[174:177], v[206:209], v[40:43]
	v_mfma_f32_16x16x32_bf16 v[28:31], v[140:143], v[214:217], v[28:31]
	v_mfma_f32_16x16x32_bf16 v[24:27], v[174:177], v[214:217], v[24:27]
	v_mfma_f32_16x16x32_bf16 v[12:15], v[140:143], v[222:225], v[12:15]
	v_mfma_f32_16x16x32_bf16 v[8:11], v[174:177], v[222:225], v[8:11]
	v_mfma_f32_16x16x32_bf16 v[60:63], v[170:173], v[202:205], v[60:63]
	v_mfma_f32_16x16x32_bf16 v[56:59], v[178:181], v[202:205], v[56:59]
	v_mfma_f32_16x16x32_bf16 v[44:47], v[170:173], v[210:213], v[44:47]
	v_mfma_f32_16x16x32_bf16 v[40:43], v[178:181], v[210:213], v[40:43]
	v_mfma_f32_16x16x32_bf16 v[28:31], v[170:173], v[218:221], v[28:31]
	v_mfma_f32_16x16x32_bf16 v[24:27], v[178:181], v[218:221], v[24:27]
	v_mfma_f32_16x16x32_bf16 v[12:15], v[170:173], v[226:229], v[12:15]
	v_mfma_f32_16x16x32_bf16 v[8:11], v[178:181], v[226:229], v[8:11]
	s_setprio 0
	s_setprio 1
	v_mfma_f32_16x16x32_bf16 v[52:55], v[182:185], v[198:201], v[52:55]
	v_mfma_f32_16x16x32_bf16 v[48:51], v[190:193], v[198:201], v[48:51]
	v_mfma_f32_16x16x32_bf16 v[36:39], v[182:185], v[206:209], v[36:39]
	v_mfma_f32_16x16x32_bf16 v[32:35], v[190:193], v[206:209], v[32:35]
	v_mfma_f32_16x16x32_bf16 v[20:23], v[182:185], v[214:217], v[20:23]
	v_mfma_f32_16x16x32_bf16 v[16:19], v[190:193], v[214:217], v[16:19]
	v_mfma_f32_16x16x32_bf16 v[4:7], v[182:185], v[222:225], v[4:7]
	v_mfma_f32_16x16x32_bf16 v[0:3], v[190:193], v[222:225], v[0:3]
	v_mfma_f32_16x16x32_bf16 v[52:55], v[186:189], v[202:205], v[52:55]
	v_mfma_f32_16x16x32_bf16 v[48:51], v[194:197], v[202:205], v[48:51]
	v_mfma_f32_16x16x32_bf16 v[36:39], v[186:189], v[210:213], v[36:39]
	v_mfma_f32_16x16x32_bf16 v[32:35], v[194:197], v[210:213], v[32:35]
	v_mfma_f32_16x16x32_bf16 v[20:23], v[186:189], v[218:221], v[20:23]
	v_mfma_f32_16x16x32_bf16 v[16:19], v[194:197], v[218:221], v[16:19]
	v_mfma_f32_16x16x32_bf16 v[4:7], v[186:189], v[226:229], v[4:7]
	v_mfma_f32_16x16x32_bf16 v[0:3], v[194:197], v[226:229], v[0:3]
	s_setprio 0
	s_barrier
	ds_read_b128 v[140:143], v162
	ds_read_b128 v[170:173], v163
	ds_read_b128 v[174:177], v164
	ds_read_b128 v[178:181], v165
	ds_read_b128 v[182:185], v166
	ds_read_b128 v[186:189], v167
	ds_read_b128 v[190:193], v168
	ds_read_b128 v[194:197], v169
	s_add_u32 s36, s36, 0x40000
	s_addc_u32 s37, s37, 0
	s_mov_b32 m0, s33
	v_lshl_add_u64 v[238:239], s[36:37], 0, v[128:129]
	ds_read_b128 v[198:201], v149 offset:32768
	ds_read_b128 v[202:205], v149 offset:33792
	ds_read_b128 v[206:209], v149 offset:34816
	ds_read_b128 v[210:213], v149 offset:35840
	ds_read_b128 v[214:217], v149 offset:36864
	ds_read_b128 v[218:221], v149 offset:37888
	ds_read_b128 v[222:225], v149 offset:38912
	ds_read_b128 v[226:229], v149 offset:39936
	global_load_lds_dwordx4 v[238:239], off
	v_lshl_add_u64 v[238:239], s[36:37], 0, v[130:131]
	s_mov_b32 m0, s38
	s_nop 0
	global_load_lds_dwordx4 v[238:239], off
	s_waitcnt vmcnt(8)
	s_waitcnt lgkmcnt(0)
	s_barrier
	s_setprio 1
	s_waitcnt lgkmcnt(0)
	v_mfma_f32_16x16x32_bf16 v[124:127], v[140:143], v[198:201], v[124:127]
	v_mfma_f32_16x16x32_bf16 v[120:123], v[174:177], v[198:201], v[120:123]
	v_mfma_f32_16x16x32_bf16 v[108:111], v[140:143], v[206:209], v[108:111]
	v_mfma_f32_16x16x32_bf16 v[104:107], v[174:177], v[206:209], v[104:107]
	v_mfma_f32_16x16x32_bf16 v[92:95], v[140:143], v[214:217], v[92:95]
	v_mfma_f32_16x16x32_bf16 v[88:91], v[174:177], v[214:217], v[88:91]
	v_mfma_f32_16x16x32_bf16 v[76:79], v[140:143], v[222:225], v[76:79]
	v_mfma_f32_16x16x32_bf16 v[72:75], v[174:177], v[222:225], v[72:75]
	v_mfma_f32_16x16x32_bf16 v[124:127], v[170:173], v[202:205], v[124:127]
	v_mfma_f32_16x16x32_bf16 v[120:123], v[178:181], v[202:205], v[120:123]
	v_mfma_f32_16x16x32_bf16 v[108:111], v[170:173], v[210:213], v[108:111]
	v_mfma_f32_16x16x32_bf16 v[104:107], v[178:181], v[210:213], v[104:107]
	v_mfma_f32_16x16x32_bf16 v[92:95], v[170:173], v[218:221], v[92:95]
	v_mfma_f32_16x16x32_bf16 v[88:91], v[178:181], v[218:221], v[88:91]
	v_mfma_f32_16x16x32_bf16 v[76:79], v[170:173], v[226:229], v[76:79]
	v_mfma_f32_16x16x32_bf16 v[72:75], v[178:181], v[226:229], v[72:75]
	s_setprio 0
	s_setprio 1
	v_mfma_f32_16x16x32_bf16 v[116:119], v[182:185], v[198:201], v[116:119]
	v_mfma_f32_16x16x32_bf16 v[112:115], v[190:193], v[198:201], v[112:115]
	v_mfma_f32_16x16x32_bf16 v[100:103], v[182:185], v[206:209], v[100:103]
	v_mfma_f32_16x16x32_bf16 v[96:99], v[190:193], v[206:209], v[96:99]
	v_mfma_f32_16x16x32_bf16 v[84:87], v[182:185], v[214:217], v[84:87]
	v_mfma_f32_16x16x32_bf16 v[80:83], v[190:193], v[214:217], v[80:83]
	v_mfma_f32_16x16x32_bf16 v[68:71], v[182:185], v[222:225], v[68:71]
	v_mfma_f32_16x16x32_bf16 v[64:67], v[190:193], v[222:225], v[64:67]
	v_mfma_f32_16x16x32_bf16 v[116:119], v[186:189], v[202:205], v[116:119]
	v_mfma_f32_16x16x32_bf16 v[112:115], v[194:197], v[202:205], v[112:115]
	v_mfma_f32_16x16x32_bf16 v[100:103], v[186:189], v[210:213], v[100:103]
	v_mfma_f32_16x16x32_bf16 v[96:99], v[194:197], v[210:213], v[96:99]
	v_mfma_f32_16x16x32_bf16 v[84:87], v[186:189], v[218:221], v[84:87]
	v_mfma_f32_16x16x32_bf16 v[80:83], v[194:197], v[218:221], v[80:83]
	v_mfma_f32_16x16x32_bf16 v[68:71], v[186:189], v[226:229], v[68:71]
	v_mfma_f32_16x16x32_bf16 v[64:67], v[194:197], v[226:229], v[64:67]
	s_setprio 0
	s_barrier
	s_mov_b32 m0, s40
	v_lshl_add_u64 v[230:231], v[230:231], 0, s[16:17]
	s_add_u32 s34, s34, 0x40080
	ds_read_b128 v[198:201], v149 offset:49152
	ds_read_b128 v[202:205], v149 offset:50176
	ds_read_b128 v[206:209], v149 offset:51200
	ds_read_b128 v[210:213], v149 offset:52224
	ds_read_b128 v[214:217], v149 offset:53248
	ds_read_b128 v[218:221], v149 offset:54272
	ds_read_b128 v[222:225], v149 offset:55296
	ds_read_b128 v[226:229], v149 offset:56320
	global_load_lds_dwordx4 v[230:231], off
	v_lshl_add_u64 v[230:231], v[232:233], 0, s[16:17]
	s_mov_b32 m0, s41
	s_addc_u32 s35, s35, 0
	global_load_lds_dwordx4 v[230:231], off
	v_lshl_add_u64 v[230:231], s[34:35], 0, v[128:129]
	s_mov_b32 m0, s44
	s_nop 0
	global_load_lds_dwordx4 v[230:231], off
	v_lshl_add_u64 v[230:231], s[34:35], 0, v[130:131]
	s_mov_b32 m0, s45
	s_nop 0
	global_load_lds_dwordx4 v[230:231], off
	v_lshl_add_u64 v[230:231], v[234:235], 0, s[16:17]
	s_mov_b32 m0, s42
	s_nop 0
	global_load_lds_dwordx4 v[230:231], off
	v_lshl_add_u64 v[230:231], v[236:237], 0, s[16:17]
	s_mov_b32 m0, s43
	s_nop 0
	global_load_lds_dwordx4 v[230:231], off
	s_waitcnt vmcnt(8)
	s_waitcnt lgkmcnt(0)
	s_barrier
	s_setprio 1
	s_waitcnt lgkmcnt(0)
	v_mfma_f32_16x16x32_bf16 v[60:63], v[140:143], v[198:201], v[60:63]
	v_mfma_f32_16x16x32_bf16 v[56:59], v[174:177], v[198:201], v[56:59]
	v_mfma_f32_16x16x32_bf16 v[44:47], v[140:143], v[206:209], v[44:47]
	v_mfma_f32_16x16x32_bf16 v[40:43], v[174:177], v[206:209], v[40:43]
	v_mfma_f32_16x16x32_bf16 v[28:31], v[140:143], v[214:217], v[28:31]
	v_mfma_f32_16x16x32_bf16 v[24:27], v[174:177], v[214:217], v[24:27]
	v_mfma_f32_16x16x32_bf16 v[12:15], v[140:143], v[222:225], v[12:15]
	v_mfma_f32_16x16x32_bf16 v[8:11], v[174:177], v[222:225], v[8:11]
	v_mfma_f32_16x16x32_bf16 v[60:63], v[170:173], v[202:205], v[60:63]
	v_mfma_f32_16x16x32_bf16 v[56:59], v[178:181], v[202:205], v[56:59]
	v_mfma_f32_16x16x32_bf16 v[44:47], v[170:173], v[210:213], v[44:47]
	v_mfma_f32_16x16x32_bf16 v[40:43], v[178:181], v[210:213], v[40:43]
	v_mfma_f32_16x16x32_bf16 v[28:31], v[170:173], v[218:221], v[28:31]
	v_mfma_f32_16x16x32_bf16 v[24:27], v[178:181], v[218:221], v[24:27]
	v_mfma_f32_16x16x32_bf16 v[12:15], v[170:173], v[226:229], v[12:15]
	v_mfma_f32_16x16x32_bf16 v[8:11], v[178:181], v[226:229], v[8:11]
	s_setprio 0
	s_setprio 1
	v_mfma_f32_16x16x32_bf16 v[52:55], v[182:185], v[198:201], v[52:55]
	v_mfma_f32_16x16x32_bf16 v[48:51], v[190:193], v[198:201], v[48:51]
	v_mfma_f32_16x16x32_bf16 v[36:39], v[182:185], v[206:209], v[36:39]
	v_mfma_f32_16x16x32_bf16 v[32:35], v[190:193], v[206:209], v[32:35]
	v_mfma_f32_16x16x32_bf16 v[20:23], v[182:185], v[214:217], v[20:23]
	v_mfma_f32_16x16x32_bf16 v[16:19], v[190:193], v[214:217], v[16:19]
	v_mfma_f32_16x16x32_bf16 v[4:7], v[182:185], v[222:225], v[4:7]
	v_mfma_f32_16x16x32_bf16 v[0:3], v[190:193], v[222:225], v[0:3]
	v_mfma_f32_16x16x32_bf16 v[52:55], v[186:189], v[202:205], v[52:55]
	v_mfma_f32_16x16x32_bf16 v[48:51], v[194:197], v[202:205], v[48:51]
	v_mfma_f32_16x16x32_bf16 v[36:39], v[186:189], v[210:213], v[36:39]
	v_mfma_f32_16x16x32_bf16 v[32:35], v[194:197], v[210:213], v[32:35]
	v_mfma_f32_16x16x32_bf16 v[20:23], v[186:189], v[218:221], v[20:23]
	v_mfma_f32_16x16x32_bf16 v[16:19], v[194:197], v[218:221], v[16:19]
	v_mfma_f32_16x16x32_bf16 v[4:7], v[186:189], v[226:229], v[4:7]
	v_mfma_f32_16x16x32_bf16 v[0:3], v[194:197], v[226:229], v[0:3]
	s_setprio 0
	s_barrier
	s_add_i32 s54, s54, 2
	s_add_u32 s14, s14, 0x100
	s_addc_u32 s15, s15, 0
	s_add_u32 s23, s23, 0x100
	s_addc_u32 s25, s25, 0
	s_cmp_gt_u32 s54, 13
	s_cbranch_scc0 .LBB0_3179
	s_and_b64 vcc, exec, s[18:19]
	s_cbranch_vccz .LBB0_3182
	s_barrier

.LBB0_3534:
	ds_read_b128 v[128:131], v188
	ds_read_b128 v[132:135], v189
	ds_read_b128 v[136:139], v190
	ds_read_b128 v[140:143], v191
	ds_read_b128 v[166:169], v192
	ds_read_b128 v[170:173], v193
	ds_read_b128 v[174:177], v194
	ds_read_b128 v[178:181], v195
	s_add_u32 s34, s30, 0x100
	s_addc_u32 s35, s31, 0
	s_cmp_eq_u32 s68, 12
	s_cselect_b32 s39, s4, s35
	s_cselect_b32 s38, s5, s34
	s_cselect_b32 s37, s21, s67
	s_cselect_b32 s36, s23, s66
	s_mov_b32 m0, s55
	v_lshl_add_u64 v[186:187], s[30:31], 0, v[158:159]
	ds_read_b128 v[182:185], v149
	ds_read_b128 v[206:209], v149 offset:1024
	ds_read_b128 v[210:213], v149 offset:2048
	ds_read_b128 v[214:217], v149 offset:3072
	ds_read_b128 v[218:221], v149 offset:4096
	ds_read_b128 v[222:225], v149 offset:5120
	ds_read_b128 v[226:229], v149 offset:6144
	ds_read_b128 v[230:233], v149 offset:7168
	global_load_lds_dwordx4 v[186:187], off
	v_lshl_add_u64 v[186:187], s[30:31], 0, v[160:161]
	s_mov_b32 m0, s60
	s_nop 0
	global_load_lds_dwordx4 v[186:187], off
	s_waitcnt vmcnt(8)
	s_waitcnt lgkmcnt(0)
	s_barrier
	s_setprio 1
	s_waitcnt lgkmcnt(0)
	v_mfma_f32_16x16x32_bf16 v[124:127], v[128:131], v[182:185], v[124:127]
	v_mfma_f32_16x16x32_bf16 v[120:123], v[136:139], v[182:185], v[120:123]
	v_mfma_f32_16x16x32_bf16 v[108:111], v[128:131], v[210:213], v[108:111]
	v_mfma_f32_16x16x32_bf16 v[104:107], v[136:139], v[210:213], v[104:107]
	v_mfma_f32_16x16x32_bf16 v[92:95], v[128:131], v[218:221], v[92:95]
	v_mfma_f32_16x16x32_bf16 v[88:91], v[136:139], v[218:221], v[88:91]
	v_mfma_f32_16x16x32_bf16 v[76:79], v[128:131], v[226:229], v[76:79]
	v_mfma_f32_16x16x32_bf16 v[72:75], v[136:139], v[226:229], v[72:75]
	v_mfma_f32_16x16x32_bf16 v[124:127], v[132:135], v[206:209], v[124:127]
	v_mfma_f32_16x16x32_bf16 v[120:123], v[140:143], v[206:209], v[120:123]
	v_mfma_f32_16x16x32_bf16 v[108:111], v[132:135], v[214:217], v[108:111]
	v_mfma_f32_16x16x32_bf16 v[104:107], v[140:143], v[214:217], v[104:107]
	v_mfma_f32_16x16x32_bf16 v[92:95], v[132:135], v[222:225], v[92:95]
	v_mfma_f32_16x16x32_bf16 v[88:91], v[140:143], v[222:225], v[88:91]
	v_mfma_f32_16x16x32_bf16 v[76:79], v[132:135], v[230:233], v[76:79]
	v_mfma_f32_16x16x32_bf16 v[72:75], v[140:143], v[230:233], v[72:75]
	s_setprio 0
	s_setprio 1
	v_mfma_f32_16x16x32_bf16 v[116:119], v[166:169], v[182:185], v[116:119]
	v_mfma_f32_16x16x32_bf16 v[112:115], v[174:177], v[182:185], v[112:115]
	v_mfma_f32_16x16x32_bf16 v[100:103], v[166:169], v[210:213], v[100:103]
	v_mfma_f32_16x16x32_bf16 v[96:99], v[174:177], v[210:213], v[96:99]
	v_mfma_f32_16x16x32_bf16 v[84:87], v[166:169], v[218:221], v[84:87]
	v_mfma_f32_16x16x32_bf16 v[80:83], v[174:177], v[218:221], v[80:83]
	v_mfma_f32_16x16x32_bf16 v[68:71], v[166:169], v[226:229], v[68:71]
	v_mfma_f32_16x16x32_bf16 v[64:67], v[174:177], v[226:229], v[64:67]
	v_mfma_f32_16x16x32_bf16 v[116:119], v[170:173], v[206:209], v[116:119]
	v_mfma_f32_16x16x32_bf16 v[112:115], v[178:181], v[206:209], v[112:115]
	v_mfma_f32_16x16x32_bf16 v[100:103], v[170:173], v[214:217], v[100:103]
	v_mfma_f32_16x16x32_bf16 v[96:99], v[178:181], v[214:217], v[96:99]
	v_mfma_f32_16x16x32_bf16 v[84:87], v[170:173], v[222:225], v[84:87]
	v_mfma_f32_16x16x32_bf16 v[80:83], v[178:181], v[222:225], v[80:83]
	v_mfma_f32_16x16x32_bf16 v[68:71], v[170:173], v[230:233], v[68:71]
	v_mfma_f32_16x16x32_bf16 v[64:67], v[178:181], v[230:233], v[64:67]
	s_setprio 0
	s_barrier
	s_mov_b32 m0, s29
	v_lshl_add_u64 v[186:187], s[36:37], 0, v[154:155]
	s_add_u32 s30, s36, 0x40000
	ds_read_b128 v[182:185], v149 offset:16384
	ds_read_b128 v[206:209], v149 offset:17408
	ds_read_b128 v[210:213], v149 offset:18432
	ds_read_b128 v[214:217], v149 offset:19456
	ds_read_b128 v[218:221], v149 offset:20480
	ds_read_b128 v[222:225], v149 offset:21504
	ds_read_b128 v[226:229], v149 offset:22528
	ds_read_b128 v[230:233], v149 offset:23552
	global_load_lds_dwordx4 v[186:187], off
	v_lshl_add_u64 v[234:235], s[36:37], 0, v[156:157]
	s_mov_b32 m0, s33
	s_addc_u32 s31, s37, 0
	global_load_lds_dwordx4 v[234:235], off
	v_lshl_add_u64 v[236:237], s[30:31], 0, v[154:155]
	s_mov_b32 m0, s40
	v_lshl_add_u64 v[238:239], s[38:39], 0, v[156:157]
	global_load_lds_dwordx4 v[236:237], off
	v_lshl_add_u64 v[236:237], s[30:31], 0, v[156:157]
	s_mov_b32 m0, s41
	s_nop 0
	global_load_lds_dwordx4 v[236:237], off
	v_lshl_add_u64 v[236:237], s[38:39], 0, v[154:155]
	s_mov_b32 m0, s19
	s_nop 0
	global_load_lds_dwordx4 v[236:237], off
	s_mov_b32 m0, s42
	s_nop 0
	global_load_lds_dwordx4 v[238:239], off
	s_waitcnt vmcnt(8)
	s_waitcnt lgkmcnt(0)
	s_barrier
	s_setprio 1
	s_waitcnt lgkmcnt(0)
	v_mfma_f32_16x16x32_bf16 v[60:63], v[128:131], v[182:185], v[60:63]
	v_mfma_f32_16x16x32_bf16 v[56:59], v[136:139], v[182:185], v[56:59]
	v_mfma_f32_16x16x32_bf16 v[44:47], v[128:131], v[210:213], v[44:47]
	v_mfma_f32_16x16x32_bf16 v[40:43], v[136:139], v[210:213], v[40:43]
	v_mfma_f32_16x16x32_bf16 v[28:31], v[128:131], v[218:221], v[28:31]
	v_mfma_f32_16x16x32_bf16 v[24:27], v[136:139], v[218:221], v[24:27]
	v_mfma_f32_16x16x32_bf16 v[12:15], v[128:131], v[226:229], v[12:15]
	v_mfma_f32_16x16x32_bf16 v[8:11], v[136:139], v[226:229], v[8:11]
	v_mfma_f32_16x16x32_bf16 v[60:63], v[132:135], v[206:209], v[60:63]
	v_mfma_f32_16x16x32_bf16 v[56:59], v[140:143], v[206:209], v[56:59]
	v_mfma_f32_16x16x32_bf16 v[44:47], v[132:135], v[214:217], v[44:47]
	v_mfma_f32_16x16x32_bf16 v[40:43], v[140:143], v[214:217], v[40:43]
	v_mfma_f32_16x16x32_bf16 v[28:31], v[132:135], v[222:225], v[28:31]
	v_mfma_f32_16x16x32_bf16 v[24:27], v[140:143], v[222:225], v[24:27]
	v_mfma_f32_16x16x32_bf16 v[12:15], v[132:135], v[230:233], v[12:15]
	v_mfma_f32_16x16x32_bf16 v[8:11], v[140:143], v[230:233], v[8:11]
	s_setprio 0
	s_setprio 1
	v_mfma_f32_16x16x32_bf16 v[52:55], v[166:169], v[182:185], v[52:55]
	v_mfma_f32_16x16x32_bf16 v[48:51], v[174:177], v[182:185], v[48:51]
	v_mfma_f32_16x16x32_bf16 v[36:39], v[166:169], v[210:213], v[36:39]
	v_mfma_f32_16x16x32_bf16 v[32:35], v[174:177], v[210:213], v[32:35]
	v_mfma_f32_16x16x32_bf16 v[20:23], v[166:169], v[218:221], v[20:23]
	v_mfma_f32_16x16x32_bf16 v[16:19], v[174:177], v[218:221], v[16:19]
	v_mfma_f32_16x16x32_bf16 v[4:7], v[166:169], v[226:229], v[4:7]
	v_mfma_f32_16x16x32_bf16 v[0:3], v[174:177], v[226:229], v[0:3]
	v_mfma_f32_16x16x32_bf16 v[52:55], v[170:173], v[206:209], v[52:55]
	v_mfma_f32_16x16x32_bf16 v[48:51], v[178:181], v[206:209], v[48:51]
	v_mfma_f32_16x16x32_bf16 v[36:39], v[170:173], v[214:217], v[36:39]
	v_mfma_f32_16x16x32_bf16 v[32:35], v[178:181], v[214:217], v[32:35]
	v_mfma_f32_16x16x32_bf16 v[20:23], v[170:173], v[222:225], v[20:23]
	v_mfma_f32_16x16x32_bf16 v[16:19], v[178:181], v[222:225], v[16:19]
	v_mfma_f32_16x16x32_bf16 v[4:7], v[170:173], v[230:233], v[4:7]
	v_mfma_f32_16x16x32_bf16 v[0:3], v[178:181], v[230:233], v[0:3]
	s_setprio 0
	s_barrier
	ds_read_b128 v[128:131], v196
	ds_read_b128 v[132:135], v197
	ds_read_b128 v[136:139], v198
	ds_read_b128 v[140:143], v199
	ds_read_b128 v[166:169], v200
	ds_read_b128 v[170:173], v201
	ds_read_b128 v[174:177], v202
	ds_read_b128 v[178:181], v203
	s_add_u32 s30, s38, 0x40000
	s_addc_u32 s31, s39, 0
	s_mov_b32 m0, s43
	v_lshl_add_u64 v[240:241], s[30:31], 0, v[154:155]
	ds_read_b128 v[182:185], v149 offset:32768
	ds_read_b128 v[206:209], v149 offset:33792
	ds_read_b128 v[210:213], v149 offset:34816
	ds_read_b128 v[214:217], v149 offset:35840
	ds_read_b128 v[218:221], v149 offset:36864
	ds_read_b128 v[222:225], v149 offset:37888
	ds_read_b128 v[226:229], v149 offset:38912
	ds_read_b128 v[230:233], v149 offset:39936
	global_load_lds_dwordx4 v[240:241], off
	v_lshl_add_u64 v[240:241], s[30:31], 0, v[156:157]
	s_mov_b32 m0, s44
	s_nop 0
	global_load_lds_dwordx4 v[240:241], off
	s_waitcnt vmcnt(8)
	s_waitcnt lgkmcnt(0)
	s_barrier
	s_setprio 1
	s_waitcnt lgkmcnt(0)
	v_mfma_f32_16x16x32_bf16 v[124:127], v[128:131], v[182:185], v[124:127]
	v_mfma_f32_16x16x32_bf16 v[120:123], v[136:139], v[182:185], v[120:123]
	v_mfma_f32_16x16x32_bf16 v[108:111], v[128:131], v[210:213], v[108:111]
	v_mfma_f32_16x16x32_bf16 v[104:107], v[136:139], v[210:213], v[104:107]
	v_mfma_f32_16x16x32_bf16 v[92:95], v[128:131], v[218:221], v[92:95]
	v_mfma_f32_16x16x32_bf16 v[88:91], v[136:139], v[218:221], v[88:91]
	v_mfma_f32_16x16x32_bf16 v[76:79], v[128:131], v[226:229], v[76:79]
	v_mfma_f32_16x16x32_bf16 v[72:75], v[136:139], v[226:229], v[72:75]
	v_mfma_f32_16x16x32_bf16 v[124:127], v[132:135], v[206:209], v[124:127]
	v_mfma_f32_16x16x32_bf16 v[120:123], v[140:143], v[206:209], v[120:123]
	v_mfma_f32_16x16x32_bf16 v[108:111], v[132:135], v[214:217], v[108:111]
	v_mfma_f32_16x16x32_bf16 v[104:107], v[140:143], v[214:217], v[104:107]
	v_mfma_f32_16x16x32_bf16 v[92:95], v[132:135], v[222:225], v[92:95]
	v_mfma_f32_16x16x32_bf16 v[88:91], v[140:143], v[222:225], v[88:91]
	v_mfma_f32_16x16x32_bf16 v[76:79], v[132:135], v[230:233], v[76:79]
	v_mfma_f32_16x16x32_bf16 v[72:75], v[140:143], v[230:233], v[72:75]
	s_setprio 0
	s_setprio 1
	v_mfma_f32_16x16x32_bf16 v[116:119], v[166:169], v[182:185], v[116:119]
	v_mfma_f32_16x16x32_bf16 v[112:115], v[174:177], v[182:185], v[112:115]
	v_mfma_f32_16x16x32_bf16 v[100:103], v[166:169], v[210:213], v[100:103]
	v_mfma_f32_16x16x32_bf16 v[96:99], v[174:177], v[210:213], v[96:99]
	v_mfma_f32_16x16x32_bf16 v[84:87], v[166:169], v[218:221], v[84:87]
	v_mfma_f32_16x16x32_bf16 v[80:83], v[174:177], v[218:221], v[80:83]
	v_mfma_f32_16x16x32_bf16 v[68:71], v[166:169], v[226:229], v[68:71]
	v_mfma_f32_16x16x32_bf16 v[64:67], v[174:177], v[226:229], v[64:67]
	v_mfma_f32_16x16x32_bf16 v[116:119], v[170:173], v[206:209], v[116:119]
	v_mfma_f32_16x16x32_bf16 v[112:115], v[178:181], v[206:209], v[112:115]
	v_mfma_f32_16x16x32_bf16 v[100:103], v[170:173], v[214:217], v[100:103]
	v_mfma_f32_16x16x32_bf16 v[96:99], v[178:181], v[214:217], v[96:99]
	v_mfma_f32_16x16x32_bf16 v[84:87], v[170:173], v[222:225], v[84:87]
	v_mfma_f32_16x16x32_bf16 v[80:83], v[178:181], v[222:225], v[80:83]
	v_mfma_f32_16x16x32_bf16 v[68:71], v[170:173], v[230:233], v[68:71]
	v_mfma_f32_16x16x32_bf16 v[64:67], v[178:181], v[230:233], v[64:67]
	s_setprio 0
	s_barrier
	s_mov_b32 m0, s45
	v_lshl_add_u64 v[186:187], v[186:187], 0, s[14:15]
	s_add_u32 s30, s36, 0x40080
	ds_read_b128 v[182:185], v149 offset:49152
	ds_read_b128 v[206:209], v149 offset:50176
	ds_read_b128 v[210:213], v149 offset:51200
	ds_read_b128 v[214:217], v149 offset:52224
	ds_read_b128 v[218:221], v149 offset:53248
	ds_read_b128 v[222:225], v149 offset:54272
	ds_read_b128 v[226:229], v149 offset:55296
	ds_read_b128 v[230:233], v149 offset:56320
	global_load_lds_dwordx4 v[186:187], off
	v_lshl_add_u64 v[186:187], v[234:235], 0, s[14:15]
	s_mov_b32 m0, s46
	s_addc_u32 s31, s37, 0
	global_load_lds_dwordx4 v[186:187], off
	v_lshl_add_u64 v[186:187], s[30:31], 0, v[154:155]
	s_mov_b32 m0, s49
	s_nop 0
	global_load_lds_dwordx4 v[186:187], off
	v_lshl_add_u64 v[186:187], s[30:31], 0, v[156:157]
	s_mov_b32 m0, s50
	s_nop 0
	global_load_lds_dwordx4 v[186:187], off
	v_lshl_add_u64 v[186:187], v[236:237], 0, s[14:15]
	s_mov_b32 m0, s47
	s_nop 0
	global_load_lds_dwordx4 v[186:187], off
	v_lshl_add_u64 v[186:187], v[238:239], 0, s[14:15]
	s_mov_b32 m0, s48
	s_nop 0
	global_load_lds_dwordx4 v[186:187], off
	s_waitcnt vmcnt(8)
	s_waitcnt lgkmcnt(0)
	s_barrier
	s_setprio 1
	s_waitcnt lgkmcnt(0)
	v_mfma_f32_16x16x32_bf16 v[60:63], v[128:131], v[182:185], v[60:63]
	v_mfma_f32_16x16x32_bf16 v[56:59], v[136:139], v[182:185], v[56:59]
	v_mfma_f32_16x16x32_bf16 v[44:47], v[128:131], v[210:213], v[44:47]
	v_mfma_f32_16x16x32_bf16 v[40:43], v[136:139], v[210:213], v[40:43]
	v_mfma_f32_16x16x32_bf16 v[28:31], v[128:131], v[218:221], v[28:31]
	v_mfma_f32_16x16x32_bf16 v[24:27], v[136:139], v[218:221], v[24:27]
	v_mfma_f32_16x16x32_bf16 v[12:15], v[128:131], v[226:229], v[12:15]
	v_mfma_f32_16x16x32_bf16 v[8:11], v[136:139], v[226:229], v[8:11]
	v_mfma_f32_16x16x32_bf16 v[60:63], v[132:135], v[206:209], v[60:63]
	v_mfma_f32_16x16x32_bf16 v[56:59], v[140:143], v[206:209], v[56:59]
	v_mfma_f32_16x16x32_bf16 v[44:47], v[132:135], v[214:217], v[44:47]
	v_mfma_f32_16x16x32_bf16 v[40:43], v[140:143], v[214:217], v[40:43]
	v_mfma_f32_16x16x32_bf16 v[28:31], v[132:135], v[222:225], v[28:31]
	v_mfma_f32_16x16x32_bf16 v[24:27], v[140:143], v[222:225], v[24:27]
	v_mfma_f32_16x16x32_bf16 v[12:15], v[132:135], v[230:233], v[12:15]
	v_mfma_f32_16x16x32_bf16 v[8:11], v[140:143], v[230:233], v[8:11]
	s_setprio 0
	s_setprio 1
	v_mfma_f32_16x16x32_bf16 v[52:55], v[166:169], v[182:185], v[52:55]
	v_mfma_f32_16x16x32_bf16 v[48:51], v[174:177], v[182:185], v[48:51]
	v_mfma_f32_16x16x32_bf16 v[36:39], v[166:169], v[210:213], v[36:39]
	v_mfma_f32_16x16x32_bf16 v[32:35], v[174:177], v[210:213], v[32:35]
	v_mfma_f32_16x16x32_bf16 v[20:23], v[166:169], v[218:221], v[20:23]
	v_mfma_f32_16x16x32_bf16 v[16:19], v[174:177], v[218:221], v[16:19]
	v_mfma_f32_16x16x32_bf16 v[4:7], v[166:169], v[226:229], v[4:7]
	v_mfma_f32_16x16x32_bf16 v[0:3], v[174:177], v[226:229], v[0:3]
	v_mfma_f32_16x16x32_bf16 v[52:55], v[170:173], v[206:209], v[52:55]
	v_mfma_f32_16x16x32_bf16 v[48:51], v[178:181], v[206:209], v[48:51]
	v_mfma_f32_16x16x32_bf16 v[36:39], v[170:173], v[214:217], v[36:39]
	v_mfma_f32_16x16x32_bf16 v[32:35], v[178:181], v[214:217], v[32:35]
	v_mfma_f32_16x16x32_bf16 v[20:23], v[170:173], v[222:225], v[20:23]
	v_mfma_f32_16x16x32_bf16 v[16:19], v[178:181], v[222:225], v[16:19]
	v_mfma_f32_16x16x32_bf16 v[4:7], v[170:173], v[230:233], v[4:7]
	v_mfma_f32_16x16x32_bf16 v[0:3], v[178:181], v[230:233], v[0:3]
	s_setprio 0
	s_barrier
	s_add_i32 s68, s68, 2
	s_add_u32 s66, s66, 0x100
	s_addc_u32 s67, s67, 0
	s_cmp_gt_u32 s68, 13
	s_mov_b64 s[30:31], s[34:35]
	s_cbranch_scc0 .LBB0_3534
	s_and_b64 vcc, exec, s[16:17]
	s_cbranch_vccz .LBB0_3537
	s_barrier

.LBB0_3663:
	ds_read_b128 v[164:167], v143
	ds_read_b128 v[168:171], v147
	ds_read_b128 v[172:175], v148
	ds_read_b128 v[176:179], v149
	ds_read_b128 v[180:183], v151
	ds_read_b128 v[184:187], v153
	ds_read_b128 v[188:191], v154
	ds_read_b128 v[192:195], v155
	s_add_u32 s24, s22, 0xfffc0080
	s_addc_u32 s25, s23, -1
	s_cmp_eq_u32 s53, 12
	s_cselect_b32 s27, s4, s25
	s_cselect_b32 s26, s5, s24
	s_cselect_b32 s25, s13, s52
	s_cselect_b32 s24, s15, s51
	s_mov_b32 m0, s47
	v_lshl_add_u64 v[228:229], s[22:23], 0, v[132:133]
	ds_read_b128 v[196:199], v141
	ds_read_b128 v[200:203], v141 offset:1024
	ds_read_b128 v[204:207], v141 offset:2048
	ds_read_b128 v[208:211], v141 offset:3072
	ds_read_b128 v[212:215], v141 offset:4096
	ds_read_b128 v[216:219], v141 offset:5120
	ds_read_b128 v[220:223], v141 offset:6144
	ds_read_b128 v[224:227], v141 offset:7168
	global_load_lds_dwordx4 v[228:229], off
	v_lshl_add_u64 v[228:229], s[22:23], 0, v[134:135]
	s_mov_b32 m0, s48
	s_nop 0
	global_load_lds_dwordx4 v[228:229], off
	s_waitcnt vmcnt(8)
	s_waitcnt lgkmcnt(0)
	s_barrier
	s_setprio 1
	s_waitcnt lgkmcnt(0)
	v_mfma_f32_16x16x32_bf16 v[124:127], v[164:167], v[196:199], v[124:127]
	v_mfma_f32_16x16x32_bf16 v[120:123], v[172:175], v[196:199], v[120:123]
	v_mfma_f32_16x16x32_bf16 v[108:111], v[164:167], v[204:207], v[108:111]
	v_mfma_f32_16x16x32_bf16 v[104:107], v[172:175], v[204:207], v[104:107]
	v_mfma_f32_16x16x32_bf16 v[92:95], v[164:167], v[212:215], v[92:95]
	v_mfma_f32_16x16x32_bf16 v[88:91], v[172:175], v[212:215], v[88:91]
	v_mfma_f32_16x16x32_bf16 v[76:79], v[164:167], v[220:223], v[76:79]
	v_mfma_f32_16x16x32_bf16 v[72:75], v[172:175], v[220:223], v[72:75]
	v_mfma_f32_16x16x32_bf16 v[124:127], v[168:171], v[200:203], v[124:127]
	v_mfma_f32_16x16x32_bf16 v[120:123], v[176:179], v[200:203], v[120:123]
	v_mfma_f32_16x16x32_bf16 v[108:111], v[168:171], v[208:211], v[108:111]
	v_mfma_f32_16x16x32_bf16 v[104:107], v[176:179], v[208:211], v[104:107]
	v_mfma_f32_16x16x32_bf16 v[92:95], v[168:171], v[216:219], v[92:95]
	v_mfma_f32_16x16x32_bf16 v[88:91], v[176:179], v[216:219], v[88:91]
	v_mfma_f32_16x16x32_bf16 v[76:79], v[168:171], v[224:227], v[76:79]
	v_mfma_f32_16x16x32_bf16 v[72:75], v[176:179], v[224:227], v[72:75]
	s_setprio 0
	s_setprio 1
	v_mfma_f32_16x16x32_bf16 v[116:119], v[180:183], v[196:199], v[116:119]
	v_mfma_f32_16x16x32_bf16 v[112:115], v[188:191], v[196:199], v[112:115]
	v_mfma_f32_16x16x32_bf16 v[100:103], v[180:183], v[204:207], v[100:103]
	v_mfma_f32_16x16x32_bf16 v[96:99], v[188:191], v[204:207], v[96:99]
	v_mfma_f32_16x16x32_bf16 v[84:87], v[180:183], v[212:215], v[84:87]
	v_mfma_f32_16x16x32_bf16 v[80:83], v[188:191], v[212:215], v[80:83]
	v_mfma_f32_16x16x32_bf16 v[68:71], v[180:183], v[220:223], v[68:71]
	v_mfma_f32_16x16x32_bf16 v[64:67], v[188:191], v[220:223], v[64:67]
	v_mfma_f32_16x16x32_bf16 v[116:119], v[184:187], v[200:203], v[116:119]
	v_mfma_f32_16x16x32_bf16 v[112:115], v[192:195], v[200:203], v[112:115]
	v_mfma_f32_16x16x32_bf16 v[100:103], v[184:187], v[208:211], v[100:103]
	v_mfma_f32_16x16x32_bf16 v[96:99], v[192:195], v[208:211], v[96:99]
	v_mfma_f32_16x16x32_bf16 v[84:87], v[184:187], v[216:219], v[84:87]
	v_mfma_f32_16x16x32_bf16 v[80:83], v[192:195], v[216:219], v[80:83]
	v_mfma_f32_16x16x32_bf16 v[68:71], v[184:187], v[224:227], v[68:71]
	v_mfma_f32_16x16x32_bf16 v[64:67], v[192:195], v[224:227], v[64:67]
	s_setprio 0
	s_barrier
	s_mov_b32 m0, s21
	v_lshl_add_u64 v[228:229], s[24:25], 0, v[130:131]
	s_add_u32 s54, s24, 0x40000
	ds_read_b128 v[196:199], v141 offset:16384
	ds_read_b128 v[200:203], v141 offset:17408
	ds_read_b128 v[204:207], v141 offset:18432
	ds_read_b128 v[208:211], v141 offset:19456
	ds_read_b128 v[212:215], v141 offset:20480
	ds_read_b128 v[216:219], v141 offset:21504
	ds_read_b128 v[220:223], v141 offset:22528
	ds_read_b128 v[224:227], v141 offset:23552
	global_load_lds_dwordx4 v[228:229], off
	v_lshl_add_u64 v[230:231], s[24:25], 0, v[128:129]
	s_mov_b32 m0, s30
	s_addc_u32 s55, s25, 0
	global_load_lds_dwordx4 v[230:231], off
	v_lshl_add_u64 v[232:233], s[54:55], 0, v[130:131]
	s_mov_b32 m0, s31
	v_lshl_add_u64 v[234:235], s[26:27], 0, v[128:129]
	global_load_lds_dwordx4 v[232:233], off
	v_lshl_add_u64 v[232:233], s[54:55], 0, v[128:129]
	s_mov_b32 m0, s33
	s_nop 0
	global_load_lds_dwordx4 v[232:233], off
	v_lshl_add_u64 v[232:233], s[26:27], 0, v[130:131]
	s_mov_b32 m0, s2
	s_nop 0
	global_load_lds_dwordx4 v[232:233], off
	s_mov_b32 m0, s34
	s_nop 0
	global_load_lds_dwordx4 v[234:235], off
	s_waitcnt vmcnt(8)
	s_waitcnt lgkmcnt(0)
	s_barrier
	s_setprio 1
	s_waitcnt lgkmcnt(0)
	v_mfma_f32_16x16x32_bf16 v[60:63], v[164:167], v[196:199], v[60:63]
	v_mfma_f32_16x16x32_bf16 v[56:59], v[172:175], v[196:199], v[56:59]
	v_mfma_f32_16x16x32_bf16 v[44:47], v[164:167], v[204:207], v[44:47]
	v_mfma_f32_16x16x32_bf16 v[40:43], v[172:175], v[204:207], v[40:43]
	v_mfma_f32_16x16x32_bf16 v[28:31], v[164:167], v[212:215], v[28:31]
	v_mfma_f32_16x16x32_bf16 v[24:27], v[172:175], v[212:215], v[24:27]
	v_mfma_f32_16x16x32_bf16 v[12:15], v[164:167], v[220:223], v[12:15]
	v_mfma_f32_16x16x32_bf16 v[8:11], v[172:175], v[220:223], v[8:11]
	v_mfma_f32_16x16x32_bf16 v[60:63], v[168:171], v[200:203], v[60:63]
	v_mfma_f32_16x16x32_bf16 v[56:59], v[176:179], v[200:203], v[56:59]
	v_mfma_f32_16x16x32_bf16 v[44:47], v[168:171], v[208:211], v[44:47]
	v_mfma_f32_16x16x32_bf16 v[40:43], v[176:179], v[208:211], v[40:43]
	v_mfma_f32_16x16x32_bf16 v[28:31], v[168:171], v[216:219], v[28:31]
	v_mfma_f32_16x16x32_bf16 v[24:27], v[176:179], v[216:219], v[24:27]
	v_mfma_f32_16x16x32_bf16 v[12:15], v[168:171], v[224:227], v[12:15]
	v_mfma_f32_16x16x32_bf16 v[8:11], v[176:179], v[224:227], v[8:11]
	s_setprio 0
	s_setprio 1
	v_mfma_f32_16x16x32_bf16 v[52:55], v[180:183], v[196:199], v[52:55]
	v_mfma_f32_16x16x32_bf16 v[48:51], v[188:191], v[196:199], v[48:51]
	v_mfma_f32_16x16x32_bf16 v[36:39], v[180:183], v[204:207], v[36:39]
	v_mfma_f32_16x16x32_bf16 v[32:35], v[188:191], v[204:207], v[32:35]
	v_mfma_f32_16x16x32_bf16 v[20:23], v[180:183], v[212:215], v[20:23]
	v_mfma_f32_16x16x32_bf16 v[16:19], v[188:191], v[212:215], v[16:19]
	v_mfma_f32_16x16x32_bf16 v[4:7], v[180:183], v[220:223], v[4:7]
	v_mfma_f32_16x16x32_bf16 v[0:3], v[188:191], v[220:223], v[0:3]
	v_mfma_f32_16x16x32_bf16 v[52:55], v[184:187], v[200:203], v[52:55]
	v_mfma_f32_16x16x32_bf16 v[48:51], v[192:195], v[200:203], v[48:51]
	v_mfma_f32_16x16x32_bf16 v[36:39], v[184:187], v[208:211], v[36:39]
	v_mfma_f32_16x16x32_bf16 v[32:35], v[192:195], v[208:211], v[32:35]
	v_mfma_f32_16x16x32_bf16 v[20:23], v[184:187], v[216:219], v[20:23]
	v_mfma_f32_16x16x32_bf16 v[16:19], v[192:195], v[216:219], v[16:19]
	v_mfma_f32_16x16x32_bf16 v[4:7], v[184:187], v[224:227], v[4:7]
	v_mfma_f32_16x16x32_bf16 v[0:3], v[192:195], v[224:227], v[0:3]
	s_setprio 0
	s_barrier
	ds_read_b128 v[164:167], v156
	ds_read_b128 v[168:171], v157
	ds_read_b128 v[172:175], v158
	ds_read_b128 v[176:179], v159
	ds_read_b128 v[180:183], v160
	ds_read_b128 v[184:187], v161
	ds_read_b128 v[188:191], v162
	ds_read_b128 v[192:195], v163
	s_add_u32 s26, s26, 0x40000
	s_addc_u32 s27, s27, 0
	s_mov_b32 m0, s35
	v_lshl_add_u64 v[236:237], s[26:27], 0, v[130:131]
	ds_read_b128 v[196:199], v141 offset:32768
	ds_read_b128 v[200:203], v141 offset:33792
	ds_read_b128 v[204:207], v141 offset:34816
	ds_read_b128 v[208:211], v141 offset:35840
	ds_read_b128 v[212:215], v141 offset:36864
	ds_read_b128 v[216:219], v141 offset:37888
	ds_read_b128 v[220:223], v141 offset:38912
	ds_read_b128 v[224:227], v141 offset:39936
	global_load_lds_dwordx4 v[236:237], off
	v_lshl_add_u64 v[236:237], s[26:27], 0, v[128:129]
	s_mov_b32 m0, s36
	s_nop 0
	global_load_lds_dwordx4 v[236:237], off
	s_waitcnt vmcnt(8)
	s_waitcnt lgkmcnt(0)
	s_barrier
	s_setprio 1
	s_waitcnt lgkmcnt(0)
	v_mfma_f32_16x16x32_bf16 v[124:127], v[164:167], v[196:199], v[124:127]
	v_mfma_f32_16x16x32_bf16 v[120:123], v[172:175], v[196:199], v[120:123]
	v_mfma_f32_16x16x32_bf16 v[108:111], v[164:167], v[204:207], v[108:111]
	v_mfma_f32_16x16x32_bf16 v[104:107], v[172:175], v[204:207], v[104:107]
	v_mfma_f32_16x16x32_bf16 v[92:95], v[164:167], v[212:215], v[92:95]
	v_mfma_f32_16x16x32_bf16 v[88:91], v[172:175], v[212:215], v[88:91]
	v_mfma_f32_16x16x32_bf16 v[76:79], v[164:167], v[220:223], v[76:79]
	v_mfma_f32_16x16x32_bf16 v[72:75], v[172:175], v[220:223], v[72:75]
	v_mfma_f32_16x16x32_bf16 v[124:127], v[168:171], v[200:203], v[124:127]
	v_mfma_f32_16x16x32_bf16 v[120:123], v[176:179], v[200:203], v[120:123]
	v_mfma_f32_16x16x32_bf16 v[108:111], v[168:171], v[208:211], v[108:111]
	v_mfma_f32_16x16x32_bf16 v[104:107], v[176:179], v[208:211], v[104:107]
	v_mfma_f32_16x16x32_bf16 v[92:95], v[168:171], v[216:219], v[92:95]
	v_mfma_f32_16x16x32_bf16 v[88:91], v[176:179], v[216:219], v[88:91]
	v_mfma_f32_16x16x32_bf16 v[76:79], v[168:171], v[224:227], v[76:79]
	v_mfma_f32_16x16x32_bf16 v[72:75], v[176:179], v[224:227], v[72:75]
	s_setprio 0
	s_setprio 1
	v_mfma_f32_16x16x32_bf16 v[116:119], v[180:183], v[196:199], v[116:119]
	v_mfma_f32_16x16x32_bf16 v[112:115], v[188:191], v[196:199], v[112:115]
	v_mfma_f32_16x16x32_bf16 v[100:103], v[180:183], v[204:207], v[100:103]
	v_mfma_f32_16x16x32_bf16 v[96:99], v[188:191], v[204:207], v[96:99]
	v_mfma_f32_16x16x32_bf16 v[84:87], v[180:183], v[212:215], v[84:87]
	v_mfma_f32_16x16x32_bf16 v[80:83], v[188:191], v[212:215], v[80:83]
	v_mfma_f32_16x16x32_bf16 v[68:71], v[180:183], v[220:223], v[68:71]
	v_mfma_f32_16x16x32_bf16 v[64:67], v[188:191], v[220:223], v[64:67]
	v_mfma_f32_16x16x32_bf16 v[116:119], v[184:187], v[200:203], v[116:119]
	v_mfma_f32_16x16x32_bf16 v[112:115], v[192:195], v[200:203], v[112:115]
	v_mfma_f32_16x16x32_bf16 v[100:103], v[184:187], v[208:211], v[100:103]
	v_mfma_f32_16x16x32_bf16 v[96:99], v[192:195], v[208:211], v[96:99]
	v_mfma_f32_16x16x32_bf16 v[84:87], v[184:187], v[216:219], v[84:87]
	v_mfma_f32_16x16x32_bf16 v[80:83], v[192:195], v[216:219], v[80:83]
	v_mfma_f32_16x16x32_bf16 v[68:71], v[184:187], v[224:227], v[68:71]
	v_mfma_f32_16x16x32_bf16 v[64:67], v[192:195], v[224:227], v[64:67]
	s_setprio 0
	s_barrier
	s_mov_b32 m0, s39
	v_lshl_add_u64 v[228:229], v[228:229], 0, s[8:9]
	s_add_u32 s24, s24, 0x40080
	ds_read_b128 v[196:199], v141 offset:49152
	ds_read_b128 v[200:203], v141 offset:50176
	ds_read_b128 v[204:207], v141 offset:51200
	ds_read_b128 v[208:211], v141 offset:52224
	ds_read_b128 v[212:215], v141 offset:53248
	ds_read_b128 v[216:219], v141 offset:54272
	ds_read_b128 v[220:223], v141 offset:55296
	ds_read_b128 v[224:227], v141 offset:56320
	global_load_lds_dwordx4 v[228:229], off
	v_lshl_add_u64 v[228:229], v[230:231], 0, s[8:9]
	s_mov_b32 m0, s40
	s_addc_u32 s25, s25, 0
	global_load_lds_dwordx4 v[228:229], off
	v_lshl_add_u64 v[228:229], s[24:25], 0, v[130:131]
	s_mov_b32 m0, s43
	s_nop 0
	global_load_lds_dwordx4 v[228:229], off
	v_lshl_add_u64 v[228:229], s[24:25], 0, v[128:129]
	s_mov_b32 m0, s44
	s_nop 0
	global_load_lds_dwordx4 v[228:229], off
	v_lshl_add_u64 v[228:229], v[232:233], 0, s[8:9]
	s_mov_b32 m0, s41
	s_nop 0
	global_load_lds_dwordx4 v[228:229], off
	v_lshl_add_u64 v[228:229], v[234:235], 0, s[8:9]
	s_mov_b32 m0, s42
	s_nop 0
	global_load_lds_dwordx4 v[228:229], off
	s_waitcnt vmcnt(8)
	s_waitcnt lgkmcnt(0)
	s_barrier
	s_setprio 1
	s_waitcnt lgkmcnt(0)
	v_mfma_f32_16x16x32_bf16 v[60:63], v[164:167], v[196:199], v[60:63]
	v_mfma_f32_16x16x32_bf16 v[56:59], v[172:175], v[196:199], v[56:59]
	v_mfma_f32_16x16x32_bf16 v[44:47], v[164:167], v[204:207], v[44:47]
	v_mfma_f32_16x16x32_bf16 v[40:43], v[172:175], v[204:207], v[40:43]
	v_mfma_f32_16x16x32_bf16 v[28:31], v[164:167], v[212:215], v[28:31]
	v_mfma_f32_16x16x32_bf16 v[24:27], v[172:175], v[212:215], v[24:27]
	v_mfma_f32_16x16x32_bf16 v[12:15], v[164:167], v[220:223], v[12:15]
	v_mfma_f32_16x16x32_bf16 v[8:11], v[172:175], v[220:223], v[8:11]
	v_mfma_f32_16x16x32_bf16 v[60:63], v[168:171], v[200:203], v[60:63]
	v_mfma_f32_16x16x32_bf16 v[56:59], v[176:179], v[200:203], v[56:59]
	v_mfma_f32_16x16x32_bf16 v[44:47], v[168:171], v[208:211], v[44:47]
	v_mfma_f32_16x16x32_bf16 v[40:43], v[176:179], v[208:211], v[40:43]
	v_mfma_f32_16x16x32_bf16 v[28:31], v[168:171], v[216:219], v[28:31]
	v_mfma_f32_16x16x32_bf16 v[24:27], v[176:179], v[216:219], v[24:27]
	v_mfma_f32_16x16x32_bf16 v[12:15], v[168:171], v[224:227], v[12:15]
	v_mfma_f32_16x16x32_bf16 v[8:11], v[176:179], v[224:227], v[8:11]
	s_setprio 0
	s_setprio 1
	v_mfma_f32_16x16x32_bf16 v[52:55], v[180:183], v[196:199], v[52:55]
	v_mfma_f32_16x16x32_bf16 v[48:51], v[188:191], v[196:199], v[48:51]
	v_mfma_f32_16x16x32_bf16 v[36:39], v[180:183], v[204:207], v[36:39]
	v_mfma_f32_16x16x32_bf16 v[32:35], v[188:191], v[204:207], v[32:35]
	v_mfma_f32_16x16x32_bf16 v[20:23], v[180:183], v[212:215], v[20:23]
	v_mfma_f32_16x16x32_bf16 v[16:19], v[188:191], v[212:215], v[16:19]
	v_mfma_f32_16x16x32_bf16 v[4:7], v[180:183], v[220:223], v[4:7]
	v_mfma_f32_16x16x32_bf16 v[0:3], v[188:191], v[220:223], v[0:3]
	v_mfma_f32_16x16x32_bf16 v[52:55], v[184:187], v[200:203], v[52:55]
	v_mfma_f32_16x16x32_bf16 v[48:51], v[192:195], v[200:203], v[48:51]
	v_mfma_f32_16x16x32_bf16 v[36:39], v[184:187], v[208:211], v[36:39]
	v_mfma_f32_16x16x32_bf16 v[32:35], v[192:195], v[208:211], v[32:35]
	v_mfma_f32_16x16x32_bf16 v[20:23], v[184:187], v[216:219], v[20:23]
	v_mfma_f32_16x16x32_bf16 v[16:19], v[192:195], v[216:219], v[16:19]
	v_mfma_f32_16x16x32_bf16 v[4:7], v[184:187], v[224:227], v[4:7]
	v_mfma_f32_16x16x32_bf16 v[0:3], v[192:195], v[224:227], v[0:3]
	s_setprio 0
	s_barrier
	s_add_i32 s53, s53, 2
	s_add_u32 s22, s22, 0x100
	s_addc_u32 s23, s23, 0
	s_add_u32 s51, s51, 0x100
	s_addc_u32 s52, s52, 0
	s_cmp_gt_u32 s53, 13
	s_cbranch_scc0 .LBB0_3663
	s_and_b64 vcc, exec, s[10:11]
	s_cbranch_vccz .LBB0_3666
	s_barrier

.LBB0_3743:
	ds_read_b128 v[128:131], v185
	ds_read_b128 v[132:135], v186
	ds_read_b128 v[136:139], v187
	ds_read_b128 v[140:143], v188
	ds_read_b128 v[162:165], v189
	ds_read_b128 v[166:169], v190
	ds_read_b128 v[170:173], v191
	ds_read_b128 v[174:177], v192
	s_add_u32 s26, s24, 0x100
	s_addc_u32 s27, s25, 0
	s_cmp_eq_u32 s60, 40
	s_cselect_b32 s31, s7, s27
	s_cselect_b32 s30, s6, s26
	s_cselect_b32 s29, s23, s59
	s_cselect_b32 s28, s22, s58
	s_mov_b32 m0, s48
	v_lshl_add_u64 v[182:183], s[24:25], 0, v[146:147]
	ds_read_b128 v[178:181], v153
	ds_read_b128 v[202:205], v153 offset:1024
	ds_read_b128 v[206:209], v153 offset:2048
	ds_read_b128 v[210:213], v153 offset:3072
	ds_read_b128 v[214:217], v153 offset:4096
	ds_read_b128 v[218:221], v153 offset:5120
	ds_read_b128 v[222:225], v153 offset:6144
	ds_read_b128 v[226:229], v153 offset:7168
	global_load_lds_dwordx4 v[182:183], off
	v_lshl_add_u64 v[182:183], s[24:25], 0, v[156:157]
	s_mov_b32 m0, s49
	s_nop 0
	global_load_lds_dwordx4 v[182:183], off
	s_waitcnt vmcnt(8)
	s_waitcnt lgkmcnt(0)
	s_barrier
	s_setprio 1
	s_waitcnt lgkmcnt(0)
	v_mfma_f32_16x16x32_bf16 v[124:127], v[128:131], v[178:181], v[124:127]
	v_mfma_f32_16x16x32_bf16 v[120:123], v[136:139], v[178:181], v[120:123]
	v_mfma_f32_16x16x32_bf16 v[108:111], v[128:131], v[206:209], v[108:111]
	v_mfma_f32_16x16x32_bf16 v[104:107], v[136:139], v[206:209], v[104:107]
	v_mfma_f32_16x16x32_bf16 v[92:95], v[128:131], v[214:217], v[92:95]
	v_mfma_f32_16x16x32_bf16 v[88:91], v[136:139], v[214:217], v[88:91]
	v_mfma_f32_16x16x32_bf16 v[76:79], v[128:131], v[222:225], v[76:79]
	v_mfma_f32_16x16x32_bf16 v[72:75], v[136:139], v[222:225], v[72:75]
	v_mfma_f32_16x16x32_bf16 v[124:127], v[132:135], v[202:205], v[124:127]
	v_mfma_f32_16x16x32_bf16 v[120:123], v[140:143], v[202:205], v[120:123]
	v_mfma_f32_16x16x32_bf16 v[108:111], v[132:135], v[210:213], v[108:111]
	v_mfma_f32_16x16x32_bf16 v[104:107], v[140:143], v[210:213], v[104:107]
	v_mfma_f32_16x16x32_bf16 v[92:95], v[132:135], v[218:221], v[92:95]
	v_mfma_f32_16x16x32_bf16 v[88:91], v[140:143], v[218:221], v[88:91]
	v_mfma_f32_16x16x32_bf16 v[76:79], v[132:135], v[226:229], v[76:79]
	v_mfma_f32_16x16x32_bf16 v[72:75], v[140:143], v[226:229], v[72:75]
	s_setprio 0
	s_setprio 1
	v_mfma_f32_16x16x32_bf16 v[116:119], v[162:165], v[178:181], v[116:119]
	v_mfma_f32_16x16x32_bf16 v[112:115], v[170:173], v[178:181], v[112:115]
	v_mfma_f32_16x16x32_bf16 v[100:103], v[162:165], v[206:209], v[100:103]
	v_mfma_f32_16x16x32_bf16 v[96:99], v[170:173], v[206:209], v[96:99]
	v_mfma_f32_16x16x32_bf16 v[84:87], v[162:165], v[214:217], v[84:87]
	v_mfma_f32_16x16x32_bf16 v[80:83], v[170:173], v[214:217], v[80:83]
	v_mfma_f32_16x16x32_bf16 v[68:71], v[162:165], v[222:225], v[68:71]
	v_mfma_f32_16x16x32_bf16 v[64:67], v[170:173], v[222:225], v[64:67]
	v_mfma_f32_16x16x32_bf16 v[116:119], v[166:169], v[202:205], v[116:119]
	v_mfma_f32_16x16x32_bf16 v[112:115], v[174:177], v[202:205], v[112:115]
	v_mfma_f32_16x16x32_bf16 v[100:103], v[166:169], v[210:213], v[100:103]
	v_mfma_f32_16x16x32_bf16 v[96:99], v[174:177], v[210:213], v[96:99]
	v_mfma_f32_16x16x32_bf16 v[84:87], v[166:169], v[218:221], v[84:87]
	v_mfma_f32_16x16x32_bf16 v[80:83], v[174:177], v[218:221], v[80:83]
	v_mfma_f32_16x16x32_bf16 v[68:71], v[166:169], v[226:229], v[68:71]
	v_mfma_f32_16x16x32_bf16 v[64:67], v[174:177], v[226:229], v[64:67]
	s_setprio 0
	s_barrier
	s_mov_b32 m0, s5
	v_lshl_add_u64 v[182:183], s[28:29], 0, v[148:149]
	s_add_u32 s24, s28, 0xb0000
	ds_read_b128 v[178:181], v153 offset:16384
	ds_read_b128 v[202:205], v153 offset:17408
	ds_read_b128 v[206:209], v153 offset:18432
	ds_read_b128 v[210:213], v153 offset:19456
	ds_read_b128 v[214:217], v153 offset:20480
	ds_read_b128 v[218:221], v153 offset:21504
	ds_read_b128 v[222:225], v153 offset:22528
	ds_read_b128 v[226:229], v153 offset:23552
	global_load_lds_dwordx4 v[182:183], off
	v_lshl_add_u64 v[230:231], s[28:29], 0, v[154:155]
	s_mov_b32 m0, s21
	s_addc_u32 s25, s29, 0
	global_load_lds_dwordx4 v[230:231], off
	v_lshl_add_u64 v[232:233], s[24:25], 0, v[148:149]
	s_mov_b32 m0, s33
	v_lshl_add_u64 v[234:235], s[30:31], 0, v[154:155]
	global_load_lds_dwordx4 v[232:233], off
	v_lshl_add_u64 v[232:233], s[24:25], 0, v[154:155]
	s_mov_b32 m0, s34
	s_nop 0
	global_load_lds_dwordx4 v[232:233], off
	v_lshl_add_u64 v[232:233], s[30:31], 0, v[148:149]
	s_mov_b32 m0, s4
	s_nop 0
	global_load_lds_dwordx4 v[232:233], off
	s_mov_b32 m0, s35
	s_nop 0
	global_load_lds_dwordx4 v[234:235], off
	s_waitcnt vmcnt(8)
	s_waitcnt lgkmcnt(0)
	s_barrier
	s_setprio 1
	s_waitcnt lgkmcnt(0)
	v_mfma_f32_16x16x32_bf16 v[60:63], v[128:131], v[178:181], v[60:63]
	v_mfma_f32_16x16x32_bf16 v[56:59], v[136:139], v[178:181], v[56:59]
	v_mfma_f32_16x16x32_bf16 v[44:47], v[128:131], v[206:209], v[44:47]
	v_mfma_f32_16x16x32_bf16 v[40:43], v[136:139], v[206:209], v[40:43]
	v_mfma_f32_16x16x32_bf16 v[28:31], v[128:131], v[214:217], v[28:31]
	v_mfma_f32_16x16x32_bf16 v[24:27], v[136:139], v[214:217], v[24:27]
	v_mfma_f32_16x16x32_bf16 v[12:15], v[128:131], v[222:225], v[12:15]
	v_mfma_f32_16x16x32_bf16 v[8:11], v[136:139], v[222:225], v[8:11]
	v_mfma_f32_16x16x32_bf16 v[60:63], v[132:135], v[202:205], v[60:63]
	v_mfma_f32_16x16x32_bf16 v[56:59], v[140:143], v[202:205], v[56:59]
	v_mfma_f32_16x16x32_bf16 v[44:47], v[132:135], v[210:213], v[44:47]
	v_mfma_f32_16x16x32_bf16 v[40:43], v[140:143], v[210:213], v[40:43]
	v_mfma_f32_16x16x32_bf16 v[28:31], v[132:135], v[218:221], v[28:31]
	v_mfma_f32_16x16x32_bf16 v[24:27], v[140:143], v[218:221], v[24:27]
	v_mfma_f32_16x16x32_bf16 v[12:15], v[132:135], v[226:229], v[12:15]
	v_mfma_f32_16x16x32_bf16 v[8:11], v[140:143], v[226:229], v[8:11]
	s_setprio 0
	s_setprio 1
	v_mfma_f32_16x16x32_bf16 v[52:55], v[162:165], v[178:181], v[52:55]
	v_mfma_f32_16x16x32_bf16 v[48:51], v[170:173], v[178:181], v[48:51]
	v_mfma_f32_16x16x32_bf16 v[36:39], v[162:165], v[206:209], v[36:39]
	v_mfma_f32_16x16x32_bf16 v[32:35], v[170:173], v[206:209], v[32:35]
	v_mfma_f32_16x16x32_bf16 v[20:23], v[162:165], v[214:217], v[20:23]
	v_mfma_f32_16x16x32_bf16 v[16:19], v[170:173], v[214:217], v[16:19]
	v_mfma_f32_16x16x32_bf16 v[4:7], v[162:165], v[222:225], v[4:7]
	v_mfma_f32_16x16x32_bf16 v[0:3], v[170:173], v[222:225], v[0:3]
	v_mfma_f32_16x16x32_bf16 v[52:55], v[166:169], v[202:205], v[52:55]
	v_mfma_f32_16x16x32_bf16 v[48:51], v[174:177], v[202:205], v[48:51]
	v_mfma_f32_16x16x32_bf16 v[36:39], v[166:169], v[210:213], v[36:39]
	v_mfma_f32_16x16x32_bf16 v[32:35], v[174:177], v[210:213], v[32:35]
	v_mfma_f32_16x16x32_bf16 v[20:23], v[166:169], v[218:221], v[20:23]
	v_mfma_f32_16x16x32_bf16 v[16:19], v[174:177], v[218:221], v[16:19]
	v_mfma_f32_16x16x32_bf16 v[4:7], v[166:169], v[226:229], v[4:7]
	v_mfma_f32_16x16x32_bf16 v[0:3], v[174:177], v[226:229], v[0:3]
	s_setprio 0
	s_barrier
	ds_read_b128 v[128:131], v193
	ds_read_b128 v[132:135], v194
	ds_read_b128 v[136:139], v195
	ds_read_b128 v[140:143], v196
	ds_read_b128 v[162:165], v197
	ds_read_b128 v[166:169], v198
	ds_read_b128 v[170:173], v199
	ds_read_b128 v[174:177], v200
	s_add_u32 s24, s30, 0xb0000
	s_addc_u32 s25, s31, 0
	s_mov_b32 m0, s36
	v_lshl_add_u64 v[236:237], s[24:25], 0, v[148:149]
	ds_read_b128 v[178:181], v153 offset:32768
	ds_read_b128 v[202:205], v153 offset:33792
	ds_read_b128 v[206:209], v153 offset:34816
	ds_read_b128 v[210:213], v153 offset:35840
	ds_read_b128 v[214:217], v153 offset:36864
	ds_read_b128 v[218:221], v153 offset:37888
	ds_read_b128 v[222:225], v153 offset:38912
	ds_read_b128 v[226:229], v153 offset:39936
	global_load_lds_dwordx4 v[236:237], off
	v_lshl_add_u64 v[236:237], s[24:25], 0, v[154:155]
	s_mov_b32 m0, s37
	s_nop 0
	global_load_lds_dwordx4 v[236:237], off
	s_waitcnt vmcnt(8)
	s_waitcnt lgkmcnt(0)
	s_barrier
	s_setprio 1
	s_waitcnt lgkmcnt(0)
	v_mfma_f32_16x16x32_bf16 v[124:127], v[128:131], v[178:181], v[124:127]
	v_mfma_f32_16x16x32_bf16 v[120:123], v[136:139], v[178:181], v[120:123]
	v_mfma_f32_16x16x32_bf16 v[108:111], v[128:131], v[206:209], v[108:111]
	v_mfma_f32_16x16x32_bf16 v[104:107], v[136:139], v[206:209], v[104:107]
	v_mfma_f32_16x16x32_bf16 v[92:95], v[128:131], v[214:217], v[92:95]
	v_mfma_f32_16x16x32_bf16 v[88:91], v[136:139], v[214:217], v[88:91]
	v_mfma_f32_16x16x32_bf16 v[76:79], v[128:131], v[222:225], v[76:79]
	v_mfma_f32_16x16x32_bf16 v[72:75], v[136:139], v[222:225], v[72:75]
	v_mfma_f32_16x16x32_bf16 v[124:127], v[132:135], v[202:205], v[124:127]
	v_mfma_f32_16x16x32_bf16 v[120:123], v[140:143], v[202:205], v[120:123]
	v_mfma_f32_16x16x32_bf16 v[108:111], v[132:135], v[210:213], v[108:111]
	v_mfma_f32_16x16x32_bf16 v[104:107], v[140:143], v[210:213], v[104:107]
	v_mfma_f32_16x16x32_bf16 v[92:95], v[132:135], v[218:221], v[92:95]
	v_mfma_f32_16x16x32_bf16 v[88:91], v[140:143], v[218:221], v[88:91]
	v_mfma_f32_16x16x32_bf16 v[76:79], v[132:135], v[226:229], v[76:79]
	v_mfma_f32_16x16x32_bf16 v[72:75], v[140:143], v[226:229], v[72:75]
	s_setprio 0
	s_setprio 1
	v_mfma_f32_16x16x32_bf16 v[116:119], v[162:165], v[178:181], v[116:119]
	v_mfma_f32_16x16x32_bf16 v[112:115], v[170:173], v[178:181], v[112:115]
	v_mfma_f32_16x16x32_bf16 v[100:103], v[162:165], v[206:209], v[100:103]
	v_mfma_f32_16x16x32_bf16 v[96:99], v[170:173], v[206:209], v[96:99]
	v_mfma_f32_16x16x32_bf16 v[84:87], v[162:165], v[214:217], v[84:87]
	v_mfma_f32_16x16x32_bf16 v[80:83], v[170:173], v[214:217], v[80:83]
	v_mfma_f32_16x16x32_bf16 v[68:71], v[162:165], v[222:225], v[68:71]
	v_mfma_f32_16x16x32_bf16 v[64:67], v[170:173], v[222:225], v[64:67]
	v_mfma_f32_16x16x32_bf16 v[116:119], v[166:169], v[202:205], v[116:119]
	v_mfma_f32_16x16x32_bf16 v[112:115], v[174:177], v[202:205], v[112:115]
	v_mfma_f32_16x16x32_bf16 v[100:103], v[166:169], v[210:213], v[100:103]
	v_mfma_f32_16x16x32_bf16 v[96:99], v[174:177], v[210:213], v[96:99]
	v_mfma_f32_16x16x32_bf16 v[84:87], v[166:169], v[218:221], v[84:87]
	v_mfma_f32_16x16x32_bf16 v[80:83], v[174:177], v[218:221], v[80:83]
	v_mfma_f32_16x16x32_bf16 v[68:71], v[166:169], v[226:229], v[68:71]
	v_mfma_f32_16x16x32_bf16 v[64:67], v[174:177], v[226:229], v[64:67]
	s_setprio 0
	s_barrier
	s_mov_b32 m0, s38
	v_lshl_add_u64 v[182:183], v[182:183], 0, s[16:17]
	s_add_u32 s24, s28, 0xb0080
	ds_read_b128 v[178:181], v153 offset:49152
	ds_read_b128 v[202:205], v153 offset:50176
	ds_read_b128 v[206:209], v153 offset:51200
	ds_read_b128 v[210:213], v153 offset:52224
	ds_read_b128 v[214:217], v153 offset:53248
	ds_read_b128 v[218:221], v153 offset:54272
	ds_read_b128 v[222:225], v153 offset:55296
	ds_read_b128 v[226:229], v153 offset:56320
	global_load_lds_dwordx4 v[182:183], off
	v_lshl_add_u64 v[182:183], v[230:231], 0, s[16:17]
	s_mov_b32 m0, s39
	s_addc_u32 s25, s29, 0
	global_load_lds_dwordx4 v[182:183], off
	v_lshl_add_u64 v[182:183], s[24:25], 0, v[148:149]
	s_mov_b32 m0, s42
	s_nop 0
	global_load_lds_dwordx4 v[182:183], off
	v_lshl_add_u64 v[182:183], s[24:25], 0, v[154:155]
	s_mov_b32 m0, s43
	s_nop 0
	global_load_lds_dwordx4 v[182:183], off
	v_lshl_add_u64 v[182:183], v[232:233], 0, s[16:17]
	s_mov_b32 m0, s40
	s_nop 0
	global_load_lds_dwordx4 v[182:183], off
	v_lshl_add_u64 v[182:183], v[234:235], 0, s[16:17]
	s_mov_b32 m0, s41
	s_nop 0
	global_load_lds_dwordx4 v[182:183], off
	s_waitcnt vmcnt(8)
	s_waitcnt lgkmcnt(0)
	s_barrier
	s_setprio 1
	s_waitcnt lgkmcnt(0)
	v_mfma_f32_16x16x32_bf16 v[60:63], v[128:131], v[178:181], v[60:63]
	v_mfma_f32_16x16x32_bf16 v[56:59], v[136:139], v[178:181], v[56:59]
	v_mfma_f32_16x16x32_bf16 v[44:47], v[128:131], v[206:209], v[44:47]
	v_mfma_f32_16x16x32_bf16 v[40:43], v[136:139], v[206:209], v[40:43]
	v_mfma_f32_16x16x32_bf16 v[28:31], v[128:131], v[214:217], v[28:31]
	v_mfma_f32_16x16x32_bf16 v[24:27], v[136:139], v[214:217], v[24:27]
	v_mfma_f32_16x16x32_bf16 v[12:15], v[128:131], v[222:225], v[12:15]
	v_mfma_f32_16x16x32_bf16 v[8:11], v[136:139], v[222:225], v[8:11]
	v_mfma_f32_16x16x32_bf16 v[60:63], v[132:135], v[202:205], v[60:63]
	v_mfma_f32_16x16x32_bf16 v[56:59], v[140:143], v[202:205], v[56:59]
	v_mfma_f32_16x16x32_bf16 v[44:47], v[132:135], v[210:213], v[44:47]
	v_mfma_f32_16x16x32_bf16 v[40:43], v[140:143], v[210:213], v[40:43]
	v_mfma_f32_16x16x32_bf16 v[28:31], v[132:135], v[218:221], v[28:31]
	v_mfma_f32_16x16x32_bf16 v[24:27], v[140:143], v[218:221], v[24:27]
	v_mfma_f32_16x16x32_bf16 v[12:15], v[132:135], v[226:229], v[12:15]
	v_mfma_f32_16x16x32_bf16 v[8:11], v[140:143], v[226:229], v[8:11]
	s_setprio 0
	s_setprio 1
	v_mfma_f32_16x16x32_bf16 v[52:55], v[162:165], v[178:181], v[52:55]
	v_mfma_f32_16x16x32_bf16 v[48:51], v[170:173], v[178:181], v[48:51]
	v_mfma_f32_16x16x32_bf16 v[36:39], v[162:165], v[206:209], v[36:39]
	v_mfma_f32_16x16x32_bf16 v[32:35], v[170:173], v[206:209], v[32:35]
	v_mfma_f32_16x16x32_bf16 v[20:23], v[162:165], v[214:217], v[20:23]
	v_mfma_f32_16x16x32_bf16 v[16:19], v[170:173], v[214:217], v[16:19]
	v_mfma_f32_16x16x32_bf16 v[4:7], v[162:165], v[222:225], v[4:7]
	v_mfma_f32_16x16x32_bf16 v[0:3], v[170:173], v[222:225], v[0:3]
	v_mfma_f32_16x16x32_bf16 v[52:55], v[166:169], v[202:205], v[52:55]
	v_mfma_f32_16x16x32_bf16 v[48:51], v[174:177], v[202:205], v[48:51]
	v_mfma_f32_16x16x32_bf16 v[36:39], v[166:169], v[210:213], v[36:39]
	v_mfma_f32_16x16x32_bf16 v[32:35], v[174:177], v[210:213], v[32:35]
	v_mfma_f32_16x16x32_bf16 v[20:23], v[166:169], v[218:221], v[20:23]
	v_mfma_f32_16x16x32_bf16 v[16:19], v[174:177], v[218:221], v[16:19]
	v_mfma_f32_16x16x32_bf16 v[4:7], v[166:169], v[226:229], v[4:7]
	v_mfma_f32_16x16x32_bf16 v[0:3], v[174:177], v[226:229], v[0:3]
	s_setprio 0
	s_barrier
	s_add_i32 s60, s60, 2
	s_add_u32 s58, s58, 0x100
	s_addc_u32 s59, s59, 0
	s_cmp_gt_u32 s60, 41
	s_mov_b64 s[24:25], s[26:27]
	s_cbranch_scc0 .LBB0_3743
	s_and_b64 vcc, exec, s[18:19]
	s_cbranch_vccz .LBB0_3746
	s_barrier
